# dv256 far-tile fast path: no S-tile register copies, skip alpha calc when max unchanged; m0 save/restore removed; GEMM L-phase ds_reads before DMA issue
# speedup vs baseline: 1.0064x; 1.0064x over previous
; __device__ __forceinline__ int tid_of(int wave) { return opqv(wave * 64 + (int)__builtin_amdgcn_mbcnt_hi(~0u, __builtin_amdgcn_mbcnt_lo(~0u, 0u))); }
; __host__ __device__ __forceinline__ int lds_byte(int r, int c) { return (r >> 3) * 1024 + (r & 7) * 128 + ((((c >> 3)) ^ ((r >> 1) & 7)) << 4) + (c & 7) * 2; }
; #define PG8_WAIT_V(n) asm volatile("s_waitcnt vmcnt(" #n ")" ::: "memory")
; #define PG8_BAR __builtin_amdgcn_s_barrier()
; template <class Epi>
; __device__ __forceinline__ void gemm_phase(LAS unsigned char* lds, const Gemm g, const StaticOrder& S, const Epi& E, int wave_) {
;     const int tid = tid_of(wave_), wid = wave_, lane = tid & 63, wr = wid >> 2, wc = wid & 3, fr = lane & 15, fq = lane >> 4;
;     const int K = g.K, nt = K / BK;
;     unsigned voffA[2], voffB[2];
; #pragma unroll
;     for (int i = 0; i < 2; ++i) { int R, C; stage_rc(tid * 16 + i * 8192, R, C); const int Rb = (R & ~31) + perm32(R & 31);
;         voffA[i] = (unsigned)(R * g.lda + C) * 2u; voffB[i] = (unsigned)(Rb * g.ldb + C) * 2u; }
;     const size_t kstep = (size_t)(BK * 2);
;     const size_t hstepA = (size_t)HALF * g.lda * 2, hstepB = (size_t)HALF * g.ldb * 2;
;     const size_t tstepA = 2 * hstepA, tstepB = 2 * hstepB;
;     const unsigned ldsw = (unsigned)wid * 1024u, ldsb = (unsigned)(uintptr_t)lds;
;     const int aoff0 = lds_byte(wr * 64 + fr, fq * 8), boff0 = lds_byte(wc * 32 + fr, fq * 8);
;     ...
;     Unit cur, nxt; int ui = 0;
;     if (!S.next(0, cur)) return;
;     f32x4 acc[2][2][4][2];
; #pragma unroll
;     for (int a = 0; a < 2; ++a)
; #pragma unroll
;         for (int b = 0; b < 2; ++b)
; #pragma unroll
;             for (int m = 0; m < 4; ++m)
; #pragma unroll
;                 for (int n = 0; n < 2; ++n) acc[a][b][m][n] = (f32x4){0.f, 0.f, 0.f, 0.f};
;     bf16x8 At[4][2], B0[2][2], B1[2][2];
;     const char* cA = (const char*)g.A + (size_t)cur.pm * tstepA; const char* cB = (const char*)g.Bt + (size_t)cur.pn * tstepB;
;     PG8_STAGE(PG8_SB(0, 0), cB, voffB); PG8_STAGE(PG8_SB(0, 1), cB + hstepB, voffB); PG8_STAGE(PG8_SA(0, 0), cA, voffA); PG8_STAGE(PG8_SA(0, 1), cA + hstepA, voffA);
;     if (wr == 1) PG8_BAR;
;     PG8_WAIT_V(2); PG8_BAR;
;     PG8_STAGE(PG8_SB(1, 0), cB + kstep, voffB); PG8_STAGE(PG8_SA(1, 0), cA + kstep, voffA); PG8_STAGE(PG8_SB(1, 1), cB + hstepB + kstep, voffB);
;     PG8_WAIT_V(6); PG8_BAR;
.LBB0_181:
	v_readlane_b32 s6, v254, 51
	v_readlane_b32 s7, v254, 52
	s_mov_b32 s8, s6
	s_ashr_i32 s9, s6, 31
	v_writelane_b32 v254, s6, 51
	s_nop 1
	v_writelane_b32 v254, s7, 52
	s_lshl_b64 s[6:7], s[8:9], 13
	v_writelane_b32 v255, s6, 25
	s_nop 1
	v_writelane_b32 v255, s7, 26
	s_nop 0
	v_readlane_b32 s6, v255, 22
	s_add_i32 s20, s6, 1
	v_readlane_b32 s6, v252, 16
	v_readlane_b32 s7, v252, 17
	s_cmp_ge_i32 s20, s7
	s_cselect_b64 s[8:9], -1, 0
	v_writelane_b32 v255, s8, 27
	s_cmp_lt_i32 s20, s7
	s_cselect_b32 s6, 0, 8
	v_writelane_b32 v255, s9, 28
	v_writelane_b32 v255, s6, 29
	s_mov_b64 s[6:7], -1
	s_and_b64 vcc, exec, s[4:5]
	s_cbranch_vccz .LBB0_564
	v_readlane_b32 s4, v252, 12
	v_readlane_b32 s10, v253, 8
	v_readlane_b32 s5, v252, 13
	v_readlane_b32 s11, v253, 9
	s_mov_b64 s[6:7], s[4:5]
	s_mov_b64 s[8:9], s[4:5]
	v_mov_b32_e32 v0, v220
	s_andn2_b64 vcc, exec, s[10:11]
	s_cbranch_vccnz .LBB0_198
	v_bfe_i32 v3, v0, 27, 1
	v_lshlrev_b32_e32 v1, 4, v0
	v_lshrrev_b32_e32 v4, 22, v3
	v_add_u32_e32 v4, v1, v4
	v_and_b32_e32 v4, 0xfc00, v4
	v_sub_u32_e32 v4, v1, v4
	v_ashrrev_i16_e32 v5, 15, v4
	v_ashrrev_i32_e32 v2, 31, v0
	v_lshrrev_b16_e32 v5, 9, v5
	v_lshrrev_b32_e32 v3, 25, v3
	v_lshrrev_b32_e32 v2, 26, v2
	v_add_u16_e32 v4, v4, v5
	v_add_u32_e32 v3, v1, v3
	v_add_u32_e32 v2, v0, v2
	v_ashrrev_i16_e32 v4, 7, v4
	v_and_b32_e32 v3, 0x80, v3
	v_ashrrev_i32_e32 v2, 6, v2
	v_bfe_i32 v4, v4, 0, 16
	v_sub_u32_e32 v3, v1, v3
	v_mov_b32_e32 v7, 4
	v_ashrrev_i16_sdwa v3, v7, sext(v3) dst_sel:DWORD dst_unused:UNUSED_PAD src0_sel:DWORD src1_sel:BYTE_0
	v_lshl_add_u32 v2, v2, 3, v4
	v_bfe_i32 v3, v3, 0, 16
	v_lshrrev_b32_e32 v5, 1, v2
	s_add_u32 s16, s6, 0x8000000
	v_bitop3_b32 v3, v5, v3, 7 bitop3:0x6c
	v_lshlrev_b32_e32 v5, 1, v2
	v_lshrrev_b32_e32 v6, 2, v2
	v_and_b32_e32 v4, 3, v4
	s_mov_b32 s6, 0xfffe0
	v_lshlrev_b32_e32 v3, 4, v3
	v_and_b32_e32 v5, 24, v5
	v_and_b32_e32 v6, 4, v6
	v_and_or_b32 v4, v2, s6, v4
	v_add_u32_e32 v1, 0x2000, v1
	v_or3_b32 v4, v4, v6, v5
	v_lshl_add_u32 v129, v2, 12, v3
	v_ashrrev_i32_e32 v2, 31, v1
	v_lshl_add_u32 v134, v4, 12, v3
	v_lshrrev_b32_e32 v3, 22, v2
	v_add_u32_e32 v3, v1, v3
	v_ashrrev_i32_e32 v3, 10, v3
	v_mul_i32_i24_e32 v4, 0x400, v3
	v_sub_u32_e32 v4, v1, v4
	v_ashrrev_i16_e32 v5, 15, v4
	v_lshrrev_b16_e32 v5, 9, v5
	v_lshrrev_b32_e32 v2, 25, v2
	v_add_u16_e32 v4, v4, v5
	v_add_u32_e32 v2, v1, v2
	v_ashrrev_i16_e32 v4, 7, v4
	v_and_b32_e32 v2, 0x80, v2
	v_bfe_i32 v4, v4, 0, 16
	v_sub_u32_e32 v1, v1, v2
	s_addc_u32 s17, s7, 0
	v_ashrrev_i16_sdwa v1, v7, sext(v1) dst_sel:DWORD dst_unused:UNUSED_PAD src0_sel:DWORD src1_sel:BYTE_0
	v_lshl_add_u32 v2, v3, 3, v4
	s_add_u32 s21, s8, 0x39500000
	v_bfe_i32 v1, v1, 0, 16
	v_lshrrev_b32_e32 v3, 1, v2
	v_and_b32_e32 v4, 3, v4
	s_addc_u32 s30, s9, 0
	v_bitop3_b32 v1, v3, v1, 7 bitop3:0x6c
	v_lshlrev_b32_e32 v3, 1, v2
	v_lshrrev_b32_e32 v5, 2, v2
	v_and_or_b32 v4, v2, s6, v4
	v_readlane_b32 s6, v253, 60
	v_and_b32_e32 v3, 24, v3
	v_and_b32_e32 v5, 4, v5
	v_readlane_b32 s7, v253, 61
	s_add_u32 s12, s21, s6
	v_lshlrev_b32_e32 v1, 4, v1
	v_or3_b32 v3, v4, v5, v3
	s_addc_u32 s13, s30, s7
	s_mov_b32 m0, s80
	s_nop 0
	global_load_lds_dwordx4 v134, s[12:13]
	v_lshl_add_u32 v136, v3, 12, v1
	s_mov_b32 m0, s81
	s_nop 0
	global_load_lds_dwordx4 v136, s[12:13]
	s_add_u32 s6, s12, 0x80000
	s_addc_u32 s7, s13, 0
	s_mov_b32 m0, s29
	s_nop 0
	global_load_lds_dwordx4 v134, s[6:7]
	v_lshl_add_u32 v135, v2, 12, v1
	s_mov_b32 m0, s88
	s_nop 0
	global_load_lds_dwordx4 v136, s[6:7]
	v_readlane_b32 s6, v254, 17
	v_readlane_b32 s7, v254, 18
	s_add_u32 s18, s16, s6
	s_addc_u32 s19, s17, s7
	s_mov_b32 m0, s76
	s_nop 0
	global_load_lds_dwordx4 v129, s[18:19]
	s_nop 0
	s_mov_b32 m0, s89
	s_nop 0
	global_load_lds_dwordx4 v135, s[18:19]
	s_add_u32 s6, s18, 0x80000
	s_addc_u32 s7, s19, 0
	s_mov_b32 m0, s1
	s_nop 0
	global_load_lds_dwordx4 v129, s[6:7]
	s_nop 0
	s_mov_b32 m0, s69
	s_nop 0
	global_load_lds_dwordx4 v135, s[6:7]
	v_readlane_b32 s6, v253, 11
	v_readlane_b32 s7, v253, 12
	s_andn2_b64 vcc, exec, s[6:7]
	s_nop 0
	v_cndmask_b32_e64 v1, 0, 1, s[6:7]
	v_cmp_ne_u32_e64 s[38:39], 1, v1
	s_cbranch_vccnz .LBB0_185
	s_barrier
.LBB0_185:
	s_add_u32 s31, s4, 0x19000000
	s_addc_u32 s36, s5, 0
	v_and_b32_e32 v2, 15, v0
	v_readlane_b32 s4, v253, 6
	s_waitcnt vmcnt(2)
	s_barrier
	v_lshrrev_b32_e32 v1, 4, v0
	v_or_b32_e32 v137, s4, v2
	s_add_u32 s4, s12, 0x80
	s_addc_u32 s5, s13, 0
	s_mov_b32 m0, s35
	s_nop 0
	global_load_lds_dwordx4 v134, s[4:5]
	v_bfe_u32 v3, v0, 4, 2
	s_mov_b32 m0, s33
	s_nop 0
	global_load_lds_dwordx4 v136, s[4:5]
	s_add_u32 s4, s18, 0x80
	s_addc_u32 s5, s19, 0
	s_mov_b32 m0, s22
	s_nop 0
	global_load_lds_dwordx4 v129, s[4:5]
	v_bfe_u32 v0, v0, 1, 3
	s_mov_b32 m0, s2
	s_nop 0
	global_load_lds_dwordx4 v135, s[4:5]
	s_add_u32 s4, s12, 0x80080
	s_addc_u32 s5, s13, 0
	s_mov_b32 m0, s77
	s_nop 0
	global_load_lds_dwordx4 v134, s[4:5]
	v_bitop3_b32 v0, v1, v0, 3 bitop3:0x6c
	s_mov_b32 m0, s3
	s_nop 0
	global_load_lds_dwordx4 v136, s[4:5]
	v_readlane_b32 s7, v253, 7
	s_waitcnt vmcnt(6)
	v_lshlrev_b32_e32 v0, 4, v0
	v_readlane_b32 s4, v254, 15
	v_or_b32_e32 v1, s7, v2
	v_lshl_or_b32 v138, v137, 7, v0
	v_lshl_or_b32 v139, v1, 7, v0
	v_lshl_or_b32 v140, v3, 3, s7
	s_mov_b32 s37, 0
	v_readlane_b32 s44, v253, 59
	s_mov_b32 s43, s4
	s_barrier
	v_readlane_b32 s5, v254, 16
	s_branch .LBB0_188

; #define PG8_STAGE(bufoff, gbase, voff) do { _Pragma("unroll") for (int _i = 0; _i < 2; ++_i) \
;         dma16((const char*)(gbase), (voff)[_i], ldsb + (bufoff) + ldsw + _i * 8192); } while (0)
; #define PG8_LDA(dst, b, h) do { const int a1_ = opqv(aoff0) ^ 64; _Pragma("unroll") for (int m = 0; m < 4; ++m) { dst[m][0] = *(const LAS bf16x8*)(lds + PG8_SA(b, h) + aoff0 + m * 2048); dst[m][1] = *(const LAS bf16x8*)(lds + PG8_SA(b, h) + a1_ + m * 2048); } } while (0)
; #define PG8_LDB(dst, b, h) do { const int b1_ = opqv(boff0) ^ 64; _Pragma("unroll") for (int n = 0; n < 2; ++n) { dst[n][0] = *(const LAS bf16x8*)(lds + PG8_SB(b, h) + boff0 + n * 2048); dst[n][1] = *(const LAS bf16x8*)(lds + PG8_SB(b, h) + b1_ + n * 2048); } } while (0)
; #define PG8_MMA(ai, bj, At, Bt) do { __builtin_amdgcn_s_setprio(1); _Pragma("unroll") for (int m = 0; m < 4; ++m) _Pragma("unroll") for (int n = 0; n < 2; ++n) _Pragma("unroll") for (int k = 0; k < 2; ++k) \
;         acc[ai][bj][m][n] = __builtin_amdgcn_mfma_f32_16x16x32_bf16(Bt[n][k], At[m][k], acc[ai][bj][m][n], 0, 0, 0); __builtin_amdgcn_s_setprio(0); } while (0)
; #define PG8_WAIT_V(n) asm volatile("s_waitcnt vmcnt(" #n ")" ::: "memory")
; #define PG8_WAIT_L(n) asm volatile("s_waitcnt lgkmcnt(" #n ")" ::: "memory")
; #define PG8_BAR __builtin_amdgcn_s_barrier()
; #define PG8_SCHED __builtin_amdgcn_sched_barrier(0)
; template <class Epi>
; __device__ __forceinline__ void gemm_phase(LAS unsigned char* lds, const Gemm g, const StaticOrder& S, const Epi& E, int wave_) {
;     ...
;         for (int t = 0; t < nt; t += 2) {
;             const bool last = (t == nt - 2);
;             const char* a1 = cA + (size_t)(t + 1) * kstep;
;             const char* a2 = last ? nA : cA + (size_t)(t + 2) * kstep; const char* b2 = last ? nB : cB + (size_t)(t + 2) * kstep;
;             const char* a3 = a2 + kstep; const char* b3 = b2 + kstep;
;             PG8_STAGE(PG8_SA(1, 1), a1 + hstepA, voffA); PG8_LDB(B0, 0, 0); PG8_LDB(B1, 0, 1); PG8_SCHED; PG8_LDA(At, 0, 0);
;             PG8_WAIT_V(8); PG8_WAIT_L(0); PG8_BAR; PG8_MMA(0, 0, At, B0); PG8_MMA(0, 1, At, B1); PG8_BAR; PG8_SCHED;
;             PG8_STAGE(PG8_SB(0, 0), b2, voffB); PG8_STAGE(PG8_SB(0, 1), b2 + hstepB, voffB); PG8_STAGE(PG8_SA(0, 0), a2, voffA); PG8_LDA(At, 0, 1);
;             PG8_WAIT_V(8); PG8_WAIT_L(0); PG8_BAR; PG8_MMA(1, 0, At, B0); PG8_MMA(1, 1, At, B1); PG8_BAR; PG8_SCHED;
.LBB0_191:
	s_add_u32 s18, s12, 0xfff80080
	s_addc_u32 s19, s13, -1
	s_cmp_eq_u32 s49, 28
	s_cselect_b32 s26, s45, s18
	v_mov_b32_e32 v128, v139
	s_cselect_b32 s27, s7, s19
	s_cselect_b32 s24, s46, s47
	s_cselect_b32 s25, s5, s48
	s_add_u32 s18, s26, 0x80
	v_xad_u32 v128, v128, 64, s23
	v_add_u32_e32 v141, s23, v139
	s_addc_u32 s19, s27, 0
	ds_read_b128 v[130:133], v141
	ds_read_b128 v[142:145], v141 offset:2048
	ds_read_b128 v[146:149], v128
	ds_read_b128 v[150:153], v128 offset:2048
	v_mov_b32_e32 v128, v139
	s_add_i32 s52, 0, 0x14000
	v_add_u32_e32 v141, s52, v139
	v_xad_u32 v128, v128, 64, s52
	ds_read_b128 v[154:157], v141
	ds_read_b128 v[158:161], v141 offset:2048
	ds_read_b128 v[162:165], v128
	ds_read_b128 v[166:169], v128 offset:2048
	v_mov_b32_e32 v128, v138
	v_add_u32_e32 v141, 0, v138
	v_xad_u32 v128, v128, 64, 0
	ds_read_b128 v[170:173], v141
	ds_read_b128 v[174:177], v141 offset:2048
	ds_read_b128 v[178:181], v128
	ds_read_b128 v[192:195], v128 offset:2048
	ds_read_b128 v[196:199], v141 offset:4096
	ds_read_b128 v[200:203], v141 offset:6144
	ds_read_b128 v[204:207], v128 offset:4096
	ds_read_b128 v[208:211], v128 offset:6144
	s_mov_b32 m0, s14
	s_nop 0
	global_load_lds_dwordx4 v129, s[12:13]
	s_mov_b32 m0, s15
	s_nop 0
	global_load_lds_dwordx4 v135, s[12:13]
	s_waitcnt vmcnt(8)
	s_waitcnt lgkmcnt(0)
	s_barrier
	s_setprio 1
	s_waitcnt lgkmcnt(0)
	v_mfma_f32_16x16x32_bf16 v[124:127], v[130:133], v[170:173], v[124:127]
	v_mfma_f32_16x16x32_bf16 v[120:123], v[142:145], v[170:173], v[120:123]
	v_mfma_f32_16x16x32_bf16 v[112:115], v[130:133], v[174:177], v[112:115]
	v_mfma_f32_16x16x32_bf16 v[104:107], v[142:145], v[174:177], v[104:107]
	v_mfma_f32_16x16x32_bf16 v[96:99], v[130:133], v[196:199], v[96:99]
	v_mfma_f32_16x16x32_bf16 v[88:91], v[142:145], v[196:199], v[88:91]
	v_mfma_f32_16x16x32_bf16 v[80:83], v[130:133], v[200:203], v[80:83]
	v_mfma_f32_16x16x32_bf16 v[72:75], v[142:145], v[200:203], v[72:75]
	v_mfma_f32_16x16x32_bf16 v[124:127], v[146:149], v[178:181], v[124:127]
	v_mfma_f32_16x16x32_bf16 v[120:123], v[150:153], v[178:181], v[120:123]
	v_mfma_f32_16x16x32_bf16 v[112:115], v[146:149], v[192:195], v[112:115]
	v_mfma_f32_16x16x32_bf16 v[104:107], v[150:153], v[192:195], v[104:107]
	v_mfma_f32_16x16x32_bf16 v[96:99], v[146:149], v[204:207], v[96:99]
	v_mfma_f32_16x16x32_bf16 v[88:91], v[150:153], v[204:207], v[88:91]
	v_mfma_f32_16x16x32_bf16 v[80:83], v[146:149], v[208:211], v[80:83]
	v_mfma_f32_16x16x32_bf16 v[72:75], v[150:153], v[208:211], v[72:75]
	s_setprio 0
	s_setprio 1
	v_mfma_f32_16x16x32_bf16 v[116:119], v[154:157], v[170:173], v[116:119]
	v_mfma_f32_16x16x32_bf16 v[108:111], v[158:161], v[170:173], v[108:111]
	v_mfma_f32_16x16x32_bf16 v[100:103], v[154:157], v[174:177], v[100:103]
	v_mfma_f32_16x16x32_bf16 v[92:95], v[158:161], v[174:177], v[92:95]
	v_mfma_f32_16x16x32_bf16 v[84:87], v[154:157], v[196:199], v[84:87]
	v_mfma_f32_16x16x32_bf16 v[76:79], v[158:161], v[196:199], v[76:79]
	v_mfma_f32_16x16x32_bf16 v[68:71], v[154:157], v[200:203], v[68:71]
	v_mfma_f32_16x16x32_bf16 v[64:67], v[158:161], v[200:203], v[64:67]
	v_mfma_f32_16x16x32_bf16 v[116:119], v[162:165], v[178:181], v[116:119]
	v_mfma_f32_16x16x32_bf16 v[108:111], v[166:169], v[178:181], v[108:111]
	v_mfma_f32_16x16x32_bf16 v[100:103], v[162:165], v[192:195], v[100:103]
	v_mfma_f32_16x16x32_bf16 v[92:95], v[166:169], v[192:195], v[92:95]
	v_mfma_f32_16x16x32_bf16 v[84:87], v[162:165], v[204:207], v[84:87]
	v_mfma_f32_16x16x32_bf16 v[76:79], v[166:169], v[204:207], v[76:79]
	v_mfma_f32_16x16x32_bf16 v[68:71], v[162:165], v[208:211], v[68:71]
	v_mfma_f32_16x16x32_bf16 v[64:67], v[166:169], v[208:211], v[64:67]
	s_setprio 0
	s_barrier
	s_add_u32 s54, s24, 0x80000
	s_addc_u32 s55, s25, 0
	v_mov_b32_e32 v128, v138
	s_nop 0
	s_nop 0
	s_nop 0
	v_xad_u32 v128, v128, 64, 0
	ds_read_b128 v[170:173], v141 offset:16384
	ds_read_b128 v[174:177], v141 offset:18432
	ds_read_b128 v[178:181], v128 offset:16384
	ds_read_b128 v[192:195], v128 offset:18432
	ds_read_b128 v[196:199], v141 offset:20480
	ds_read_b128 v[200:203], v141 offset:22528
	ds_read_b128 v[204:207], v128 offset:20480
	ds_read_b128 v[208:211], v128 offset:22528
	s_mov_b32 m0, s80
	s_nop 0
	global_load_lds_dwordx4 v134, s[24:25]
	s_mov_b32 m0, s81
	s_nop 0
	global_load_lds_dwordx4 v136, s[24:25]
	s_mov_b32 m0, s29
	s_nop 0
	global_load_lds_dwordx4 v134, s[54:55]
	s_mov_b32 m0, s88
	s_nop 0
	global_load_lds_dwordx4 v136, s[54:55]
	s_mov_b32 m0, s76
	s_nop 0
	global_load_lds_dwordx4 v129, s[26:27]
	s_mov_b32 m0, s89
	s_nop 0
	global_load_lds_dwordx4 v135, s[26:27]
	s_waitcnt vmcnt(8)
	s_waitcnt lgkmcnt(0)
	s_barrier
; #define PG8_STAGE(bufoff, gbase, voff) do { _Pragma("unroll") for (int _i = 0; _i < 2; ++_i) \
;         dma16((const char*)(gbase), (voff)[_i], ldsb + (bufoff) + ldsw + _i * 8192); } while (0)
; #define PG8_LDA(dst, b, h) do { const int a1_ = opqv(aoff0) ^ 64; _Pragma("unroll") for (int m = 0; m < 4; ++m) { dst[m][0] = *(const LAS bf16x8*)(lds + PG8_SA(b, h) + aoff0 + m * 2048); dst[m][1] = *(const LAS bf16x8*)(lds + PG8_SA(b, h) + a1_ + m * 2048); } } while (0)
; #define PG8_LDB(dst, b, h) do { const int b1_ = opqv(boff0) ^ 64; _Pragma("unroll") for (int n = 0; n < 2; ++n) { dst[n][0] = *(const LAS bf16x8*)(lds + PG8_SB(b, h) + boff0 + n * 2048); dst[n][1] = *(const LAS bf16x8*)(lds + PG8_SB(b, h) + b1_ + n * 2048); } } while (0)
; #define PG8_MMA(ai, bj, At, Bt) do { __builtin_amdgcn_s_setprio(1); _Pragma("unroll") for (int m = 0; m < 4; ++m) _Pragma("unroll") for (int n = 0; n < 2; ++n) _Pragma("unroll") for (int k = 0; k < 2; ++k) \
;         acc[ai][bj][m][n] = __builtin_amdgcn_mfma_f32_16x16x32_bf16(Bt[n][k], At[m][k], acc[ai][bj][m][n], 0, 0, 0); __builtin_amdgcn_s_setprio(0); } while (0)
; #define PG8_WAIT_V(n) asm volatile("s_waitcnt vmcnt(" #n ")" ::: "memory")
; #define PG8_WAIT_L(n) asm volatile("s_waitcnt lgkmcnt(" #n ")" ::: "memory")
; #define PG8_BAR __builtin_amdgcn_s_barrier()
; #define PG8_SCHED __builtin_amdgcn_sched_barrier(0)
; template <class Epi>
; __device__ __forceinline__ void gemm_phase(LAS unsigned char* lds, const Gemm g, const StaticOrder& S, const Epi& E, int wave_) {
;     ...
;             PG8_WAIT_V(8); PG8_WAIT_L(0); PG8_BAR; PG8_MMA(1, 0, At, B0); PG8_MMA(1, 1, At, B1); PG8_BAR; PG8_SCHED;
;             PG8_STAGE(PG8_SA(0, 1), a2 + hstepA, voffA); PG8_LDB(B0, 1, 0); PG8_LDB(B1, 1, 1); PG8_SCHED; PG8_LDA(At, 1, 0);
;             PG8_WAIT_V(8); PG8_WAIT_L(0); PG8_BAR; PG8_MMA(0, 0, At, B0); PG8_MMA(0, 1, At, B1); PG8_BAR; PG8_SCHED;
	s_setprio 1
	s_waitcnt lgkmcnt(0)
	v_mfma_f32_16x16x32_bf16 v[60:63], v[130:133], v[170:173], v[60:63]
	v_mfma_f32_16x16x32_bf16 v[56:59], v[142:145], v[170:173], v[56:59]
	v_mfma_f32_16x16x32_bf16 v[48:51], v[130:133], v[174:177], v[48:51]
	v_mfma_f32_16x16x32_bf16 v[40:43], v[142:145], v[174:177], v[40:43]
	v_mfma_f32_16x16x32_bf16 v[32:35], v[130:133], v[196:199], v[32:35]
	v_mfma_f32_16x16x32_bf16 v[24:27], v[142:145], v[196:199], v[24:27]
	v_mfma_f32_16x16x32_bf16 v[16:19], v[130:133], v[200:203], v[16:19]
	v_mfma_f32_16x16x32_bf16 v[8:11], v[142:145], v[200:203], v[8:11]
	v_mfma_f32_16x16x32_bf16 v[60:63], v[146:149], v[178:181], v[60:63]
	v_mfma_f32_16x16x32_bf16 v[56:59], v[150:153], v[178:181], v[56:59]
	v_mfma_f32_16x16x32_bf16 v[48:51], v[146:149], v[192:195], v[48:51]
	v_mfma_f32_16x16x32_bf16 v[40:43], v[150:153], v[192:195], v[40:43]
	v_mfma_f32_16x16x32_bf16 v[32:35], v[146:149], v[204:207], v[32:35]
	v_mfma_f32_16x16x32_bf16 v[24:27], v[150:153], v[204:207], v[24:27]
	v_mfma_f32_16x16x32_bf16 v[16:19], v[146:149], v[208:211], v[16:19]
	v_mfma_f32_16x16x32_bf16 v[8:11], v[150:153], v[208:211], v[8:11]
	s_setprio 0
	s_setprio 1
	v_mfma_f32_16x16x32_bf16 v[52:55], v[154:157], v[170:173], v[52:55]
	v_mfma_f32_16x16x32_bf16 v[44:47], v[158:161], v[170:173], v[44:47]
	v_mfma_f32_16x16x32_bf16 v[36:39], v[154:157], v[174:177], v[36:39]
	v_mfma_f32_16x16x32_bf16 v[28:31], v[158:161], v[174:177], v[28:31]
	v_mfma_f32_16x16x32_bf16 v[20:23], v[154:157], v[196:199], v[20:23]
	v_mfma_f32_16x16x32_bf16 v[12:15], v[158:161], v[196:199], v[12:15]
	v_mfma_f32_16x16x32_bf16 v[4:7], v[154:157], v[200:203], v[4:7]
	v_mfma_f32_16x16x32_bf16 v[0:3], v[158:161], v[200:203], v[0:3]
	v_mfma_f32_16x16x32_bf16 v[52:55], v[162:165], v[178:181], v[52:55]
	v_mfma_f32_16x16x32_bf16 v[44:47], v[166:169], v[178:181], v[44:47]
	v_mfma_f32_16x16x32_bf16 v[36:39], v[162:165], v[192:195], v[36:39]
	v_mfma_f32_16x16x32_bf16 v[28:31], v[166:169], v[192:195], v[28:31]
	v_mfma_f32_16x16x32_bf16 v[20:23], v[162:165], v[204:207], v[20:23]
	v_mfma_f32_16x16x32_bf16 v[12:15], v[166:169], v[204:207], v[12:15]
	v_mfma_f32_16x16x32_bf16 v[4:7], v[162:165], v[208:211], v[4:7]
	v_mfma_f32_16x16x32_bf16 v[0:3], v[166:169], v[208:211], v[0:3]
	s_setprio 0
	s_barrier
	s_add_u32 s26, s26, 0x80000
	s_addc_u32 s27, s27, 0
	s_mov_b32 m0, s1
	s_nop 0
	global_load_lds_dwordx4 v129, s[26:27]
	v_mov_b32_e32 v128, v139
	s_mov_b32 m0, s69
	s_nop 0
	global_load_lds_dwordx4 v135, s[26:27]
	v_add_u32_e32 v142, s34, v139
	v_xad_u32 v128, v128, 64, s34
	ds_read_b128 v[130:133], v142
	ds_read_b128 v[142:145], v142 offset:2048
	ds_read_b128 v[146:149], v128
	ds_read_b128 v[150:153], v128 offset:2048
	v_mov_b32_e32 v128, v139
	s_add_i32 s26, 0, 0x1c000
	v_add_u32_e32 v158, s26, v139
	v_xad_u32 v128, v128, 64, s26
	ds_read_b128 v[154:157], v158
	ds_read_b128 v[158:161], v158 offset:2048
	ds_read_b128 v[162:165], v128
	ds_read_b128 v[166:169], v128 offset:2048
	v_mov_b32_e32 v128, v138
	s_nop 0
	v_xad_u32 v128, v128, 64, 0
	ds_read_b128 v[170:173], v141 offset:32768
	ds_read_b128 v[174:177], v141 offset:34816
	ds_read_b128 v[178:181], v128 offset:32768
	ds_read_b128 v[192:195], v128 offset:34816
	ds_read_b128 v[196:199], v141 offset:36864
	ds_read_b128 v[200:203], v141 offset:38912
	ds_read_b128 v[204:207], v128 offset:36864
	ds_read_b128 v[208:211], v128 offset:38912
	s_waitcnt vmcnt(8)
	s_waitcnt lgkmcnt(0)
	s_barrier
	s_setprio 1
	s_waitcnt lgkmcnt(0)
	v_mfma_f32_16x16x32_bf16 v[124:127], v[130:133], v[170:173], v[124:127]
	v_mfma_f32_16x16x32_bf16 v[120:123], v[142:145], v[170:173], v[120:123]
	v_mfma_f32_16x16x32_bf16 v[112:115], v[130:133], v[174:177], v[112:115]
	v_mfma_f32_16x16x32_bf16 v[104:107], v[142:145], v[174:177], v[104:107]
	v_mfma_f32_16x16x32_bf16 v[96:99], v[130:133], v[196:199], v[96:99]
	v_mfma_f32_16x16x32_bf16 v[88:91], v[142:145], v[196:199], v[88:91]
	v_mfma_f32_16x16x32_bf16 v[80:83], v[130:133], v[200:203], v[80:83]
	v_mfma_f32_16x16x32_bf16 v[72:75], v[142:145], v[200:203], v[72:75]
	v_mfma_f32_16x16x32_bf16 v[124:127], v[146:149], v[178:181], v[124:127]
	v_mfma_f32_16x16x32_bf16 v[120:123], v[150:153], v[178:181], v[120:123]
	v_mfma_f32_16x16x32_bf16 v[112:115], v[146:149], v[192:195], v[112:115]
	v_mfma_f32_16x16x32_bf16 v[104:107], v[150:153], v[192:195], v[104:107]
	v_mfma_f32_16x16x32_bf16 v[96:99], v[146:149], v[204:207], v[96:99]
	v_mfma_f32_16x16x32_bf16 v[88:91], v[150:153], v[204:207], v[88:91]
	v_mfma_f32_16x16x32_bf16 v[80:83], v[146:149], v[208:211], v[80:83]
	v_mfma_f32_16x16x32_bf16 v[72:75], v[150:153], v[208:211], v[72:75]
	s_setprio 0
	s_setprio 1
	v_mfma_f32_16x16x32_bf16 v[116:119], v[154:157], v[170:173], v[116:119]
	s_add_u32 s26, s24, 0x80
	s_addc_u32 s27, s25, 0
	v_mfma_f32_16x16x32_bf16 v[108:111], v[158:161], v[170:173], v[108:111]
	v_mfma_f32_16x16x32_bf16 v[100:103], v[154:157], v[174:177], v[100:103]
	v_mfma_f32_16x16x32_bf16 v[92:95], v[158:161], v[174:177], v[92:95]
	v_mfma_f32_16x16x32_bf16 v[84:87], v[154:157], v[196:199], v[84:87]
	v_mfma_f32_16x16x32_bf16 v[76:79], v[158:161], v[196:199], v[76:79]
	v_mfma_f32_16x16x32_bf16 v[68:71], v[154:157], v[200:203], v[68:71]
	v_mfma_f32_16x16x32_bf16 v[64:67], v[158:161], v[200:203], v[64:67]
	v_mfma_f32_16x16x32_bf16 v[116:119], v[162:165], v[178:181], v[116:119]
	v_mfma_f32_16x16x32_bf16 v[108:111], v[166:169], v[178:181], v[108:111]
	v_mfma_f32_16x16x32_bf16 v[100:103], v[162:165], v[192:195], v[100:103]
	v_mfma_f32_16x16x32_bf16 v[92:95], v[166:169], v[192:195], v[92:95]
	v_mfma_f32_16x16x32_bf16 v[84:87], v[162:165], v[204:207], v[84:87]
	v_mfma_f32_16x16x32_bf16 v[76:79], v[166:169], v[204:207], v[76:79]
	v_mfma_f32_16x16x32_bf16 v[68:71], v[162:165], v[208:211], v[68:71]
	v_mfma_f32_16x16x32_bf16 v[64:67], v[166:169], v[208:211], v[64:67]
	s_setprio 0
	s_barrier
; #define PG8_STAGE(bufoff, gbase, voff) do { _Pragma("unroll") for (int _i = 0; _i < 2; ++_i) \
;         dma16((const char*)(gbase), (voff)[_i], ldsb + (bufoff) + ldsw + _i * 8192); } while (0)
; #define PG8_LDA(dst, b, h) do { const int a1_ = opqv(aoff0) ^ 64; _Pragma("unroll") for (int m = 0; m < 4; ++m) { dst[m][0] = *(const LAS bf16x8*)(lds + PG8_SA(b, h) + aoff0 + m * 2048); dst[m][1] = *(const LAS bf16x8*)(lds + PG8_SA(b, h) + a1_ + m * 2048); } } while (0)
; #define PG8_MMA(ai, bj, At, Bt) do { __builtin_amdgcn_s_setprio(1); _Pragma("unroll") for (int m = 0; m < 4; ++m) _Pragma("unroll") for (int n = 0; n < 2; ++n) _Pragma("unroll") for (int k = 0; k < 2; ++k) \
;         acc[ai][bj][m][n] = __builtin_amdgcn_mfma_f32_16x16x32_bf16(Bt[n][k], At[m][k], acc[ai][bj][m][n], 0, 0, 0); __builtin_amdgcn_s_setprio(0); } while (0)
; #define PG8_WAIT_V(n) asm volatile("s_waitcnt vmcnt(" #n ")" ::: "memory")
; #define PG8_WAIT_L(n) asm volatile("s_waitcnt lgkmcnt(" #n ")" ::: "memory")
; #define PG8_BAR __builtin_amdgcn_s_barrier()
; #define PG8_SCHED __builtin_amdgcn_sched_barrier(0)
; template <class Epi>
; __device__ __forceinline__ void gemm_phase(LAS unsigned char* lds, const Gemm g, const StaticOrder& S, const Epi& E, int wave_) {
;     ...
;             PG8_STAGE(PG8_SB(1, 0), b3, voffB); PG8_STAGE(PG8_SB(1, 1), b3 + hstepB, voffB); PG8_STAGE(PG8_SA(1, 0), a3, voffA); PG8_LDA(At, 1, 1);
;             PG8_WAIT_V(8); PG8_WAIT_L(0); PG8_BAR; PG8_MMA(1, 0, At, B0); PG8_MMA(1, 1, At, B1); PG8_BAR; PG8_SCHED;
;         }
;         if (wr == 0) PG8_BAR;
	s_add_u32 s24, s24, 0x80080
	s_addc_u32 s25, s25, 0
	v_mov_b32_e32 v128, v138
	s_nop 0
	s_nop 0
	v_xad_u32 v128, v128, 64, 0
	ds_read_b128 v[170:173], v141 offset:49152
	ds_read_b128 v[174:177], v141 offset:51200
	ds_read_b128 v[178:181], v128 offset:49152
	ds_read_b128 v[192:195], v128 offset:51200
	ds_read_b128 v[196:199], v141 offset:53248
	ds_read_b128 v[200:203], v141 offset:55296
	ds_read_b128 v[204:207], v128 offset:53248
	ds_read_b128 v[208:211], v128 offset:55296
	s_mov_b32 m0, s35
	s_nop 0
	global_load_lds_dwordx4 v134, s[26:27]
	s_mov_b32 m0, s33
	s_nop 0
	global_load_lds_dwordx4 v136, s[26:27]
	s_mov_b32 m0, s77
	s_nop 0
	global_load_lds_dwordx4 v134, s[24:25]
	s_mov_b32 m0, s3
	s_nop 0
	global_load_lds_dwordx4 v136, s[24:25]
	s_mov_b32 m0, s22
	s_nop 0
	global_load_lds_dwordx4 v129, s[18:19]
	s_mov_b32 m0, s2
	s_nop 0
	global_load_lds_dwordx4 v135, s[18:19]
	s_waitcnt vmcnt(8)
	s_waitcnt lgkmcnt(0)
	s_barrier
	s_setprio 1
	s_waitcnt lgkmcnt(0)
	v_mfma_f32_16x16x32_bf16 v[60:63], v[130:133], v[170:173], v[60:63]
	v_mfma_f32_16x16x32_bf16 v[56:59], v[142:145], v[170:173], v[56:59]
	v_mfma_f32_16x16x32_bf16 v[48:51], v[130:133], v[174:177], v[48:51]
	v_mfma_f32_16x16x32_bf16 v[40:43], v[142:145], v[174:177], v[40:43]
	v_mfma_f32_16x16x32_bf16 v[32:35], v[130:133], v[196:199], v[32:35]
	v_mfma_f32_16x16x32_bf16 v[24:27], v[142:145], v[196:199], v[24:27]
	v_mfma_f32_16x16x32_bf16 v[16:19], v[130:133], v[200:203], v[16:19]
	v_mfma_f32_16x16x32_bf16 v[8:11], v[142:145], v[200:203], v[8:11]
	v_mfma_f32_16x16x32_bf16 v[60:63], v[146:149], v[178:181], v[60:63]
	v_mfma_f32_16x16x32_bf16 v[56:59], v[150:153], v[178:181], v[56:59]
	v_mfma_f32_16x16x32_bf16 v[48:51], v[146:149], v[192:195], v[48:51]
	v_mfma_f32_16x16x32_bf16 v[40:43], v[150:153], v[192:195], v[40:43]
	v_mfma_f32_16x16x32_bf16 v[32:35], v[146:149], v[204:207], v[32:35]
	v_mfma_f32_16x16x32_bf16 v[24:27], v[150:153], v[204:207], v[24:27]
	v_mfma_f32_16x16x32_bf16 v[16:19], v[146:149], v[208:211], v[16:19]
	v_mfma_f32_16x16x32_bf16 v[8:11], v[150:153], v[208:211], v[8:11]
	s_setprio 0
	s_setprio 1
	v_mfma_f32_16x16x32_bf16 v[52:55], v[154:157], v[170:173], v[52:55]
	v_mfma_f32_16x16x32_bf16 v[44:47], v[158:161], v[170:173], v[44:47]
	v_mfma_f32_16x16x32_bf16 v[36:39], v[154:157], v[174:177], v[36:39]
	v_mfma_f32_16x16x32_bf16 v[28:31], v[158:161], v[174:177], v[28:31]
	v_mfma_f32_16x16x32_bf16 v[20:23], v[154:157], v[196:199], v[20:23]
	v_mfma_f32_16x16x32_bf16 v[12:15], v[158:161], v[196:199], v[12:15]
	v_mfma_f32_16x16x32_bf16 v[4:7], v[154:157], v[200:203], v[4:7]
	v_mfma_f32_16x16x32_bf16 v[0:3], v[158:161], v[200:203], v[0:3]
	v_mfma_f32_16x16x32_bf16 v[52:55], v[162:165], v[178:181], v[52:55]
	v_mfma_f32_16x16x32_bf16 v[44:47], v[166:169], v[178:181], v[44:47]
	v_mfma_f32_16x16x32_bf16 v[36:39], v[162:165], v[192:195], v[36:39]
	v_mfma_f32_16x16x32_bf16 v[28:31], v[166:169], v[192:195], v[28:31]
	v_mfma_f32_16x16x32_bf16 v[20:23], v[162:165], v[204:207], v[20:23]
	v_mfma_f32_16x16x32_bf16 v[12:15], v[166:169], v[204:207], v[12:15]
	v_mfma_f32_16x16x32_bf16 v[4:7], v[162:165], v[208:211], v[4:7]
	v_mfma_f32_16x16x32_bf16 v[0:3], v[166:169], v[208:211], v[0:3]
	s_setprio 0
	s_barrier
	s_add_i32 s49, s49, 2
	s_add_u32 s47, s47, 0x100
	s_addc_u32 s48, s48, 0
	s_add_u32 s12, s12, 0x100
	s_addc_u32 s13, s13, 0
	s_cmp_gt_u32 s49, 29
	s_cbranch_scc0 .LBB0_191
	v_readlane_b32 s12, v253, 13
	v_readlane_b32 s13, v253, 14
	s_and_b64 vcc, exec, s[12:13]
	s_cbranch_vccz .LBB0_194
	s_barrier

; #define LAS __attribute__((address_space(3)))
; __device__ __forceinline__ int tid_of(int wave) { return opqv(wave * 64 + (int)__builtin_amdgcn_mbcnt_hi(~0u, __builtin_amdgcn_mbcnt_lo(~0u, 0u))); }
; __device__ __forceinline__ int v_rd_base(int lane) { return ((lane & 3) << 3) | (((lane >> 2) & 3) << 6) | (((lane >> 4) & 1) << 5) | (((lane >> 5) & 1) << 8); }
; #define BARL() asm volatile("s_waitcnt lgkmcnt(0)\n\ts_barrier" ::: "memory")
; #define BARL() asm volatile("s_waitcnt lgkmcnt(0)\n\ts_barrier" ::: "memory")
; __device__ __forceinline__ void attn_pass_dv256(const bf16_t* __restrict__ Qb, const bf16_t* __restrict__ Kh, const bf16_t* __restrict__ Vh, int qpos0,
;                                                 LAS unsigned char* lds, f32x16 (&o)[8], float& l_out, int wave_) {
;   const int tid = tid_of(wave_), wid = wave_, lane = tid & 63, r32 = lane & 31, hi = lane >> 5;
;   LAS unsigned char* K_lds = lds + K2_OFF;
;   LAS float* al_l = (LAS float*)(lds + WS2_OFF) + wid * 64 + 32;
;   const LAS float* tbl = (const LAS float*)(lds + TBL2_OFF);
;   float m_reg = -1e30f, l_reg = 0;
; #pragma unroll
;   for (int d = 0; d < 8; ++d) o[d] = f32x16{};
;   bf16x8 qr[4];
;   LAS unsigned char* qf = lds + Q2_OFF + wid * 4096;
;   const bf16_t* Qw = Qb + (size_t)(wid * 32 + r32) * LDX + hi * 8;
; #pragma unroll
;   for (int d0 = 0; d0 < 4; ++d0) qr[d0] = *(const bf16x8*)(Qw + d0 * 16);
; #pragma unroll
;   for (int d0 = 4; d0 < 8; ++d0) *(LAS bf16x8*)(qf + ((d0 - 4) * 64 + lane) * 16) = *(const bf16x8*)(Qw + d0 * 16);
;   const unsigned ldsb = (unsigned)(uintptr_t)lds;
;   const unsigned vb0 = ldsb + V2_OFF + v_rd_base(lane);
;   const int krow = 4 * wid + (lane >> 4);
;   const unsigned voffK = (unsigned)(krow * (LDX * 2) + (((lane & 15) ^ (krow & 15)) << 4));
;   const int vst_ = 2 * wid + (lane >> 5), vkk = (vst_ >> 2) * 8 + ((lane >> 2) & 7), vk = (vkk & ~0xC) | ((vkk & 4) << 1) | ((vkk & 8) >> 1);
;   const unsigned voffV = (unsigned)(vk * (LDX * 2) + ((vst_ & 3) * 4 + (lane & 3)) * 16);
;   const int qw0 = qpos0 + wid * 32, qme = qw0 + r32;
;   constexpr int NT = SEQ / KVBLK;
;     ...
;   f32x16 p0, p1; float mn, al, cadd; bf16x8 pa0, pa1, pa2, pa3;
;   DMA_KV(0, 0); DMA_KV(1, 1);
;   asm volatile("s_waitcnt vmcnt(6)" ::: "memory"); BARL();
.LBB0_373:
	s_or_b64 exec, exec, s[4:5]
	s_lshr_b32 s4, s26, 4
	s_and_b32 s4, s4, 7
	s_ashr_i32 s6, s26, 7
	s_lshl_b32 s27, s4, 9
	s_and_b32 s16, s21, 0xf00
	v_readlane_b32 s4, v254, 56
	s_ashr_i32 s7, s6, 31
	s_lshl_b32 s8, s26, 8
	v_readlane_b32 s38, v252, 12
	s_sub_i32 s30, s4, s16
	s_lshl_b64 s[4:5], s[6:7], 12
	s_and_b32 s8, s8, 0xf00
	v_readlane_b32 s39, v252, 13
	s_or_b32 s4, s4, s8
	s_mov_b64 s[18:19], s[38:39]
	s_mov_b64 s[10:11], s[38:39]
	s_waitcnt lgkmcnt(0)
	s_barrier
	s_lshl_b32 s36, s24, 8
	s_lshl_b64 s[8:9], s[4:5], 11
	s_lshl_b64 s[12:13], s[4:5], 12
	s_add_u32 s10, s10, s12
	s_addc_u32 s11, s11, s13
	s_lshl_b32 s17, s24, 9
	s_mov_b64 s[24:25], s[38:39]
	s_mov_b64 s[12:13], s[38:39]
	v_mov_b32_e32 v20, v220
	v_readlane_b32 s48, v254, 55
	v_and_b32_e32 v22, 31, v20
	s_add_u32 s10, s10, s17
	v_or_b32_e32 v184, s48, v22
	s_addc_u32 s11, s11, 0
	v_bfe_u32 v21, v20, 5, 1
	v_lshlrev_b64 v[0:1], 12, v[184:185]
	v_lshl_add_u64 v[0:1], s[10:11], 0, v[0:1]
	v_lshlrev_b32_e32 v184, 4, v21
	v_lshl_add_u64 v[16:17], v[0:1], 0, v[184:185]
	s_mov_b64 s[10:11], 0x19000000
	v_lshl_add_u64 v[18:19], v[16:17], 0, s[10:11]
	flat_load_dwordx4 v[0:3], v[18:19] offset:128
	flat_load_dwordx4 v[4:7], v[18:19] offset:160
	flat_load_dwordx4 v[8:11], v[18:19] offset:192
	flat_load_dwordx4 v[12:15], v[18:19] offset:224
	v_bfe_u32 v26, v20, 4, 2
	v_readlane_b32 s10, v253, 19
	v_and_b32_e32 v23, 63, v20
	v_lshlrev_b32_e32 v24, 3, v20
	v_lshlrev_b32_e32 v25, 1, v20
	v_bfe_u32 v27, v20, 2, 2
	v_lshrrev_b32_e32 v28, 1, v20
	v_lshlrev_b32_e32 v29, 4, v20
	v_or_b32_e32 v31, s10, v26
	v_bitop3_b32 v20, v26, v20, s10 bitop3:0x36
	v_readlane_b32 s10, v253, 22
	v_lshlrev_b32_e32 v30, 4, v23
	v_and_b32_e32 v26, 8, v28
	v_or_b32_e32 v28, s10, v21
	v_readlane_b32 s10, v253, 23
	v_lshlrev_b32_e32 v31, 12, v31
	v_lshlrev_b32_e32 v20, 4, v20
	v_add_u32_e32 v234, s10, v30
	v_readlane_b32 s10, v253, 20
	s_movk_i32 s49, 0xf0
	v_and_b32_e32 v32, 48, v29
	v_or3_b32 v26, v27, v26, s10
	s_lshl_b64 s[10:11], s[6:7], 23
	s_lshl_b64 s[6:7], s[6:7], 24
	s_add_u32 s40, s24, s6
	s_mov_b32 s24, 0x19000000
	v_add_co_u32_e32 v16, vcc, s24, v16
	s_addc_u32 s41, s25, s7
	s_nop 0
	v_addc_co_u32_e32 v17, vcc, 0, v17, vcc
	flat_load_dwordx4 v[160:163], v[16:17]
	flat_load_dwordx4 v[164:167], v[18:19] offset:96
	flat_load_dwordx4 v[168:171], v[18:19] offset:32
	flat_load_dwordx4 v[172:175], v[18:19] offset:64
	s_add_u32 s31, s40, s17
	s_addc_u32 s45, s41, 0
	s_add_u32 s24, s31, 0x21000000
	s_addc_u32 s25, s45, 0
	s_add_u32 s43, s12, s6
	s_addc_u32 s44, s13, s7
	s_add_u32 s17, s43, s17
	s_addc_u32 s46, s44, 0
	s_add_u32 s12, s17, 0x29000000
	s_addc_u32 s13, s46, 0
	v_and_or_b32 v235, v20, s49, v31
	s_add_u32 s38, s31, 0x21020000
	v_lshl_or_b32 v27, v28, 6, v32
	s_addc_u32 s39, s45, 0
	v_lshl_or_b32 v236, v26, 12, v27
	s_waitcnt vmcnt(0) lgkmcnt(0)
	ds_write_b128 v234, v[0:3]
	ds_write_b128 v234, v[4:7] offset:1024
	ds_write_b128 v234, v[8:11] offset:2048
	ds_write_b128 v234, v[12:15] offset:3072
	s_mov_b32 m0, s80
	s_nop 0
	global_load_lds_dwordx4 v235, s[24:25]
	s_mov_b32 m0, s81
	s_nop 0
	global_load_lds_dwordx4 v235, s[38:39]
	v_and_b32_e32 v0, 0xf0, v29
	s_mov_b32 m0, s76
	s_nop 0
	global_load_lds_dwordx4 v236, s[12:13]
	s_add_u32 s12, s17, 0x29020000
	s_addc_u32 s13, s46, 0
	s_mov_b32 m0, s89
	s_nop 0
	global_load_lds_dwordx4 v236, s[12:13]
	s_add_u32 s12, s17, 0x29000100
	s_addc_u32 s13, s46, 0
	s_mov_b32 m0, s1
	s_nop 0
	global_load_lds_dwordx4 v236, s[12:13]
	s_add_u32 s12, s17, 0x29020100
	s_addc_u32 s13, s46, 0
	s_mov_b32 m0, s69
	s_nop 0
	global_load_lds_dwordx4 v236, s[12:13]
	s_add_u32 s12, s31, 0x21040000
	s_addc_u32 s13, s45, 0
	s_add_u32 s24, s17, 0x29040000
	s_addc_u32 s25, s46, 0
	s_mov_b32 m0, s29
	s_nop 0
	global_load_lds_dwordx4 v235, s[12:13]
	s_add_u32 s12, s31, 0x21060000
	s_addc_u32 s13, s45, 0
	s_mov_b32 m0, s88
	s_nop 0
	global_load_lds_dwordx4 v235, s[12:13]
	s_mov_b32 m0, s22
	s_nop 0
	global_load_lds_dwordx4 v236, s[24:25]
	s_add_u32 s12, s17, 0x29060000
	s_addc_u32 s13, s46, 0
	s_mov_b32 m0, s2
	s_nop 0
	global_load_lds_dwordx4 v236, s[12:13]
	s_add_u32 s12, s17, 0x29040100
	s_addc_u32 s13, s46, 0
	s_mov_b32 m0, s14
	s_nop 0
	global_load_lds_dwordx4 v236, s[12:13]
	s_add_u32 s12, s17, 0x29060100
	s_addc_u32 s13, s46, 0
	s_mov_b32 m0, s15
	s_nop 0
	global_load_lds_dwordx4 v236, s[12:13]
	s_movk_i32 s12, 0x60
	v_bitop3_b32 v242, v184, v0, s12 bitop3:0x36
	s_movk_i32 s12, 0x80
	v_bitop3_b32 v243, v184, v0, s12 bitop3:0x36
	s_movk_i32 s12, 0xa0
	v_bitop3_b32 v244, v184, v0, s12 bitop3:0x36
	s_movk_i32 s12, 0xc0
	s_waitcnt vmcnt(6)
	v_and_b32_e32 v1, 0x118, v24
	v_bitop3_b32 v245, v184, v0, s12 bitop3:0x36
	s_movk_i32 s12, 0xe0
	v_and_b32_e32 v30, 0xc0, v30
	s_waitcnt lgkmcnt(0)
	s_barrier
; #define LAS __attribute__((address_space(3)))
; __device__ __forceinline__ int v_rd_base(int lane) { return ((lane & 3) << 3) | (((lane >> 2) & 3) << 6) | (((lane >> 4) & 1) << 5) | (((lane >> 5) & 1) << 8); }
; #define BARL() asm volatile("s_waitcnt lgkmcnt(0)\n\ts_barrier" ::: "memory")
; #define BARL() asm volatile("s_waitcnt lgkmcnt(0)\n\ts_barrier" ::: "memory")
; __device__ __forceinline__ void attn_pass_dv256(const bf16_t* __restrict__ Qb, const bf16_t* __restrict__ Kh, const bf16_t* __restrict__ Vh, int qpos0,
;                                                 LAS unsigned char* lds, f32x16 (&o)[8], float& l_out, int wave_) {
;     ...
;   float m_reg = -1e30f, l_reg = 0;
; #pragma unroll
;   for (int d = 0; d < 8; ++d) o[d] = f32x16{};
;   bf16x8 qr[4];
;   LAS unsigned char* qf = lds + Q2_OFF + wid * 4096;
;   const bf16_t* Qw = Qb + (size_t)(wid * 32 + r32) * LDX + hi * 8;
; #pragma unroll
;   for (int d0 = 0; d0 < 4; ++d0) qr[d0] = *(const bf16x8*)(Qw + d0 * 16);
; #pragma unroll
;   for (int d0 = 4; d0 < 8; ++d0) *(LAS bf16x8*)(qf + ((d0 - 4) * 64 + lane) * 16) = *(const bf16x8*)(Qw + d0 * 16);
;   const unsigned ldsb = (unsigned)(uintptr_t)lds;
;   const unsigned vb0 = ldsb + V2_OFF + v_rd_base(lane);
;   const int krow = 4 * wid + (lane >> 4);
;   const unsigned voffK = (unsigned)(krow * (LDX * 2) + (((lane & 15) ^ (krow & 15)) << 4));
;   const int vst_ = 2 * wid + (lane >> 5), vkk = (vst_ >> 2) * 8 + ((lane >> 2) & 7), vk = (vkk & ~0xC) | ((vkk & 4) << 1) | ((vkk & 8) >> 1);
;   const unsigned voffV = (unsigned)(vk * (LDX * 2) + ((vst_ & 3) * 4 + (lane & 3)) * 16);
;   const int qw0 = qpos0 + wid * 32, qme = qw0 + r32;
;   constexpr int NT = SEQ / KVBLK;
;     ...
;   f32x16 p0, p1; float mn, al, cadd; bf16x8 pa0, pa1, pa2, pa3;
;   DMA_KV(0, 0); DMA_KV(1, 1);
;   asm volatile("s_waitcnt vmcnt(6)" ::: "memory"); BARL();
	v_bitop3_b32 v240, v184, v0, 32 bitop3:0x36
	v_bitop3_b32 v241, v184, v0, 64 bitop3:0x36
	v_bitop3_b32 v246, v184, v0, s12 bitop3:0x36
	v_and_or_b32 v0, v25, 32, v1
	s_add_i32 s31, s48, s16
	v_mov_b32_e32 v96, v185
	v_mov_b32_e32 v97, v185
	v_lshl_add_u32 v237, v22, 8, s23
	v_lshlrev_b32_e32 v2, 2, v21
	v_cmp_gt_u32_e64 s[38:39], 32, v23
	v_lshl_add_u32 v238, v22, 2, s59
	v_bitop3_b32 v239, v184, v29, s49 bitop3:0x78
	v_add3_u32 v247, v30, 0, v0
	v_add_u32_e32 v0, s31, v22
	v_mov_b32_e32 v98, v185
	v_mov_b32_e32 v99, v185
	v_mov_b32_e32 v100, v185
	v_mov_b32_e32 v101, v185
	v_mov_b32_e32 v102, v185
	v_mov_b32_e32 v103, v185
	v_mov_b32_e32 v104, v185
	v_mov_b32_e32 v105, v185
	v_mov_b32_e32 v106, v185
	v_mov_b32_e32 v107, v185
	v_mov_b32_e32 v108, v185
	v_mov_b32_e32 v109, v185
	v_mov_b32_e32 v110, v185
	v_mov_b32_e32 v111, v185
	v_mov_b32_e32 v250, 0
	v_mov_b64_e32 v[64:65], v[96:97]
	v_mov_b64_e32 v[32:33], v[96:97]
	v_mov_b64_e32 v[16:17], v[96:97]
	v_mov_b64_e32 v[218:219], 0x3ff
	v_mov_b64_e32 v[188:189], 0x400
	v_mov_b64_e32 v[186:187], 0x15ff
	s_mov_b32 s37, 0
	v_sub_u32_e32 v248, v2, v0
	v_mov_b32_e32 v249, 0xf149f2ca
	v_mov_b64_e32 v[66:67], v[98:99]
	v_mov_b64_e32 v[68:69], v[100:101]
	v_mov_b64_e32 v[70:71], v[102:103]
	v_mov_b64_e32 v[72:73], v[104:105]
	v_mov_b64_e32 v[74:75], v[106:107]
	v_mov_b64_e32 v[76:77], v[108:109]
	v_mov_b64_e32 v[78:79], v[110:111]
	v_mov_b64_e32 v[34:35], v[98:99]
	v_mov_b64_e32 v[36:37], v[100:101]
	v_mov_b64_e32 v[38:39], v[102:103]
	v_mov_b64_e32 v[40:41], v[104:105]
	v_mov_b64_e32 v[42:43], v[106:107]
	v_mov_b64_e32 v[44:45], v[108:109]
	v_mov_b64_e32 v[46:47], v[110:111]
	v_mov_b64_e32 v[18:19], v[98:99]
	v_mov_b64_e32 v[20:21], v[100:101]
	v_mov_b64_e32 v[22:23], v[102:103]
	v_mov_b64_e32 v[24:25], v[104:105]
	v_mov_b64_e32 v[26:27], v[106:107]
	v_mov_b64_e32 v[28:29], v[108:109]
	v_mov_b64_e32 v[30:31], v[110:111]
	s_mov_b32 s45, 0
	v_mov_b32_e32 v112, 0
	v_mov_b32_e32 v113, v250
	v_mov_b32_e32 v114, v250
	v_mov_b32_e32 v115, v250
	v_mov_b32_e32 v116, v250
	v_mov_b32_e32 v117, v250
	v_mov_b32_e32 v118, v250
	v_mov_b32_e32 v119, v250
	v_mov_b32_e32 v120, v250
	v_mov_b32_e32 v121, v250
	v_mov_b32_e32 v122, v250
	v_mov_b32_e32 v123, v250
	v_mov_b32_e32 v124, v250
	v_mov_b32_e32 v125, v250
	v_mov_b32_e32 v126, v250
	v_mov_b32_e32 v127, v250
	v_mov_b32_e32 v80, 0
	v_mov_b32_e32 v81, v250
	v_mov_b32_e32 v82, v250
	v_mov_b32_e32 v83, v250
	v_mov_b32_e32 v84, v250
	v_mov_b32_e32 v85, v250
	v_mov_b32_e32 v86, v250
	v_mov_b32_e32 v87, v250
	v_mov_b32_e32 v88, v250
	v_mov_b32_e32 v89, v250
	v_mov_b32_e32 v90, v250
	v_mov_b32_e32 v91, v250
	v_mov_b32_e32 v92, v250
	v_mov_b32_e32 v93, v250
	v_mov_b32_e32 v94, v250
	v_mov_b32_e32 v95, v250
	v_mov_b32_e32 v48, 0
	v_mov_b32_e32 v49, v250
	v_mov_b32_e32 v50, v250
	v_mov_b32_e32 v51, v250
	v_mov_b32_e32 v52, v250
	v_mov_b32_e32 v53, v250
	v_mov_b32_e32 v54, v250
	v_mov_b32_e32 v55, v250
	v_mov_b32_e32 v56, v250
	v_mov_b32_e32 v57, v250
	v_mov_b32_e32 v58, v250
	v_mov_b32_e32 v59, v250
	v_mov_b32_e32 v60, v250
	v_mov_b32_e32 v61, v250
	v_mov_b32_e32 v62, v250
	v_mov_b32_e32 v63, v250
	v_mov_b32_e32 v0, 0
	v_mov_b32_e32 v1, v250
	v_mov_b32_e32 v2, v250
	v_mov_b32_e32 v3, v250
	v_mov_b32_e32 v4, v250
	v_mov_b32_e32 v5, v250
	v_mov_b32_e32 v6, v250
	v_mov_b32_e32 v7, v250
	v_mov_b32_e32 v8, v250
	v_mov_b32_e32 v9, v250
	v_mov_b32_e32 v10, v250
	v_mov_b32_e32 v11, v250
	v_mov_b32_e32 v12, v250
	v_mov_b32_e32 v13, v250
	v_mov_b32_e32 v14, v250
	v_mov_b32_e32 v15, v250

; __device__ __forceinline__ void partialSM(f32x16& p0, f32x16& p1, float& m_reg, float& mn, float& alpha, float cadd) {
;   float pmax = p0[0];
; #pragma unroll
;   for (int r = 1; r < 16; ++r) pmax = fmaxf(pmax, p0[r]);
; #pragma unroll
;   for (int r = 0; r < 16; ++r) pmax = fmaxf(pmax, p1[r]);
;   { auto rr = __builtin_amdgcn_permlane32_swap(__float_as_uint(pmax), __float_as_uint(pmax), false, false);
;     pmax = fmaxf(__uint_as_float(rr[0]), __uint_as_float(rr[1])); }
;   pmax += cadd;
;   if (__builtin_expect(__all(pmax - m_reg <= THRL), 1)) { mn = m_reg; alpha = 1.f; }
;   else { mn = fmaxf(m_reg, pmax); alpha = __builtin_amdgcn_exp2f(m_reg - mn); m_reg = mn; }
;   const float off = cadd - mn;
; #pragma unroll
;   for (int r = 0; r < 16; ++r) p0[r] += off;
; #pragma unroll
;   for (int r = 0; r < 16; ++r) p1[r] += off;
; #pragma unroll
;   for (int r = 0; r < 16; ++r) p0[r] = __builtin_amdgcn_exp2f(p0[r]);
; }
; __device__ __forceinline__ void attn_pass_dv256(const bf16_t* __restrict__ Qb, const bf16_t* __restrict__ Kh, const bf16_t* __restrict__ Vh, int qpos0,
;                                                 LAS unsigned char* lds, f32x16 (&o)[8], float& l_out, int wave_) {
;     ...
;     { const int dd = j * KVBLK - qw0;
;       if (dd <= -191 || dd >= 159) { cadd = (dd < 0) ? tbl[0] : tbl[256]; partialSM(p0, p1, m_reg, mn, al, cadd); }
;       else { add_bias(p0, p1, tbl, j * KVBLK - qme, hi); partialSM(p0, p1, m_reg, mn, al, 0.f); } }
.LBB0_376:
	s_andn2_b64 vcc, exec, s[24:25]
	v_mov_b32_e32 v251, 0
	s_cbranch_vccnz .LBB0_378
	s_cmp_lt_i32 s16, 0
	s_mov_b32 s12, 0x18c00
	s_cselect_b32 s12, 0x18800, s12
	s_add_i32 s12, s12, 0
	v_mov_b32_e32 v178, s12
	ds_read_b32 v251, v178
	s_nop 0
	v_max_f32_e32 v178, v129, v129
	v_max_f32_e32 v179, v128, v128
	v_max_f32_e32 v178, v179, v178
	v_max3_f32 v178, v178, v130, v131
	v_max3_f32 v178, v178, v132, v133
	v_max3_f32 v178, v178, v134, v135
	v_max3_f32 v178, v178, v136, v137
	v_max3_f32 v178, v178, v138, v139
	v_max3_f32 v178, v178, v140, v141
	v_max3_f32 v178, v178, v142, v143
	v_max3_f32 v178, v178, v144, v145
	v_max3_f32 v178, v178, v146, v147
	v_max3_f32 v178, v178, v148, v149
	v_max3_f32 v178, v178, v150, v151
	v_max3_f32 v178, v178, v152, v153
	v_max3_f32 v178, v178, v154, v155
	v_max3_f32 v178, v178, v156, v157
	v_max3_f32 v178, v178, v158, v159
	v_mov_b32_e32 v179, v178
	s_nop 1
	v_permlane32_swap_b32_e32 v178, v179
	v_max_f32_e32 v179, v179, v179
	v_max_f32_e32 v178, v178, v178
	v_max_f32_e32 v178, v178, v179
	s_waitcnt lgkmcnt(0)
	v_add_f32_e32 v221, v251, v178
	v_sub_f32_e32 v178, v221, v249
	v_cmp_ge_f32_e32 vcc, s94, v178
	s_cmp_eq_u64 vcc, exec
	s_cselect_b64 s[12:13], -1, 0
	s_cbranch_scc0 .Lslow_p1
	v_sub_f32_e32 v180, v251, v249
	v_add_f32_e32 v181, v180, v159
	v_add_f32_e32 v159, v180, v157
	v_add_f32_e32 v178, v180, v158
	v_add_f32_e32 v157, v180, v155
	v_add_f32_e32 v158, v180, v156
	v_add_f32_e32 v155, v180, v153
	v_add_f32_e32 v156, v180, v154
	v_add_f32_e32 v153, v180, v151
	v_add_f32_e32 v154, v180, v152
	v_add_f32_e32 v151, v180, v149
	v_add_f32_e32 v152, v180, v150
	v_add_f32_e32 v149, v180, v147
	v_add_f32_e32 v150, v180, v148
	v_add_f32_e32 v147, v180, v145
	v_add_f32_e32 v148, v180, v146
	v_add_f32_e32 v145, v180, v143
	v_add_f32_e32 v146, v180, v144
	v_add_f32_e32 v143, v180, v142
	v_add_f32_e32 v142, v180, v141
	v_add_f32_e32 v141, v180, v140
	v_add_f32_e32 v140, v180, v139
	v_add_f32_e32 v139, v180, v138
	v_add_f32_e32 v138, v180, v137
	v_add_f32_e32 v137, v180, v136
	v_add_f32_e32 v136, v180, v135
	v_add_f32_e32 v135, v180, v134
	v_add_f32_e32 v134, v180, v133
	v_add_f32_e32 v133, v180, v132
	v_add_f32_e32 v132, v180, v131
	v_add_f32_e32 v131, v180, v130
	v_add_f32_e32 v130, v180, v129
	v_add_f32_e32 v129, v180, v128
	v_mov_b32_e32 v128, v181
	v_exp_f32_e32 v129, v129
	v_exp_f32_e32 v130, v130
	v_exp_f32_e32 v131, v131
	v_mov_b32_e32 v144, 1.0
	s_branch .Ljoin_p1
.Lslow_p1:
	v_mov_b32_e32 v213, v159
	v_mov_b32_e32 v212, v158
	v_mov_b32_e32 v211, v157
	v_mov_b32_e32 v210, v156
	v_mov_b32_e32 v209, v155
	v_mov_b32_e32 v208, v154
	v_mov_b32_e32 v203, v153
	v_mov_b32_e32 v202, v152
	v_mov_b32_e32 v197, v151
	v_mov_b32_e32 v196, v150
	v_mov_b32_e32 v195, v149
	v_mov_b32_e32 v194, v148
	v_mov_b32_e32 v193, v147
	v_mov_b32_e32 v192, v146
	v_mov_b32_e32 v179, v145
	v_mov_b32_e32 v178, v144
	v_mov_b32_e32 v217, v143
	v_mov_b32_e32 v216, v142
	v_mov_b32_e32 v215, v141
	v_mov_b32_e32 v214, v140
	v_mov_b32_e32 v207, v139
	v_mov_b32_e32 v206, v138
	v_mov_b32_e32 v205, v137
	v_mov_b32_e32 v204, v136
	v_mov_b32_e32 v201, v135
	v_mov_b32_e32 v200, v134
	v_mov_b32_e32 v199, v133
	v_mov_b32_e32 v198, v132
	v_mov_b32_e32 v183, v131
	v_mov_b32_e32 v182, v130
	v_mov_b32_e32 v181, v129
	v_mov_b32_e32 v180, v128

; #define SBAR() __builtin_amdgcn_sched_barrier(0)
; template <int OFF> __device__ __forceinline__ s16x4 tr_read(unsigned vb) { s16x4 r; asm volatile("ds_read_b64_tr_b16 %0, %1 offset:%2" : "=&v"(r) : "v"(vb), "i"(OFF) : "memory"); return r; }
; template <int D0> __device__ __forceinline__ void pv_one(f32x16& od, unsigned vb, bf16x8 pa0, bf16x8 pa1, bf16x8 pa2, bf16x8 pa3) {
;   const s16x4 l0 = tr_read<v_rd_off(D0, 0, 0)>(vb), h0 = tr_read<v_rd_off(D0, 0, 1)>(vb), l1 = tr_read<v_rd_off(D0, 1, 0)>(vb), h1 = tr_read<v_rd_off(D0, 1, 1)>(vb);
;   const s16x4 l2 = tr_read<v_rd_off(D0, 2, 0)>(vb), h2 = tr_read<v_rd_off(D0, 2, 1)>(vb), l3 = tr_read<v_rd_off(D0, 3, 0)>(vb), h3 = tr_read<v_rd_off(D0, 3, 1)>(vb);
;   asm volatile("s_waitcnt lgkmcnt(0)" ::: "memory"); SBAR();
;     ...
;   od = __builtin_amdgcn_mfma_f32_32x32x16_bf16(pa0, PK(l0, h0), od, 0, 0, 0);
;   od = __builtin_amdgcn_mfma_f32_32x32x16_bf16(pa1, PK(l1, h1), od, 0, 0, 0);
;   od = __builtin_amdgcn_mfma_f32_32x32x16_bf16(pa2, PK(l2, h2), od, 0, 0, 0);
;   od = __builtin_amdgcn_mfma_f32_32x32x16_bf16(pa3, PK(l3, h3), od, 0, 0, 0);
; __device__ __forceinline__ void finishSM(f32x16& p0, f32x16& p1, float alpha, float& l_reg, bf16x8& pa0, bf16x8& pa1, bf16x8& pa2, bf16x8& pa3) {
; #pragma unroll
;   for (int r = 0; r < 16; ++r) p1[r] = __builtin_amdgcn_exp2f(p1[r]);
;   float ps = 0;
; #pragma unroll
;   for (int r = 0; r < 16; ++r) ps += p0[r];
; #pragma unroll
;   for (int r = 0; r < 16; ++r) ps += p1[r];
;   { auto rr = __builtin_amdgcn_permlane32_swap(__float_as_uint(ps), __float_as_uint(ps), false, false);
;     ps = __uint_as_float(rr[0]) + __uint_as_float(rr[1]); }
;   l_reg = l_reg * alpha + ps;
;     ...
;   PK4(p0, 0, pa0); PK4(p0, 8, pa1); PK4(p1, 0, pa2); PK4(p1, 8, pa3);
.Ljoin_p1:
	v_exp_f32_e32 v132, v132
	v_exp_f32_e32 v133, v133
	v_exp_f32_e32 v181, v128
	v_add_f32_e32 v128, 0, v129
	v_exp_f32_e32 v134, v134
	v_add_f32_e32 v128, v130, v128
	v_exp_f32_e32 v135, v135
	v_add_f32_e32 v128, v131, v128
	v_exp_f32_e32 v136, v136
	v_add_f32_e32 v128, v132, v128
	v_exp_f32_e32 v137, v137
	v_add_f32_e32 v128, v133, v128
	v_exp_f32_e32 v138, v138
	v_add_f32_e32 v128, v134, v128
	v_exp_f32_e32 v139, v139
	v_add_f32_e32 v128, v135, v128
	v_exp_f32_e32 v140, v140
	v_add_f32_e32 v128, v136, v128
	v_exp_f32_e32 v141, v141
	v_add_f32_e32 v128, v137, v128
	v_exp_f32_e32 v142, v142
	v_add_f32_e32 v128, v138, v128
	v_exp_f32_e32 v143, v143
	v_add_f32_e32 v128, v139, v128
	v_exp_f32_e32 v179, v145
	v_add_f32_e32 v128, v140, v128
	v_exp_f32_e32 v180, v146
	v_add_f32_e32 v128, v141, v128
	v_exp_f32_e32 v147, v147
	v_add_f32_e32 v128, v142, v128
	v_exp_f32_e32 v148, v148
	v_add_f32_e32 v128, v143, v128
	v_exp_f32_e32 v149, v149
	v_add_f32_e32 v128, v179, v128
	v_exp_f32_e32 v150, v150
	v_add_f32_e32 v128, v180, v128
	v_exp_f32_e32 v151, v151
	v_add_f32_e32 v128, v147, v128
	v_exp_f32_e32 v152, v152
	v_add_f32_e32 v128, v148, v128
	v_exp_f32_e32 v153, v153
	v_add_f32_e32 v128, v149, v128
	v_exp_f32_e32 v154, v154
	v_add_f32_e32 v128, v150, v128
	v_exp_f32_e32 v155, v155
	v_add_f32_e32 v128, v151, v128
	v_exp_f32_e32 v156, v156
	v_add_f32_e32 v128, v152, v128
	v_exp_f32_e32 v157, v157
	v_add_f32_e32 v128, v153, v128
	v_exp_f32_e32 v158, v158
	v_add_f32_e32 v128, v154, v128
	v_exp_f32_e32 v159, v159
	v_add_f32_e32 v128, v155, v128
	v_exp_f32_e32 v178, v178
	v_add_f32_e32 v128, v156, v128
	v_add_f32_e32 v128, v157, v128
	v_add_f32_e32 v128, v158, v128
	v_add_f32_e32 v128, v159, v128
	v_add_f32_e32 v128, v178, v128
	v_add_f32_e32 v145, v181, v128
	v_mov_b32_e32 v146, v145
	s_nop 1
	v_permlane32_swap_b32_e32 v145, v146
	v_cvt_pk_bf16_f32 v128, v129, v130
	v_cvt_pk_bf16_f32 v129, v131, v132
	v_cvt_pk_bf16_f32 v130, v133, v134
	v_cvt_pk_bf16_f32 v131, v135, v136
	v_cvt_pk_bf16_f32 v132, v137, v138
	v_cvt_pk_bf16_f32 v133, v139, v140
	v_cvt_pk_bf16_f32 v134, v141, v142
	v_cvt_pk_bf16_f32 v135, v143, v179
	v_cvt_pk_bf16_f32 v136, v180, v147
	v_cvt_pk_bf16_f32 v137, v148, v149
	v_cvt_pk_bf16_f32 v138, v150, v151
	v_cvt_pk_bf16_f32 v139, v152, v153
	v_cvt_pk_bf16_f32 v140, v154, v155
	v_cvt_pk_bf16_f32 v141, v156, v157
	v_cvt_pk_bf16_f32 v142, v158, v159
	v_cvt_pk_bf16_f32 v143, v178, v181
	v_permlane32_swap_b32_e32 v128, v130
	v_permlane32_swap_b32_e32 v129, v131
	v_permlane32_swap_b32_e32 v132, v134
	v_permlane32_swap_b32_e32 v133, v135
	v_permlane32_swap_b32_e32 v136, v138
	v_permlane32_swap_b32_e32 v137, v139
	v_permlane32_swap_b32_e32 v140, v142
	v_permlane32_swap_b32_e32 v141, v143
	s_lshl_b32 s12, s47, 15
	v_add_u32_e32 v147, s12, v247
	ds_read_b64_tr_b16 v[148:149], v147 offset:0
	ds_read_b64_tr_b16 v[150:151], v147 offset:0x800
	ds_read_b64_tr_b16 v[152:153], v147 offset:0x1000
	ds_read_b64_tr_b16 v[154:155], v147 offset:0x1800
	ds_read_b64_tr_b16 v[156:157], v147 offset:0x2000
	ds_read_b64_tr_b16 v[158:159], v147 offset:0x2800
	ds_read_b64_tr_b16 v[178:179], v147 offset:0x3000
	ds_read_b64_tr_b16 v[180:181], v147 offset:0x3800
	s_waitcnt lgkmcnt(0)
	s_nop 0
	v_mfma_f32_32x32x16_bf16 v[96:111], v[128:131], v[148:151], v[96:111]
	ds_read_b64_tr_b16 v[148:149], v147 offset:0x200
	ds_read_b64_tr_b16 v[150:151], v147 offset:0xa00
	v_mfma_f32_32x32x16_bf16 v[96:111], v[132:135], v[152:155], v[96:111]
	ds_read_b64_tr_b16 v[152:153], v147 offset:0x1200
	ds_read_b64_tr_b16 v[154:155], v147 offset:0x1a00
	v_mfma_f32_32x32x16_bf16 v[96:111], v[136:139], v[156:159], v[96:111]
	ds_read_b64_tr_b16 v[156:157], v147 offset:0x2200
	ds_read_b64_tr_b16 v[158:159], v147 offset:0x2a00
	v_mfma_f32_32x32x16_bf16 v[96:111], v[140:143], v[178:181], v[96:111]
	ds_read_b64_tr_b16 v[178:179], v147 offset:0x3200
	ds_read_b64_tr_b16 v[180:181], v147 offset:0x3a00
	s_waitcnt lgkmcnt(0)
	v_mfma_f32_32x32x16_bf16 v[112:127], v[128:131], v[148:151], v[112:127]
	ds_read_b64_tr_b16 v[148:149], v147 offset:0x400
	ds_read_b64_tr_b16 v[150:151], v147 offset:0xc00
	v_mfma_f32_32x32x16_bf16 v[112:127], v[132:135], v[152:155], v[112:127]
	ds_read_b64_tr_b16 v[152:153], v147 offset:0x1400
	ds_read_b64_tr_b16 v[154:155], v147 offset:0x1c00
	v_mfma_f32_32x32x16_bf16 v[112:127], v[136:139], v[156:159], v[112:127]
	ds_read_b64_tr_b16 v[156:157], v147 offset:0x2400
	ds_read_b64_tr_b16 v[158:159], v147 offset:0x2c00
	v_mfma_f32_32x32x16_bf16 v[112:127], v[140:143], v[178:181], v[112:127]
	ds_read_b64_tr_b16 v[178:179], v147 offset:0x3400
	ds_read_b64_tr_b16 v[180:181], v147 offset:0x3c00
	s_waitcnt lgkmcnt(0)
; #define BARL() asm volatile("s_waitcnt lgkmcnt(0)\n\ts_barrier" ::: "memory")
; #define BARL() asm volatile("s_waitcnt lgkmcnt(0)\n\ts_barrier" ::: "memory")
; __device__ __forceinline__ void attn_pass_dv256(const bf16_t* __restrict__ Qb, const bf16_t* __restrict__ Kh, const bf16_t* __restrict__ Vh, int qpos0,
;                                                 LAS unsigned char* lds, f32x16 (&o)[8], float& l_out, int wave_) {
;     ...
;     pv_one<0>(o[0], vbs, pa0, pa1, pa2, pa3); pv_one<1>(o[1], vbs, pa0, pa1, pa2, pa3); pv_one<2>(o[2], vbs, pa0, pa1, pa2, pa3); pv_one<3>(o[3], vbs, pa0, pa1, pa2, pa3);
;     pv_one<0>(o[4], vbs + 16384, pa0, pa1, pa2, pa3); pv_one<1>(o[5], vbs + 16384, pa0, pa1, pa2, pa3); pv_one<2>(o[6], vbs + 16384, pa0, pa1, pa2, pa3); pv_one<3>(o[7], vbs + 16384, pa0, pa1, pa2, pa3);
;     asm volatile("s_waitcnt vmcnt(0)" ::: "memory"); BARL();
;     if (j + 2 < NT) DMA_KV(j + 2, sl);
	v_mfma_f32_32x32x16_bf16 v[64:79], v[128:131], v[148:151], v[64:79]
	ds_read_b64_tr_b16 v[148:149], v147 offset:0x600
	ds_read_b64_tr_b16 v[150:151], v147 offset:0xe00
	v_mfma_f32_32x32x16_bf16 v[64:79], v[132:135], v[152:155], v[64:79]
	ds_read_b64_tr_b16 v[152:153], v147 offset:0x1600
	ds_read_b64_tr_b16 v[154:155], v147 offset:0x1e00
	v_mfma_f32_32x32x16_bf16 v[64:79], v[136:139], v[156:159], v[64:79]
	ds_read_b64_tr_b16 v[156:157], v147 offset:0x2600
	ds_read_b64_tr_b16 v[158:159], v147 offset:0x2e00
	v_mfma_f32_32x32x16_bf16 v[64:79], v[140:143], v[178:181], v[64:79]
	ds_read_b64_tr_b16 v[178:179], v147 offset:0x3600
	ds_read_b64_tr_b16 v[180:181], v147 offset:0x3e00
	s_waitcnt lgkmcnt(0)
	v_mfma_f32_32x32x16_bf16 v[80:95], v[128:131], v[148:151], v[80:95]
	v_add_u32_e32 v147, 0x4000, v147
	ds_read_b64_tr_b16 v[148:149], v147 offset:0
	ds_read_b64_tr_b16 v[150:151], v147 offset:0x800
	v_mfma_f32_32x32x16_bf16 v[80:95], v[132:135], v[152:155], v[80:95]
	ds_read_b64_tr_b16 v[152:153], v147 offset:0x1000
	ds_read_b64_tr_b16 v[154:155], v147 offset:0x1800
	v_mfma_f32_32x32x16_bf16 v[80:95], v[136:139], v[156:159], v[80:95]
	ds_read_b64_tr_b16 v[156:157], v147 offset:0x2000
	ds_read_b64_tr_b16 v[158:159], v147 offset:0x2800
	v_mfma_f32_32x32x16_bf16 v[80:95], v[140:143], v[178:181], v[80:95]
	ds_read_b64_tr_b16 v[178:179], v147 offset:0x3000
	ds_read_b64_tr_b16 v[180:181], v147 offset:0x3800
	s_waitcnt lgkmcnt(0)
	v_mfma_f32_32x32x16_bf16 v[32:47], v[128:131], v[148:151], v[32:47]
	ds_read_b64_tr_b16 v[148:149], v147 offset:0x200
	ds_read_b64_tr_b16 v[150:151], v147 offset:0xa00
	v_mfma_f32_32x32x16_bf16 v[32:47], v[132:135], v[152:155], v[32:47]
	ds_read_b64_tr_b16 v[152:153], v147 offset:0x1200
	ds_read_b64_tr_b16 v[154:155], v147 offset:0x1a00
	v_mfma_f32_32x32x16_bf16 v[32:47], v[136:139], v[156:159], v[32:47]
	ds_read_b64_tr_b16 v[156:157], v147 offset:0x2200
	ds_read_b64_tr_b16 v[158:159], v147 offset:0x2a00
	v_mfma_f32_32x32x16_bf16 v[32:47], v[140:143], v[178:181], v[32:47]
	ds_read_b64_tr_b16 v[178:179], v147 offset:0x3200
	ds_read_b64_tr_b16 v[180:181], v147 offset:0x3a00
	s_waitcnt lgkmcnt(0)
	v_mfma_f32_32x32x16_bf16 v[48:63], v[128:131], v[148:151], v[48:63]
	ds_read_b64_tr_b16 v[148:149], v147 offset:0x400
	ds_read_b64_tr_b16 v[150:151], v147 offset:0xc00
	v_mfma_f32_32x32x16_bf16 v[48:63], v[132:135], v[152:155], v[48:63]
	ds_read_b64_tr_b16 v[152:153], v147 offset:0x1400
	ds_read_b64_tr_b16 v[154:155], v147 offset:0x1c00
	v_mfma_f32_32x32x16_bf16 v[48:63], v[136:139], v[156:159], v[48:63]
	ds_read_b64_tr_b16 v[156:157], v147 offset:0x2400
	ds_read_b64_tr_b16 v[158:159], v147 offset:0x2c00
	v_mfma_f32_32x32x16_bf16 v[48:63], v[140:143], v[178:181], v[48:63]
	ds_read_b64_tr_b16 v[178:179], v147 offset:0x3400
	ds_read_b64_tr_b16 v[180:181], v147 offset:0x3c00
	s_waitcnt lgkmcnt(0)
	v_mfma_f32_32x32x16_bf16 v[16:31], v[128:131], v[148:151], v[16:31]
	ds_read_b64_tr_b16 v[148:149], v147 offset:0x600
	ds_read_b64_tr_b16 v[150:151], v147 offset:0xe00
	v_mfma_f32_32x32x16_bf16 v[16:31], v[132:135], v[152:155], v[16:31]
	ds_read_b64_tr_b16 v[152:153], v147 offset:0x1600
	ds_read_b64_tr_b16 v[154:155], v147 offset:0x1e00
	v_mfma_f32_32x32x16_bf16 v[16:31], v[136:139], v[156:159], v[16:31]
	ds_read_b64_tr_b16 v[156:157], v147 offset:0x2600
	ds_read_b64_tr_b16 v[158:159], v147 offset:0x2e00
	v_mfma_f32_32x32x16_bf16 v[16:31], v[140:143], v[178:181], v[16:31]
	ds_read_b64_tr_b16 v[178:179], v147 offset:0x3600
	ds_read_b64_tr_b16 v[180:181], v147 offset:0x3e00
	s_waitcnt lgkmcnt(0)
	v_mfma_f32_32x32x16_bf16 v[0:15], v[128:131], v[148:151], v[0:15]
	s_waitcnt vmcnt(0)
	s_waitcnt lgkmcnt(0)
	s_barrier
	s_cmp_gt_u32 s45, 61
	v_mfma_f32_32x32x16_bf16 v[0:15], v[132:135], v[152:155], v[0:15]
	v_mfma_f32_32x32x16_bf16 v[0:15], v[136:139], v[156:159], v[0:15]
	v_mfma_f32_32x32x16_bf16 v[0:15], v[140:143], v[178:181], v[0:15]
	s_cbranch_scc1 .LBB0_384
	s_add_u32 s13, s40, s27
	s_addc_u32 s47, s41, 0
	s_add_u32 s16, s13, 0x21080000
	s_addc_u32 s17, s47, 0
	s_add_u32 s48, s43, s27
	s_addc_u32 s49, s44, 0
	s_add_u32 s24, s48, 0x29080000
	s_addc_u32 s25, s49, 0
	s_add_i32 s46, s46, 0
	s_add_i32 s46, s46, 0x10000
	s_add_i32 s52, s46, s68
	s_mov_b32 m0, s52
	s_nop 0
	global_load_lds_dwordx4 v235, s[16:17]
	s_add_u32 s16, s13, 0x210a0000
	s_addc_u32 s17, s47, 0
	s_add_i32 s46, s46, s0
	s_mov_b32 m0, s46
	s_nop 0
	global_load_lds_dwordx4 v235, s[16:17]
	s_add_i32 s16, s12, 0
	s_add_i32 s12, s16, s68
	s_mov_b32 m0, s12
	s_nop 0
	global_load_lds_dwordx4 v236, s[24:25]
	s_add_u32 s12, s48, 0x290a0000
	s_addc_u32 s13, s49, 0
	s_add_i32 s17, s16, s0
	s_mov_b32 m0, s17
	s_nop 0
	global_load_lds_dwordx4 v236, s[12:13]
	s_add_u32 s12, s48, 0x29080100
	s_addc_u32 s13, s49, 0
	s_addk_i32 s16, 0x4000
	s_add_i32 s17, s16, s68
	s_mov_b32 m0, s17
	s_nop 0
	global_load_lds_dwordx4 v236, s[12:13]
	s_add_u32 s12, s48, 0x290a0100
	s_addc_u32 s13, s49, 0
	s_add_i32 s16, s16, s0
	s_mov_b32 m0, s16
	s_nop 0
	global_load_lds_dwordx4 v236, s[12:13]

; #define LAS __attribute__((address_space(3)))
; __device__ __forceinline__ int opqv(int x) { asm volatile("" : "+v"(x)); return x; }
; __device__ __forceinline__ int crow(int r, int hi) { return (r & 3) + 8 * (r >> 2) + 4 * hi; }
; __device__ __forceinline__ unsigned cvtpk(float lo, float hi) { const f32x2 v = {lo, hi}; return __builtin_bit_cast(unsigned, __builtin_convertvector(v, bf16x2_t)); }
; __device__ __forceinline__ void row_inv_l(float l_reg, LAS unsigned char* lds, int wid, int r32_, int hi_, float (&rli)[16], int ws_off = WS_OFF) {
;   const int r32 = opqv(r32_), hi = opqv(hi_);
;   LAS float* li_l = (LAS float*)(lds + ws_off) + wid * 64;
;   if (hi == 0) li_l[r32] = l_reg; asm volatile("s_waitcnt lgkmcnt(0)" ::: "memory");
; #pragma unroll
;   for (int r = 0; r < 16; ++r) rli[r] = __builtin_amdgcn_rcpf(li_l[crow(r, hi)]);
; }
; __device__ __forceinline__ void stage_tile(const f32x16* o, LAS unsigned char* stg, int r32_, int hi_) {
;   const int r32 = opqv(r32_), hi = opqv(hi_);
; #pragma unroll
;   for (int d0 = 0; d0 < 4; ++d0)
; #pragma unroll
;     for (int r = 0; r < 16; r += 2) { const unsigned w = cvtpk(o[d0][r], o[d0][r + 1]);
;       *(LAS bf16_t*)(stg + crow(r, hi) * 256 + (32 * d0 + r32) * 2) = (bf16_t)(w & 0xffffu); *(LAS bf16_t*)(stg + crow(r + 1, hi) * 256 + (32 * d0 + r32) * 2) = (bf16_t)(w >> 16); }
;   asm volatile("s_waitcnt lgkmcnt(0)" ::: "memory");
; }
; template <int PH> __global__ void __launch_bounds__(512, 2) fwd(Params P, int L0, int L1) {
;     ...
;                     att::row_inv_l(l, F.lds, wid, r32, hi, rli, att::WS2_OFF);
; #pragma unroll
;                     for (int d = 0; d < 8; ++d)
; #pragma unroll
;                         for (int r = 0; r < 16; ++r) o[d][r] *= rli[r];
.LBB0_388:
	s_or_b64 exec, exec, s[12:13]
	v_readlane_b32 s12, v253, 28
	s_waitcnt lgkmcnt(0)
	v_readlane_b32 s17, v254, 55
	s_add_u32 s4, s4, s17
	v_lshl_add_u32 v142, v129, 4, s12
	ds_read_b128 v[128:131], v142
	ds_read_b128 v[132:135], v142 offset:32
	v_readlane_b32 s12, v253, 21
	s_addc_u32 s5, s5, 0
	s_lshl_b64 s[4:5], s[4:5], 12
	s_waitcnt lgkmcnt(1)
	v_rcp_f32_e32 v146, v128
	v_rcp_f32_e32 v147, v129
	v_rcp_f32_e32 v140, v130
	v_rcp_f32_e32 v141, v131
	ds_read_b128 v[128:131], v142 offset:64
	ds_read_b128 v[142:145], v142 offset:96
	s_waitcnt lgkmcnt(2)
	v_rcp_f32_e32 v136, v134
	v_rcp_f32_e32 v137, v135
	v_rcp_f32_e32 v138, v132
	s_waitcnt lgkmcnt(1)
	v_rcp_f32_e32 v134, v128
	v_rcp_f32_e32 v135, v129
	s_waitcnt lgkmcnt(0)
	v_rcp_f32_e32 v128, v144
	v_rcp_f32_e32 v129, v145
	v_rcp_f32_e32 v139, v133
	v_rcp_f32_e32 v132, v130
	v_rcp_f32_e32 v133, v131
	v_pk_mul_f32 v[158:159], v[128:129], v[78:79]
	v_pk_mul_f32 v[78:79], v[146:147], v[32:33]
	v_pk_mul_f32 v[32:33], v[146:147], v[48:49]
	v_mov_b32_e32 v48, v232
	v_mov_b32_e32 v49, v233
	v_pk_mul_f32 v[96:97], v[146:147], v[96:97]
	v_pk_mul_f32 v[98:99], v[140:141], v[98:99]
	v_lshlrev_b32_e32 v49, 10, v49
	v_lshlrev_b32_e32 v48, 1, v48
	v_rcp_f32_e32 v130, v142
	v_rcp_f32_e32 v131, v143
	v_pk_mul_f32 v[100:101], v[138:139], v[100:101]
	v_pk_mul_f32 v[142:143], v[146:147], v[64:65]
	v_pk_mul_f32 v[64:65], v[140:141], v[34:35]
	v_pk_mul_f32 v[34:35], v[140:141], v[50:51]
	v_cvt_pk_bf16_f32 v50, v96, v97
	v_add3_u32 v48, s12, v48, v49
	v_cvt_pk_bf16_f32 v49, v98, v99
	v_pk_mul_f32 v[102:103], v[136:137], v[102:103]
	ds_write_b16 v48, v50
	ds_write_b16_d16_hi v48, v50 offset:256
	ds_write_b16 v48, v49 offset:512
	ds_write_b16_d16_hi v48, v49 offset:768
	v_cvt_pk_bf16_f32 v49, v100, v101
	v_pk_mul_f32 v[104:105], v[134:135], v[104:105]
	ds_write_b16 v48, v49 offset:2048
	ds_write_b16_d16_hi v48, v49 offset:2304
	v_cvt_pk_bf16_f32 v49, v102, v103
	v_pk_mul_f32 v[106:107], v[132:133], v[106:107]
	ds_write_b16 v48, v49 offset:2560
	ds_write_b16_d16_hi v48, v49 offset:2816
	v_cvt_pk_bf16_f32 v49, v104, v105
	v_pk_mul_f32 v[108:109], v[130:131], v[108:109]
	ds_write_b16 v48, v49 offset:4096
	ds_write_b16_d16_hi v48, v49 offset:4352
	v_cvt_pk_bf16_f32 v49, v106, v107
	v_pk_mul_f32 v[110:111], v[128:129], v[110:111]
	ds_write_b16 v48, v49 offset:4608
	ds_write_b16_d16_hi v48, v49 offset:4864
	v_cvt_pk_bf16_f32 v49, v108, v109
	v_pk_mul_f32 v[112:113], v[146:147], v[112:113]
	ds_write_b16 v48, v49 offset:6144
	ds_write_b16_d16_hi v48, v49 offset:6400
	v_cvt_pk_bf16_f32 v49, v110, v111
	v_pk_mul_f32 v[114:115], v[140:141], v[114:115]
	ds_write_b16 v48, v49 offset:6656
	ds_write_b16_d16_hi v48, v49 offset:6912
	v_cvt_pk_bf16_f32 v49, v112, v113
	v_pk_mul_f32 v[116:117], v[138:139], v[116:117]
	ds_write_b16 v48, v49 offset:64
	ds_write_b16_d16_hi v48, v49 offset:320
	v_cvt_pk_bf16_f32 v49, v114, v115
	v_pk_mul_f32 v[118:119], v[136:137], v[118:119]
	ds_write_b16 v48, v49 offset:576
	ds_write_b16_d16_hi v48, v49 offset:832
	v_cvt_pk_bf16_f32 v49, v116, v117
	v_pk_mul_f32 v[120:121], v[134:135], v[120:121]
	ds_write_b16 v48, v49 offset:2112
	ds_write_b16_d16_hi v48, v49 offset:2368
	v_cvt_pk_bf16_f32 v49, v118, v119
	v_pk_mul_f32 v[122:123], v[132:133], v[122:123]
	ds_write_b16 v48, v49 offset:2624
	ds_write_b16_d16_hi v48, v49 offset:2880
	v_cvt_pk_bf16_f32 v49, v120, v121
	v_pk_mul_f32 v[124:125], v[130:131], v[124:125]
	ds_write_b16 v48, v49 offset:4160
	ds_write_b16_d16_hi v48, v49 offset:4416
	v_cvt_pk_bf16_f32 v49, v122, v123
	v_pk_mul_f32 v[126:127], v[128:129], v[126:127]
	ds_write_b16 v48, v49 offset:4672
	ds_write_b16_d16_hi v48, v49 offset:4928
	v_cvt_pk_bf16_f32 v49, v124, v125
	ds_write_b16 v48, v49 offset:6208
	ds_write_b16_d16_hi v48, v49 offset:6464
	v_cvt_pk_bf16_f32 v49, v126, v127
	v_pk_mul_f32 v[144:145], v[140:141], v[66:67]
	ds_write_b16 v48, v49 offset:6720
	ds_write_b16_d16_hi v48, v49 offset:6976
	v_cvt_pk_bf16_f32 v49, v142, v143
	v_pk_mul_f32 v[148:149], v[138:139], v[68:69]
	ds_write_b16 v48, v49 offset:128
	ds_write_b16_d16_hi v48, v49 offset:384
	v_cvt_pk_bf16_f32 v49, v144, v145
	v_pk_mul_f32 v[150:151], v[136:137], v[70:71]
	ds_write_b16 v48, v49 offset:640
	ds_write_b16_d16_hi v48, v49 offset:896
	v_cvt_pk_bf16_f32 v49, v148, v149
	v_pk_mul_f32 v[152:153], v[134:135], v[72:73]
	ds_write_b16 v48, v49 offset:2176
	ds_write_b16_d16_hi v48, v49 offset:2432
	v_cvt_pk_bf16_f32 v49, v150, v151
	v_pk_mul_f32 v[154:155], v[132:133], v[74:75]
	ds_write_b16 v48, v49 offset:2688
	ds_write_b16_d16_hi v48, v49 offset:2944
	v_cvt_pk_bf16_f32 v49, v152, v153
	v_pk_mul_f32 v[156:157], v[130:131], v[76:77]
	ds_write_b16 v48, v49 offset:4224
	ds_write_b16_d16_hi v48, v49 offset:4480
	v_cvt_pk_bf16_f32 v49, v154, v155
	ds_write_b16 v48, v49 offset:4736
	ds_write_b16_d16_hi v48, v49 offset:4992
	v_cvt_pk_bf16_f32 v49, v156, v157
	v_pk_mul_f32 v[80:81], v[146:147], v[80:81]
	ds_write_b16 v48, v49 offset:6272
	ds_write_b16_d16_hi v48, v49 offset:6528
	v_cvt_pk_bf16_f32 v49, v158, v159
	v_pk_mul_f32 v[82:83], v[140:141], v[82:83]
	ds_write_b16 v48, v49 offset:6784
	ds_write_b16_d16_hi v48, v49 offset:7040
	v_cvt_pk_bf16_f32 v49, v80, v81
	v_pk_mul_f32 v[84:85], v[138:139], v[84:85]
	ds_write_b16 v48, v49 offset:192
	ds_write_b16_d16_hi v48, v49 offset:448
	v_cvt_pk_bf16_f32 v49, v82, v83
	v_pk_mul_f32 v[86:87], v[136:137], v[86:87]
	ds_write_b16 v48, v49 offset:704
	ds_write_b16_d16_hi v48, v49 offset:960
	v_cvt_pk_bf16_f32 v49, v84, v85
	v_pk_mul_f32 v[88:89], v[134:135], v[88:89]
	ds_write_b16 v48, v49 offset:2240
	ds_write_b16_d16_hi v48, v49 offset:2496
	v_cvt_pk_bf16_f32 v49, v86, v87
	v_pk_mul_f32 v[90:91], v[132:133], v[90:91]
	ds_write_b16 v48, v49 offset:2752
	ds_write_b16_d16_hi v48, v49 offset:3008
	v_cvt_pk_bf16_f32 v49, v88, v89
	v_pk_mul_f32 v[92:93], v[130:131], v[92:93]
	ds_write_b16 v48, v49 offset:4288
	ds_write_b16_d16_hi v48, v49 offset:4544
	v_cvt_pk_bf16_f32 v49, v90, v91
	v_pk_mul_f32 v[94:95], v[128:129], v[94:95]
	ds_write_b16 v48, v49 offset:4800
	ds_write_b16_d16_hi v48, v49 offset:5056
	v_cvt_pk_bf16_f32 v49, v92, v93
	ds_write_b16 v48, v49 offset:6336
	ds_write_b16_d16_hi v48, v49 offset:6592
	v_cvt_pk_bf16_f32 v49, v94, v95
	v_pk_mul_f32 v[72:73], v[132:133], v[42:43]
	v_pk_mul_f32 v[42:43], v[132:133], v[58:59]
	ds_write_b16 v48, v49 offset:6848
	ds_write_b16_d16_hi v48, v49 offset:7104
	v_mov_b32_e32 v58, v231
	s_waitcnt lgkmcnt(0)
; #define LAS __attribute__((address_space(3)))
; __device__ __forceinline__ u32x4 pack8(f32x4 a, f32x4 b) { u32x4 w; w.x = cvt_pk_bf16(a[0], a[1]); w.y = cvt_pk_bf16(a[2], a[3]); w.z = cvt_pk_bf16(b[0], b[1]); w.w = cvt_pk_bf16(b[2], b[3]); return w; }
; __device__ __forceinline__ float bf_lo(unsigned w) { return __uint_as_float(w << 16); }
; __device__ __forceinline__ float bf_hi(unsigned w) { return __uint_as_float(w & 0xffff0000u); }
; __device__ __forceinline__ void stage_tile(const f32x16* o, LAS unsigned char* stg, int r32_, int hi_) {
;   const int r32 = opqv(r32_), hi = opqv(hi_);
; #pragma unroll
;   for (int d0 = 0; d0 < 4; ++d0)
; #pragma unroll
;     for (int r = 0; r < 16; r += 2) { const unsigned w = cvtpk(o[d0][r], o[d0][r + 1]);
;       *(LAS bf16_t*)(stg + crow(r, hi) * 256 + (32 * d0 + r32) * 2) = (bf16_t)(w & 0xffffu); *(LAS bf16_t*)(stg + crow(r + 1, hi) * 256 + (32 * d0 + r32) * 2) = (bf16_t)(w >> 16); }
;   asm volatile("s_waitcnt lgkmcnt(0)" ::: "memory");
; }
; template <int M> __device__ __forceinline__ void flush_tile(LAS unsigned char* stg, bf16_t* Ob, LAS float* ssq_l, int lane_) {
;   const int lane = opqv(lane_);
; #pragma unroll
;   for (int it = 0; it < 8; ++it) { const int idx = it * 64 + lane, row = idx >> 4, ch = idx & 15;
;     u32x4 w = *(const LAS u32x4*)(stg + row * 256 + ch * 16);
;     if constexpr (M > 0) {
;       f32x4 a = {bf_lo(w.x), bf_hi(w.x), bf_lo(w.y), bf_hi(w.y)}, b = {bf_lo(w.z), bf_hi(w.z), bf_lo(w.w), bf_hi(w.w)};
;       float t = (a[0] * a[0] + a[1] * a[1]) + (a[2] * a[2] + a[3] * a[3]) + (b[0] * b[0] + b[1] * b[1]) + (b[2] * b[2] + b[3] * b[3]);
;       t = row16_sum(t);
;       if constexpr (M == 1) { if (ch == 0) ssq_l[row] = t; }
;       else { const float sc = rsqrtf((ssq_l[row] + t) * (1.0f / 256.0f) + 1e-6f); w = pack8(a * sc, b * sc);
;         asm volatile("s_waitcnt lgkmcnt(0)" ::: "memory"); if (ch == 0) ssq_l[row] = sc; }
;     }
;     *(u32x4*)(Ob + (size_t)row * LDX + ch * 8) = w; }
;   asm volatile("s_waitcnt lgkmcnt(0)" ::: "memory");
; }
; template <int PH> __global__ void __launch_bounds__(512, 2) fwd(Params P, int L0, int L1) {
;     ...
;                     att::stage_tile(o, stg, r32, hi); att::flush_tile<0>(stg, Ow, nullptr, lane);
;                     att::stage_tile(o + 4, stg, r32, hi); att::flush_tile<0>(stg, Ow + 128, nullptr, lane);
	s_add_u32 s4, s18, s4
	v_lshlrev_b32_e32 v48, 4, v58
	v_and_b32_e32 v184, 0xf0, v48
	s_addc_u32 s5, s19, s5
	s_lshl_b32 s16, s36, 1
	v_pk_mul_f32 v[66:67], v[138:139], v[36:37]
	v_pk_mul_f32 v[36:37], v[138:139], v[52:53]
	v_add_u32_e32 v59, s12, v184
	v_ashrrev_i32_e32 v52, 4, v58
	s_add_u32 s4, s4, s16
	v_lshl_add_u32 v48, v52, 8, v59
	s_addc_u32 s5, s5, 0
	ds_read_b128 v[48:51], v48
	s_add_u32 s4, s4, 0x10000000
	s_addc_u32 s5, s5, 0
	v_ashrrev_i32_e32 v53, 31, v52
	v_pk_mul_f32 v[68:69], v[136:137], v[38:39]
	v_pk_mul_f32 v[38:39], v[136:137], v[54:55]
	v_lshl_add_u64 v[54:55], s[4:5], 0, v[184:185]
	v_lshlrev_b64 v[52:53], 12, v[52:53]
	v_lshl_add_u64 v[52:53], v[54:55], 0, v[52:53]
	s_waitcnt lgkmcnt(0)
	flat_store_dwordx4 v[52:53], v[48:51]
	v_pk_mul_f32 v[70:71], v[134:135], v[40:41]
	v_pk_mul_f32 v[40:41], v[134:135], v[56:57]
	v_add_u32_e32 v48, 64, v58
	v_ashrrev_i32_e32 v52, 4, v48
	v_lshl_add_u32 v48, v52, 8, v59
	ds_read_b128 v[48:51], v48
	v_ashrrev_i32_e32 v53, 31, v52
	v_pk_mul_f32 v[56:57], v[140:141], v[2:3]
	v_lshlrev_b64 v[2:3], 12, v[52:53]
	v_lshl_add_u64 v[2:3], v[54:55], 0, v[2:3]
	s_waitcnt lgkmcnt(0)
	flat_store_dwordx4 v[2:3], v[48:51]
	v_add_u32_e32 v2, 0x80, v58
	v_ashrrev_i32_e32 v2, 4, v2
	v_lshl_add_u32 v3, v2, 8, v59
	ds_read_b128 v[48:51], v3
	v_ashrrev_i32_e32 v3, 31, v2
	v_lshlrev_b64 v[2:3], 12, v[2:3]
	v_lshl_add_u64 v[2:3], v[54:55], 0, v[2:3]
	v_pk_mul_f32 v[52:53], v[138:139], v[4:5]
	s_waitcnt lgkmcnt(0)
	flat_store_dwordx4 v[2:3], v[48:51]
	v_add_u32_e32 v2, 0xc0, v58
	v_pk_mul_f32 v[74:75], v[130:131], v[44:45]
	v_ashrrev_i32_e32 v48, 4, v2
	v_lshl_add_u32 v2, v48, 8, v59
	ds_read_b128 v[2:5], v2
	v_ashrrev_i32_e32 v49, 31, v48
	v_lshlrev_b64 v[48:49], 12, v[48:49]
	v_lshl_add_u64 v[48:49], v[54:55], 0, v[48:49]
	v_pk_mul_f32 v[76:77], v[128:129], v[46:47]
	s_waitcnt lgkmcnt(0)
	flat_store_dwordx4 v[48:49], v[2:5]
	v_pk_mul_f32 v[44:45], v[130:131], v[60:61]
	v_pk_mul_f32 v[46:47], v[128:129], v[62:63]
	v_add_u32_e32 v2, 0x100, v58
	v_ashrrev_i32_e32 v48, 4, v2
	v_lshl_add_u32 v2, v48, 8, v59
	ds_read_b128 v[2:5], v2
	v_ashrrev_i32_e32 v49, 31, v48
	v_lshlrev_b64 v[48:49], 12, v[48:49]
	v_lshl_add_u64 v[48:49], v[54:55], 0, v[48:49]
	v_pk_mul_f32 v[16:17], v[146:147], v[16:17]
	s_waitcnt lgkmcnt(0)
	flat_store_dwordx4 v[48:49], v[2:5]
	v_pk_mul_f32 v[18:19], v[140:141], v[18:19]
	v_pk_mul_f32 v[20:21], v[138:139], v[20:21]
	v_add_u32_e32 v2, 0x140, v58
	v_ashrrev_i32_e32 v48, 4, v2
	v_lshl_add_u32 v2, v48, 8, v59
	ds_read_b128 v[2:5], v2
	v_ashrrev_i32_e32 v49, 31, v48
	v_lshlrev_b64 v[48:49], 12, v[48:49]
	v_lshl_add_u64 v[48:49], v[54:55], 0, v[48:49]
	v_pk_mul_f32 v[22:23], v[136:137], v[22:23]
	s_waitcnt lgkmcnt(0)
	flat_store_dwordx4 v[48:49], v[2:5]
	v_pk_mul_f32 v[24:25], v[134:135], v[24:25]
	v_pk_mul_f32 v[26:27], v[132:133], v[26:27]
	v_add_u32_e32 v2, 0x180, v58
	v_ashrrev_i32_e32 v48, 4, v2
	v_lshl_add_u32 v2, v48, 8, v59
	ds_read_b128 v[2:5], v2
	v_ashrrev_i32_e32 v49, 31, v48
	v_lshlrev_b64 v[48:49], 12, v[48:49]
	v_lshl_add_u64 v[48:49], v[54:55], 0, v[48:49]
	v_pk_mul_f32 v[28:29], v[130:131], v[28:29]
	s_waitcnt lgkmcnt(0)
	flat_store_dwordx4 v[48:49], v[2:5]
	v_pk_mul_f32 v[30:31], v[128:129], v[30:31]
	v_pk_mul_f32 v[0:1], v[146:147], v[0:1]
	v_add_u32_e32 v2, 0x1c0, v58
	v_ashrrev_i32_e32 v48, 4, v2
	v_lshl_add_u32 v2, v48, 8, v59
	ds_read_b128 v[2:5], v2
	v_ashrrev_i32_e32 v49, 31, v48
	v_lshlrev_b64 v[48:49], 12, v[48:49]
	v_lshl_add_u64 v[48:49], v[54:55], 0, v[48:49]
	v_cvt_pk_bf16_f32 v0, v0, v1
	s_waitcnt lgkmcnt(0)
	flat_store_dwordx4 v[48:49], v[2:5]
	s_waitcnt lgkmcnt(0)
	v_pk_mul_f32 v[6:7], v[136:137], v[6:7]
	v_pk_mul_f32 v[8:9], v[134:135], v[8:9]
	v_mov_b32_e32 v2, v232
	v_mov_b32_e32 v3, v233
	v_cvt_pk_bf16_f32 v4, v78, v79
	v_lshlrev_b32_e32 v3, 10, v3
	v_lshlrev_b32_e32 v2, 1, v2
	v_add3_u32 v2, s12, v2, v3
	v_cvt_pk_bf16_f32 v3, v64, v65
	ds_write_b16 v2, v4
	ds_write_b16_d16_hi v2, v4 offset:256
	ds_write_b16 v2, v3 offset:512
	ds_write_b16_d16_hi v2, v3 offset:768
	v_cvt_pk_bf16_f32 v3, v66, v67
	ds_write_b16 v2, v3 offset:2048
	ds_write_b16_d16_hi v2, v3 offset:2304
	v_cvt_pk_bf16_f32 v3, v68, v69
	ds_write_b16 v2, v3 offset:2560
	ds_write_b16_d16_hi v2, v3 offset:2816
	v_cvt_pk_bf16_f32 v3, v70, v71
	ds_write_b16 v2, v3 offset:4096
	ds_write_b16_d16_hi v2, v3 offset:4352
	v_cvt_pk_bf16_f32 v3, v72, v73
	ds_write_b16 v2, v3 offset:4608
	ds_write_b16_d16_hi v2, v3 offset:4864
	v_cvt_pk_bf16_f32 v3, v74, v75
	ds_write_b16 v2, v3 offset:6144
	ds_write_b16_d16_hi v2, v3 offset:6400
	v_cvt_pk_bf16_f32 v3, v76, v77
	ds_write_b16 v2, v3 offset:6656
	ds_write_b16_d16_hi v2, v3 offset:6912
	v_cvt_pk_bf16_f32 v3, v32, v33
	ds_write_b16 v2, v3 offset:64
	ds_write_b16_d16_hi v2, v3 offset:320
	v_cvt_pk_bf16_f32 v3, v34, v35
	ds_write_b16 v2, v3 offset:576
	ds_write_b16_d16_hi v2, v3 offset:832
	v_cvt_pk_bf16_f32 v3, v36, v37
	ds_write_b16 v2, v3 offset:2112
	ds_write_b16_d16_hi v2, v3 offset:2368
	v_cvt_pk_bf16_f32 v3, v38, v39
	ds_write_b16 v2, v3 offset:2624
	ds_write_b16_d16_hi v2, v3 offset:2880
	v_cvt_pk_bf16_f32 v3, v40, v41
	ds_write_b16 v2, v3 offset:4160
	ds_write_b16_d16_hi v2, v3 offset:4416
	v_cvt_pk_bf16_f32 v3, v42, v43
	ds_write_b16 v2, v3 offset:4672
	ds_write_b16_d16_hi v2, v3 offset:4928
	v_cvt_pk_bf16_f32 v3, v44, v45
	ds_write_b16 v2, v3 offset:6208
	ds_write_b16_d16_hi v2, v3 offset:6464
	v_cvt_pk_bf16_f32 v3, v46, v47
	ds_write_b16 v2, v3 offset:6720
	ds_write_b16_d16_hi v2, v3 offset:6976
	v_cvt_pk_bf16_f32 v3, v16, v17
	ds_write_b16 v2, v3 offset:128
	ds_write_b16_d16_hi v2, v3 offset:384
	v_cvt_pk_bf16_f32 v3, v18, v19
	ds_write_b16 v2, v3 offset:640
; #define LAS __attribute__((address_space(3)))
; __device__ __forceinline__ u32x4 pack8(f32x4 a, f32x4 b) { u32x4 w; w.x = cvt_pk_bf16(a[0], a[1]); w.y = cvt_pk_bf16(a[2], a[3]); w.z = cvt_pk_bf16(b[0], b[1]); w.w = cvt_pk_bf16(b[2], b[3]); return w; }
; __device__ __forceinline__ float bf_lo(unsigned w) { return __uint_as_float(w << 16); }
; __device__ __forceinline__ float bf_hi(unsigned w) { return __uint_as_float(w & 0xffff0000u); }
; __device__ __forceinline__ void stage_tile(const f32x16* o, LAS unsigned char* stg, int r32_, int hi_) {
;   const int r32 = opqv(r32_), hi = opqv(hi_);
; #pragma unroll
;   for (int d0 = 0; d0 < 4; ++d0)
; #pragma unroll
;     for (int r = 0; r < 16; r += 2) { const unsigned w = cvtpk(o[d0][r], o[d0][r + 1]);
;       *(LAS bf16_t*)(stg + crow(r, hi) * 256 + (32 * d0 + r32) * 2) = (bf16_t)(w & 0xffffu); *(LAS bf16_t*)(stg + crow(r + 1, hi) * 256 + (32 * d0 + r32) * 2) = (bf16_t)(w >> 16); }
;   asm volatile("s_waitcnt lgkmcnt(0)" ::: "memory");
; }
; template <int M> __device__ __forceinline__ void flush_tile(LAS unsigned char* stg, bf16_t* Ob, LAS float* ssq_l, int lane_) {
;   const int lane = opqv(lane_);
; #pragma unroll
;   for (int it = 0; it < 8; ++it) { const int idx = it * 64 + lane, row = idx >> 4, ch = idx & 15;
;     u32x4 w = *(const LAS u32x4*)(stg + row * 256 + ch * 16);
;     if constexpr (M > 0) {
;       f32x4 a = {bf_lo(w.x), bf_hi(w.x), bf_lo(w.y), bf_hi(w.y)}, b = {bf_lo(w.z), bf_hi(w.z), bf_lo(w.w), bf_hi(w.w)};
;       float t = (a[0] * a[0] + a[1] * a[1]) + (a[2] * a[2] + a[3] * a[3]) + (b[0] * b[0] + b[1] * b[1]) + (b[2] * b[2] + b[3] * b[3]);
;       t = row16_sum(t);
;       if constexpr (M == 1) { if (ch == 0) ssq_l[row] = t; }
;       else { const float sc = rsqrtf((ssq_l[row] + t) * (1.0f / 256.0f) + 1e-6f); w = pack8(a * sc, b * sc);
;         asm volatile("s_waitcnt lgkmcnt(0)" ::: "memory"); if (ch == 0) ssq_l[row] = sc; }
;     }
;     *(u32x4*)(Ob + (size_t)row * LDX + ch * 8) = w; }
;   asm volatile("s_waitcnt lgkmcnt(0)" ::: "memory");
; }
; template <int PH> __global__ void __launch_bounds__(512, 2) fwd(Params P, int L0, int L1) {
;     ...
;                     att::stage_tile(o, stg, r32, hi); att::flush_tile<0>(stg, Ow, nullptr, lane);
;                     att::stage_tile(o + 4, stg, r32, hi); att::flush_tile<0>(stg, Ow + 128, nullptr, lane);
;                     __syncthreads();
	ds_write_b16_d16_hi v2, v3 offset:896
	v_cvt_pk_bf16_f32 v3, v20, v21
	ds_write_b16 v2, v3 offset:2176
	ds_write_b16_d16_hi v2, v3 offset:2432
	v_cvt_pk_bf16_f32 v3, v22, v23
	ds_write_b16 v2, v3 offset:2688
	ds_write_b16_d16_hi v2, v3 offset:2944
	v_cvt_pk_bf16_f32 v3, v24, v25
	ds_write_b16 v2, v3 offset:4224
	ds_write_b16_d16_hi v2, v3 offset:4480
	v_cvt_pk_bf16_f32 v3, v26, v27
	ds_write_b16 v2, v3 offset:4736
	ds_write_b16_d16_hi v2, v3 offset:4992
	v_cvt_pk_bf16_f32 v3, v28, v29
	ds_write_b16 v2, v3 offset:6272
	ds_write_b16_d16_hi v2, v3 offset:6528
	v_cvt_pk_bf16_f32 v3, v30, v31
	ds_write_b16 v2, v3 offset:6784
	ds_write_b16_d16_hi v2, v3 offset:7040
	ds_write_b16 v2, v0 offset:192
	ds_write_b16_d16_hi v2, v0 offset:448
	v_cvt_pk_bf16_f32 v0, v56, v57
	ds_write_b16 v2, v0 offset:704
	ds_write_b16_d16_hi v2, v0 offset:960
	v_cvt_pk_bf16_f32 v0, v52, v53
	ds_write_b16 v2, v0 offset:2240
	ds_write_b16_d16_hi v2, v0 offset:2496
	v_cvt_pk_bf16_f32 v0, v6, v7
	v_pk_mul_f32 v[10:11], v[132:133], v[10:11]
	ds_write_b16 v2, v0 offset:2752
	ds_write_b16_d16_hi v2, v0 offset:3008
	v_cvt_pk_bf16_f32 v0, v8, v9
	v_pk_mul_f32 v[12:13], v[130:131], v[12:13]
	ds_write_b16 v2, v0 offset:4288
	ds_write_b16_d16_hi v2, v0 offset:4544
	v_cvt_pk_bf16_f32 v0, v10, v11
	v_pk_mul_f32 v[14:15], v[128:129], v[14:15]
	ds_write_b16 v2, v0 offset:4800
	ds_write_b16_d16_hi v2, v0 offset:5056
	v_cvt_pk_bf16_f32 v0, v12, v13
	ds_write_b16 v2, v0 offset:6336
	ds_write_b16_d16_hi v2, v0 offset:6592
	v_cvt_pk_bf16_f32 v0, v14, v15
	ds_write_b16 v2, v0 offset:6848
	ds_write_b16_d16_hi v2, v0 offset:7104
	v_mov_b32_e32 v8, v231
	s_waitcnt lgkmcnt(0)
	v_readlane_b32 s24, v252, 12
	v_lshlrev_b32_e32 v0, 4, v8
	v_and_b32_e32 v184, 0xf0, v0
	v_add_u32_e32 v9, s12, v184
	v_ashrrev_i32_e32 v4, 4, v8
	v_lshl_add_u32 v0, v4, 8, v9
	ds_read_b128 v[0:3], v0
	v_ashrrev_i32_e32 v5, 31, v4
	v_lshl_add_u64 v[6:7], s[4:5], 0, v[184:185]
	v_lshlrev_b64 v[4:5], 12, v[4:5]
	v_lshl_add_u64 v[4:5], v[6:7], 0, v[4:5]
	s_waitcnt lgkmcnt(0)
	flat_store_dwordx4 v[4:5], v[0:3] offset:256
	v_readlane_b32 s25, v252, 13
	s_mov_b64 s[12:13], s[24:25]
	v_add_u32_e32 v0, 64, v8
	v_ashrrev_i32_e32 v4, 4, v0
	v_lshl_add_u32 v0, v4, 8, v9
	ds_read_b128 v[0:3], v0
	v_ashrrev_i32_e32 v5, 31, v4
	v_lshlrev_b64 v[4:5], 12, v[4:5]
	v_lshl_add_u64 v[4:5], v[6:7], 0, v[4:5]
	s_lshl_b64 s[8:9], s[8:9], 1
	s_waitcnt lgkmcnt(0)
	flat_store_dwordx4 v[4:5], v[0:3] offset:256
	v_mov_b32_e32 v18, v220
	s_movk_i32 s40, 0xf0
	v_add_u32_e32 v0, 0x80, v8
	v_ashrrev_i32_e32 v4, 4, v0
	v_lshl_add_u32 v0, v4, 8, v9
	ds_read_b128 v[0:3], v0
	v_ashrrev_i32_e32 v5, 31, v4
	v_lshlrev_b64 v[4:5], 12, v[4:5]
	v_lshl_add_u64 v[4:5], v[6:7], 0, v[4:5]
	v_mov_b32_e32 v250, 0
	s_waitcnt lgkmcnt(0)
	flat_store_dwordx4 v[4:5], v[0:3] offset:256
	v_mov_b32_e32 v249, 0xf149f2ca
	v_mov_b32_e32 v22, v250
	v_add_u32_e32 v0, 0xc0, v8
	v_ashrrev_i32_e32 v4, 4, v0
	v_lshl_add_u32 v0, v4, 8, v9
	ds_read_b128 v[0:3], v0
	v_ashrrev_i32_e32 v5, 31, v4
	v_lshlrev_b64 v[4:5], 12, v[4:5]
	v_lshl_add_u64 v[4:5], v[6:7], 0, v[4:5]
	v_mov_b32_e32 v23, v250
	s_waitcnt lgkmcnt(0)
	flat_store_dwordx4 v[4:5], v[0:3] offset:256
	v_mov_b32_e32 v24, v250
	v_mov_b32_e32 v25, v250
	v_add_u32_e32 v0, 0x100, v8
	v_ashrrev_i32_e32 v4, 4, v0
	v_lshl_add_u32 v0, v4, 8, v9
	ds_read_b128 v[0:3], v0
	v_ashrrev_i32_e32 v5, 31, v4
	v_lshlrev_b64 v[4:5], 12, v[4:5]
	v_lshl_add_u64 v[4:5], v[6:7], 0, v[4:5]
	v_mov_b32_e32 v26, v250
	s_waitcnt lgkmcnt(0)
	flat_store_dwordx4 v[4:5], v[0:3] offset:256
	v_mov_b32_e32 v27, v250
	v_mov_b32_e32 v28, v250
	v_add_u32_e32 v0, 0x140, v8
	v_ashrrev_i32_e32 v4, 4, v0
	v_lshl_add_u32 v0, v4, 8, v9
	ds_read_b128 v[0:3], v0
	v_ashrrev_i32_e32 v5, 31, v4
	v_lshlrev_b64 v[4:5], 12, v[4:5]
	v_lshl_add_u64 v[4:5], v[6:7], 0, v[4:5]
	v_mov_b32_e32 v29, v250
	s_waitcnt lgkmcnt(0)
	flat_store_dwordx4 v[4:5], v[0:3] offset:256
	v_mov_b32_e32 v30, v250
	v_mov_b32_e32 v31, v250
	v_add_u32_e32 v0, 0x180, v8
	v_ashrrev_i32_e32 v4, 4, v0
	v_lshl_add_u32 v0, v4, 8, v9
	ds_read_b128 v[0:3], v0
	v_ashrrev_i32_e32 v5, 31, v4
	v_lshlrev_b64 v[4:5], 12, v[4:5]
	v_lshl_add_u64 v[4:5], v[6:7], 0, v[4:5]
	v_mov_b32_e32 v64, 0
	s_waitcnt lgkmcnt(0)
	flat_store_dwordx4 v[4:5], v[0:3] offset:256
	v_mov_b32_e32 v65, v250
	v_mov_b32_e32 v66, v250
	v_add_u32_e32 v0, 0x1c0, v8
	v_ashrrev_i32_e32 v4, 4, v0
	v_lshl_add_u32 v0, v4, 8, v9
	ds_read_b128 v[0:3], v0
	v_ashrrev_i32_e32 v5, 31, v4
	v_lshlrev_b64 v[4:5], 12, v[4:5]
	v_lshl_add_u64 v[4:5], v[6:7], 0, v[4:5]
	v_mov_b32_e32 v67, v250
	s_waitcnt lgkmcnt(0)
	flat_store_dwordx4 v[4:5], v[0:3] offset:256
	s_waitcnt lgkmcnt(0)
	s_waitcnt lgkmcnt(0)
	s_barrier
; #define LAS __attribute__((address_space(3)))
; __device__ __forceinline__ int tid_of(int wave) { return opqv(wave * 64 + (int)__builtin_amdgcn_mbcnt_hi(~0u, __builtin_amdgcn_mbcnt_lo(~0u, 0u))); }
; __device__ __forceinline__ int v_rd_base(int lane) { return ((lane & 3) << 3) | (((lane >> 2) & 3) << 6) | (((lane >> 4) & 1) << 5) | (((lane >> 5) & 1) << 8); }
; __device__ __forceinline__ void attn_pass_dv256(const bf16_t* __restrict__ Qb, const bf16_t* __restrict__ Kh, const bf16_t* __restrict__ Vh, int qpos0,
;                                                 LAS unsigned char* lds, f32x16 (&o)[8], float& l_out, int wave_) {
;   const int tid = tid_of(wave_), wid = wave_, lane = tid & 63, r32 = lane & 31, hi = lane >> 5;
;   LAS unsigned char* K_lds = lds + K2_OFF;
;   LAS float* al_l = (LAS float*)(lds + WS2_OFF) + wid * 64 + 32;
;   const LAS float* tbl = (const LAS float*)(lds + TBL2_OFF);
;   float m_reg = -1e30f, l_reg = 0;
; #pragma unroll
;   for (int d = 0; d < 8; ++d) o[d] = f32x16{};
;   bf16x8 qr[4];
;   LAS unsigned char* qf = lds + Q2_OFF + wid * 4096;
;   const bf16_t* Qw = Qb + (size_t)(wid * 32 + r32) * LDX + hi * 8;
; #pragma unroll
;   for (int d0 = 0; d0 < 4; ++d0) qr[d0] = *(const bf16x8*)(Qw + d0 * 16);
; #pragma unroll
;   for (int d0 = 4; d0 < 8; ++d0) *(LAS bf16x8*)(qf + ((d0 - 4) * 64 + lane) * 16) = *(const bf16x8*)(Qw + d0 * 16);
;   const unsigned ldsb = (unsigned)(uintptr_t)lds;
;   const unsigned vb0 = ldsb + V2_OFF + v_rd_base(lane);
;   const int krow = 4 * wid + (lane >> 4);
;   const unsigned voffK = (unsigned)(krow * (LDX * 2) + (((lane & 15) ^ (krow & 15)) << 4));
;   const int vst_ = 2 * wid + (lane >> 5), vkk = (vst_ >> 2) * 8 + ((lane >> 2) & 7), vk = (vkk & ~0xC) | ((vkk & 4) << 1) | ((vkk & 8) >> 1);
;   const unsigned voffV = (unsigned)(vk * (LDX * 2) + ((vst_ & 3) * 4 + (lane & 3)) * 16);
;   const int qw0 = qpos0 + wid * 32, qme = qw0 + r32;
;   constexpr int NT = SEQ / KVBLK;
;     ...
;   f32x16 p0, p1; float mn, al, cadd; bf16x8 pa0, pa1, pa2, pa3;
;   DMA_KV(0, 0); DMA_KV(1, 1);
;   asm volatile("s_waitcnt vmcnt(6)" ::: "memory"); BARL();
; template <int PH> __global__ void __launch_bounds__(512, 2) fwd(Params P, int L0, int L1) {
;     ...
;                     att::attn_pass_dv256(DQ + rows0 * 2048 + (2 * h + 1) * 128, DK + krow0 * 2048 + (2 * h + 1) * 128, DV + krow0 * 2048 + h * 256, qb * 256, F.lds, o, l, F.wave);
	s_add_u32 s8, s12, s8
	s_addc_u32 s9, s13, s9
	s_add_u32 s18, s8, s16
	s_addc_u32 s19, s9, 0
	s_mov_b64 s[8:9], s[24:25]
	s_mov_b64 s[12:13], s[24:25]
	s_lshl_b64 s[10:11], s[10:11], 1
	v_and_b32_e32 v20, 31, v18
	v_or_b32_e32 v184, s17, v20
	v_bfe_u32 v19, v18, 5, 1
	v_lshlrev_b64 v[0:1], 12, v[184:185]
	v_lshl_add_u64 v[0:1], s[18:19], 0, v[0:1]
	v_lshlrev_b32_e32 v184, 4, v19
	v_lshl_add_u64 v[0:1], v[0:1], 0, v[184:185]
	s_mov_b64 s[18:19], 0x19000000
	v_lshl_add_u64 v[16:17], v[0:1], 0, s[18:19]
	flat_load_dwordx4 v[0:3], v[16:17] offset:384
	flat_load_dwordx4 v[4:7], v[16:17] offset:416
	flat_load_dwordx4 v[8:11], v[16:17] offset:448
	flat_load_dwordx4 v[12:15], v[16:17] offset:480
	flat_load_dwordx4 v[160:163], v[16:17] offset:256
	flat_load_dwordx4 v[164:167], v[16:17] offset:288
	flat_load_dwordx4 v[168:171], v[16:17] offset:320
	flat_load_dwordx4 v[172:175], v[16:17] offset:352
	s_add_u32 s17, s8, s10
	s_addc_u32 s18, s9, s11
	s_add_u32 s24, s17, s16
	s_addc_u32 s25, s18, 0
	s_add_u32 s18, s24, 0x21000100
	s_addc_u32 s19, s25, 0
	s_add_u32 s10, s12, s10
	s_addc_u32 s11, s13, s11
	v_and_b32_e32 v21, 63, v18
	s_add_u32 s36, s10, s16
	v_lshlrev_b32_e32 v16, 4, v21
	v_readlane_b32 s16, v253, 23
	s_addc_u32 s37, s11, 0
	s_add_u32 s10, s36, 0x29000000
	v_add_u32_e32 v234, s16, v16
	s_waitcnt vmcnt(0) lgkmcnt(0)
	ds_write_b128 v234, v[0:3]
	ds_write_b128 v234, v[4:7] offset:1024
	ds_write_b128 v234, v[8:11] offset:2048
	ds_write_b128 v234, v[12:15] offset:3072
	v_bfe_u32 v3, v18, 4, 2
	v_readlane_b32 s16, v253, 19
	s_addc_u32 s11, s37, 0
	v_lshlrev_b32_e32 v5, 4, v18
	v_or_b32_e32 v4, s16, v3
	v_bitop3_b32 v3, v3, v18, s16 bitop3:0x36
	v_lshlrev_b32_e32 v4, 12, v4
	v_lshlrev_b32_e32 v3, 4, v3
	v_and_or_b32 v235, v3, s40, v4
	v_lshrrev_b32_e32 v4, 1, v18
	v_bfe_u32 v3, v18, 2, 2
	v_and_b32_e32 v4, 8, v4
	v_readlane_b32 s16, v253, 20
	v_and_b32_e32 v6, 48, v5
	v_lshlrev_b32_e32 v0, 3, v18
	v_or3_b32 v3, v3, v4, s16
	v_readlane_b32 s16, v253, 22
	v_lshlrev_b32_e32 v2, 1, v18
	v_and_b32_e32 v0, 0x118, v0
	v_or_b32_e32 v4, s16, v19
	s_mov_b32 m0, s80
	s_nop 0
	global_load_lds_dwordx4 v235, s[18:19]
	s_add_u32 s16, s24, 0x21020100
	v_lshl_or_b32 v4, v4, 6, v6
	s_addc_u32 s17, s25, 0
	s_mov_b32 m0, s81
	s_nop 0
	global_load_lds_dwordx4 v235, s[16:17]
	v_lshl_or_b32 v236, v3, 12, v4
	s_mov_b32 m0, s76
	s_nop 0
	global_load_lds_dwordx4 v236, s[10:11]
	s_add_u32 s10, s36, 0x29020000
	s_addc_u32 s11, s37, 0
	s_mov_b32 m0, s89
	s_nop 0
	global_load_lds_dwordx4 v236, s[10:11]
	s_add_u32 s10, s36, 0x29000100
	s_addc_u32 s11, s37, 0
	s_mov_b32 m0, s1
	s_nop 0
	global_load_lds_dwordx4 v236, s[10:11]
	s_add_u32 s10, s36, 0x29020100
	s_addc_u32 s11, s37, 0
	s_mov_b32 m0, s69
	s_nop 0
	global_load_lds_dwordx4 v236, s[10:11]
	s_add_u32 s10, s24, 0x21040100
	s_addc_u32 s11, s25, 0
	s_add_u32 s16, s36, 0x29040000
	s_addc_u32 s17, s37, 0
	s_mov_b32 m0, s29
	s_nop 0
	global_load_lds_dwordx4 v235, s[10:11]
	s_add_u32 s10, s24, 0x21060100
	s_addc_u32 s11, s25, 0
	s_mov_b32 m0, s88
	s_nop 0
	global_load_lds_dwordx4 v235, s[10:11]
	s_mov_b32 m0, s22
	s_nop 0
	global_load_lds_dwordx4 v236, s[16:17]
	s_add_u32 s10, s36, 0x29060000
	s_addc_u32 s11, s37, 0
	s_mov_b32 m0, s2
	s_nop 0
	global_load_lds_dwordx4 v236, s[10:11]
	s_add_u32 s10, s36, 0x29040100
	s_addc_u32 s11, s37, 0
	s_mov_b32 m0, s14
	s_nop 0
	global_load_lds_dwordx4 v236, s[10:11]
	s_add_u32 s10, s36, 0x29060100
	s_addc_u32 s11, s37, 0
	s_mov_b32 m0, s15
	s_nop 0
	global_load_lds_dwordx4 v236, s[10:11]
	v_and_b32_e32 v3, 0xf0, v5
	s_movk_i32 s10, 0x60
	v_bitop3_b32 v242, v184, v3, s10 bitop3:0x36
	s_movk_i32 s10, 0x80
	v_bitop3_b32 v243, v184, v3, s10 bitop3:0x36
	s_movk_i32 s10, 0xa0
	v_bitop3_b32 v244, v184, v3, s10 bitop3:0x36
	s_movk_i32 s10, 0xc0
	v_bitop3_b32 v245, v184, v3, s10 bitop3:0x36
	s_movk_i32 s10, 0xe0
	v_and_b32_e32 v1, 0xc0, v16
	s_waitcnt vmcnt(6)
	v_bitop3_b32 v246, v184, v3, s10 bitop3:0x36
	v_and_or_b32 v0, v2, 32, v0
	s_add_u32 s10, s12, s6
	s_waitcnt lgkmcnt(0)
	s_barrier
	v_lshlrev_b32_e32 v4, 2, v19
	v_add3_u32 v247, v1, 0, v0
	s_addc_u32 s11, s13, s7
	v_add_u32_e32 v0, s31, v20
	v_mov_b32_e32 v14, v185
	v_mov_b32_e32 v15, v185
	v_bitop3_b32 v239, v184, v5, s40 bitop3:0x78
	v_bitop3_b32 v240, v184, v3, 32 bitop3:0x36
	v_bitop3_b32 v241, v184, v3, 64 bitop3:0x36
	s_add_u32 s12, s8, s6
	v_sub_u32_e32 v248, v4, v0
	v_mov_b32_e32 v0, v185
	v_mov_b32_e32 v1, v185
	v_mov_b32_e32 v2, v185
	v_mov_b32_e32 v3, v185
	v_mov_b32_e32 v4, v185
	v_mov_b32_e32 v5, v185
	v_mov_b32_e32 v6, v185
	v_mov_b32_e32 v7, v185
	v_mov_b32_e32 v8, v185
	v_mov_b32_e32 v9, v185
	v_mov_b32_e32 v10, v185
	v_mov_b32_e32 v11, v185
	v_mov_b32_e32 v12, v185
	v_mov_b32_e32 v13, v185
	v_mov_b64_e32 v[46:47], v[14:15]
	v_mov_b64_e32 v[62:63], v[14:15]
	v_lshl_add_u32 v237, v20, 8, s23
	v_cmp_gt_u32_e64 s[38:39], 32, v21
	v_lshl_add_u32 v238, v20, 2, s59
	s_addc_u32 s13, s9, s7
	s_mov_b32 s16, 0
	v_mov_b64_e32 v[44:45], v[12:13]
	v_mov_b64_e32 v[42:43], v[10:11]
	v_mov_b64_e32 v[40:41], v[8:9]
	v_mov_b64_e32 v[38:39], v[6:7]
	v_mov_b64_e32 v[36:37], v[4:5]
	v_mov_b64_e32 v[34:35], v[2:3]
	v_mov_b64_e32 v[32:33], v[0:1]
	v_mov_b64_e32 v[60:61], v[12:13]
	v_mov_b64_e32 v[58:59], v[10:11]
	v_mov_b64_e32 v[56:57], v[8:9]
	v_mov_b64_e32 v[54:55], v[6:7]
	v_mov_b64_e32 v[52:53], v[4:5]
	v_mov_b64_e32 v[50:51], v[2:3]
	v_mov_b64_e32 v[48:49], v[0:1]
	s_mov_b32 s17, 0
	v_mov_b32_e32 v16, 0
	v_mov_b32_e32 v17, v250
	v_mov_b32_e32 v18, v250
	v_mov_b32_e32 v19, v250
	v_mov_b32_e32 v20, v250
	v_mov_b32_e32 v21, v250
	v_mov_b32_e32 v68, v250
	v_mov_b32_e32 v69, v250
	v_mov_b32_e32 v70, v250
	v_mov_b32_e32 v71, v250
	v_mov_b32_e32 v72, v250
	v_mov_b32_e32 v73, v250
	v_mov_b32_e32 v74, v250
	v_mov_b32_e32 v75, v250
	v_mov_b32_e32 v76, v250
	v_mov_b32_e32 v77, v250
	v_mov_b32_e32 v78, v250
	v_mov_b32_e32 v79, v250
	v_mov_b32_e32 v80, 0
	v_mov_b32_e32 v81, v250
	v_mov_b32_e32 v82, v250
	v_mov_b32_e32 v83, v250
	v_mov_b32_e32 v84, v250
	v_mov_b32_e32 v85, v250
	v_mov_b32_e32 v86, v250
	v_mov_b32_e32 v87, v250
	v_mov_b32_e32 v88, v250
	v_mov_b32_e32 v89, v250
	v_mov_b32_e32 v90, v250
	v_mov_b32_e32 v91, v250
	v_mov_b32_e32 v92, v250
	v_mov_b32_e32 v93, v250
	v_mov_b32_e32 v94, v250
	v_mov_b32_e32 v95, v250
	v_mov_b32_e32 v96, 0
	v_mov_b32_e32 v97, v250
	v_mov_b32_e32 v98, v250
	v_mov_b32_e32 v99, v250
	v_mov_b32_e32 v100, v250
	v_mov_b32_e32 v101, v250
	v_mov_b32_e32 v102, v250
	v_mov_b32_e32 v103, v250
	v_mov_b32_e32 v104, v250
	v_mov_b32_e32 v105, v250
	v_mov_b32_e32 v106, v250
	v_mov_b32_e32 v107, v250
	v_mov_b32_e32 v108, v250
	v_mov_b32_e32 v109, v250
	v_mov_b32_e32 v110, v250
	v_mov_b32_e32 v111, v250
	v_mov_b32_e32 v112, 0
	v_mov_b32_e32 v113, v250
	v_mov_b32_e32 v114, v250
	v_mov_b32_e32 v115, v250
	v_mov_b32_e32 v116, v250
	v_mov_b32_e32 v117, v250
	v_mov_b32_e32 v118, v250
	v_mov_b32_e32 v119, v250
	v_mov_b32_e32 v120, v250
	v_mov_b32_e32 v121, v250
	v_mov_b32_e32 v122, v250
	v_mov_b32_e32 v123, v250
	v_mov_b32_e32 v124, v250
	v_mov_b32_e32 v125, v250
	v_mov_b32_e32 v126, v250
	v_mov_b32_e32 v127, v250

; __device__ __forceinline__ void partialSM(f32x16& p0, f32x16& p1, float& m_reg, float& mn, float& alpha, float cadd) {
;   float pmax = p0[0];
; #pragma unroll
;   for (int r = 1; r < 16; ++r) pmax = fmaxf(pmax, p0[r]);
; #pragma unroll
;   for (int r = 0; r < 16; ++r) pmax = fmaxf(pmax, p1[r]);
;   { auto rr = __builtin_amdgcn_permlane32_swap(__float_as_uint(pmax), __float_as_uint(pmax), false, false);
;     pmax = fmaxf(__uint_as_float(rr[0]), __uint_as_float(rr[1])); }
;   pmax += cadd;
;   if (__builtin_expect(__all(pmax - m_reg <= THRL), 1)) { mn = m_reg; alpha = 1.f; }
;   else { mn = fmaxf(m_reg, pmax); alpha = __builtin_amdgcn_exp2f(m_reg - mn); m_reg = mn; }
;   const float off = cadd - mn;
; #pragma unroll
;   for (int r = 0; r < 16; ++r) p0[r] += off;
; #pragma unroll
;   for (int r = 0; r < 16; ++r) p1[r] += off;
; #pragma unroll
;   for (int r = 0; r < 16; ++r) p0[r] = __builtin_amdgcn_exp2f(p0[r]);
; }
; __device__ __forceinline__ void attn_pass_dv256(const bf16_t* __restrict__ Qb, const bf16_t* __restrict__ Kh, const bf16_t* __restrict__ Vh, int qpos0,
;                                                 LAS unsigned char* lds, f32x16 (&o)[8], float& l_out, int wave_) {
;     ...
;     { const int dd = j * KVBLK - qw0;
;       if (dd <= -191 || dd >= 159) { cadd = (dd < 0) ? tbl[0] : tbl[256]; partialSM(p0, p1, m_reg, mn, al, cadd); }
;       else { add_bias(p0, p1, tbl, j * KVBLK - qme, hi); partialSM(p0, p1, m_reg, mn, al, 0.f); } }
.LBB0_391:
	s_andn2_b64 vcc, exec, s[8:9]
	v_mov_b32_e32 v251, 0
	s_cbranch_vccnz .LBB0_393
	s_cmp_lt_i32 s24, 0
	s_mov_b32 s6, 0x18c00
	s_cselect_b32 s6, 0x18800, s6
	s_add_i32 s6, s6, 0
	v_mov_b32_e32 v178, s6
	ds_read_b32 v251, v178
	s_nop 0
	v_max_f32_e32 v178, v129, v129
	v_max_f32_e32 v179, v128, v128
	v_max_f32_e32 v178, v179, v178
	v_max3_f32 v178, v178, v130, v131
	v_max3_f32 v178, v178, v132, v133
	v_max3_f32 v178, v178, v134, v135
	v_max3_f32 v178, v178, v136, v137
	v_max3_f32 v178, v178, v138, v139
	v_max3_f32 v178, v178, v140, v141
	v_max3_f32 v178, v178, v142, v143
	v_max3_f32 v178, v178, v144, v145
	v_max3_f32 v178, v178, v146, v147
	v_max3_f32 v178, v178, v148, v149
	v_max3_f32 v178, v178, v150, v151
	v_max3_f32 v178, v178, v152, v153
	v_max3_f32 v178, v178, v154, v155
	v_max3_f32 v178, v178, v156, v157
	v_max3_f32 v178, v178, v158, v159
	v_mov_b32_e32 v179, v178
	s_nop 1
	v_permlane32_swap_b32_e32 v178, v179
	v_max_f32_e32 v179, v179, v179
	v_max_f32_e32 v178, v178, v178
	v_max_f32_e32 v178, v178, v179
	s_waitcnt lgkmcnt(0)
	v_add_f32_e32 v221, v251, v178
	v_sub_f32_e32 v178, v221, v249
	v_cmp_ge_f32_e32 vcc, s94, v178
	s_cmp_eq_u64 vcc, exec
	s_cselect_b64 s[6:7], -1, 0
	s_cbranch_scc0 .Lslow_p2
	v_sub_f32_e32 v180, v251, v249
	v_add_f32_e32 v181, v180, v159
	v_add_f32_e32 v159, v180, v157
	v_add_f32_e32 v178, v180, v158
	v_add_f32_e32 v157, v180, v155
	v_add_f32_e32 v158, v180, v156
	v_add_f32_e32 v155, v180, v153
	v_add_f32_e32 v156, v180, v154
	v_add_f32_e32 v153, v180, v151
	v_add_f32_e32 v154, v180, v152
	v_add_f32_e32 v151, v180, v149
	v_add_f32_e32 v152, v180, v150
	v_add_f32_e32 v149, v180, v147
	v_add_f32_e32 v150, v180, v148
	v_add_f32_e32 v147, v180, v145
	v_add_f32_e32 v148, v180, v146
	v_add_f32_e32 v145, v180, v143
	v_add_f32_e32 v146, v180, v144
	v_add_f32_e32 v143, v180, v142
	v_add_f32_e32 v142, v180, v141
	v_add_f32_e32 v141, v180, v140
	v_add_f32_e32 v140, v180, v139
	v_add_f32_e32 v139, v180, v138
	v_add_f32_e32 v138, v180, v137
	v_add_f32_e32 v137, v180, v136
	v_add_f32_e32 v136, v180, v135
	v_add_f32_e32 v135, v180, v134
	v_add_f32_e32 v134, v180, v133
	v_add_f32_e32 v133, v180, v132
	v_add_f32_e32 v132, v180, v131
	v_add_f32_e32 v131, v180, v130
	v_add_f32_e32 v130, v180, v129
	v_add_f32_e32 v129, v180, v128
	v_mov_b32_e32 v128, v181
	v_exp_f32_e32 v129, v129
	v_exp_f32_e32 v130, v130
	v_exp_f32_e32 v131, v131
	v_mov_b32_e32 v144, 1.0
	s_branch .Ljoin_p2

; #define SBAR() __builtin_amdgcn_sched_barrier(0)
; template <int OFF> __device__ __forceinline__ s16x4 tr_read(unsigned vb) { s16x4 r; asm volatile("ds_read_b64_tr_b16 %0, %1 offset:%2" : "=&v"(r) : "v"(vb), "i"(OFF) : "memory"); return r; }
; template <int D0> __device__ __forceinline__ void pv_one(f32x16& od, unsigned vb, bf16x8 pa0, bf16x8 pa1, bf16x8 pa2, bf16x8 pa3) {
;   const s16x4 l0 = tr_read<v_rd_off(D0, 0, 0)>(vb), h0 = tr_read<v_rd_off(D0, 0, 1)>(vb), l1 = tr_read<v_rd_off(D0, 1, 0)>(vb), h1 = tr_read<v_rd_off(D0, 1, 1)>(vb);
;   const s16x4 l2 = tr_read<v_rd_off(D0, 2, 0)>(vb), h2 = tr_read<v_rd_off(D0, 2, 1)>(vb), l3 = tr_read<v_rd_off(D0, 3, 0)>(vb), h3 = tr_read<v_rd_off(D0, 3, 1)>(vb);
;   asm volatile("s_waitcnt lgkmcnt(0)" ::: "memory"); SBAR();
;     ...
;   od = __builtin_amdgcn_mfma_f32_32x32x16_bf16(pa0, PK(l0, h0), od, 0, 0, 0);
;   od = __builtin_amdgcn_mfma_f32_32x32x16_bf16(pa1, PK(l1, h1), od, 0, 0, 0);
;   od = __builtin_amdgcn_mfma_f32_32x32x16_bf16(pa2, PK(l2, h2), od, 0, 0, 0);
;   od = __builtin_amdgcn_mfma_f32_32x32x16_bf16(pa3, PK(l3, h3), od, 0, 0, 0);
; __device__ __forceinline__ void finishSM(f32x16& p0, f32x16& p1, float alpha, float& l_reg, bf16x8& pa0, bf16x8& pa1, bf16x8& pa2, bf16x8& pa3) {
; #pragma unroll
;   for (int r = 0; r < 16; ++r) p1[r] = __builtin_amdgcn_exp2f(p1[r]);
;   float ps = 0;
; #pragma unroll
;   for (int r = 0; r < 16; ++r) ps += p0[r];
; #pragma unroll
;   for (int r = 0; r < 16; ++r) ps += p1[r];
;   { auto rr = __builtin_amdgcn_permlane32_swap(__float_as_uint(ps), __float_as_uint(ps), false, false);
;     ps = __uint_as_float(rr[0]) + __uint_as_float(rr[1]); }
;   l_reg = l_reg * alpha + ps;
;     ...
;   PK4(p0, 0, pa0); PK4(p0, 8, pa1); PK4(p1, 0, pa2); PK4(p1, 8, pa3);
.Ljoin_p2:
	v_exp_f32_e32 v132, v132
	v_exp_f32_e32 v133, v133
	v_exp_f32_e32 v181, v128
	v_add_f32_e32 v128, 0, v129
	v_exp_f32_e32 v134, v134
	v_add_f32_e32 v128, v130, v128
	v_exp_f32_e32 v135, v135
	v_add_f32_e32 v128, v131, v128
	v_exp_f32_e32 v136, v136
	v_add_f32_e32 v128, v132, v128
	v_exp_f32_e32 v137, v137
	v_add_f32_e32 v128, v133, v128
	v_exp_f32_e32 v138, v138
	v_add_f32_e32 v128, v134, v128
	v_exp_f32_e32 v139, v139
	v_add_f32_e32 v128, v135, v128
	v_exp_f32_e32 v140, v140
	v_add_f32_e32 v128, v136, v128
	v_exp_f32_e32 v141, v141
	v_add_f32_e32 v128, v137, v128
	v_exp_f32_e32 v142, v142
	v_add_f32_e32 v128, v138, v128
	v_exp_f32_e32 v143, v143
	v_add_f32_e32 v128, v139, v128
	v_exp_f32_e32 v179, v145
	v_add_f32_e32 v128, v140, v128
	v_exp_f32_e32 v180, v146
	v_add_f32_e32 v128, v141, v128
	v_exp_f32_e32 v147, v147
	v_add_f32_e32 v128, v142, v128
	v_exp_f32_e32 v148, v148
	v_add_f32_e32 v128, v143, v128
	v_exp_f32_e32 v149, v149
	v_add_f32_e32 v128, v179, v128
	v_exp_f32_e32 v150, v150
	v_add_f32_e32 v128, v180, v128
	v_exp_f32_e32 v151, v151
	v_add_f32_e32 v128, v147, v128
	v_exp_f32_e32 v152, v152
	v_add_f32_e32 v128, v148, v128
	v_exp_f32_e32 v153, v153
	v_add_f32_e32 v128, v149, v128
	v_exp_f32_e32 v154, v154
	v_add_f32_e32 v128, v150, v128
	v_exp_f32_e32 v155, v155
	v_add_f32_e32 v128, v151, v128
	v_exp_f32_e32 v156, v156
	v_add_f32_e32 v128, v152, v128
	v_exp_f32_e32 v157, v157
	v_add_f32_e32 v128, v153, v128
	v_exp_f32_e32 v158, v158
	v_add_f32_e32 v128, v154, v128
	v_exp_f32_e32 v159, v159
	v_add_f32_e32 v128, v155, v128
	v_exp_f32_e32 v178, v178
	v_add_f32_e32 v128, v156, v128
	v_add_f32_e32 v128, v157, v128
	v_add_f32_e32 v128, v158, v128
	v_add_f32_e32 v128, v159, v128
	v_add_f32_e32 v128, v178, v128
	v_add_f32_e32 v145, v181, v128
	v_mov_b32_e32 v146, v145
	s_nop 1
	v_permlane32_swap_b32_e32 v145, v146
	v_cvt_pk_bf16_f32 v128, v129, v130
	v_cvt_pk_bf16_f32 v129, v131, v132
	v_cvt_pk_bf16_f32 v130, v133, v134
	v_cvt_pk_bf16_f32 v131, v135, v136
	v_cvt_pk_bf16_f32 v132, v137, v138
	v_cvt_pk_bf16_f32 v133, v139, v140
	v_cvt_pk_bf16_f32 v134, v141, v142
	v_cvt_pk_bf16_f32 v135, v143, v179
	v_cvt_pk_bf16_f32 v136, v180, v147
	v_cvt_pk_bf16_f32 v137, v148, v149
	v_cvt_pk_bf16_f32 v138, v150, v151
	v_cvt_pk_bf16_f32 v139, v152, v153
	v_cvt_pk_bf16_f32 v140, v154, v155
	v_cvt_pk_bf16_f32 v141, v156, v157
	v_cvt_pk_bf16_f32 v142, v158, v159
	v_cvt_pk_bf16_f32 v143, v178, v181
	v_permlane32_swap_b32_e32 v128, v130
	v_permlane32_swap_b32_e32 v129, v131
	v_permlane32_swap_b32_e32 v132, v134
	v_permlane32_swap_b32_e32 v133, v135
	v_permlane32_swap_b32_e32 v136, v138
	v_permlane32_swap_b32_e32 v137, v139
	v_permlane32_swap_b32_e32 v140, v142
	v_permlane32_swap_b32_e32 v141, v143
	s_lshl_b32 s6, s19, 15
	v_add_u32_e32 v147, s6, v247
	ds_read_b64_tr_b16 v[148:149], v147 offset:0
	ds_read_b64_tr_b16 v[150:151], v147 offset:0x800
	ds_read_b64_tr_b16 v[152:153], v147 offset:0x1000
	ds_read_b64_tr_b16 v[154:155], v147 offset:0x1800
	ds_read_b64_tr_b16 v[156:157], v147 offset:0x2000
	ds_read_b64_tr_b16 v[158:159], v147 offset:0x2800
	ds_read_b64_tr_b16 v[178:179], v147 offset:0x3000
	ds_read_b64_tr_b16 v[180:181], v147 offset:0x3800
	s_waitcnt lgkmcnt(0)
	s_nop 0
	v_mfma_f32_32x32x16_bf16 v[48:63], v[128:131], v[148:151], v[48:63]
	ds_read_b64_tr_b16 v[148:149], v147 offset:0x200
	ds_read_b64_tr_b16 v[150:151], v147 offset:0xa00
	v_mfma_f32_32x32x16_bf16 v[48:63], v[132:135], v[152:155], v[48:63]
	ds_read_b64_tr_b16 v[152:153], v147 offset:0x1200
	ds_read_b64_tr_b16 v[154:155], v147 offset:0x1a00
	v_mfma_f32_32x32x16_bf16 v[48:63], v[136:139], v[156:159], v[48:63]
	ds_read_b64_tr_b16 v[156:157], v147 offset:0x2200
	ds_read_b64_tr_b16 v[158:159], v147 offset:0x2a00
	v_mfma_f32_32x32x16_bf16 v[48:63], v[140:143], v[178:181], v[48:63]
	ds_read_b64_tr_b16 v[178:179], v147 offset:0x3200
	ds_read_b64_tr_b16 v[180:181], v147 offset:0x3a00
	s_waitcnt lgkmcnt(0)
	v_mfma_f32_32x32x16_bf16 v[32:47], v[128:131], v[148:151], v[32:47]
	ds_read_b64_tr_b16 v[148:149], v147 offset:0x400
	ds_read_b64_tr_b16 v[150:151], v147 offset:0xc00
	v_mfma_f32_32x32x16_bf16 v[32:47], v[132:135], v[152:155], v[32:47]
	ds_read_b64_tr_b16 v[152:153], v147 offset:0x1400
	ds_read_b64_tr_b16 v[154:155], v147 offset:0x1c00
	v_mfma_f32_32x32x16_bf16 v[32:47], v[136:139], v[156:159], v[32:47]
	ds_read_b64_tr_b16 v[156:157], v147 offset:0x2400
	ds_read_b64_tr_b16 v[158:159], v147 offset:0x2c00
	v_mfma_f32_32x32x16_bf16 v[32:47], v[140:143], v[178:181], v[32:47]
	ds_read_b64_tr_b16 v[178:179], v147 offset:0x3400
	ds_read_b64_tr_b16 v[180:181], v147 offset:0x3c00
	s_waitcnt lgkmcnt(0)
; #define BARL() asm volatile("s_waitcnt lgkmcnt(0)\n\ts_barrier" ::: "memory")
; #define BARL() asm volatile("s_waitcnt lgkmcnt(0)\n\ts_barrier" ::: "memory")
; __device__ __forceinline__ void attn_pass_dv256(const bf16_t* __restrict__ Qb, const bf16_t* __restrict__ Kh, const bf16_t* __restrict__ Vh, int qpos0,
;                                                 LAS unsigned char* lds, f32x16 (&o)[8], float& l_out, int wave_) {
;     ...
;     pv_one<0>(o[0], vbs, pa0, pa1, pa2, pa3); pv_one<1>(o[1], vbs, pa0, pa1, pa2, pa3); pv_one<2>(o[2], vbs, pa0, pa1, pa2, pa3); pv_one<3>(o[3], vbs, pa0, pa1, pa2, pa3);
;     pv_one<0>(o[4], vbs + 16384, pa0, pa1, pa2, pa3); pv_one<1>(o[5], vbs + 16384, pa0, pa1, pa2, pa3); pv_one<2>(o[6], vbs + 16384, pa0, pa1, pa2, pa3); pv_one<3>(o[7], vbs + 16384, pa0, pa1, pa2, pa3);
;     asm volatile("s_waitcnt vmcnt(0)" ::: "memory"); BARL();
;     if (j + 2 < NT) DMA_KV(j + 2, sl);
	v_mfma_f32_32x32x16_bf16 v[0:15], v[128:131], v[148:151], v[0:15]
	ds_read_b64_tr_b16 v[148:149], v147 offset:0x600
	ds_read_b64_tr_b16 v[150:151], v147 offset:0xe00
	v_mfma_f32_32x32x16_bf16 v[0:15], v[132:135], v[152:155], v[0:15]
	ds_read_b64_tr_b16 v[152:153], v147 offset:0x1600
	ds_read_b64_tr_b16 v[154:155], v147 offset:0x1e00
	v_mfma_f32_32x32x16_bf16 v[0:15], v[136:139], v[156:159], v[0:15]
	ds_read_b64_tr_b16 v[156:157], v147 offset:0x2600
	ds_read_b64_tr_b16 v[158:159], v147 offset:0x2e00
	v_mfma_f32_32x32x16_bf16 v[0:15], v[140:143], v[178:181], v[0:15]
	ds_read_b64_tr_b16 v[178:179], v147 offset:0x3600
	ds_read_b64_tr_b16 v[180:181], v147 offset:0x3e00
	s_waitcnt lgkmcnt(0)
	v_mfma_f32_32x32x16_bf16 v[16:31], v[128:131], v[148:151], v[16:31]
	v_add_u32_e32 v147, 0x4000, v147
	ds_read_b64_tr_b16 v[148:149], v147 offset:0
	ds_read_b64_tr_b16 v[150:151], v147 offset:0x800
	v_mfma_f32_32x32x16_bf16 v[16:31], v[132:135], v[152:155], v[16:31]
	ds_read_b64_tr_b16 v[152:153], v147 offset:0x1000
	ds_read_b64_tr_b16 v[154:155], v147 offset:0x1800
	v_mfma_f32_32x32x16_bf16 v[16:31], v[136:139], v[156:159], v[16:31]
	ds_read_b64_tr_b16 v[156:157], v147 offset:0x2000
	ds_read_b64_tr_b16 v[158:159], v147 offset:0x2800
	v_mfma_f32_32x32x16_bf16 v[16:31], v[140:143], v[178:181], v[16:31]
	ds_read_b64_tr_b16 v[178:179], v147 offset:0x3000
	ds_read_b64_tr_b16 v[180:181], v147 offset:0x3800
	s_waitcnt lgkmcnt(0)
	v_mfma_f32_32x32x16_bf16 v[64:79], v[128:131], v[148:151], v[64:79]
	ds_read_b64_tr_b16 v[148:149], v147 offset:0x200
	ds_read_b64_tr_b16 v[150:151], v147 offset:0xa00
	v_mfma_f32_32x32x16_bf16 v[64:79], v[132:135], v[152:155], v[64:79]
	ds_read_b64_tr_b16 v[152:153], v147 offset:0x1200
	ds_read_b64_tr_b16 v[154:155], v147 offset:0x1a00
	v_mfma_f32_32x32x16_bf16 v[64:79], v[136:139], v[156:159], v[64:79]
	ds_read_b64_tr_b16 v[156:157], v147 offset:0x2200
	ds_read_b64_tr_b16 v[158:159], v147 offset:0x2a00
	v_mfma_f32_32x32x16_bf16 v[64:79], v[140:143], v[178:181], v[64:79]
	ds_read_b64_tr_b16 v[178:179], v147 offset:0x3200
	ds_read_b64_tr_b16 v[180:181], v147 offset:0x3a00
	s_waitcnt lgkmcnt(0)
	v_mfma_f32_32x32x16_bf16 v[80:95], v[128:131], v[148:151], v[80:95]
	ds_read_b64_tr_b16 v[148:149], v147 offset:0x400
	ds_read_b64_tr_b16 v[150:151], v147 offset:0xc00
	v_mfma_f32_32x32x16_bf16 v[80:95], v[132:135], v[152:155], v[80:95]
	ds_read_b64_tr_b16 v[152:153], v147 offset:0x1400
	ds_read_b64_tr_b16 v[154:155], v147 offset:0x1c00
	v_mfma_f32_32x32x16_bf16 v[80:95], v[136:139], v[156:159], v[80:95]
	ds_read_b64_tr_b16 v[156:157], v147 offset:0x2400
	ds_read_b64_tr_b16 v[158:159], v147 offset:0x2c00
	v_mfma_f32_32x32x16_bf16 v[80:95], v[140:143], v[178:181], v[80:95]
	ds_read_b64_tr_b16 v[178:179], v147 offset:0x3400
	ds_read_b64_tr_b16 v[180:181], v147 offset:0x3c00
	s_waitcnt lgkmcnt(0)
	v_mfma_f32_32x32x16_bf16 v[96:111], v[128:131], v[148:151], v[96:111]
	ds_read_b64_tr_b16 v[148:149], v147 offset:0x600
	ds_read_b64_tr_b16 v[150:151], v147 offset:0xe00
	v_mfma_f32_32x32x16_bf16 v[96:111], v[132:135], v[152:155], v[96:111]
	ds_read_b64_tr_b16 v[152:153], v147 offset:0x1600
	ds_read_b64_tr_b16 v[154:155], v147 offset:0x1e00
	v_mfma_f32_32x32x16_bf16 v[96:111], v[136:139], v[156:159], v[96:111]
	ds_read_b64_tr_b16 v[156:157], v147 offset:0x2600
	ds_read_b64_tr_b16 v[158:159], v147 offset:0x2e00
	v_mfma_f32_32x32x16_bf16 v[96:111], v[140:143], v[178:181], v[96:111]
	ds_read_b64_tr_b16 v[178:179], v147 offset:0x3600
	ds_read_b64_tr_b16 v[180:181], v147 offset:0x3e00
	s_waitcnt lgkmcnt(0)
	v_mfma_f32_32x32x16_bf16 v[112:127], v[128:131], v[148:151], v[112:127]
	s_waitcnt vmcnt(0)
	s_waitcnt lgkmcnt(0)
	s_barrier
	s_cmp_gt_u32 s17, 61
	v_mfma_f32_32x32x16_bf16 v[112:127], v[132:135], v[152:155], v[112:127]
	v_mfma_f32_32x32x16_bf16 v[112:127], v[136:139], v[156:159], v[112:127]
	v_mfma_f32_32x32x16_bf16 v[112:127], v[140:143], v[178:181], v[112:127]
	s_cbranch_scc1 .LBB0_399
	s_add_u32 s7, s12, s27
	s_addc_u32 s19, s13, 0
	s_add_u32 s8, s7, 0x21080100
	s_addc_u32 s9, s19, 0
	s_add_u32 s31, s10, s27
	s_addc_u32 s36, s11, 0
	s_add_u32 s24, s31, 0x29080000
	s_addc_u32 s25, s36, 0
	s_add_i32 s18, s18, 0
	s_add_i32 s18, s18, 0x10000
	s_add_i32 s37, s18, s68
	s_mov_b32 m0, s37
	s_nop 0
	global_load_lds_dwordx4 v235, s[8:9]
	s_add_u32 s8, s7, 0x210a0100
	s_addc_u32 s9, s19, 0
	s_add_i32 s18, s18, s0
	s_mov_b32 m0, s18
	s_nop 0
	global_load_lds_dwordx4 v235, s[8:9]
	s_add_i32 s8, s6, 0
	s_add_i32 s6, s8, s68
	s_mov_b32 m0, s6
	s_nop 0
	global_load_lds_dwordx4 v236, s[24:25]
	s_add_u32 s6, s31, 0x290a0000
	s_addc_u32 s7, s36, 0
	s_add_i32 s9, s8, s0
	s_mov_b32 m0, s9
	s_nop 0
	global_load_lds_dwordx4 v236, s[6:7]
	s_add_u32 s6, s31, 0x29080100
	s_addc_u32 s7, s36, 0
	s_addk_i32 s8, 0x4000
	s_add_i32 s9, s8, s68
	s_mov_b32 m0, s9
	s_nop 0
	global_load_lds_dwordx4 v236, s[6:7]
	s_add_u32 s6, s31, 0x290a0100
	s_addc_u32 s7, s36, 0
	s_add_i32 s8, s8, s0
	s_mov_b32 m0, s8
	s_nop 0
	global_load_lds_dwordx4 v236, s[6:7]

; __device__ __forceinline__ int tid_of(int wave) { return opqv(wave * 64 + (int)__builtin_amdgcn_mbcnt_hi(~0u, __builtin_amdgcn_mbcnt_lo(~0u, 0u))); }
; __host__ __device__ __forceinline__ int lds_byte(int r, int c) { return (r >> 3) * 1024 + (r & 7) * 128 + ((((c >> 3)) ^ ((r >> 1) & 7)) << 4) + (c & 7) * 2; }
; #define PG8_WAIT_V(n) asm volatile("s_waitcnt vmcnt(" #n ")" ::: "memory")
; #define PG8_BAR __builtin_amdgcn_s_barrier()
; template <class Epi>
; __device__ __forceinline__ void gemm_phase(LAS unsigned char* lds, const Gemm g, const StaticOrder& S, const Epi& E, int wave_) {
;     const int tid = tid_of(wave_), wid = wave_, lane = tid & 63, wr = wid >> 2, wc = wid & 3, fr = lane & 15, fq = lane >> 4;
;     const int K = g.K, nt = K / BK;
;     unsigned voffA[2], voffB[2];
; #pragma unroll
;     for (int i = 0; i < 2; ++i) { int R, C; stage_rc(tid * 16 + i * 8192, R, C); const int Rb = (R & ~31) + perm32(R & 31);
;         voffA[i] = (unsigned)(R * g.lda + C) * 2u; voffB[i] = (unsigned)(Rb * g.ldb + C) * 2u; }
;     const size_t kstep = (size_t)(BK * 2);
;     const size_t hstepA = (size_t)HALF * g.lda * 2, hstepB = (size_t)HALF * g.ldb * 2;
;     const size_t tstepA = 2 * hstepA, tstepB = 2 * hstepB;
;     const unsigned ldsw = (unsigned)wid * 1024u, ldsb = (unsigned)(uintptr_t)lds;
;     const int aoff0 = lds_byte(wr * 64 + fr, fq * 8), boff0 = lds_byte(wc * 32 + fr, fq * 8);
;     ...
;     Unit cur, nxt; int ui = 0;
;     if (!S.next(0, cur)) return;
;     f32x4 acc[2][2][4][2];
; #pragma unroll
;     for (int a = 0; a < 2; ++a)
; #pragma unroll
;         for (int b = 0; b < 2; ++b)
; #pragma unroll
;             for (int m = 0; m < 4; ++m)
; #pragma unroll
;                 for (int n = 0; n < 2; ++n) acc[a][b][m][n] = (f32x4){0.f, 0.f, 0.f, 0.f};
;     bf16x8 At[4][2], B0[2][2], B1[2][2];
;     const char* cA = (const char*)g.A + (size_t)cur.pm * tstepA; const char* cB = (const char*)g.Bt + (size_t)cur.pn * tstepB;
;     PG8_STAGE(PG8_SB(0, 0), cB, voffB); PG8_STAGE(PG8_SB(0, 1), cB + hstepB, voffB); PG8_STAGE(PG8_SA(0, 0), cA, voffA); PG8_STAGE(PG8_SA(0, 1), cA + hstepA, voffA);
;     if (wr == 1) PG8_BAR;
;     PG8_WAIT_V(2); PG8_BAR;
;     PG8_STAGE(PG8_SB(1, 0), cB + kstep, voffB); PG8_STAGE(PG8_SA(1, 0), cA + kstep, voffA); PG8_STAGE(PG8_SB(1, 1), cB + hstepB + kstep, voffB);
;     PG8_WAIT_V(6); PG8_BAR;
.LBB0_564:
	s_and_b64 vcc, exec, s[6:7]
	s_cbranch_vccz .LBB0_1088
	v_readlane_b32 s10, v252, 12
	v_readlane_b32 s18, v253, 30
	v_readlane_b32 s11, v252, 13
	s_ashr_i32 s43, s42, 31
	v_readlane_b32 s19, v253, 31
	s_mov_b64 s[12:13], s[10:11]
	s_mov_b64 s[16:17], s[10:11]
	s_mov_b64 s[4:5], s[10:11]
	s_mov_b64 s[8:9], s[10:11]
	s_mov_b64 s[6:7], s[10:11]
	s_lshl_b64 s[54:55], s[42:43], 16
	v_mov_b32_e32 v0, v220
	s_andn2_b64 vcc, exec, s[18:19]
	s_cbranch_vccnz .LBB0_603
	v_bfe_i32 v3, v0, 27, 1
	v_lshlrev_b32_e32 v1, 4, v0
	v_lshrrev_b32_e32 v4, 22, v3
	v_add_u32_e32 v4, v1, v4
	v_and_b32_e32 v4, 0xfc00, v4
	v_sub_u32_e32 v4, v1, v4
	v_ashrrev_i16_e32 v5, 15, v4
	v_ashrrev_i32_e32 v2, 31, v0
	v_lshrrev_b16_e32 v5, 9, v5
	v_lshrrev_b32_e32 v3, 25, v3
	v_lshrrev_b32_e32 v2, 26, v2
	v_add_u16_e32 v4, v4, v5
	v_add_u32_e32 v3, v1, v3
	v_add_u32_e32 v2, v0, v2
	v_ashrrev_i16_e32 v4, 7, v4
	v_and_b32_e32 v3, 0x80, v3
	v_ashrrev_i32_e32 v2, 6, v2
	v_bfe_i32 v4, v4, 0, 16
	v_sub_u32_e32 v3, v1, v3
	v_mov_b32_e32 v7, 4
	v_ashrrev_i16_sdwa v3, v7, sext(v3) dst_sel:DWORD dst_unused:UNUSED_PAD src0_sel:DWORD src1_sel:BYTE_0
	v_lshl_add_u32 v2, v2, 3, v4
	v_bfe_i32 v3, v3, 0, 16
	v_lshrrev_b32_e32 v5, 1, v2
	s_add_u32 s21, s12, 0x8000000
	v_bitop3_b32 v3, v5, v3, 7 bitop3:0x6c
	v_lshlrev_b32_e32 v5, 1, v2
	v_lshrrev_b32_e32 v6, 2, v2
	v_and_b32_e32 v4, 3, v4
	s_mov_b32 s12, 0xfffe0
	v_lshlrev_b32_e32 v3, 4, v3
	v_and_b32_e32 v5, 24, v5
	v_and_b32_e32 v6, 4, v6
	v_and_or_b32 v4, v2, s12, v4
	v_add_u32_e32 v1, 0x2000, v1
	v_or3_b32 v4, v4, v6, v5
	v_lshl_add_u32 v138, v2, 12, v3
	v_ashrrev_i32_e32 v2, 31, v1
	v_lshl_add_u32 v139, v4, 12, v3
	v_lshrrev_b32_e32 v3, 22, v2
	v_add_u32_e32 v3, v1, v3
	v_ashrrev_i32_e32 v3, 10, v3
	v_mul_i32_i24_e32 v4, 0x400, v3
	v_sub_u32_e32 v4, v1, v4
	v_ashrrev_i16_e32 v5, 15, v4
	v_lshrrev_b16_e32 v5, 9, v5
	v_lshrrev_b32_e32 v2, 25, v2
	v_add_u16_e32 v4, v4, v5
	v_add_u32_e32 v2, v1, v2
	v_ashrrev_i16_e32 v4, 7, v4
	v_and_b32_e32 v2, 0x80, v2
	v_bfe_i32 v4, v4, 0, 16
	v_sub_u32_e32 v1, v1, v2
	s_addc_u32 s44, s13, 0
	v_ashrrev_i16_sdwa v1, v7, sext(v1) dst_sel:DWORD dst_unused:UNUSED_PAD src0_sel:DWORD src1_sel:BYTE_0
	v_lshl_add_u32 v2, v3, 3, v4
	s_add_u32 s45, s16, 0x800000
	v_bfe_i32 v1, v1, 0, 16
	v_lshrrev_b32_e32 v3, 1, v2
	v_and_b32_e32 v4, 3, v4
	s_addc_u32 s46, s17, 0
	v_bitop3_b32 v1, v3, v1, 7 bitop3:0x6c
	v_lshlrev_b32_e32 v3, 1, v2
	v_lshrrev_b32_e32 v5, 2, v2
	v_and_or_b32 v4, v2, s12, v4
	v_readlane_b32 s12, v254, 6
	v_and_b32_e32 v3, 24, v3
	v_and_b32_e32 v5, 4, v5
	v_readlane_b32 s13, v254, 7
	s_add_u32 s12, s45, s12
	v_lshlrev_b32_e32 v1, 4, v1
	v_or3_b32 v3, v4, v5, v3
	s_addc_u32 s13, s46, s13
	s_mov_b32 m0, s80
	s_nop 0
	global_load_lds_dwordx4 v139, s[12:13]
	v_lshl_add_u32 v141, v3, 12, v1
	s_mov_b32 m0, s81
	s_nop 0
	global_load_lds_dwordx4 v141, s[12:13]
	s_add_u32 s16, s12, 0x80000
	s_addc_u32 s17, s13, 0
	s_mov_b32 m0, s29
	s_nop 0
	global_load_lds_dwordx4 v139, s[16:17]
	v_lshl_add_u32 v140, v2, 12, v1
	s_mov_b32 m0, s88
	s_nop 0
	global_load_lds_dwordx4 v141, s[16:17]
	v_readlane_b32 s16, v254, 31
	v_readlane_b32 s17, v254, 32
	s_add_u32 s26, s21, s16
	s_addc_u32 s27, s44, s17
	s_mov_b32 m0, s76
	s_nop 0
	global_load_lds_dwordx4 v138, s[26:27]
	s_nop 0
	s_mov_b32 m0, s89
	s_nop 0
	global_load_lds_dwordx4 v140, s[26:27]
	s_add_u32 s16, s26, 0x80000
	s_addc_u32 s17, s27, 0
	s_mov_b32 m0, s1
	s_nop 0
	global_load_lds_dwordx4 v138, s[16:17]
	s_nop 0
	v_readlane_b32 s18, v253, 11
	v_readlane_b32 s19, v253, 12
	s_andn2_b64 vcc, exec, s[18:19]
	s_nop 0
	v_cndmask_b32_e64 v1, 0, 1, s[18:19]
	s_mov_b32 m0, s69
	s_nop 0
	global_load_lds_dwordx4 v140, s[16:17]
	v_cmp_ne_u32_e64 s[38:39], 1, v1
	s_cbranch_vccnz .LBB0_568
	s_barrier
.LBB0_568:
	s_add_u32 s4, s4, 0x19000000
	s_addc_u32 s5, s5, 0
	s_lshl_b64 s[16:17], s[54:55], 3
	s_add_u32 s6, s6, s16
	s_addc_u32 s7, s7, s17
	s_add_u32 s6, s6, 0x500000
	s_addc_u32 s7, s7, 0
	v_and_b32_e32 v2, 15, v0
	v_readlane_b32 s16, v253, 6
	s_waitcnt vmcnt(2)
	s_barrier
	v_lshrrev_b32_e32 v1, 4, v0
	v_or_b32_e32 v142, s16, v2
	s_add_u32 s16, s12, 0x80
	s_addc_u32 s17, s13, 0
	s_mov_b32 m0, s35
	s_nop 0
	global_load_lds_dwordx4 v139, s[16:17]
	v_bfe_u32 v3, v0, 4, 2
	s_mov_b32 m0, s33
	s_nop 0
	global_load_lds_dwordx4 v141, s[16:17]
	s_add_u32 s16, s26, 0x80
	v_bfe_u32 v0, v0, 1, 3
	s_addc_u32 s17, s27, 0
	s_mov_b32 m0, s22
	s_nop 0
	global_load_lds_dwordx4 v138, s[16:17]
	v_bitop3_b32 v0, v1, v0, 3 bitop3:0x6c
	v_readlane_b32 s19, v253, 29
	s_mov_b32 m0, s2
	s_nop 0
	global_load_lds_dwordx4 v140, s[16:17]
	s_add_u32 s16, s12, 0x80080
	v_lshlrev_b32_e32 v0, 4, v0
	v_or_b32_e32 v1, s19, v2
	s_addc_u32 s17, s13, 0
	s_mov_b32 m0, s77
	s_nop 0
	global_load_lds_dwordx4 v139, s[16:17]
	v_lshlrev_b32_e32 v184, 5, v3
	v_lshl_or_b32 v143, v142, 7, v0
	v_lshl_or_b32 v144, v1, 7, v0
	s_mov_b32 m0, s3
	s_nop 0
	global_load_lds_dwordx4 v141, s[16:17]
	v_lshl_add_u64 v[0:1], s[10:11], 0, v[184:185]
	s_mov_b64 s[10:11], 0x39400000
	v_lshlrev_b32_e32 v184, 4, v3
	s_waitcnt vmcnt(6)
	v_lshl_add_u64 v[132:133], v[0:1], 0, s[10:11]
	v_lshl_add_u64 v[0:1], s[8:9], 0, v[184:185]
	s_mov_b64 s[8:9], 0x1d000000
	v_lshl_add_u64 v[134:135], v[0:1], 0, s[8:9]
	v_readlane_b32 s8, v254, 29
	s_mov_b32 s47, 0
	v_cmp_eq_u32_e64 s[40:41], 0, v3
	v_lshl_or_b32 v145, v3, 3, s19
	v_readlane_b32 s48, v254, 5
	s_mov_b32 s49, s8
	s_barrier
	v_readlane_b32 s9, v254, 30
	s_branch .LBB0_571

; #define PG8_STAGE(bufoff, gbase, voff) do { _Pragma("unroll") for (int _i = 0; _i < 2; ++_i) \
;         dma16((const char*)(gbase), (voff)[_i], ldsb + (bufoff) + ldsw + _i * 8192); } while (0)
; #define PG8_LDA(dst, b, h) do { const int a1_ = opqv(aoff0) ^ 64; _Pragma("unroll") for (int m = 0; m < 4; ++m) { dst[m][0] = *(const LAS bf16x8*)(lds + PG8_SA(b, h) + aoff0 + m * 2048); dst[m][1] = *(const LAS bf16x8*)(lds + PG8_SA(b, h) + a1_ + m * 2048); } } while (0)
; #define PG8_LDB(dst, b, h) do { const int b1_ = opqv(boff0) ^ 64; _Pragma("unroll") for (int n = 0; n < 2; ++n) { dst[n][0] = *(const LAS bf16x8*)(lds + PG8_SB(b, h) + boff0 + n * 2048); dst[n][1] = *(const LAS bf16x8*)(lds + PG8_SB(b, h) + b1_ + n * 2048); } } while (0)
; #define PG8_MMA(ai, bj, At, Bt) do { __builtin_amdgcn_s_setprio(1); _Pragma("unroll") for (int m = 0; m < 4; ++m) _Pragma("unroll") for (int n = 0; n < 2; ++n) _Pragma("unroll") for (int k = 0; k < 2; ++k) \
;         acc[ai][bj][m][n] = __builtin_amdgcn_mfma_f32_16x16x32_bf16(Bt[n][k], At[m][k], acc[ai][bj][m][n], 0, 0, 0); __builtin_amdgcn_s_setprio(0); } while (0)
; #define PG8_WAIT_V(n) asm volatile("s_waitcnt vmcnt(" #n ")" ::: "memory")
; #define PG8_WAIT_L(n) asm volatile("s_waitcnt lgkmcnt(" #n ")" ::: "memory")
; #define PG8_BAR __builtin_amdgcn_s_barrier()
; #define PG8_SCHED __builtin_amdgcn_sched_barrier(0)
; template <class Epi>
; __device__ __forceinline__ void gemm_phase(LAS unsigned char* lds, const Gemm g, const StaticOrder& S, const Epi& E, int wave_) {
;     ...
;         for (int t = 0; t < nt; t += 2) {
;             const bool last = (t == nt - 2);
;             const char* a1 = cA + (size_t)(t + 1) * kstep;
;             const char* a2 = last ? nA : cA + (size_t)(t + 2) * kstep; const char* b2 = last ? nB : cB + (size_t)(t + 2) * kstep;
;             const char* a3 = a2 + kstep; const char* b3 = b2 + kstep;
;             PG8_STAGE(PG8_SA(1, 1), a1 + hstepA, voffA); PG8_LDB(B0, 0, 0); PG8_LDB(B1, 0, 1); PG8_SCHED; PG8_LDA(At, 0, 0);
;             PG8_WAIT_V(8); PG8_WAIT_L(0); PG8_BAR; PG8_MMA(0, 0, At, B0); PG8_MMA(0, 1, At, B1); PG8_BAR; PG8_SCHED;
;             PG8_STAGE(PG8_SB(0, 0), b2, voffB); PG8_STAGE(PG8_SB(0, 1), b2 + hstepB, voffB); PG8_STAGE(PG8_SA(0, 0), a2, voffA); PG8_LDA(At, 0, 1);
;             PG8_WAIT_V(8); PG8_WAIT_L(0); PG8_BAR; PG8_MMA(1, 0, At, B0); PG8_MMA(1, 1, At, B1); PG8_BAR; PG8_SCHED;
.LBB0_574:
	s_add_u32 s26, s12, 0xfff80080
	s_addc_u32 s27, s13, -1
	s_cmp_eq_u32 s57, 28
	s_cselect_b32 s36, s16, s26
	v_mov_b32_e32 v128, v144
	s_cselect_b32 s37, s11, s27
	s_cselect_b32 s30, s17, s52
	s_cselect_b32 s31, s9, s56
	s_add_u32 s26, s36, 0x80
	v_add_u32_e32 v137, s23, v144
	v_xad_u32 v136, v128, 64, s23
	s_addc_u32 s27, s37, 0
	ds_read_b128 v[128:131], v137
	ds_read_b128 v[146:149], v137 offset:2048
	ds_read_b128 v[150:153], v136
	ds_read_b128 v[154:157], v136 offset:2048
	v_mov_b32_e32 v136, v144
	s_add_i32 s58, 0, 0x14000
	v_add_u32_e32 v137, s58, v144
	v_xad_u32 v136, v136, 64, s58
	ds_read_b128 v[158:161], v137
	ds_read_b128 v[162:165], v137 offset:2048
	ds_read_b128 v[166:169], v136
	ds_read_b128 v[170:173], v136 offset:2048
	v_mov_b32_e32 v136, v143
	v_add_u32_e32 v137, 0, v143
	v_xad_u32 v136, v136, 64, 0
	ds_read_b128 v[174:177], v137
	ds_read_b128 v[178:181], v137 offset:2048
	ds_read_b128 v[192:195], v136
	ds_read_b128 v[196:199], v136 offset:2048
	ds_read_b128 v[200:203], v137 offset:4096
	ds_read_b128 v[204:207], v137 offset:6144
	ds_read_b128 v[208:211], v136 offset:4096
	ds_read_b128 v[212:215], v136 offset:6144
	s_mov_b32 m0, s14
	s_nop 0
	global_load_lds_dwordx4 v138, s[12:13]
	s_mov_b32 m0, s15
	s_nop 0
	global_load_lds_dwordx4 v140, s[12:13]
	s_waitcnt vmcnt(8)
	s_waitcnt lgkmcnt(0)
	s_barrier
	s_setprio 1
	s_waitcnt lgkmcnt(0)
	v_mfma_f32_16x16x32_bf16 v[124:127], v[128:131], v[174:177], v[124:127]
	v_mfma_f32_16x16x32_bf16 v[120:123], v[146:149], v[174:177], v[120:123]
	v_mfma_f32_16x16x32_bf16 v[108:111], v[128:131], v[178:181], v[108:111]
	v_mfma_f32_16x16x32_bf16 v[104:107], v[146:149], v[178:181], v[104:107]
	v_mfma_f32_16x16x32_bf16 v[92:95], v[128:131], v[200:203], v[92:95]
	v_mfma_f32_16x16x32_bf16 v[88:91], v[146:149], v[200:203], v[88:91]
	v_mfma_f32_16x16x32_bf16 v[76:79], v[128:131], v[204:207], v[76:79]
	v_mfma_f32_16x16x32_bf16 v[72:75], v[146:149], v[204:207], v[72:75]
	v_mfma_f32_16x16x32_bf16 v[124:127], v[150:153], v[192:195], v[124:127]
	v_mfma_f32_16x16x32_bf16 v[120:123], v[154:157], v[192:195], v[120:123]
	v_mfma_f32_16x16x32_bf16 v[108:111], v[150:153], v[196:199], v[108:111]
	v_mfma_f32_16x16x32_bf16 v[104:107], v[154:157], v[196:199], v[104:107]
	v_mfma_f32_16x16x32_bf16 v[92:95], v[150:153], v[208:211], v[92:95]
	v_mfma_f32_16x16x32_bf16 v[88:91], v[154:157], v[208:211], v[88:91]
	v_mfma_f32_16x16x32_bf16 v[76:79], v[150:153], v[212:215], v[76:79]
	v_mfma_f32_16x16x32_bf16 v[72:75], v[154:157], v[212:215], v[72:75]
	s_setprio 0
	s_setprio 1
	v_mfma_f32_16x16x32_bf16 v[116:119], v[158:161], v[174:177], v[116:119]
	v_mfma_f32_16x16x32_bf16 v[112:115], v[162:165], v[174:177], v[112:115]
	v_mfma_f32_16x16x32_bf16 v[100:103], v[158:161], v[178:181], v[100:103]
	v_mfma_f32_16x16x32_bf16 v[96:99], v[162:165], v[178:181], v[96:99]
	v_mfma_f32_16x16x32_bf16 v[84:87], v[158:161], v[200:203], v[84:87]
	v_mfma_f32_16x16x32_bf16 v[80:83], v[162:165], v[200:203], v[80:83]
	v_mfma_f32_16x16x32_bf16 v[68:71], v[158:161], v[204:207], v[68:71]
	v_mfma_f32_16x16x32_bf16 v[64:67], v[162:165], v[204:207], v[64:67]
	v_mfma_f32_16x16x32_bf16 v[116:119], v[166:169], v[192:195], v[116:119]
	v_mfma_f32_16x16x32_bf16 v[112:115], v[170:173], v[192:195], v[112:115]
	v_mfma_f32_16x16x32_bf16 v[100:103], v[166:169], v[196:199], v[100:103]
	v_mfma_f32_16x16x32_bf16 v[96:99], v[170:173], v[196:199], v[96:99]
	v_mfma_f32_16x16x32_bf16 v[84:87], v[166:169], v[208:211], v[84:87]
	v_mfma_f32_16x16x32_bf16 v[80:83], v[170:173], v[208:211], v[80:83]
	v_mfma_f32_16x16x32_bf16 v[68:71], v[166:169], v[212:215], v[68:71]
	v_mfma_f32_16x16x32_bf16 v[64:67], v[170:173], v[212:215], v[64:67]
	s_setprio 0
	s_barrier
	v_mov_b32_e32 v136, v143
	s_add_u32 s58, s30, 0x80000
	s_addc_u32 s59, s31, 0
	s_nop 0
	s_nop 0
	s_nop 0
	v_xad_u32 v136, v136, 64, 0
	ds_read_b128 v[174:177], v137 offset:16384
	ds_read_b128 v[178:181], v137 offset:18432
	ds_read_b128 v[192:195], v136 offset:16384
	ds_read_b128 v[196:199], v136 offset:18432
	ds_read_b128 v[200:203], v137 offset:20480
	ds_read_b128 v[204:207], v137 offset:22528
	ds_read_b128 v[208:211], v136 offset:20480
	ds_read_b128 v[212:215], v136 offset:22528
	s_mov_b32 m0, s80
	s_nop 0
	global_load_lds_dwordx4 v139, s[30:31]
	s_mov_b32 m0, s81
	s_nop 0
	global_load_lds_dwordx4 v141, s[30:31]
	s_mov_b32 m0, s29
	s_nop 0
	global_load_lds_dwordx4 v139, s[58:59]
	s_mov_b32 m0, s88
	s_nop 0
	global_load_lds_dwordx4 v141, s[58:59]
	s_mov_b32 m0, s76
	s_nop 0
	global_load_lds_dwordx4 v138, s[36:37]
	s_mov_b32 m0, s89
	s_nop 0
	global_load_lds_dwordx4 v140, s[36:37]
	s_waitcnt vmcnt(8)
	s_waitcnt lgkmcnt(0)
	s_barrier
; #define PG8_STAGE(bufoff, gbase, voff) do { _Pragma("unroll") for (int _i = 0; _i < 2; ++_i) \
;         dma16((const char*)(gbase), (voff)[_i], ldsb + (bufoff) + ldsw + _i * 8192); } while (0)
; #define PG8_LDA(dst, b, h) do { const int a1_ = opqv(aoff0) ^ 64; _Pragma("unroll") for (int m = 0; m < 4; ++m) { dst[m][0] = *(const LAS bf16x8*)(lds + PG8_SA(b, h) + aoff0 + m * 2048); dst[m][1] = *(const LAS bf16x8*)(lds + PG8_SA(b, h) + a1_ + m * 2048); } } while (0)
; #define PG8_LDB(dst, b, h) do { const int b1_ = opqv(boff0) ^ 64; _Pragma("unroll") for (int n = 0; n < 2; ++n) { dst[n][0] = *(const LAS bf16x8*)(lds + PG8_SB(b, h) + boff0 + n * 2048); dst[n][1] = *(const LAS bf16x8*)(lds + PG8_SB(b, h) + b1_ + n * 2048); } } while (0)
; #define PG8_MMA(ai, bj, At, Bt) do { __builtin_amdgcn_s_setprio(1); _Pragma("unroll") for (int m = 0; m < 4; ++m) _Pragma("unroll") for (int n = 0; n < 2; ++n) _Pragma("unroll") for (int k = 0; k < 2; ++k) \
;         acc[ai][bj][m][n] = __builtin_amdgcn_mfma_f32_16x16x32_bf16(Bt[n][k], At[m][k], acc[ai][bj][m][n], 0, 0, 0); __builtin_amdgcn_s_setprio(0); } while (0)
; #define PG8_WAIT_V(n) asm volatile("s_waitcnt vmcnt(" #n ")" ::: "memory")
; #define PG8_WAIT_L(n) asm volatile("s_waitcnt lgkmcnt(" #n ")" ::: "memory")
; #define PG8_BAR __builtin_amdgcn_s_barrier()
; #define PG8_SCHED __builtin_amdgcn_sched_barrier(0)
; template <class Epi>
; __device__ __forceinline__ void gemm_phase(LAS unsigned char* lds, const Gemm g, const StaticOrder& S, const Epi& E, int wave_) {
;     ...
;             PG8_WAIT_V(8); PG8_WAIT_L(0); PG8_BAR; PG8_MMA(1, 0, At, B0); PG8_MMA(1, 1, At, B1); PG8_BAR; PG8_SCHED;
;             PG8_STAGE(PG8_SA(0, 1), a2 + hstepA, voffA); PG8_LDB(B0, 1, 0); PG8_LDB(B1, 1, 1); PG8_SCHED; PG8_LDA(At, 1, 0);
;             PG8_WAIT_V(8); PG8_WAIT_L(0); PG8_BAR; PG8_MMA(0, 0, At, B0); PG8_MMA(0, 1, At, B1); PG8_BAR; PG8_SCHED;
	s_setprio 1
	s_waitcnt lgkmcnt(0)
	v_mfma_f32_16x16x32_bf16 v[60:63], v[128:131], v[174:177], v[60:63]
	v_mfma_f32_16x16x32_bf16 v[56:59], v[146:149], v[174:177], v[56:59]
	v_mfma_f32_16x16x32_bf16 v[44:47], v[128:131], v[178:181], v[44:47]
	v_mfma_f32_16x16x32_bf16 v[40:43], v[146:149], v[178:181], v[40:43]
	v_mfma_f32_16x16x32_bf16 v[28:31], v[128:131], v[200:203], v[28:31]
	v_mfma_f32_16x16x32_bf16 v[24:27], v[146:149], v[200:203], v[24:27]
	v_mfma_f32_16x16x32_bf16 v[12:15], v[128:131], v[204:207], v[12:15]
	v_mfma_f32_16x16x32_bf16 v[8:11], v[146:149], v[204:207], v[8:11]
	v_mfma_f32_16x16x32_bf16 v[60:63], v[150:153], v[192:195], v[60:63]
	v_mfma_f32_16x16x32_bf16 v[56:59], v[154:157], v[192:195], v[56:59]
	v_mfma_f32_16x16x32_bf16 v[44:47], v[150:153], v[196:199], v[44:47]
	v_mfma_f32_16x16x32_bf16 v[40:43], v[154:157], v[196:199], v[40:43]
	v_mfma_f32_16x16x32_bf16 v[28:31], v[150:153], v[208:211], v[28:31]
	v_mfma_f32_16x16x32_bf16 v[24:27], v[154:157], v[208:211], v[24:27]
	v_mfma_f32_16x16x32_bf16 v[12:15], v[150:153], v[212:215], v[12:15]
	v_mfma_f32_16x16x32_bf16 v[8:11], v[154:157], v[212:215], v[8:11]
	s_setprio 0
	s_setprio 1
	v_mfma_f32_16x16x32_bf16 v[52:55], v[158:161], v[174:177], v[52:55]
	v_mfma_f32_16x16x32_bf16 v[48:51], v[162:165], v[174:177], v[48:51]
	v_mfma_f32_16x16x32_bf16 v[36:39], v[158:161], v[178:181], v[36:39]
	v_mfma_f32_16x16x32_bf16 v[32:35], v[162:165], v[178:181], v[32:35]
	v_mfma_f32_16x16x32_bf16 v[20:23], v[158:161], v[200:203], v[20:23]
	v_mfma_f32_16x16x32_bf16 v[16:19], v[162:165], v[200:203], v[16:19]
	v_mfma_f32_16x16x32_bf16 v[4:7], v[158:161], v[204:207], v[4:7]
	v_mfma_f32_16x16x32_bf16 v[0:3], v[162:165], v[204:207], v[0:3]
	v_mfma_f32_16x16x32_bf16 v[52:55], v[166:169], v[192:195], v[52:55]
	v_mfma_f32_16x16x32_bf16 v[48:51], v[170:173], v[192:195], v[48:51]
	v_mfma_f32_16x16x32_bf16 v[36:39], v[166:169], v[196:199], v[36:39]
	v_mfma_f32_16x16x32_bf16 v[32:35], v[170:173], v[196:199], v[32:35]
	v_mfma_f32_16x16x32_bf16 v[20:23], v[166:169], v[208:211], v[20:23]
	v_mfma_f32_16x16x32_bf16 v[16:19], v[170:173], v[208:211], v[16:19]
	v_mfma_f32_16x16x32_bf16 v[4:7], v[166:169], v[212:215], v[4:7]
	v_mfma_f32_16x16x32_bf16 v[0:3], v[170:173], v[212:215], v[0:3]
	s_setprio 0
	s_barrier
	s_add_u32 s36, s36, 0x80000
	s_addc_u32 s37, s37, 0
	s_mov_b32 m0, s1
	s_nop 0
	global_load_lds_dwordx4 v138, s[36:37]
	v_mov_b32_e32 v128, v144
	s_mov_b32 m0, s69
	s_nop 0
	global_load_lds_dwordx4 v140, s[36:37]
	v_add_u32_e32 v146, s34, v144
	v_xad_u32 v136, v128, 64, s34
	ds_read_b128 v[128:131], v146
	ds_read_b128 v[146:149], v146 offset:2048
	ds_read_b128 v[150:153], v136
	ds_read_b128 v[154:157], v136 offset:2048
	v_mov_b32_e32 v136, v144
	s_add_i32 s36, 0, 0x1c000
	v_add_u32_e32 v162, s36, v144
	v_xad_u32 v136, v136, 64, s36
	ds_read_b128 v[158:161], v162
	ds_read_b128 v[162:165], v162 offset:2048
	ds_read_b128 v[166:169], v136
	ds_read_b128 v[170:173], v136 offset:2048
	v_mov_b32_e32 v136, v143
	s_nop 0
	v_xad_u32 v136, v136, 64, 0
	ds_read_b128 v[174:177], v137 offset:32768
	ds_read_b128 v[178:181], v137 offset:34816
	ds_read_b128 v[192:195], v136 offset:32768
	ds_read_b128 v[196:199], v136 offset:34816
	ds_read_b128 v[200:203], v137 offset:36864
	ds_read_b128 v[204:207], v137 offset:38912
	ds_read_b128 v[208:211], v136 offset:36864
	ds_read_b128 v[212:215], v136 offset:38912
	s_waitcnt vmcnt(8)
	s_waitcnt lgkmcnt(0)
	s_barrier
	s_setprio 1
	s_waitcnt lgkmcnt(0)
	v_mfma_f32_16x16x32_bf16 v[124:127], v[128:131], v[174:177], v[124:127]
	v_mfma_f32_16x16x32_bf16 v[120:123], v[146:149], v[174:177], v[120:123]
	v_mfma_f32_16x16x32_bf16 v[108:111], v[128:131], v[178:181], v[108:111]
	v_mfma_f32_16x16x32_bf16 v[104:107], v[146:149], v[178:181], v[104:107]
	v_mfma_f32_16x16x32_bf16 v[92:95], v[128:131], v[200:203], v[92:95]
	v_mfma_f32_16x16x32_bf16 v[88:91], v[146:149], v[200:203], v[88:91]
	v_mfma_f32_16x16x32_bf16 v[76:79], v[128:131], v[204:207], v[76:79]
	v_mfma_f32_16x16x32_bf16 v[72:75], v[146:149], v[204:207], v[72:75]
	v_mfma_f32_16x16x32_bf16 v[124:127], v[150:153], v[192:195], v[124:127]
	v_mfma_f32_16x16x32_bf16 v[120:123], v[154:157], v[192:195], v[120:123]
	v_mfma_f32_16x16x32_bf16 v[108:111], v[150:153], v[196:199], v[108:111]
	v_mfma_f32_16x16x32_bf16 v[104:107], v[154:157], v[196:199], v[104:107]
	v_mfma_f32_16x16x32_bf16 v[92:95], v[150:153], v[208:211], v[92:95]
	v_mfma_f32_16x16x32_bf16 v[88:91], v[154:157], v[208:211], v[88:91]
	v_mfma_f32_16x16x32_bf16 v[76:79], v[150:153], v[212:215], v[76:79]
	v_mfma_f32_16x16x32_bf16 v[72:75], v[154:157], v[212:215], v[72:75]
	s_setprio 0
	s_setprio 1
	v_mfma_f32_16x16x32_bf16 v[116:119], v[158:161], v[174:177], v[116:119]
	s_add_u32 s36, s30, 0x80
	s_addc_u32 s37, s31, 0
	v_mfma_f32_16x16x32_bf16 v[112:115], v[162:165], v[174:177], v[112:115]
	v_mfma_f32_16x16x32_bf16 v[100:103], v[158:161], v[178:181], v[100:103]
	v_mfma_f32_16x16x32_bf16 v[96:99], v[162:165], v[178:181], v[96:99]
	v_mfma_f32_16x16x32_bf16 v[84:87], v[158:161], v[200:203], v[84:87]
	v_mfma_f32_16x16x32_bf16 v[80:83], v[162:165], v[200:203], v[80:83]
	v_mfma_f32_16x16x32_bf16 v[68:71], v[158:161], v[204:207], v[68:71]
	v_mfma_f32_16x16x32_bf16 v[64:67], v[162:165], v[204:207], v[64:67]
	v_mfma_f32_16x16x32_bf16 v[116:119], v[166:169], v[192:195], v[116:119]
	v_mfma_f32_16x16x32_bf16 v[112:115], v[170:173], v[192:195], v[112:115]
	v_mfma_f32_16x16x32_bf16 v[100:103], v[166:169], v[196:199], v[100:103]
	v_mfma_f32_16x16x32_bf16 v[96:99], v[170:173], v[196:199], v[96:99]
	v_mfma_f32_16x16x32_bf16 v[84:87], v[166:169], v[208:211], v[84:87]
	v_mfma_f32_16x16x32_bf16 v[80:83], v[170:173], v[208:211], v[80:83]
	v_mfma_f32_16x16x32_bf16 v[68:71], v[166:169], v[212:215], v[68:71]
	v_mfma_f32_16x16x32_bf16 v[64:67], v[170:173], v[212:215], v[64:67]
	s_setprio 0
	s_barrier
; #define PG8_STAGE(bufoff, gbase, voff) do { _Pragma("unroll") for (int _i = 0; _i < 2; ++_i) \
;         dma16((const char*)(gbase), (voff)[_i], ldsb + (bufoff) + ldsw + _i * 8192); } while (0)
; #define PG8_LDA(dst, b, h) do { const int a1_ = opqv(aoff0) ^ 64; _Pragma("unroll") for (int m = 0; m < 4; ++m) { dst[m][0] = *(const LAS bf16x8*)(lds + PG8_SA(b, h) + aoff0 + m * 2048); dst[m][1] = *(const LAS bf16x8*)(lds + PG8_SA(b, h) + a1_ + m * 2048); } } while (0)
; #define PG8_MMA(ai, bj, At, Bt) do { __builtin_amdgcn_s_setprio(1); _Pragma("unroll") for (int m = 0; m < 4; ++m) _Pragma("unroll") for (int n = 0; n < 2; ++n) _Pragma("unroll") for (int k = 0; k < 2; ++k) \
;         acc[ai][bj][m][n] = __builtin_amdgcn_mfma_f32_16x16x32_bf16(Bt[n][k], At[m][k], acc[ai][bj][m][n], 0, 0, 0); __builtin_amdgcn_s_setprio(0); } while (0)
; #define PG8_WAIT_V(n) asm volatile("s_waitcnt vmcnt(" #n ")" ::: "memory")
; #define PG8_WAIT_L(n) asm volatile("s_waitcnt lgkmcnt(" #n ")" ::: "memory")
; #define PG8_BAR __builtin_amdgcn_s_barrier()
; #define PG8_SCHED __builtin_amdgcn_sched_barrier(0)
; template <class Epi>
; __device__ __forceinline__ void gemm_phase(LAS unsigned char* lds, const Gemm g, const StaticOrder& S, const Epi& E, int wave_) {
;     ...
;             PG8_STAGE(PG8_SB(1, 0), b3, voffB); PG8_STAGE(PG8_SB(1, 1), b3 + hstepB, voffB); PG8_STAGE(PG8_SA(1, 0), a3, voffA); PG8_LDA(At, 1, 1);
;             PG8_WAIT_V(8); PG8_WAIT_L(0); PG8_BAR; PG8_MMA(1, 0, At, B0); PG8_MMA(1, 1, At, B1); PG8_BAR; PG8_SCHED;
;         }
;         if (wr == 0) PG8_BAR;
	s_add_u32 s30, s30, 0x80080
	s_addc_u32 s31, s31, 0
	v_mov_b32_e32 v136, v143
	s_nop 0
	s_nop 0
	v_xad_u32 v136, v136, 64, 0
	ds_read_b128 v[174:177], v137 offset:49152
	ds_read_b128 v[178:181], v137 offset:51200
	ds_read_b128 v[192:195], v136 offset:49152
	ds_read_b128 v[196:199], v136 offset:51200
	ds_read_b128 v[200:203], v137 offset:53248
	ds_read_b128 v[204:207], v137 offset:55296
	ds_read_b128 v[208:211], v136 offset:53248
	ds_read_b128 v[212:215], v136 offset:55296
	s_mov_b32 m0, s35
	s_nop 0
	global_load_lds_dwordx4 v139, s[36:37]
	s_mov_b32 m0, s33
	s_nop 0
	global_load_lds_dwordx4 v141, s[36:37]
	s_mov_b32 m0, s77
	s_nop 0
	global_load_lds_dwordx4 v139, s[30:31]
	s_mov_b32 m0, s3
	s_nop 0
	global_load_lds_dwordx4 v141, s[30:31]
	s_mov_b32 m0, s22
	s_nop 0
	global_load_lds_dwordx4 v138, s[26:27]
	s_mov_b32 m0, s2
	s_nop 0
	global_load_lds_dwordx4 v140, s[26:27]
	s_waitcnt vmcnt(8)
	s_waitcnt lgkmcnt(0)
	s_barrier
	s_setprio 1
	s_waitcnt lgkmcnt(0)
	v_mfma_f32_16x16x32_bf16 v[60:63], v[128:131], v[174:177], v[60:63]
	v_mfma_f32_16x16x32_bf16 v[56:59], v[146:149], v[174:177], v[56:59]
	v_mfma_f32_16x16x32_bf16 v[44:47], v[128:131], v[178:181], v[44:47]
	v_mfma_f32_16x16x32_bf16 v[40:43], v[146:149], v[178:181], v[40:43]
	v_mfma_f32_16x16x32_bf16 v[28:31], v[128:131], v[200:203], v[28:31]
	v_mfma_f32_16x16x32_bf16 v[24:27], v[146:149], v[200:203], v[24:27]
	v_mfma_f32_16x16x32_bf16 v[12:15], v[128:131], v[204:207], v[12:15]
	v_mfma_f32_16x16x32_bf16 v[8:11], v[146:149], v[204:207], v[8:11]
	v_mfma_f32_16x16x32_bf16 v[60:63], v[150:153], v[192:195], v[60:63]
	v_mfma_f32_16x16x32_bf16 v[56:59], v[154:157], v[192:195], v[56:59]
	v_mfma_f32_16x16x32_bf16 v[44:47], v[150:153], v[196:199], v[44:47]
	v_mfma_f32_16x16x32_bf16 v[40:43], v[154:157], v[196:199], v[40:43]
	v_mfma_f32_16x16x32_bf16 v[28:31], v[150:153], v[208:211], v[28:31]
	v_mfma_f32_16x16x32_bf16 v[24:27], v[154:157], v[208:211], v[24:27]
	v_mfma_f32_16x16x32_bf16 v[12:15], v[150:153], v[212:215], v[12:15]
	v_mfma_f32_16x16x32_bf16 v[8:11], v[154:157], v[212:215], v[8:11]
	s_setprio 0
	s_setprio 1
	v_mfma_f32_16x16x32_bf16 v[52:55], v[158:161], v[174:177], v[52:55]
	v_mfma_f32_16x16x32_bf16 v[48:51], v[162:165], v[174:177], v[48:51]
	v_mfma_f32_16x16x32_bf16 v[36:39], v[158:161], v[178:181], v[36:39]
	v_mfma_f32_16x16x32_bf16 v[32:35], v[162:165], v[178:181], v[32:35]
	v_mfma_f32_16x16x32_bf16 v[20:23], v[158:161], v[200:203], v[20:23]
	v_mfma_f32_16x16x32_bf16 v[16:19], v[162:165], v[200:203], v[16:19]
	v_mfma_f32_16x16x32_bf16 v[4:7], v[158:161], v[204:207], v[4:7]
	v_mfma_f32_16x16x32_bf16 v[0:3], v[162:165], v[204:207], v[0:3]
	v_mfma_f32_16x16x32_bf16 v[52:55], v[166:169], v[192:195], v[52:55]
	v_mfma_f32_16x16x32_bf16 v[48:51], v[170:173], v[192:195], v[48:51]
	v_mfma_f32_16x16x32_bf16 v[36:39], v[166:169], v[196:199], v[36:39]
	v_mfma_f32_16x16x32_bf16 v[32:35], v[170:173], v[196:199], v[32:35]
	v_mfma_f32_16x16x32_bf16 v[20:23], v[166:169], v[208:211], v[20:23]
	v_mfma_f32_16x16x32_bf16 v[16:19], v[170:173], v[208:211], v[16:19]
	v_mfma_f32_16x16x32_bf16 v[4:7], v[166:169], v[212:215], v[4:7]
	v_mfma_f32_16x16x32_bf16 v[0:3], v[170:173], v[212:215], v[0:3]
	s_setprio 0
	s_barrier
	s_add_i32 s57, s57, 2
	s_add_u32 s52, s52, 0x100
	s_addc_u32 s56, s56, 0
	s_add_u32 s12, s12, 0x100
	s_addc_u32 s13, s13, 0
	s_cmp_gt_u32 s57, 29
	s_cbranch_scc0 .LBB0_574
	v_readlane_b32 s12, v253, 13
	v_readlane_b32 s13, v253, 14
	s_and_b64 vcc, exec, s[12:13]
	s_cbranch_vccz .LBB0_577
	s_barrier

; __device__ __forceinline__ int tid_of(int wave) { return opqv(wave * 64 + (int)__builtin_amdgcn_mbcnt_hi(~0u, __builtin_amdgcn_mbcnt_lo(~0u, 0u))); }
; __host__ __device__ __forceinline__ int lds_byte(int r, int c) { return (r >> 3) * 1024 + (r & 7) * 128 + ((((c >> 3)) ^ ((r >> 1) & 7)) << 4) + (c & 7) * 2; }
; #define PG8_WAIT_V(n) asm volatile("s_waitcnt vmcnt(" #n ")" ::: "memory")
; #define PG8_BAR __builtin_amdgcn_s_barrier()
; template <class Epi>
; __device__ __forceinline__ void gemm_phase(LAS unsigned char* lds, const Gemm g, const StaticOrder& S, const Epi& E, int wave_) {
;     const int tid = tid_of(wave_), wid = wave_, lane = tid & 63, wr = wid >> 2, wc = wid & 3, fr = lane & 15, fq = lane >> 4;
;     const int K = g.K, nt = K / BK;
;     unsigned voffA[2], voffB[2];
; #pragma unroll
;     for (int i = 0; i < 2; ++i) { int R, C; stage_rc(tid * 16 + i * 8192, R, C); const int Rb = (R & ~31) + perm32(R & 31);
;         voffA[i] = (unsigned)(R * g.lda + C) * 2u; voffB[i] = (unsigned)(Rb * g.ldb + C) * 2u; }
;     const size_t kstep = (size_t)(BK * 2);
;     const size_t hstepA = (size_t)HALF * g.lda * 2, hstepB = (size_t)HALF * g.ldb * 2;
;     const size_t tstepA = 2 * hstepA, tstepB = 2 * hstepB;
;     const unsigned ldsw = (unsigned)wid * 1024u, ldsb = (unsigned)(uintptr_t)lds;
;     const int aoff0 = lds_byte(wr * 64 + fr, fq * 8), boff0 = lds_byte(wc * 32 + fr, fq * 8);
;     ...
;     Unit cur, nxt; int ui = 0;
;     if (!S.next(0, cur)) return;
;     f32x4 acc[2][2][4][2];
; #pragma unroll
;     for (int a = 0; a < 2; ++a)
; #pragma unroll
;         for (int b = 0; b < 2; ++b)
; #pragma unroll
;             for (int m = 0; m < 4; ++m)
; #pragma unroll
;                 for (int n = 0; n < 2; ++n) acc[a][b][m][n] = (f32x4){0.f, 0.f, 0.f, 0.f};
;     bf16x8 At[4][2], B0[2][2], B1[2][2];
;     const char* cA = (const char*)g.A + (size_t)cur.pm * tstepA; const char* cB = (const char*)g.Bt + (size_t)cur.pn * tstepB;
;     PG8_STAGE(PG8_SB(0, 0), cB, voffB); PG8_STAGE(PG8_SB(0, 1), cB + hstepB, voffB); PG8_STAGE(PG8_SA(0, 0), cA, voffA); PG8_STAGE(PG8_SA(0, 1), cA + hstepA, voffA);
;     if (wr == 1) PG8_BAR;
;     PG8_WAIT_V(2); PG8_BAR;
;     PG8_STAGE(PG8_SB(1, 0), cB + kstep, voffB); PG8_STAGE(PG8_SA(1, 0), cA + kstep, voffA); PG8_STAGE(PG8_SB(1, 1), cB + hstepB + kstep, voffB);
;     PG8_WAIT_V(6); PG8_BAR;
.LBB0_735:
	s_or_b64 exec, exec, s[4:5]
	v_readlane_b32 s10, v252, 12
	v_readlane_b32 s18, v253, 34
	v_readlane_b32 s11, v252, 13
	v_readlane_b32 s19, v253, 35
	s_mov_b64 s[12:13], s[10:11]
	s_mov_b64 s[16:17], s[10:11]
	s_mov_b64 s[4:5], s[10:11]
	s_mov_b64 s[6:7], s[10:11]
	s_mov_b64 s[8:9], s[10:11]
	v_mov_b32_e32 v0, v220
	s_andn2_b64 vcc, exec, s[18:19]
	s_barrier
	s_cbranch_vccnz .LBB0_783
	v_bfe_i32 v3, v0, 27, 1
	v_lshlrev_b32_e32 v1, 4, v0
	v_lshrrev_b32_e32 v4, 22, v3
	v_add_u32_e32 v4, v1, v4
	v_and_b32_e32 v4, 0xfc00, v4
	v_sub_u32_e32 v4, v1, v4
	v_ashrrev_i16_e32 v5, 15, v4
	v_ashrrev_i32_e32 v2, 31, v0
	v_lshrrev_b16_e32 v5, 9, v5
	v_lshrrev_b32_e32 v3, 25, v3
	v_lshrrev_b32_e32 v2, 26, v2
	v_add_u16_e32 v4, v4, v5
	v_add_u32_e32 v3, v1, v3
	v_add_u32_e32 v2, v0, v2
	v_ashrrev_i16_e32 v4, 7, v4
	v_and_b32_e32 v3, 0x80, v3
	v_ashrrev_i32_e32 v2, 6, v2
	v_bfe_i32 v4, v4, 0, 16
	v_sub_u32_e32 v3, v1, v3
	v_mov_b32_e32 v7, 4
	v_ashrrev_i16_sdwa v3, v7, sext(v3) dst_sel:DWORD dst_unused:UNUSED_PAD src0_sel:DWORD src1_sel:BYTE_0
	v_lshl_add_u32 v2, v2, 3, v4
	v_bfe_i32 v3, v3, 0, 16
	v_lshrrev_b32_e32 v5, 1, v2
	s_add_u32 s21, s12, 0x19000000
	v_bitop3_b32 v3, v5, v3, 7 bitop3:0x6c
	v_lshlrev_b32_e32 v5, 1, v2
	v_lshrrev_b32_e32 v6, 2, v2
	v_and_b32_e32 v4, 3, v4
	s_mov_b32 s12, 0x3fffe0
	v_lshlrev_b32_e32 v3, 4, v3
	v_and_b32_e32 v5, 24, v5
	v_and_b32_e32 v6, 4, v6
	v_and_or_b32 v4, v2, s12, v4
	v_add_u32_e32 v1, 0x2000, v1
	v_or3_b32 v4, v4, v6, v5
	v_lshl_add_u32 v137, v2, 11, v3
	v_ashrrev_i32_e32 v2, 31, v1
	v_lshl_add_u32 v175, v4, 10, v3
	v_lshrrev_b32_e32 v3, 22, v2
	v_add_u32_e32 v3, v1, v3
	v_ashrrev_i32_e32 v3, 10, v3
	v_mul_i32_i24_e32 v4, 0x400, v3
	v_sub_u32_e32 v4, v1, v4
	v_ashrrev_i16_e32 v5, 15, v4
	v_lshrrev_b16_e32 v5, 9, v5
	v_lshrrev_b32_e32 v2, 25, v2
	v_add_u16_e32 v4, v4, v5
	v_add_u32_e32 v2, v1, v2
	v_ashrrev_i16_e32 v4, 7, v4
	v_and_b32_e32 v2, 0x80, v2
	v_bfe_i32 v4, v4, 0, 16
	v_sub_u32_e32 v1, v1, v2
	s_addc_u32 s46, s13, 0
	v_ashrrev_i16_sdwa v1, v7, sext(v1) dst_sel:DWORD dst_unused:UNUSED_PAD src0_sel:DWORD src1_sel:BYTE_0
	v_lshl_add_u32 v2, v3, 3, v4
	s_add_u32 s47, s16, 0x2000000
	v_bfe_i32 v1, v1, 0, 16
	v_lshrrev_b32_e32 v3, 1, v2
	v_and_b32_e32 v4, 3, v4
	s_addc_u32 s48, s17, 0
	v_bitop3_b32 v1, v3, v1, 7 bitop3:0x6c
	v_lshlrev_b32_e32 v3, 1, v2
	v_lshrrev_b32_e32 v5, 2, v2
	v_and_or_b32 v4, v2, s12, v4
	v_readlane_b32 s12, v254, 9
	v_and_b32_e32 v3, 24, v3
	v_and_b32_e32 v5, 4, v5
	v_readlane_b32 s13, v254, 10
	s_add_u32 s12, s47, s12
	v_lshlrev_b32_e32 v1, 4, v1
	v_or3_b32 v3, v4, v5, v3
	s_addc_u32 s13, s48, s13
	s_mov_b32 m0, s80
	s_nop 0
	global_load_lds_dwordx4 v175, s[12:13]
	v_lshl_add_u32 v177, v3, 10, v1
	s_mov_b32 m0, s81
	s_nop 0
	global_load_lds_dwordx4 v177, s[12:13]
	s_add_u32 s16, s12, 0x20000
	s_addc_u32 s17, s13, 0
	s_mov_b32 m0, s29
	s_nop 0
	global_load_lds_dwordx4 v175, s[16:17]
	v_lshl_add_u32 v176, v2, 11, v1
	s_mov_b32 m0, s88
	s_nop 0
	global_load_lds_dwordx4 v177, s[16:17]
	v_readlane_b32 s16, v254, 35
	v_readlane_b32 s17, v254, 36
	s_add_u32 s30, s21, s16
	s_addc_u32 s31, s46, s17
	s_mov_b32 m0, s76
	s_nop 0
	global_load_lds_dwordx4 v137, s[30:31]
	s_nop 0
	s_mov_b32 m0, s89
	s_nop 0
	global_load_lds_dwordx4 v176, s[30:31]
	s_add_u32 s16, s30, 0x40000
	s_addc_u32 s17, s31, 0
	s_mov_b32 m0, s1
	s_nop 0
	global_load_lds_dwordx4 v137, s[16:17]
	s_nop 0
	s_mov_b32 m0, s69
	s_nop 0
	global_load_lds_dwordx4 v176, s[16:17]
	v_readlane_b32 s16, v253, 11
	v_readlane_b32 s17, v253, 12
	s_andn2_b64 vcc, exec, s[16:17]
	s_nop 0
	v_cndmask_b32_e64 v1, 0, 1, s[16:17]
	v_cmp_ne_u32_e64 s[38:39], 1, v1
	s_cbranch_vccnz .LBB0_738
	s_barrier
.LBB0_738:
	s_add_u32 s4, s4, 0x1d400000
	s_addc_u32 s5, s5, 0
	s_add_u32 s6, s6, 0x25400000
	s_addc_u32 s7, s7, 0
	s_lshl_b64 s[16:17], s[54:55], 3
	s_add_u32 s8, s8, s16
	s_addc_u32 s9, s9, s17
	s_add_u32 s8, s8, 0x500000
	s_addc_u32 s9, s9, 0
	v_and_b32_e32 v2, 15, v0
	v_readlane_b32 s16, v253, 6
	s_waitcnt vmcnt(2)
	s_barrier
	v_lshrrev_b32_e32 v1, 4, v0
	v_or_b32_e32 v178, s16, v2
	s_add_u32 s16, s12, 0x80
	s_addc_u32 s17, s13, 0
	s_mov_b32 m0, s35
	s_nop 0
	global_load_lds_dwordx4 v175, s[16:17]
	v_bfe_u32 v3, v0, 4, 2
	s_mov_b32 m0, s33
	s_nop 0
	global_load_lds_dwordx4 v177, s[16:17]
	s_add_u32 s16, s30, 0x80
	s_addc_u32 s17, s31, 0
	s_mov_b32 m0, s22
	s_nop 0
	global_load_lds_dwordx4 v137, s[16:17]
	v_bfe_u32 v0, v0, 1, 3
	s_mov_b32 m0, s2
	s_nop 0
	global_load_lds_dwordx4 v176, s[16:17]
	s_add_u32 s16, s12, 0x20080
	v_bitop3_b32 v0, v1, v0, 3 bitop3:0x6c
	v_readlane_b32 s19, v253, 29
	s_addc_u32 s17, s13, 0
	s_mov_b32 m0, s77
	s_nop 0
	global_load_lds_dwordx4 v175, s[16:17]
	v_lshlrev_b32_e32 v0, 4, v0
	v_or_b32_e32 v1, s19, v2
	s_mov_b32 m0, s3
	s_nop 0
	global_load_lds_dwordx4 v177, s[16:17]
	v_lshlrev_b32_e32 v184, 5, v3
	v_lshl_or_b32 v179, v178, 7, v0
	v_lshl_or_b32 v180, v1, 7, v0
	s_waitcnt vmcnt(6)
	v_lshl_add_u64 v[0:1], s[10:11], 0, v[184:185]
	s_mov_b64 s[10:11], 0x39400000
	v_lshlrev_b32_e32 v136, 3, v3
	v_lshl_add_u64 v[138:139], v[0:1], 0, s[10:11]
	v_readlane_b32 s10, v254, 33
	v_or_b32_e32 v181, s19, v136
	s_mov_b32 s49, 0
	v_readlane_b32 s44, v254, 8
	s_mov_b32 s45, s10
	s_barrier
	v_readlane_b32 s11, v254, 34
	s_branch .LBB0_741

; #define PG8_STAGE(bufoff, gbase, voff) do { _Pragma("unroll") for (int _i = 0; _i < 2; ++_i) \
;         dma16((const char*)(gbase), (voff)[_i], ldsb + (bufoff) + ldsw + _i * 8192); } while (0)
; #define PG8_LDA(dst, b, h) do { const int a1_ = opqv(aoff0) ^ 64; _Pragma("unroll") for (int m = 0; m < 4; ++m) { dst[m][0] = *(const LAS bf16x8*)(lds + PG8_SA(b, h) + aoff0 + m * 2048); dst[m][1] = *(const LAS bf16x8*)(lds + PG8_SA(b, h) + a1_ + m * 2048); } } while (0)
; #define PG8_LDB(dst, b, h) do { const int b1_ = opqv(boff0) ^ 64; _Pragma("unroll") for (int n = 0; n < 2; ++n) { dst[n][0] = *(const LAS bf16x8*)(lds + PG8_SB(b, h) + boff0 + n * 2048); dst[n][1] = *(const LAS bf16x8*)(lds + PG8_SB(b, h) + b1_ + n * 2048); } } while (0)
; #define PG8_MMA(ai, bj, At, Bt) do { __builtin_amdgcn_s_setprio(1); _Pragma("unroll") for (int m = 0; m < 4; ++m) _Pragma("unroll") for (int n = 0; n < 2; ++n) _Pragma("unroll") for (int k = 0; k < 2; ++k) \
;         acc[ai][bj][m][n] = __builtin_amdgcn_mfma_f32_16x16x32_bf16(Bt[n][k], At[m][k], acc[ai][bj][m][n], 0, 0, 0); __builtin_amdgcn_s_setprio(0); } while (0)
; #define PG8_WAIT_V(n) asm volatile("s_waitcnt vmcnt(" #n ")" ::: "memory")
; #define PG8_WAIT_L(n) asm volatile("s_waitcnt lgkmcnt(" #n ")" ::: "memory")
; #define PG8_BAR __builtin_amdgcn_s_barrier()
; #define PG8_SCHED __builtin_amdgcn_sched_barrier(0)
; template <class Epi>
; __device__ __forceinline__ void gemm_phase(LAS unsigned char* lds, const Gemm g, const StaticOrder& S, const Epi& E, int wave_) {
;     ...
;         for (int t = 0; t < nt; t += 2) {
;             const bool last = (t == nt - 2);
;             const char* a1 = cA + (size_t)(t + 1) * kstep;
;             const char* a2 = last ? nA : cA + (size_t)(t + 2) * kstep; const char* b2 = last ? nB : cB + (size_t)(t + 2) * kstep;
;             const char* a3 = a2 + kstep; const char* b3 = b2 + kstep;
;             PG8_STAGE(PG8_SA(1, 1), a1 + hstepA, voffA); PG8_LDB(B0, 0, 0); PG8_LDB(B1, 0, 1); PG8_SCHED; PG8_LDA(At, 0, 0);
;             PG8_WAIT_V(8); PG8_WAIT_L(0); PG8_BAR; PG8_MMA(0, 0, At, B0); PG8_MMA(0, 1, At, B1); PG8_BAR; PG8_SCHED;
;             PG8_STAGE(PG8_SB(0, 0), b2, voffB); PG8_STAGE(PG8_SB(0, 1), b2 + hstepB, voffB); PG8_STAGE(PG8_SA(0, 0), a2, voffA); PG8_LDA(At, 0, 1);
;             PG8_WAIT_V(8); PG8_WAIT_L(0); PG8_BAR; PG8_MMA(1, 0, At, B0); PG8_MMA(1, 1, At, B1); PG8_BAR; PG8_SCHED;
.LBB0_744:
	s_add_u32 s30, s12, 0xfffc0080
	s_addc_u32 s31, s13, -1
	s_cmp_eq_u32 s57, 4
	s_cselect_b32 s42, s17, s30
	s_cselect_b32 s43, s16, s31
	s_cselect_b32 s36, s19, s52
	s_cselect_b32 s37, s11, s56
	s_add_u32 s30, s42, 0x80
	v_mov_b32_e32 v128, v180
	s_addc_u32 s31, s43, 0
	v_add_u32_e32 v132, s23, v180
	v_xad_u32 v144, v128, 64, s23
	v_mov_b32_e32 v148, v180
	s_add_i32 s58, 0, 0x14000
	ds_read_b128 v[128:131], v132
	ds_read_b128 v[132:135], v132 offset:2048
	ds_read_b128 v[140:143], v144
	ds_read_b128 v[144:147], v144 offset:2048
	v_add_u32_e32 v152, s58, v180
	v_xad_u32 v160, v148, 64, s58
	ds_read_b128 v[148:151], v152
	ds_read_b128 v[152:155], v152 offset:2048
	ds_read_b128 v[156:159], v160
	ds_read_b128 v[160:163], v160 offset:2048
	v_mov_b32_e32 v164, v179
	v_add_u32_e32 v182, 0, v179
	v_xad_u32 v172, v164, 64, 0
	ds_read_b128 v[164:167], v182
	ds_read_b128 v[168:171], v182 offset:2048
	ds_read_b128 v[192:195], v172
	ds_read_b128 v[196:199], v172 offset:2048
	ds_read_b128 v[200:203], v182 offset:4096
	ds_read_b128 v[204:207], v182 offset:6144
	ds_read_b128 v[208:211], v172 offset:4096
	ds_read_b128 v[212:215], v172 offset:6144
	s_mov_b32 m0, s14
	s_nop 0
	global_load_lds_dwordx4 v137, s[12:13]
	s_mov_b32 m0, s15
	s_nop 0
	global_load_lds_dwordx4 v176, s[12:13]
	s_waitcnt vmcnt(8)
	s_waitcnt lgkmcnt(0)
	s_barrier
	s_setprio 1
	s_waitcnt lgkmcnt(0)
	v_mfma_f32_16x16x32_bf16 v[124:127], v[128:131], v[164:167], v[124:127]
	v_mfma_f32_16x16x32_bf16 v[120:123], v[132:135], v[164:167], v[120:123]
	v_mfma_f32_16x16x32_bf16 v[108:111], v[128:131], v[168:171], v[108:111]
	v_mfma_f32_16x16x32_bf16 v[104:107], v[132:135], v[168:171], v[104:107]
	v_mfma_f32_16x16x32_bf16 v[92:95], v[128:131], v[200:203], v[92:95]
	v_mfma_f32_16x16x32_bf16 v[88:91], v[132:135], v[200:203], v[88:91]
	v_mfma_f32_16x16x32_bf16 v[76:79], v[128:131], v[204:207], v[76:79]
	v_mfma_f32_16x16x32_bf16 v[72:75], v[132:135], v[204:207], v[72:75]
	v_mfma_f32_16x16x32_bf16 v[124:127], v[140:143], v[192:195], v[124:127]
	v_mfma_f32_16x16x32_bf16 v[120:123], v[144:147], v[192:195], v[120:123]
	v_mfma_f32_16x16x32_bf16 v[108:111], v[140:143], v[196:199], v[108:111]
	v_mfma_f32_16x16x32_bf16 v[104:107], v[144:147], v[196:199], v[104:107]
	v_mfma_f32_16x16x32_bf16 v[92:95], v[140:143], v[208:211], v[92:95]
	v_mfma_f32_16x16x32_bf16 v[88:91], v[144:147], v[208:211], v[88:91]
	v_mfma_f32_16x16x32_bf16 v[76:79], v[140:143], v[212:215], v[76:79]
	v_mfma_f32_16x16x32_bf16 v[72:75], v[144:147], v[212:215], v[72:75]
	s_setprio 0
	s_setprio 1
	v_mfma_f32_16x16x32_bf16 v[116:119], v[148:151], v[164:167], v[116:119]
	v_mfma_f32_16x16x32_bf16 v[112:115], v[152:155], v[164:167], v[112:115]
	v_mfma_f32_16x16x32_bf16 v[100:103], v[148:151], v[168:171], v[100:103]
	v_mfma_f32_16x16x32_bf16 v[96:99], v[152:155], v[168:171], v[96:99]
	v_mfma_f32_16x16x32_bf16 v[84:87], v[148:151], v[200:203], v[84:87]
	v_mfma_f32_16x16x32_bf16 v[80:83], v[152:155], v[200:203], v[80:83]
	v_mfma_f32_16x16x32_bf16 v[68:71], v[148:151], v[204:207], v[68:71]
	v_mfma_f32_16x16x32_bf16 v[64:67], v[152:155], v[204:207], v[64:67]
	v_mfma_f32_16x16x32_bf16 v[116:119], v[156:159], v[192:195], v[116:119]
	v_mfma_f32_16x16x32_bf16 v[112:115], v[160:163], v[192:195], v[112:115]
	v_mfma_f32_16x16x32_bf16 v[100:103], v[156:159], v[196:199], v[100:103]
	v_mfma_f32_16x16x32_bf16 v[96:99], v[160:163], v[196:199], v[96:99]
	v_mfma_f32_16x16x32_bf16 v[84:87], v[156:159], v[208:211], v[84:87]
	v_mfma_f32_16x16x32_bf16 v[80:83], v[160:163], v[208:211], v[80:83]
	v_mfma_f32_16x16x32_bf16 v[68:71], v[156:159], v[212:215], v[68:71]
	v_mfma_f32_16x16x32_bf16 v[64:67], v[160:163], v[212:215], v[64:67]
	s_setprio 0
	s_barrier
	v_mov_b32_e32 v164, v179
	s_add_u32 s58, s36, 0x20000
	s_addc_u32 s59, s37, 0
	s_nop 0
	s_nop 0
	s_nop 0
	v_xad_u32 v172, v164, 64, 0
	ds_read_b128 v[164:167], v182 offset:16384
	ds_read_b128 v[168:171], v182 offset:18432
	ds_read_b128 v[192:195], v172 offset:16384
	ds_read_b128 v[196:199], v172 offset:18432
	ds_read_b128 v[200:203], v182 offset:20480
	ds_read_b128 v[204:207], v182 offset:22528
	ds_read_b128 v[208:211], v172 offset:20480
	ds_read_b128 v[212:215], v172 offset:22528
	s_mov_b32 m0, s80
	s_nop 0
	global_load_lds_dwordx4 v175, s[36:37]
	s_mov_b32 m0, s81
	s_nop 0
	global_load_lds_dwordx4 v177, s[36:37]
	s_mov_b32 m0, s29
	s_nop 0
	global_load_lds_dwordx4 v175, s[58:59]
	s_mov_b32 m0, s88
	s_nop 0
	global_load_lds_dwordx4 v177, s[58:59]
	s_mov_b32 m0, s76
	s_nop 0
	global_load_lds_dwordx4 v137, s[42:43]
	s_mov_b32 m0, s89
	s_nop 0
	global_load_lds_dwordx4 v176, s[42:43]
	s_waitcnt vmcnt(8)
	s_waitcnt lgkmcnt(0)
	s_barrier
; #define PG8_STAGE(bufoff, gbase, voff) do { _Pragma("unroll") for (int _i = 0; _i < 2; ++_i) \
;         dma16((const char*)(gbase), (voff)[_i], ldsb + (bufoff) + ldsw + _i * 8192); } while (0)
; #define PG8_LDA(dst, b, h) do { const int a1_ = opqv(aoff0) ^ 64; _Pragma("unroll") for (int m = 0; m < 4; ++m) { dst[m][0] = *(const LAS bf16x8*)(lds + PG8_SA(b, h) + aoff0 + m * 2048); dst[m][1] = *(const LAS bf16x8*)(lds + PG8_SA(b, h) + a1_ + m * 2048); } } while (0)
; #define PG8_LDB(dst, b, h) do { const int b1_ = opqv(boff0) ^ 64; _Pragma("unroll") for (int n = 0; n < 2; ++n) { dst[n][0] = *(const LAS bf16x8*)(lds + PG8_SB(b, h) + boff0 + n * 2048); dst[n][1] = *(const LAS bf16x8*)(lds + PG8_SB(b, h) + b1_ + n * 2048); } } while (0)
; #define PG8_MMA(ai, bj, At, Bt) do { __builtin_amdgcn_s_setprio(1); _Pragma("unroll") for (int m = 0; m < 4; ++m) _Pragma("unroll") for (int n = 0; n < 2; ++n) _Pragma("unroll") for (int k = 0; k < 2; ++k) \
;         acc[ai][bj][m][n] = __builtin_amdgcn_mfma_f32_16x16x32_bf16(Bt[n][k], At[m][k], acc[ai][bj][m][n], 0, 0, 0); __builtin_amdgcn_s_setprio(0); } while (0)
; #define PG8_WAIT_V(n) asm volatile("s_waitcnt vmcnt(" #n ")" ::: "memory")
; #define PG8_WAIT_L(n) asm volatile("s_waitcnt lgkmcnt(" #n ")" ::: "memory")
; #define PG8_BAR __builtin_amdgcn_s_barrier()
; #define PG8_SCHED __builtin_amdgcn_sched_barrier(0)
; template <class Epi>
; __device__ __forceinline__ void gemm_phase(LAS unsigned char* lds, const Gemm g, const StaticOrder& S, const Epi& E, int wave_) {
;     ...
;             PG8_WAIT_V(8); PG8_WAIT_L(0); PG8_BAR; PG8_MMA(1, 0, At, B0); PG8_MMA(1, 1, At, B1); PG8_BAR; PG8_SCHED;
;             PG8_STAGE(PG8_SA(0, 1), a2 + hstepA, voffA); PG8_LDB(B0, 1, 0); PG8_LDB(B1, 1, 1); PG8_SCHED; PG8_LDA(At, 1, 0);
;             PG8_WAIT_V(8); PG8_WAIT_L(0); PG8_BAR; PG8_MMA(0, 0, At, B0); PG8_MMA(0, 1, At, B1); PG8_BAR; PG8_SCHED;
	s_setprio 1
	s_waitcnt lgkmcnt(0)
	v_mfma_f32_16x16x32_bf16 v[60:63], v[128:131], v[164:167], v[60:63]
	v_mfma_f32_16x16x32_bf16 v[56:59], v[132:135], v[164:167], v[56:59]
	v_mfma_f32_16x16x32_bf16 v[44:47], v[128:131], v[168:171], v[44:47]
	v_mfma_f32_16x16x32_bf16 v[40:43], v[132:135], v[168:171], v[40:43]
	v_mfma_f32_16x16x32_bf16 v[28:31], v[128:131], v[200:203], v[28:31]
	v_mfma_f32_16x16x32_bf16 v[24:27], v[132:135], v[200:203], v[24:27]
	v_mfma_f32_16x16x32_bf16 v[12:15], v[128:131], v[204:207], v[12:15]
	v_mfma_f32_16x16x32_bf16 v[8:11], v[132:135], v[204:207], v[8:11]
	v_mfma_f32_16x16x32_bf16 v[60:63], v[140:143], v[192:195], v[60:63]
	v_mfma_f32_16x16x32_bf16 v[56:59], v[144:147], v[192:195], v[56:59]
	v_mfma_f32_16x16x32_bf16 v[44:47], v[140:143], v[196:199], v[44:47]
	v_mfma_f32_16x16x32_bf16 v[40:43], v[144:147], v[196:199], v[40:43]
	v_mfma_f32_16x16x32_bf16 v[28:31], v[140:143], v[208:211], v[28:31]
	v_mfma_f32_16x16x32_bf16 v[24:27], v[144:147], v[208:211], v[24:27]
	v_mfma_f32_16x16x32_bf16 v[12:15], v[140:143], v[212:215], v[12:15]
	v_mfma_f32_16x16x32_bf16 v[8:11], v[144:147], v[212:215], v[8:11]
	s_setprio 0
	s_setprio 1
	v_mfma_f32_16x16x32_bf16 v[52:55], v[148:151], v[164:167], v[52:55]
	v_mfma_f32_16x16x32_bf16 v[48:51], v[152:155], v[164:167], v[48:51]
	v_mfma_f32_16x16x32_bf16 v[36:39], v[148:151], v[168:171], v[36:39]
	v_mfma_f32_16x16x32_bf16 v[32:35], v[152:155], v[168:171], v[32:35]
	v_mfma_f32_16x16x32_bf16 v[20:23], v[148:151], v[200:203], v[20:23]
	v_mfma_f32_16x16x32_bf16 v[16:19], v[152:155], v[200:203], v[16:19]
	v_mfma_f32_16x16x32_bf16 v[4:7], v[148:151], v[204:207], v[4:7]
	v_mfma_f32_16x16x32_bf16 v[0:3], v[152:155], v[204:207], v[0:3]
	v_mfma_f32_16x16x32_bf16 v[52:55], v[156:159], v[192:195], v[52:55]
	v_mfma_f32_16x16x32_bf16 v[48:51], v[160:163], v[192:195], v[48:51]
	v_mfma_f32_16x16x32_bf16 v[36:39], v[156:159], v[196:199], v[36:39]
	v_mfma_f32_16x16x32_bf16 v[32:35], v[160:163], v[196:199], v[32:35]
	v_mfma_f32_16x16x32_bf16 v[20:23], v[156:159], v[208:211], v[20:23]
	v_mfma_f32_16x16x32_bf16 v[16:19], v[160:163], v[208:211], v[16:19]
	v_mfma_f32_16x16x32_bf16 v[4:7], v[156:159], v[212:215], v[4:7]
	v_mfma_f32_16x16x32_bf16 v[0:3], v[160:163], v[212:215], v[0:3]
	s_setprio 0
	s_barrier
	s_add_u32 s42, s42, 0x40000
	s_addc_u32 s43, s43, 0
	s_mov_b32 m0, s1
	s_nop 0
	global_load_lds_dwordx4 v137, s[42:43]
	v_mov_b32_e32 v128, v180
	s_mov_b32 m0, s69
	s_nop 0
	global_load_lds_dwordx4 v176, s[42:43]
	v_add_u32_e32 v132, s34, v180
	v_xad_u32 v144, v128, 64, s34
	v_mov_b32_e32 v148, v180
	s_add_i32 s42, 0, 0x1c000
	ds_read_b128 v[128:131], v132
	ds_read_b128 v[132:135], v132 offset:2048
	ds_read_b128 v[140:143], v144
	ds_read_b128 v[144:147], v144 offset:2048
	v_add_u32_e32 v152, s42, v180
	v_xad_u32 v160, v148, 64, s42
	ds_read_b128 v[148:151], v152
	ds_read_b128 v[152:155], v152 offset:2048
	ds_read_b128 v[156:159], v160
	ds_read_b128 v[160:163], v160 offset:2048
	v_mov_b32_e32 v164, v179
	s_nop 0
	v_xad_u32 v172, v164, 64, 0
	ds_read_b128 v[164:167], v182 offset:32768
	ds_read_b128 v[168:171], v182 offset:34816
	ds_read_b128 v[192:195], v172 offset:32768
	ds_read_b128 v[196:199], v172 offset:34816
	ds_read_b128 v[200:203], v182 offset:36864
	ds_read_b128 v[204:207], v182 offset:38912
	ds_read_b128 v[208:211], v172 offset:36864
	ds_read_b128 v[212:215], v172 offset:38912
	s_waitcnt vmcnt(8)
	s_waitcnt lgkmcnt(0)
	s_barrier
	s_setprio 1
	s_waitcnt lgkmcnt(0)
	v_mfma_f32_16x16x32_bf16 v[124:127], v[128:131], v[164:167], v[124:127]
	v_mfma_f32_16x16x32_bf16 v[120:123], v[132:135], v[164:167], v[120:123]
	v_mfma_f32_16x16x32_bf16 v[108:111], v[128:131], v[168:171], v[108:111]
	v_mfma_f32_16x16x32_bf16 v[104:107], v[132:135], v[168:171], v[104:107]
	v_mfma_f32_16x16x32_bf16 v[92:95], v[128:131], v[200:203], v[92:95]
	v_mfma_f32_16x16x32_bf16 v[88:91], v[132:135], v[200:203], v[88:91]
	v_mfma_f32_16x16x32_bf16 v[76:79], v[128:131], v[204:207], v[76:79]
	v_mfma_f32_16x16x32_bf16 v[72:75], v[132:135], v[204:207], v[72:75]
	v_mfma_f32_16x16x32_bf16 v[124:127], v[140:143], v[192:195], v[124:127]
	v_mfma_f32_16x16x32_bf16 v[120:123], v[144:147], v[192:195], v[120:123]
	v_mfma_f32_16x16x32_bf16 v[108:111], v[140:143], v[196:199], v[108:111]
	v_mfma_f32_16x16x32_bf16 v[104:107], v[144:147], v[196:199], v[104:107]
	v_mfma_f32_16x16x32_bf16 v[92:95], v[140:143], v[208:211], v[92:95]
	v_mfma_f32_16x16x32_bf16 v[88:91], v[144:147], v[208:211], v[88:91]
	v_mfma_f32_16x16x32_bf16 v[76:79], v[140:143], v[212:215], v[76:79]
	v_mfma_f32_16x16x32_bf16 v[72:75], v[144:147], v[212:215], v[72:75]
	s_setprio 0
	s_setprio 1
	v_mfma_f32_16x16x32_bf16 v[116:119], v[148:151], v[164:167], v[116:119]
	s_add_u32 s42, s36, 0x80
	s_addc_u32 s43, s37, 0
	v_mfma_f32_16x16x32_bf16 v[112:115], v[152:155], v[164:167], v[112:115]
	v_mfma_f32_16x16x32_bf16 v[100:103], v[148:151], v[168:171], v[100:103]
	v_mfma_f32_16x16x32_bf16 v[96:99], v[152:155], v[168:171], v[96:99]
	v_mfma_f32_16x16x32_bf16 v[84:87], v[148:151], v[200:203], v[84:87]
	v_mfma_f32_16x16x32_bf16 v[80:83], v[152:155], v[200:203], v[80:83]
	v_mfma_f32_16x16x32_bf16 v[68:71], v[148:151], v[204:207], v[68:71]
	v_mfma_f32_16x16x32_bf16 v[64:67], v[152:155], v[204:207], v[64:67]
	v_mfma_f32_16x16x32_bf16 v[116:119], v[156:159], v[192:195], v[116:119]
	v_mfma_f32_16x16x32_bf16 v[112:115], v[160:163], v[192:195], v[112:115]
	v_mfma_f32_16x16x32_bf16 v[100:103], v[156:159], v[196:199], v[100:103]
	v_mfma_f32_16x16x32_bf16 v[96:99], v[160:163], v[196:199], v[96:99]
	v_mfma_f32_16x16x32_bf16 v[84:87], v[156:159], v[208:211], v[84:87]
	v_mfma_f32_16x16x32_bf16 v[80:83], v[160:163], v[208:211], v[80:83]
	v_mfma_f32_16x16x32_bf16 v[68:71], v[156:159], v[212:215], v[68:71]
	v_mfma_f32_16x16x32_bf16 v[64:67], v[160:163], v[212:215], v[64:67]
	s_setprio 0
	s_barrier
; #define PG8_STAGE(bufoff, gbase, voff) do { _Pragma("unroll") for (int _i = 0; _i < 2; ++_i) \
;         dma16((const char*)(gbase), (voff)[_i], ldsb + (bufoff) + ldsw + _i * 8192); } while (0)
; #define PG8_LDA(dst, b, h) do { const int a1_ = opqv(aoff0) ^ 64; _Pragma("unroll") for (int m = 0; m < 4; ++m) { dst[m][0] = *(const LAS bf16x8*)(lds + PG8_SA(b, h) + aoff0 + m * 2048); dst[m][1] = *(const LAS bf16x8*)(lds + PG8_SA(b, h) + a1_ + m * 2048); } } while (0)
; #define PG8_MMA(ai, bj, At, Bt) do { __builtin_amdgcn_s_setprio(1); _Pragma("unroll") for (int m = 0; m < 4; ++m) _Pragma("unroll") for (int n = 0; n < 2; ++n) _Pragma("unroll") for (int k = 0; k < 2; ++k) \
;         acc[ai][bj][m][n] = __builtin_amdgcn_mfma_f32_16x16x32_bf16(Bt[n][k], At[m][k], acc[ai][bj][m][n], 0, 0, 0); __builtin_amdgcn_s_setprio(0); } while (0)
; #define PG8_WAIT_V(n) asm volatile("s_waitcnt vmcnt(" #n ")" ::: "memory")
; #define PG8_WAIT_L(n) asm volatile("s_waitcnt lgkmcnt(" #n ")" ::: "memory")
; #define PG8_BAR __builtin_amdgcn_s_barrier()
; #define PG8_SCHED __builtin_amdgcn_sched_barrier(0)
; template <class Epi>
; __device__ __forceinline__ void gemm_phase(LAS unsigned char* lds, const Gemm g, const StaticOrder& S, const Epi& E, int wave_) {
;     ...
;             PG8_STAGE(PG8_SB(1, 0), b3, voffB); PG8_STAGE(PG8_SB(1, 1), b3 + hstepB, voffB); PG8_STAGE(PG8_SA(1, 0), a3, voffA); PG8_LDA(At, 1, 1);
;             PG8_WAIT_V(8); PG8_WAIT_L(0); PG8_BAR; PG8_MMA(1, 0, At, B0); PG8_MMA(1, 1, At, B1); PG8_BAR; PG8_SCHED;
;         }
;         if (wr == 0) PG8_BAR;
	s_add_u32 s36, s36, 0x20080
	s_addc_u32 s37, s37, 0
	v_mov_b32_e32 v164, v179
	s_nop 0
	s_nop 0
	v_xad_u32 v172, v164, 64, 0
	ds_read_b128 v[164:167], v182 offset:49152
	ds_read_b128 v[168:171], v182 offset:51200
	ds_read_b128 v[192:195], v172 offset:49152
	ds_read_b128 v[196:199], v172 offset:51200
	ds_read_b128 v[200:203], v182 offset:53248
	ds_read_b128 v[204:207], v182 offset:55296
	ds_read_b128 v[208:211], v172 offset:53248
	ds_read_b128 v[212:215], v172 offset:55296
	s_mov_b32 m0, s35
	s_nop 0
	global_load_lds_dwordx4 v175, s[42:43]
	s_mov_b32 m0, s33
	s_nop 0
	global_load_lds_dwordx4 v177, s[42:43]
	s_mov_b32 m0, s77
	s_nop 0
	global_load_lds_dwordx4 v175, s[36:37]
	s_mov_b32 m0, s3
	s_nop 0
	global_load_lds_dwordx4 v177, s[36:37]
	s_mov_b32 m0, s22
	s_nop 0
	global_load_lds_dwordx4 v137, s[30:31]
	s_mov_b32 m0, s2
	s_nop 0
	global_load_lds_dwordx4 v176, s[30:31]
	s_waitcnt vmcnt(8)
	s_waitcnt lgkmcnt(0)
	s_barrier
	s_setprio 1
	s_waitcnt lgkmcnt(0)
	v_mfma_f32_16x16x32_bf16 v[60:63], v[128:131], v[164:167], v[60:63]
	v_mfma_f32_16x16x32_bf16 v[56:59], v[132:135], v[164:167], v[56:59]
	v_mfma_f32_16x16x32_bf16 v[44:47], v[128:131], v[168:171], v[44:47]
	v_mfma_f32_16x16x32_bf16 v[40:43], v[132:135], v[168:171], v[40:43]
	v_mfma_f32_16x16x32_bf16 v[28:31], v[128:131], v[200:203], v[28:31]
	v_mfma_f32_16x16x32_bf16 v[24:27], v[132:135], v[200:203], v[24:27]
	v_mfma_f32_16x16x32_bf16 v[12:15], v[128:131], v[204:207], v[12:15]
	v_mfma_f32_16x16x32_bf16 v[8:11], v[132:135], v[204:207], v[8:11]
	v_mfma_f32_16x16x32_bf16 v[60:63], v[140:143], v[192:195], v[60:63]
	v_mfma_f32_16x16x32_bf16 v[56:59], v[144:147], v[192:195], v[56:59]
	v_mfma_f32_16x16x32_bf16 v[44:47], v[140:143], v[196:199], v[44:47]
	v_mfma_f32_16x16x32_bf16 v[40:43], v[144:147], v[196:199], v[40:43]
	v_mfma_f32_16x16x32_bf16 v[28:31], v[140:143], v[208:211], v[28:31]
	v_mfma_f32_16x16x32_bf16 v[24:27], v[144:147], v[208:211], v[24:27]
	v_mfma_f32_16x16x32_bf16 v[12:15], v[140:143], v[212:215], v[12:15]
	v_mfma_f32_16x16x32_bf16 v[8:11], v[144:147], v[212:215], v[8:11]
	s_setprio 0
	s_setprio 1
	v_mfma_f32_16x16x32_bf16 v[52:55], v[148:151], v[164:167], v[52:55]
	v_mfma_f32_16x16x32_bf16 v[48:51], v[152:155], v[164:167], v[48:51]
	v_mfma_f32_16x16x32_bf16 v[36:39], v[148:151], v[168:171], v[36:39]
	v_mfma_f32_16x16x32_bf16 v[32:35], v[152:155], v[168:171], v[32:35]
	v_mfma_f32_16x16x32_bf16 v[20:23], v[148:151], v[200:203], v[20:23]
	v_mfma_f32_16x16x32_bf16 v[16:19], v[152:155], v[200:203], v[16:19]
	v_mfma_f32_16x16x32_bf16 v[4:7], v[148:151], v[204:207], v[4:7]
	v_mfma_f32_16x16x32_bf16 v[0:3], v[152:155], v[204:207], v[0:3]
	v_mfma_f32_16x16x32_bf16 v[52:55], v[156:159], v[192:195], v[52:55]
	v_mfma_f32_16x16x32_bf16 v[48:51], v[160:163], v[192:195], v[48:51]
	v_mfma_f32_16x16x32_bf16 v[36:39], v[156:159], v[196:199], v[36:39]
	v_mfma_f32_16x16x32_bf16 v[32:35], v[160:163], v[196:199], v[32:35]
	v_mfma_f32_16x16x32_bf16 v[20:23], v[156:159], v[208:211], v[20:23]
	v_mfma_f32_16x16x32_bf16 v[16:19], v[160:163], v[208:211], v[16:19]
	v_mfma_f32_16x16x32_bf16 v[4:7], v[156:159], v[212:215], v[4:7]
	v_mfma_f32_16x16x32_bf16 v[0:3], v[160:163], v[212:215], v[0:3]
	s_setprio 0
	s_barrier
	s_add_i32 s57, s57, 2
	s_add_u32 s52, s52, 0x100
	s_addc_u32 s56, s56, 0
	s_add_u32 s12, s12, 0x100
	s_addc_u32 s13, s13, 0
	s_cmp_gt_u32 s57, 5
	s_cbranch_scc0 .LBB0_744
	v_readlane_b32 s12, v253, 13
	v_readlane_b32 s13, v253, 14
	s_and_b64 vcc, exec, s[12:13]
	s_cbranch_vccz .LBB0_747
	s_barrier

; __host__ __device__ __forceinline__ int lds_byte(int r, int c) { return (r >> 3) * 1024 + (r & 7) * 128 + ((((c >> 3)) ^ ((r >> 1) & 7)) << 4) + (c & 7) * 2; }
; #define PG8_STAGE(bufoff, gbase, voff) do { _Pragma("unroll") for (int _i = 0; _i < 2; ++_i) \
;         dma16((const char*)(gbase), (voff)[_i], ldsb + (bufoff) + ldsw + _i * 8192); } while (0)
; #define PG8_WAIT_V(n) asm volatile("s_waitcnt vmcnt(" #n ")" ::: "memory")
; #define PG8_BAR __builtin_amdgcn_s_barrier()
; template <class Epi>
; __device__ __forceinline__ void gemm_phase(LAS unsigned char* lds, const Gemm g, const StaticOrder& S, const Epi& E, int wave_) {
;     ...
;     for (int i = 0; i < 2; ++i) { int R, C; stage_rc(tid * 16 + i * 8192, R, C); const int Rb = (R & ~31) + perm32(R & 31);
;         voffA[i] = (unsigned)(R * g.lda + C) * 2u; voffB[i] = (unsigned)(Rb * g.ldb + C) * 2u; }
;     const size_t kstep = (size_t)(BK * 2);
;     const size_t hstepA = (size_t)HALF * g.lda * 2, hstepB = (size_t)HALF * g.ldb * 2;
;     const size_t tstepA = 2 * hstepA, tstepB = 2 * hstepB;
;     const unsigned ldsw = (unsigned)wid * 1024u, ldsb = (unsigned)(uintptr_t)lds;
;     const int aoff0 = lds_byte(wr * 64 + fr, fq * 8), boff0 = lds_byte(wc * 32 + fr, fq * 8);
;     ...
;     Unit cur, nxt; int ui = 0;
;     if (!S.next(0, cur)) return;
;     f32x4 acc[2][2][4][2];
; #pragma unroll
;     for (int a = 0; a < 2; ++a)
; #pragma unroll
;         for (int b = 0; b < 2; ++b)
; #pragma unroll
;             for (int m = 0; m < 4; ++m)
; #pragma unroll
;                 for (int n = 0; n < 2; ++n) acc[a][b][m][n] = (f32x4){0.f, 0.f, 0.f, 0.f};
;     bf16x8 At[4][2], B0[2][2], B1[2][2];
;     const char* cA = (const char*)g.A + (size_t)cur.pm * tstepA; const char* cB = (const char*)g.Bt + (size_t)cur.pn * tstepB;
;     PG8_STAGE(PG8_SB(0, 0), cB, voffB); PG8_STAGE(PG8_SB(0, 1), cB + hstepB, voffB); PG8_STAGE(PG8_SA(0, 0), cA, voffA); PG8_STAGE(PG8_SA(0, 1), cA + hstepA, voffA);
;     if (wr == 1) PG8_BAR;
;     PG8_WAIT_V(2); PG8_BAR;
;     PG8_STAGE(PG8_SB(1, 0), cB + kstep, voffB); PG8_STAGE(PG8_SA(1, 0), cA + kstep, voffA); PG8_STAGE(PG8_SB(1, 1), cB + hstepB + kstep, voffB);
;     PG8_WAIT_V(6); PG8_BAR;
.LBB0_783:
	v_readlane_b32 s8, v252, 12
	v_readlane_b32 s16, v253, 37
	v_readlane_b32 s9, v252, 13
	v_readlane_b32 s17, v253, 38
	s_mov_b64 s[10:11], s[8:9]
	s_mov_b64 s[12:13], s[8:9]
	s_mov_b64 s[4:5], s[8:9]
	s_mov_b64 s[6:7], s[8:9]
	v_mov_b32_e32 v0, v220
	s_andn2_b64 vcc, exec, s[16:17]
	s_cbranch_vccnz .LBB0_803
	v_bfe_i32 v3, v0, 27, 1
	v_lshlrev_b32_e32 v1, 4, v0
	v_lshrrev_b32_e32 v4, 22, v3
	v_add_u32_e32 v4, v1, v4
	v_and_b32_e32 v4, 0xfc00, v4
	v_sub_u32_e32 v4, v1, v4
	v_ashrrev_i16_e32 v5, 15, v4
	v_ashrrev_i32_e32 v2, 31, v0
	v_lshrrev_b16_e32 v5, 9, v5
	v_lshrrev_b32_e32 v3, 25, v3
	v_lshrrev_b32_e32 v2, 26, v2
	v_add_u16_e32 v4, v4, v5
	v_add_u32_e32 v3, v1, v3
	v_add_u32_e32 v2, v0, v2
	v_ashrrev_i16_e32 v4, 7, v4
	v_and_b32_e32 v3, 0x80, v3
	v_ashrrev_i32_e32 v2, 6, v2
	v_bfe_i32 v4, v4, 0, 16
	v_sub_u32_e32 v3, v1, v3
	v_mov_b32_e32 v7, 4
	v_ashrrev_i16_sdwa v3, v7, sext(v3) dst_sel:DWORD dst_unused:UNUSED_PAD src0_sel:DWORD src1_sel:BYTE_0
	v_lshl_add_u32 v2, v2, 3, v4
	v_bfe_i32 v3, v3, 0, 16
	v_lshrrev_b32_e32 v5, 1, v2
	s_add_u32 s21, s10, 0x19000400
	v_bitop3_b32 v3, v5, v3, 7 bitop3:0x6c
	v_lshlrev_b32_e32 v5, 1, v2
	v_lshrrev_b32_e32 v6, 2, v2
	v_and_b32_e32 v4, 3, v4
	s_mov_b32 s10, 0x3fffe0
	v_lshlrev_b32_e32 v3, 4, v3
	v_and_b32_e32 v5, 24, v5
	v_and_b32_e32 v6, 4, v6
	v_and_or_b32 v4, v2, s10, v4
	v_add_u32_e32 v1, 0x2000, v1
	v_or3_b32 v4, v4, v6, v5
	v_lshl_add_u32 v129, v2, 11, v3
	v_ashrrev_i32_e32 v2, 31, v1
	v_lshl_add_u32 v156, v4, 10, v3
	v_lshrrev_b32_e32 v3, 22, v2
	v_add_u32_e32 v3, v1, v3
	v_ashrrev_i32_e32 v3, 10, v3
	v_mul_i32_i24_e32 v4, 0x400, v3
	v_sub_u32_e32 v4, v1, v4
	v_ashrrev_i16_e32 v5, 15, v4
	v_lshrrev_b16_e32 v5, 9, v5
	v_lshrrev_b32_e32 v2, 25, v2
	v_add_u16_e32 v4, v4, v5
	v_add_u32_e32 v2, v1, v2
	v_ashrrev_i16_e32 v4, 7, v4
	v_and_b32_e32 v2, 0x80, v2
	v_bfe_i32 v4, v4, 0, 16
	v_sub_u32_e32 v1, v1, v2
	s_addc_u32 s44, s11, 0
	v_ashrrev_i16_sdwa v1, v7, sext(v1) dst_sel:DWORD dst_unused:UNUSED_PAD src0_sel:DWORD src1_sel:BYTE_0
	v_lshl_add_u32 v2, v3, 3, v4
	s_add_u32 s45, s12, 0x2300000
	v_bfe_i32 v1, v1, 0, 16
	v_lshrrev_b32_e32 v3, 1, v2
	v_and_b32_e32 v4, 3, v4
	s_addc_u32 s46, s13, 0
	v_bitop3_b32 v1, v3, v1, 7 bitop3:0x6c
	v_lshlrev_b32_e32 v3, 1, v2
	v_lshrrev_b32_e32 v5, 2, v2
	v_and_or_b32 v4, v2, s10, v4
	v_readlane_b32 s10, v253, 63
	v_and_b32_e32 v3, 24, v3
	v_and_b32_e32 v5, 4, v5
	v_readlane_b32 s11, v254, 0
	s_add_u32 s12, s45, s10
	v_lshlrev_b32_e32 v1, 4, v1
	v_or3_b32 v3, v4, v5, v3
	s_addc_u32 s13, s46, s11
	s_mov_b32 m0, s80
	s_nop 0
	global_load_lds_dwordx4 v156, s[12:13]
	v_lshl_add_u32 v158, v3, 10, v1
	s_mov_b32 m0, s81
	s_nop 0
	global_load_lds_dwordx4 v158, s[12:13]
	s_add_u32 s10, s12, 0x20000
	s_addc_u32 s11, s13, 0
	s_mov_b32 m0, s29
	s_nop 0
	global_load_lds_dwordx4 v156, s[10:11]
	v_lshl_add_u32 v157, v2, 11, v1
	s_mov_b32 m0, s88
	s_nop 0
	global_load_lds_dwordx4 v158, s[10:11]
	v_readlane_b32 s10, v254, 21
	v_readlane_b32 s11, v254, 22
	s_add_u32 s30, s21, s10
	s_addc_u32 s31, s44, s11
	s_mov_b32 m0, s76
	s_nop 0
	global_load_lds_dwordx4 v129, s[30:31]
	s_nop 0
	s_mov_b32 m0, s89
	s_nop 0
	global_load_lds_dwordx4 v157, s[30:31]
	s_add_u32 s10, s30, 0x40000
	s_addc_u32 s11, s31, 0
	s_mov_b32 m0, s1
	s_nop 0
	global_load_lds_dwordx4 v129, s[10:11]
	s_nop 0
	s_mov_b32 m0, s69
	s_nop 0
	global_load_lds_dwordx4 v157, s[10:11]
	v_readlane_b32 s10, v253, 11
	v_readlane_b32 s11, v253, 12
	s_andn2_b64 vcc, exec, s[10:11]
	s_nop 0
	v_cndmask_b32_e64 v1, 0, 1, s[10:11]
	v_cmp_ne_u32_e64 s[38:39], 1, v1
	s_cbranch_vccnz .LBB0_786
	s_barrier
.LBB0_786:
	s_add_u32 s4, s4, 0x29400000
	s_addc_u32 s5, s5, 0
	s_add_u32 s6, s6, 0x31400000
	s_addc_u32 s7, s7, 0
	s_lshl_b64 s[10:11], s[54:55], 3
	s_add_u32 s8, s8, s10
	s_addc_u32 s9, s9, s11
	s_add_u32 s8, s8, 0x500000
	s_addc_u32 s9, s9, 0
	v_and_b32_e32 v2, 15, v0
	v_readlane_b32 s10, v253, 6
	s_waitcnt vmcnt(2)
	s_barrier
	v_lshrrev_b32_e32 v1, 4, v0
	v_or_b32_e32 v159, s10, v2
	s_add_u32 s10, s12, 0x80
	s_addc_u32 s11, s13, 0
	s_mov_b32 m0, s35
	s_nop 0
	global_load_lds_dwordx4 v156, s[10:11]
	v_bfe_u32 v3, v0, 4, 2
	s_mov_b32 m0, s33
	s_nop 0
	global_load_lds_dwordx4 v158, s[10:11]
	s_add_u32 s10, s30, 0x80
	s_addc_u32 s11, s31, 0
	s_mov_b32 m0, s22
	s_nop 0
	global_load_lds_dwordx4 v129, s[10:11]
	v_bfe_u32 v0, v0, 1, 3
	s_mov_b32 m0, s2
	s_nop 0
	global_load_lds_dwordx4 v157, s[10:11]
	s_add_u32 s10, s12, 0x20080
	s_addc_u32 s11, s13, 0
	s_mov_b32 m0, s77
	s_nop 0
	global_load_lds_dwordx4 v156, s[10:11]
	v_bitop3_b32 v0, v1, v0, 3 bitop3:0x6c
	s_mov_b32 m0, s3
	s_nop 0
	global_load_lds_dwordx4 v158, s[10:11]
	v_readlane_b32 s17, v253, 7
	s_waitcnt vmcnt(6)
	v_lshlrev_b32_e32 v0, 4, v0
	v_readlane_b32 s10, v254, 19
	v_or_b32_e32 v1, s17, v2
	v_lshl_or_b32 v160, v159, 7, v0
	v_lshl_or_b32 v161, v1, 7, v0
	v_lshl_or_b32 v128, v3, 3, s17
	s_mov_b32 s47, 0
	v_readlane_b32 s48, v253, 62
	s_mov_b32 s49, s10
	s_barrier
	v_readlane_b32 s11, v254, 20
	s_branch .LBB0_789

; #define PG8_STAGE(bufoff, gbase, voff) do { _Pragma("unroll") for (int _i = 0; _i < 2; ++_i) \
;         dma16((const char*)(gbase), (voff)[_i], ldsb + (bufoff) + ldsw + _i * 8192); } while (0)
; #define PG8_LDA(dst, b, h) do { const int a1_ = opqv(aoff0) ^ 64; _Pragma("unroll") for (int m = 0; m < 4; ++m) { dst[m][0] = *(const LAS bf16x8*)(lds + PG8_SA(b, h) + aoff0 + m * 2048); dst[m][1] = *(const LAS bf16x8*)(lds + PG8_SA(b, h) + a1_ + m * 2048); } } while (0)
; #define PG8_LDB(dst, b, h) do { const int b1_ = opqv(boff0) ^ 64; _Pragma("unroll") for (int n = 0; n < 2; ++n) { dst[n][0] = *(const LAS bf16x8*)(lds + PG8_SB(b, h) + boff0 + n * 2048); dst[n][1] = *(const LAS bf16x8*)(lds + PG8_SB(b, h) + b1_ + n * 2048); } } while (0)
; #define PG8_MMA(ai, bj, At, Bt) do { __builtin_amdgcn_s_setprio(1); _Pragma("unroll") for (int m = 0; m < 4; ++m) _Pragma("unroll") for (int n = 0; n < 2; ++n) _Pragma("unroll") for (int k = 0; k < 2; ++k) \
;         acc[ai][bj][m][n] = __builtin_amdgcn_mfma_f32_16x16x32_bf16(Bt[n][k], At[m][k], acc[ai][bj][m][n], 0, 0, 0); __builtin_amdgcn_s_setprio(0); } while (0)
; #define PG8_WAIT_V(n) asm volatile("s_waitcnt vmcnt(" #n ")" ::: "memory")
; #define PG8_WAIT_L(n) asm volatile("s_waitcnt lgkmcnt(" #n ")" ::: "memory")
; #define PG8_BAR __builtin_amdgcn_s_barrier()
; #define PG8_SCHED __builtin_amdgcn_sched_barrier(0)
; template <class Epi>
; __device__ __forceinline__ void gemm_phase(LAS unsigned char* lds, const Gemm g, const StaticOrder& S, const Epi& E, int wave_) {
;     ...
;             PG8_STAGE(PG8_SA(1, 1), a1 + hstepA, voffA); PG8_LDB(B0, 0, 0); PG8_LDB(B1, 0, 1); PG8_SCHED; PG8_LDA(At, 0, 0);
;             PG8_WAIT_V(8); PG8_WAIT_L(0); PG8_BAR; PG8_MMA(0, 0, At, B0); PG8_MMA(0, 1, At, B1); PG8_BAR; PG8_SCHED;
;             PG8_STAGE(PG8_SB(0, 0), b2, voffB); PG8_STAGE(PG8_SB(0, 1), b2 + hstepB, voffB); PG8_STAGE(PG8_SA(0, 0), a2, voffA); PG8_LDA(At, 0, 1);
;             PG8_WAIT_V(8); PG8_WAIT_L(0); PG8_BAR; PG8_MMA(1, 0, At, B0); PG8_MMA(1, 1, At, B1); PG8_BAR; PG8_SCHED;
.LBB0_796:
	s_add_u32 s30, s12, 0xfffc0080
	s_addc_u32 s31, s13, -1
	s_cmp_eq_u32 s55, 4
	s_cselect_b32 s42, s17, s30
	s_cselect_b32 s43, s16, s31
	s_cselect_b32 s36, s19, s52
	s_cselect_b32 s37, s11, s54
	s_add_u32 s30, s42, 0x80
	v_mov_b32_e32 v130, v161
	s_addc_u32 s31, s43, 0
	v_add_u32_e32 v134, s23, v161
	v_xad_u32 v142, v130, 64, s23
	v_mov_b32_e32 v146, v161
	s_add_i32 s56, 0, 0x14000
	ds_read_b128 v[130:133], v134
	ds_read_b128 v[134:137], v134 offset:2048
	ds_read_b128 v[138:141], v142
	ds_read_b128 v[142:145], v142 offset:2048
	v_add_u32_e32 v150, s56, v161
	v_xad_u32 v154, v146, 64, s56
	ds_read_b128 v[146:149], v150
	ds_read_b128 v[150:153], v150 offset:2048
	ds_read_b128 v[162:165], v154
	ds_read_b128 v[166:169], v154 offset:2048
	v_mov_b32_e32 v154, v160
	v_add_u32_e32 v155, 0, v160
	v_xad_u32 v154, v154, 64, 0
	ds_read_b128 v[176:179], v155
	ds_read_b128 v[180:183], v155 offset:2048
	ds_read_b128 v[192:195], v154
	ds_read_b128 v[196:199], v154 offset:2048
	ds_read_b128 v[200:203], v155 offset:4096
	ds_read_b128 v[204:207], v155 offset:6144
	ds_read_b128 v[208:211], v154 offset:4096
	ds_read_b128 v[212:215], v154 offset:6144
	s_mov_b32 m0, s14
	s_nop 0
	global_load_lds_dwordx4 v129, s[12:13]
	s_mov_b32 m0, s15
	s_nop 0
	global_load_lds_dwordx4 v157, s[12:13]
	s_waitcnt vmcnt(8)
	s_waitcnt lgkmcnt(0)
	s_barrier
	s_setprio 1
	s_waitcnt lgkmcnt(0)
	v_mfma_f32_16x16x32_bf16 v[124:127], v[130:133], v[176:179], v[124:127]
	v_mfma_f32_16x16x32_bf16 v[120:123], v[134:137], v[176:179], v[120:123]
	v_mfma_f32_16x16x32_bf16 v[108:111], v[130:133], v[180:183], v[108:111]
	v_mfma_f32_16x16x32_bf16 v[104:107], v[134:137], v[180:183], v[104:107]
	v_mfma_f32_16x16x32_bf16 v[92:95], v[130:133], v[200:203], v[92:95]
	v_mfma_f32_16x16x32_bf16 v[88:91], v[134:137], v[200:203], v[88:91]
	v_mfma_f32_16x16x32_bf16 v[76:79], v[130:133], v[204:207], v[76:79]
	v_mfma_f32_16x16x32_bf16 v[72:75], v[134:137], v[204:207], v[72:75]
	v_mfma_f32_16x16x32_bf16 v[124:127], v[138:141], v[192:195], v[124:127]
	v_mfma_f32_16x16x32_bf16 v[120:123], v[142:145], v[192:195], v[120:123]
	v_mfma_f32_16x16x32_bf16 v[108:111], v[138:141], v[196:199], v[108:111]
	v_mfma_f32_16x16x32_bf16 v[104:107], v[142:145], v[196:199], v[104:107]
	v_mfma_f32_16x16x32_bf16 v[92:95], v[138:141], v[208:211], v[92:95]
	v_mfma_f32_16x16x32_bf16 v[88:91], v[142:145], v[208:211], v[88:91]
	v_mfma_f32_16x16x32_bf16 v[76:79], v[138:141], v[212:215], v[76:79]
	v_mfma_f32_16x16x32_bf16 v[72:75], v[142:145], v[212:215], v[72:75]
	s_setprio 0
	s_setprio 1
	v_mfma_f32_16x16x32_bf16 v[116:119], v[146:149], v[176:179], v[116:119]
	v_mfma_f32_16x16x32_bf16 v[112:115], v[150:153], v[176:179], v[112:115]
	v_mfma_f32_16x16x32_bf16 v[100:103], v[146:149], v[180:183], v[100:103]
	v_mfma_f32_16x16x32_bf16 v[96:99], v[150:153], v[180:183], v[96:99]
	v_mfma_f32_16x16x32_bf16 v[84:87], v[146:149], v[200:203], v[84:87]
	v_mfma_f32_16x16x32_bf16 v[80:83], v[150:153], v[200:203], v[80:83]
	v_mfma_f32_16x16x32_bf16 v[68:71], v[146:149], v[204:207], v[68:71]
	v_mfma_f32_16x16x32_bf16 v[64:67], v[150:153], v[204:207], v[64:67]
	v_mfma_f32_16x16x32_bf16 v[116:119], v[162:165], v[192:195], v[116:119]
	v_mfma_f32_16x16x32_bf16 v[112:115], v[166:169], v[192:195], v[112:115]
	v_mfma_f32_16x16x32_bf16 v[100:103], v[162:165], v[196:199], v[100:103]
	v_mfma_f32_16x16x32_bf16 v[96:99], v[166:169], v[196:199], v[96:99]
	v_mfma_f32_16x16x32_bf16 v[84:87], v[162:165], v[208:211], v[84:87]
	v_mfma_f32_16x16x32_bf16 v[80:83], v[166:169], v[208:211], v[80:83]
	v_mfma_f32_16x16x32_bf16 v[68:71], v[162:165], v[212:215], v[68:71]
	v_mfma_f32_16x16x32_bf16 v[64:67], v[166:169], v[212:215], v[64:67]
	s_setprio 0
	s_barrier
	v_mov_b32_e32 v154, v160
	s_add_u32 s56, s36, 0x20000
	s_addc_u32 s57, s37, 0
	s_nop 0
	s_nop 0
	s_nop 0
	v_xad_u32 v154, v154, 64, 0
	ds_read_b128 v[176:179], v155 offset:16384
	ds_read_b128 v[180:183], v155 offset:18432
	ds_read_b128 v[192:195], v154 offset:16384
	ds_read_b128 v[196:199], v154 offset:18432
	ds_read_b128 v[200:203], v155 offset:20480
	ds_read_b128 v[204:207], v155 offset:22528
	ds_read_b128 v[208:211], v154 offset:20480
	ds_read_b128 v[212:215], v154 offset:22528
	s_mov_b32 m0, s80
	s_nop 0
	global_load_lds_dwordx4 v156, s[36:37]
	s_mov_b32 m0, s81
	s_nop 0
	global_load_lds_dwordx4 v158, s[36:37]
	s_mov_b32 m0, s29
	s_nop 0
	global_load_lds_dwordx4 v156, s[56:57]
	s_mov_b32 m0, s88
	s_nop 0
	global_load_lds_dwordx4 v158, s[56:57]
	s_mov_b32 m0, s76
	s_nop 0
	global_load_lds_dwordx4 v129, s[42:43]
	s_mov_b32 m0, s89
	s_nop 0
	global_load_lds_dwordx4 v157, s[42:43]
	s_waitcnt vmcnt(8)
	s_waitcnt lgkmcnt(0)
	s_barrier
; #define PG8_STAGE(bufoff, gbase, voff) do { _Pragma("unroll") for (int _i = 0; _i < 2; ++_i) \
;         dma16((const char*)(gbase), (voff)[_i], ldsb + (bufoff) + ldsw + _i * 8192); } while (0)
; #define PG8_LDA(dst, b, h) do { const int a1_ = opqv(aoff0) ^ 64; _Pragma("unroll") for (int m = 0; m < 4; ++m) { dst[m][0] = *(const LAS bf16x8*)(lds + PG8_SA(b, h) + aoff0 + m * 2048); dst[m][1] = *(const LAS bf16x8*)(lds + PG8_SA(b, h) + a1_ + m * 2048); } } while (0)
; #define PG8_LDB(dst, b, h) do { const int b1_ = opqv(boff0) ^ 64; _Pragma("unroll") for (int n = 0; n < 2; ++n) { dst[n][0] = *(const LAS bf16x8*)(lds + PG8_SB(b, h) + boff0 + n * 2048); dst[n][1] = *(const LAS bf16x8*)(lds + PG8_SB(b, h) + b1_ + n * 2048); } } while (0)
; #define PG8_MMA(ai, bj, At, Bt) do { __builtin_amdgcn_s_setprio(1); _Pragma("unroll") for (int m = 0; m < 4; ++m) _Pragma("unroll") for (int n = 0; n < 2; ++n) _Pragma("unroll") for (int k = 0; k < 2; ++k) \
;         acc[ai][bj][m][n] = __builtin_amdgcn_mfma_f32_16x16x32_bf16(Bt[n][k], At[m][k], acc[ai][bj][m][n], 0, 0, 0); __builtin_amdgcn_s_setprio(0); } while (0)
; #define PG8_WAIT_V(n) asm volatile("s_waitcnt vmcnt(" #n ")" ::: "memory")
; #define PG8_WAIT_L(n) asm volatile("s_waitcnt lgkmcnt(" #n ")" ::: "memory")
; #define PG8_BAR __builtin_amdgcn_s_barrier()
; #define PG8_SCHED __builtin_amdgcn_sched_barrier(0)
; template <class Epi>
; __device__ __forceinline__ void gemm_phase(LAS unsigned char* lds, const Gemm g, const StaticOrder& S, const Epi& E, int wave_) {
;     ...
;             PG8_WAIT_V(8); PG8_WAIT_L(0); PG8_BAR; PG8_MMA(1, 0, At, B0); PG8_MMA(1, 1, At, B1); PG8_BAR; PG8_SCHED;
;             PG8_STAGE(PG8_SA(0, 1), a2 + hstepA, voffA); PG8_LDB(B0, 1, 0); PG8_LDB(B1, 1, 1); PG8_SCHED; PG8_LDA(At, 1, 0);
;             PG8_WAIT_V(8); PG8_WAIT_L(0); PG8_BAR; PG8_MMA(0, 0, At, B0); PG8_MMA(0, 1, At, B1); PG8_BAR; PG8_SCHED;
;             PG8_STAGE(PG8_SB(1, 0), b3, voffB); PG8_STAGE(PG8_SB(1, 1), b3 + hstepB, voffB); PG8_STAGE(PG8_SA(1, 0), a3, voffA); PG8_LDA(At, 1, 1);
	s_setprio 1
	s_waitcnt lgkmcnt(0)
	v_mfma_f32_16x16x32_bf16 v[60:63], v[130:133], v[176:179], v[60:63]
	v_mfma_f32_16x16x32_bf16 v[56:59], v[134:137], v[176:179], v[56:59]
	v_mfma_f32_16x16x32_bf16 v[44:47], v[130:133], v[180:183], v[44:47]
	v_mfma_f32_16x16x32_bf16 v[40:43], v[134:137], v[180:183], v[40:43]
	v_mfma_f32_16x16x32_bf16 v[28:31], v[130:133], v[200:203], v[28:31]
	v_mfma_f32_16x16x32_bf16 v[24:27], v[134:137], v[200:203], v[24:27]
	v_mfma_f32_16x16x32_bf16 v[12:15], v[130:133], v[204:207], v[12:15]
	v_mfma_f32_16x16x32_bf16 v[8:11], v[134:137], v[204:207], v[8:11]
	v_mfma_f32_16x16x32_bf16 v[60:63], v[138:141], v[192:195], v[60:63]
	v_mfma_f32_16x16x32_bf16 v[56:59], v[142:145], v[192:195], v[56:59]
	v_mfma_f32_16x16x32_bf16 v[44:47], v[138:141], v[196:199], v[44:47]
	v_mfma_f32_16x16x32_bf16 v[40:43], v[142:145], v[196:199], v[40:43]
	v_mfma_f32_16x16x32_bf16 v[28:31], v[138:141], v[208:211], v[28:31]
	v_mfma_f32_16x16x32_bf16 v[24:27], v[142:145], v[208:211], v[24:27]
	v_mfma_f32_16x16x32_bf16 v[12:15], v[138:141], v[212:215], v[12:15]
	v_mfma_f32_16x16x32_bf16 v[8:11], v[142:145], v[212:215], v[8:11]
	s_setprio 0
	s_setprio 1
	v_mfma_f32_16x16x32_bf16 v[52:55], v[146:149], v[176:179], v[52:55]
	v_mfma_f32_16x16x32_bf16 v[48:51], v[150:153], v[176:179], v[48:51]
	v_mfma_f32_16x16x32_bf16 v[36:39], v[146:149], v[180:183], v[36:39]
	v_mfma_f32_16x16x32_bf16 v[32:35], v[150:153], v[180:183], v[32:35]
	v_mfma_f32_16x16x32_bf16 v[20:23], v[146:149], v[200:203], v[20:23]
	v_mfma_f32_16x16x32_bf16 v[16:19], v[150:153], v[200:203], v[16:19]
	v_mfma_f32_16x16x32_bf16 v[4:7], v[146:149], v[204:207], v[4:7]
	v_mfma_f32_16x16x32_bf16 v[0:3], v[150:153], v[204:207], v[0:3]
	v_mfma_f32_16x16x32_bf16 v[52:55], v[162:165], v[192:195], v[52:55]
	v_mfma_f32_16x16x32_bf16 v[48:51], v[166:169], v[192:195], v[48:51]
	v_mfma_f32_16x16x32_bf16 v[36:39], v[162:165], v[196:199], v[36:39]
	v_mfma_f32_16x16x32_bf16 v[32:35], v[166:169], v[196:199], v[32:35]
	v_mfma_f32_16x16x32_bf16 v[20:23], v[162:165], v[208:211], v[20:23]
	v_mfma_f32_16x16x32_bf16 v[16:19], v[166:169], v[208:211], v[16:19]
	v_mfma_f32_16x16x32_bf16 v[4:7], v[162:165], v[212:215], v[4:7]
	v_mfma_f32_16x16x32_bf16 v[0:3], v[166:169], v[212:215], v[0:3]
	s_setprio 0
	s_barrier
	s_add_u32 s42, s42, 0x40000
	s_addc_u32 s43, s43, 0
	s_mov_b32 m0, s1
	s_nop 0
	global_load_lds_dwordx4 v129, s[42:43]
	v_mov_b32_e32 v130, v161
	s_mov_b32 m0, s69
	s_nop 0
	global_load_lds_dwordx4 v157, s[42:43]
	v_add_u32_e32 v134, s34, v161
	v_xad_u32 v142, v130, 64, s34
	v_mov_b32_e32 v146, v161
	s_add_i32 s42, 0, 0x1c000
	ds_read_b128 v[130:133], v134
	ds_read_b128 v[134:137], v134 offset:2048
	ds_read_b128 v[138:141], v142
	ds_read_b128 v[142:145], v142 offset:2048
	v_add_u32_e32 v150, s42, v161
	v_xad_u32 v154, v146, 64, s42
	ds_read_b128 v[146:149], v150
	ds_read_b128 v[150:153], v150 offset:2048
	ds_read_b128 v[162:165], v154
	ds_read_b128 v[166:169], v154 offset:2048
	v_mov_b32_e32 v154, v160
	s_nop 0
	v_xad_u32 v154, v154, 64, 0
	ds_read_b128 v[176:179], v155 offset:32768
	ds_read_b128 v[180:183], v155 offset:34816
	ds_read_b128 v[192:195], v154 offset:32768
	ds_read_b128 v[196:199], v154 offset:34816
	ds_read_b128 v[200:203], v155 offset:36864
	ds_read_b128 v[204:207], v155 offset:38912
	ds_read_b128 v[208:211], v154 offset:36864
	ds_read_b128 v[212:215], v154 offset:38912
	s_waitcnt vmcnt(8)
	s_waitcnt lgkmcnt(0)
	s_barrier
	s_setprio 1
	s_waitcnt lgkmcnt(0)
	v_mfma_f32_16x16x32_bf16 v[124:127], v[130:133], v[176:179], v[124:127]
	v_mfma_f32_16x16x32_bf16 v[120:123], v[134:137], v[176:179], v[120:123]
	v_mfma_f32_16x16x32_bf16 v[108:111], v[130:133], v[180:183], v[108:111]
	v_mfma_f32_16x16x32_bf16 v[104:107], v[134:137], v[180:183], v[104:107]
	v_mfma_f32_16x16x32_bf16 v[92:95], v[130:133], v[200:203], v[92:95]
	v_mfma_f32_16x16x32_bf16 v[88:91], v[134:137], v[200:203], v[88:91]
	v_mfma_f32_16x16x32_bf16 v[76:79], v[130:133], v[204:207], v[76:79]
	v_mfma_f32_16x16x32_bf16 v[72:75], v[134:137], v[204:207], v[72:75]
	v_mfma_f32_16x16x32_bf16 v[124:127], v[138:141], v[192:195], v[124:127]
	v_mfma_f32_16x16x32_bf16 v[120:123], v[142:145], v[192:195], v[120:123]
	v_mfma_f32_16x16x32_bf16 v[108:111], v[138:141], v[196:199], v[108:111]
	v_mfma_f32_16x16x32_bf16 v[104:107], v[142:145], v[196:199], v[104:107]
	v_mfma_f32_16x16x32_bf16 v[92:95], v[138:141], v[208:211], v[92:95]
	v_mfma_f32_16x16x32_bf16 v[88:91], v[142:145], v[208:211], v[88:91]
	v_mfma_f32_16x16x32_bf16 v[76:79], v[138:141], v[212:215], v[76:79]
	v_mfma_f32_16x16x32_bf16 v[72:75], v[142:145], v[212:215], v[72:75]
	s_setprio 0
	s_setprio 1
	v_mfma_f32_16x16x32_bf16 v[116:119], v[146:149], v[176:179], v[116:119]
	s_add_u32 s42, s36, 0x80
	s_addc_u32 s43, s37, 0
	v_mfma_f32_16x16x32_bf16 v[112:115], v[150:153], v[176:179], v[112:115]
	v_mfma_f32_16x16x32_bf16 v[100:103], v[146:149], v[180:183], v[100:103]
	v_mfma_f32_16x16x32_bf16 v[96:99], v[150:153], v[180:183], v[96:99]
	v_mfma_f32_16x16x32_bf16 v[84:87], v[146:149], v[200:203], v[84:87]
	v_mfma_f32_16x16x32_bf16 v[80:83], v[150:153], v[200:203], v[80:83]
	v_mfma_f32_16x16x32_bf16 v[68:71], v[146:149], v[204:207], v[68:71]
	v_mfma_f32_16x16x32_bf16 v[64:67], v[150:153], v[204:207], v[64:67]
	v_mfma_f32_16x16x32_bf16 v[116:119], v[162:165], v[192:195], v[116:119]
	v_mfma_f32_16x16x32_bf16 v[112:115], v[166:169], v[192:195], v[112:115]
	v_mfma_f32_16x16x32_bf16 v[100:103], v[162:165], v[196:199], v[100:103]
	v_mfma_f32_16x16x32_bf16 v[96:99], v[166:169], v[196:199], v[96:99]
	v_mfma_f32_16x16x32_bf16 v[84:87], v[162:165], v[208:211], v[84:87]
	v_mfma_f32_16x16x32_bf16 v[80:83], v[166:169], v[208:211], v[80:83]
	v_mfma_f32_16x16x32_bf16 v[68:71], v[162:165], v[212:215], v[68:71]
	v_mfma_f32_16x16x32_bf16 v[64:67], v[166:169], v[212:215], v[64:67]
	s_setprio 0
	s_barrier
; #define PG8_STAGE(bufoff, gbase, voff) do { _Pragma("unroll") for (int _i = 0; _i < 2; ++_i) \
;         dma16((const char*)(gbase), (voff)[_i], ldsb + (bufoff) + ldsw + _i * 8192); } while (0)
; #define PG8_LDA(dst, b, h) do { const int a1_ = opqv(aoff0) ^ 64; _Pragma("unroll") for (int m = 0; m < 4; ++m) { dst[m][0] = *(const LAS bf16x8*)(lds + PG8_SA(b, h) + aoff0 + m * 2048); dst[m][1] = *(const LAS bf16x8*)(lds + PG8_SA(b, h) + a1_ + m * 2048); } } while (0)
; #define PG8_MMA(ai, bj, At, Bt) do { __builtin_amdgcn_s_setprio(1); _Pragma("unroll") for (int m = 0; m < 4; ++m) _Pragma("unroll") for (int n = 0; n < 2; ++n) _Pragma("unroll") for (int k = 0; k < 2; ++k) \
;         acc[ai][bj][m][n] = __builtin_amdgcn_mfma_f32_16x16x32_bf16(Bt[n][k], At[m][k], acc[ai][bj][m][n], 0, 0, 0); __builtin_amdgcn_s_setprio(0); } while (0)
; #define PG8_WAIT_V(n) asm volatile("s_waitcnt vmcnt(" #n ")" ::: "memory")
; #define PG8_WAIT_L(n) asm volatile("s_waitcnt lgkmcnt(" #n ")" ::: "memory")
; #define PG8_BAR __builtin_amdgcn_s_barrier()
; #define PG8_SCHED __builtin_amdgcn_sched_barrier(0)
; template <class Epi>
; __device__ __forceinline__ void gemm_phase(LAS unsigned char* lds, const Gemm g, const StaticOrder& S, const Epi& E, int wave_) {
;     ...
;             PG8_STAGE(PG8_SB(1, 0), b3, voffB); PG8_STAGE(PG8_SB(1, 1), b3 + hstepB, voffB); PG8_STAGE(PG8_SA(1, 0), a3, voffA); PG8_LDA(At, 1, 1);
;             PG8_WAIT_V(8); PG8_WAIT_L(0); PG8_BAR; PG8_MMA(1, 0, At, B0); PG8_MMA(1, 1, At, B1); PG8_BAR; PG8_SCHED;
;         }
;         if (wr == 0) PG8_BAR;
	s_add_u32 s36, s36, 0x20080
	s_addc_u32 s37, s37, 0
	v_mov_b32_e32 v154, v160
	s_nop 0
	s_nop 0
	v_xad_u32 v154, v154, 64, 0
	ds_read_b128 v[176:179], v155 offset:49152
	ds_read_b128 v[180:183], v155 offset:51200
	ds_read_b128 v[192:195], v154 offset:49152
	ds_read_b128 v[196:199], v154 offset:51200
	ds_read_b128 v[200:203], v155 offset:53248
	ds_read_b128 v[204:207], v155 offset:55296
	ds_read_b128 v[208:211], v154 offset:53248
	ds_read_b128 v[212:215], v154 offset:55296
	s_mov_b32 m0, s35
	s_nop 0
	global_load_lds_dwordx4 v156, s[42:43]
	s_mov_b32 m0, s33
	s_nop 0
	global_load_lds_dwordx4 v158, s[42:43]
	s_mov_b32 m0, s77
	s_nop 0
	global_load_lds_dwordx4 v156, s[36:37]
	s_mov_b32 m0, s3
	s_nop 0
	global_load_lds_dwordx4 v158, s[36:37]
	s_mov_b32 m0, s22
	s_nop 0
	global_load_lds_dwordx4 v129, s[30:31]
	s_mov_b32 m0, s2
	s_nop 0
	global_load_lds_dwordx4 v157, s[30:31]
	s_waitcnt vmcnt(8)
	s_waitcnt lgkmcnt(0)
	s_barrier
	s_setprio 1
	s_waitcnt lgkmcnt(0)
	v_mfma_f32_16x16x32_bf16 v[60:63], v[130:133], v[176:179], v[60:63]
	v_mfma_f32_16x16x32_bf16 v[56:59], v[134:137], v[176:179], v[56:59]
	v_mfma_f32_16x16x32_bf16 v[44:47], v[130:133], v[180:183], v[44:47]
	v_mfma_f32_16x16x32_bf16 v[40:43], v[134:137], v[180:183], v[40:43]
	v_mfma_f32_16x16x32_bf16 v[28:31], v[130:133], v[200:203], v[28:31]
	v_mfma_f32_16x16x32_bf16 v[24:27], v[134:137], v[200:203], v[24:27]
	v_mfma_f32_16x16x32_bf16 v[12:15], v[130:133], v[204:207], v[12:15]
	v_mfma_f32_16x16x32_bf16 v[8:11], v[134:137], v[204:207], v[8:11]
	v_mfma_f32_16x16x32_bf16 v[60:63], v[138:141], v[192:195], v[60:63]
	v_mfma_f32_16x16x32_bf16 v[56:59], v[142:145], v[192:195], v[56:59]
	v_mfma_f32_16x16x32_bf16 v[44:47], v[138:141], v[196:199], v[44:47]
	v_mfma_f32_16x16x32_bf16 v[40:43], v[142:145], v[196:199], v[40:43]
	v_mfma_f32_16x16x32_bf16 v[28:31], v[138:141], v[208:211], v[28:31]
	v_mfma_f32_16x16x32_bf16 v[24:27], v[142:145], v[208:211], v[24:27]
	v_mfma_f32_16x16x32_bf16 v[12:15], v[138:141], v[212:215], v[12:15]
	v_mfma_f32_16x16x32_bf16 v[8:11], v[142:145], v[212:215], v[8:11]
	s_setprio 0
	s_setprio 1
	v_mfma_f32_16x16x32_bf16 v[52:55], v[146:149], v[176:179], v[52:55]
	v_mfma_f32_16x16x32_bf16 v[48:51], v[150:153], v[176:179], v[48:51]
	v_mfma_f32_16x16x32_bf16 v[36:39], v[146:149], v[180:183], v[36:39]
	v_mfma_f32_16x16x32_bf16 v[32:35], v[150:153], v[180:183], v[32:35]
	v_mfma_f32_16x16x32_bf16 v[20:23], v[146:149], v[200:203], v[20:23]
	v_mfma_f32_16x16x32_bf16 v[16:19], v[150:153], v[200:203], v[16:19]
	v_mfma_f32_16x16x32_bf16 v[4:7], v[146:149], v[204:207], v[4:7]
	v_mfma_f32_16x16x32_bf16 v[0:3], v[150:153], v[204:207], v[0:3]
	v_mfma_f32_16x16x32_bf16 v[52:55], v[162:165], v[192:195], v[52:55]
	v_mfma_f32_16x16x32_bf16 v[48:51], v[166:169], v[192:195], v[48:51]
	v_mfma_f32_16x16x32_bf16 v[36:39], v[162:165], v[196:199], v[36:39]
	v_mfma_f32_16x16x32_bf16 v[32:35], v[166:169], v[196:199], v[32:35]
	v_mfma_f32_16x16x32_bf16 v[20:23], v[162:165], v[208:211], v[20:23]
	v_mfma_f32_16x16x32_bf16 v[16:19], v[166:169], v[208:211], v[16:19]
	v_mfma_f32_16x16x32_bf16 v[4:7], v[162:165], v[212:215], v[4:7]
	v_mfma_f32_16x16x32_bf16 v[0:3], v[166:169], v[212:215], v[0:3]
	s_setprio 0
	s_barrier
	s_add_i32 s55, s55, 2
	s_add_u32 s52, s52, 0x100
	s_addc_u32 s54, s54, 0
	s_add_u32 s12, s12, 0x100
	s_addc_u32 s13, s13, 0
	s_cmp_gt_u32 s55, 5
	s_cbranch_scc0 .LBB0_796
	v_readlane_b32 s12, v253, 13
	v_readlane_b32 s13, v253, 14
	s_and_b64 vcc, exec, s[12:13]
	s_cbranch_vccz .LBB0_799
	s_barrier

; #define LAS __attribute__((address_space(3)))
; __device__ __forceinline__ int tid_of(int wave) { return opqv(wave * 64 + (int)__builtin_amdgcn_mbcnt_hi(~0u, __builtin_amdgcn_mbcnt_lo(~0u, 0u))); }
; __device__ __forceinline__ int v_rd_base(int lane) { return ((lane & 3) << 3) | (((lane >> 2) & 3) << 6) | (((lane >> 4) & 1) << 5) | (((lane >> 5) & 1) << 8); }
; #define BARL() asm volatile("s_waitcnt lgkmcnt(0)\n\ts_barrier" ::: "memory")
; template <int MODE> ...
;   const int tid = tid_of(wave_), wid = wave_, lane = tid & 63, r32 = lane & 31, hi = lane >> 5;
;   LAS unsigned char* V_lds = lds + V_OFF; LAS unsigned char* K_lds = lds + K_OFF; LAS unsigned char* KR_lds = lds + KR_OFF;
;   LAS float* al_l = (LAS float*)(lds + WS_OFF) + wid * 64 + 32;
;   const LAS float* tbl = (const LAS float*)(lds + TBL_OFF);
;   LAS unsigned char* qrf = lds + QR_OFF + wid * 4096;
;   float m_reg = -1e30f, l_reg = 0;
; #pragma unroll
;   for (int d = 0; d < 4; ++d) o[d] = f32x16{};
;   bf16x8 qr[8];
;   const bf16_t* Qw = Qb + (size_t)(wid * 32 + r32) * LDX + hi * 8;
; #pragma unroll
;   for (int d0 = 0; d0 < 8; ++d0) qr[d0] = *(const bf16x8*)(Qw + d0 * 16);
;   if constexpr (MODE == 0) {
;     const bf16_t* Qrw = Qrb + (size_t)(wid * 32 + r32) * 1024 + hi * 8;
; #pragma unroll
;     for (int d0 = 0; d0 < 4; ++d0) *(LAS bf16x8*)(qrf + (d0 * 64 + lane) * 16) = *(const bf16x8*)(Qrw + d0 * 16);
;   }
;   const unsigned ldsb = (unsigned)(uintptr_t)lds;
;   const unsigned vb0 = ldsb + V_OFF + v_rd_base(lane);
;   const int krow = 4 * wid + (lane >> 4);
;   const unsigned voffK = (unsigned)(krow * (LDX * 2) + (((lane & 15) ^ (krow & 15)) << 4));
;   const int vst_ = 2 * wid + (lane >> 5), vkk = (vst_ >> 2) * 8 + ((lane >> 2) & 7), vk = (vkk & ~0xC) | ((vkk & 4) << 1) | ((vkk & 8) >> 1);
;   const unsigned voffV = (unsigned)(vk * (LDX * 2) + ((vst_ & 3) * 4 + (lane & 3)) * 16);
;   const int rrow = 8 * wid + (lane >> 3);
;   const unsigned voffR = (unsigned)(rrow * 128 + (((lane & 7) ^ ((rrow >> 1) & 7)) << 4));
;   const int qw0 = qpos0 + wid * 32, qme = qw0 + r32;
;   const float cL = (MODE == 1) ? tbl[0] : 0.f, cR = (MODE == 1) ? tbl[256] : 0.f;
;   constexpr int NT = SEQ / KVBLK;
;     ...
;   f32x16 pA0, pA1, pB0, pB1; float mnA, mnB, alA, alB, cadd; bf16x8 pa0, pa1, pa2, pa3;
;   DMA_K(0, 0); DMA_V(0, 0); DMA_K(1, 1);
;   asm volatile("s_waitcnt vmcnt(0)" ::: "memory"); BARL();
.LBB0_938:
	s_ashr_i32 s8, s16, 8
	s_ashr_i32 s9, s8, 31
	s_lshl_b32 s6, s16, 8
	s_lshl_b64 s[4:5], s[8:9], 12
	s_and_b32 s6, s6, 0xf00
	s_bfe_u32 s12, s16, 0x40004
	s_or_b32 s4, s4, s6
	s_mov_b64 s[6:7], s[40:41]
	s_lshl_b32 s18, s12, 8
	s_lshl_b64 s[10:11], s[4:5], 12
	s_add_u32 s6, s6, s10
	s_addc_u32 s7, s7, s11
	s_lshl_b32 s17, s12, 7
	s_add_u32 s36, s6, s18
	s_addc_u32 s37, s7, 0
	s_mov_b64 s[6:7], s[40:41]
	s_lshl_b64 s[10:11], s[8:9], 24
	s_add_u32 s19, s6, s10
	s_addc_u32 s21, s7, s11
	s_add_u32 s30, s19, s18
	s_addc_u32 s31, s21, 0
	s_add_u32 s6, s30, 0x29400000
	s_addc_u32 s7, s31, 0
	s_mov_b64 s[12:13], s[40:41]
	s_add_u32 s24, s12, s10
	s_addc_u32 s25, s13, s11
	s_add_u32 s26, s24, s18
	s_addc_u32 s27, s25, 0
	s_add_u32 s10, s26, 0x31400000
	s_mov_b64 s[12:13], s[40:41]
	s_addc_u32 s11, s27, 0
	s_lshl_b64 s[38:39], s[4:5], 11
	s_add_u32 s12, s12, s38
	s_addc_u32 s13, s13, s39
	s_add_u32 s38, s12, s17
	s_addc_u32 s39, s13, 0
	s_mov_b64 s[12:13], s[40:41]
	v_mov_b32_e32 v49, v220
	v_mov_b32_e32 v141, v185
	v_and_b32_e32 v48, 31, v49
	v_or_b32_e32 v184, s42, v48
	v_bfe_u32 v54, v49, 5, 1
	v_lshlrev_b64 v[0:1], 11, v[184:185]
	v_lshlrev_b32_e32 v140, 4, v54
	v_lshl_add_u64 v[0:1], s[38:39], 0, v[0:1]
	v_lshl_add_u64 v[0:1], v[0:1], 0, v[140:141]
	s_mov_b64 s[38:39], 0x25400000
	v_lshl_add_u64 v[12:13], v[0:1], 0, s[38:39]
	s_mov_b32 s38, 0x25400000
	v_add_co_u32_e32 v0, vcc, s38, v0
	v_lshlrev_b64 v[16:17], 12, v[184:185]
	s_nop 0
	v_addc_co_u32_e32 v1, vcc, 0, v1, vcc
	flat_load_dwordx4 v[0:3], v[0:1]
	s_nop 0
	flat_load_dwordx4 v[4:7], v[12:13] offset:32
	flat_load_dwordx4 v[8:11], v[12:13] offset:64
	s_nop 0
	flat_load_dwordx4 v[12:15], v[12:13] offset:96
	v_lshl_add_u64 v[16:17], s[36:37], 0, v[16:17]
	v_lshl_add_u64 v[16:17], v[16:17], 0, v[140:141]
	s_mov_b32 s36, 0x1d400000
	v_add_co_u32_e32 v18, vcc, s36, v16
	v_readlane_b32 s36, v253, 19
	s_nop 0
	v_addc_co_u32_e32 v19, vcc, 0, v17, vcc
	flat_load_dwordx4 v[100:103], v[18:19]
	v_bfe_u32 v18, v49, 4, 2
	v_or_b32_e32 v22, s36, v18
	v_bitop3_b32 v18, v18, v49, s36 bitop3:0x36
	v_readlane_b32 s36, v253, 22
	v_bfe_u32 v21, v49, 3, 3
	v_and_b32_e32 v58, 63, v49
	v_or_b32_e32 v24, s36, v54
	v_readlane_b32 s36, v253, 42
	v_lshrrev_b32_e32 v50, 1, v49
	v_lshlrev_b32_e32 v20, 4, v49
	v_or_b32_e32 v21, s36, v21
	s_mov_b64 s[36:37], 0x1d400000
	v_lshl_add_u64 v[16:17], v[16:17], 0, s[36:37]
	flat_load_dwordx4 v[116:119], v[16:17] offset:32
	flat_load_dwordx4 v[124:127], v[16:17] offset:64
	flat_load_dwordx4 v[120:123], v[16:17] offset:96
	flat_load_dwordx4 v[112:115], v[16:17] offset:128
	flat_load_dwordx4 v[108:111], v[16:17] offset:160
	flat_load_dwordx4 v[104:107], v[16:17] offset:192
	flat_load_dwordx4 v[96:99], v[16:17] offset:224
	v_lshlrev_b32_e32 v51, 4, v58
	v_readlane_b32 s36, v253, 41
	v_bfe_u32 v19, v49, 2, 2
	v_and_b32_e32 v23, 8, v50
	v_and_b32_e32 v25, 48, v20
	v_add_u32_e32 v153, s36, v51
	v_readlane_b32 s36, v253, 20
	s_lshl_b64 s[8:9], s[8:9], 19
	v_lshlrev_b32_e32 v22, 12, v22
	v_lshlrev_b32_e32 v18, 4, v18
	v_or3_b32 v19, v19, v23, s36
	v_lshl_or_b32 v23, v24, 6, v25
	v_lshlrev_b32_e32 v24, 7, v21
	v_lshrrev_b32_e32 v21, 1, v21
	s_movk_i32 s39, 0xf0
	s_add_u32 s12, s12, s8
	v_and_or_b32 v155, v18, s39, v22
	v_xor_b32_e32 v18, v21, v49
	s_addc_u32 s13, s13, s9
	s_add_u32 s8, s12, 0x1d000000
	s_movk_i32 s36, 0x70
	s_addc_u32 s9, s13, 0
	v_lshl_or_b32 v156, v19, 12, v23
	v_lshlrev_b32_e32 v59, 7, v48
	v_bfe_u32 v56, v49, 1, 3
	s_mov_b32 s52, s53
	s_mov_b32 s54, s53
	s_mov_b32 s55, s53
	s_waitcnt vmcnt(0) lgkmcnt(0)
	ds_write_b128 v153, v[0:3]
	ds_write_b128 v153, v[4:7] offset:1024
	ds_write_b128 v153, v[8:11] offset:2048
	ds_write_b128 v153, v[12:15] offset:3072
	v_lshlrev_b32_e32 v0, 4, v18
	v_and_or_b32 v157, v0, s36, v24
	s_mov_b32 m0, s22
	s_nop 0
	global_load_lds_dwordx4 v155, s[6:7]
	s_add_u32 s36, s30, 0x29420000
	s_addc_u32 s37, s31, 0
	s_mov_b32 m0, s2
	s_nop 0
	global_load_lds_dwordx4 v155, s[36:37]
	s_mov_b32 m0, s95
	s_nop 0
	global_load_lds_dwordx4 v157, s[8:9]
	v_lshl_add_u32 v8, v48, 8, 0
	s_mov_b32 m0, s76
	s_nop 0
	global_load_lds_dwordx4 v156, s[10:11]
	s_add_u32 s10, s26, 0x31420000
	s_addc_u32 s11, s27, 0
	s_mov_b32 m0, s89
	s_nop 0
	global_load_lds_dwordx4 v156, s[10:11]
	s_add_u32 s10, s30, 0x29440000
	s_addc_u32 s11, s31, 0
	s_mov_b32 m0, s14
	s_nop 0
	global_load_lds_dwordx4 v155, s[10:11]
	s_add_u32 s10, s30, 0x29460000
	s_addc_u32 s11, s31, 0
	s_mov_b32 m0, s15
	s_nop 0
	global_load_lds_dwordx4 v155, s[10:11]
	s_add_u32 s10, s12, 0x1d002000
	s_addc_u32 s11, s13, 0
	v_readlane_b32 s38, v253, 48
	s_mov_b32 m0, s38
	s_nop 0
	global_load_lds_dwordx4 v157, s[10:11]
	s_waitcnt vmcnt(0)
	v_bitop3_b32 v0, v140, v20, s39 bitop3:0x78
	s_waitcnt lgkmcnt(0)
	s_barrier
; #define LAS __attribute__((address_space(3)))
; #define BARL() asm volatile("s_waitcnt lgkmcnt(0)\n\ts_barrier" ::: "memory")
; #define BIAS(P0, P1, k0, CADD) do { CADD = 0.f; if constexpr (MODE == 1) { const int dd = (k0) - qw0; \
;     if (dd <= -191) CADD = cL; else if (dd >= 159) CADD = cR; else add_bias(P0, P1, tbl, (k0) - qme, hi); } } while (0)
; #define BARL() asm volatile("s_waitcnt lgkmcnt(0)\n\ts_barrier" ::: "memory")
; template <int MODE>
; __device__ __forceinline__ void qkt(f32x16& p0, f32x16& p1, const LAS unsigned char* Ks, const LAS unsigned char* Krs, const LAS unsigned char* qrf, const bf16x8* qr, int r32, int hi, int lane) {
;   p0 = f32x16{}; p1 = f32x16{};
; #pragma unroll
;   for (int d0 = 0; d0 < 8; ++d0) { const int cb = (d0 * 16 + hi * 8) * 2;
;     const bf16x8 b0 = *(const LAS bf16x8*)(Ks + KSWZ(r32, cb));
;     const bf16x8 b1 = *(const LAS bf16x8*)(Ks + KSWZ(32 + r32, cb));
;     p0 = __builtin_amdgcn_mfma_f32_32x32x16_bf16(b0, qr[d0], p0, 0, 0, 0);
;     p1 = __builtin_amdgcn_mfma_f32_32x32x16_bf16(b1, qr[d0], p1, 0, 0, 0); }
;   if constexpr (MODE == 0) {
; #pragma unroll
;     for (int d0 = 0; d0 < 4; ++d0) { const int ch = d0 * 2 + hi;
;       const bf16x8 b0 = *(const LAS bf16x8*)(Krs + KRSWZ(r32, ch));
;       const bf16x8 b1 = *(const LAS bf16x8*)(Krs + KRSWZ(32 + r32, ch));
;       const bf16x8 q = *(const LAS bf16x8*)(qrf + (d0 * 64 + lane) * 16);
;       p0 = __builtin_amdgcn_mfma_f32_32x32x16_bf16(b0, q, p0, 0, 0, 0);
;       p1 = __builtin_amdgcn_mfma_f32_32x32x16_bf16(b1, q, p1, 0, 0, 0); }
;   }
; }
; template <int MODE> ...
;     ...
;   qkt<MODE>(pA0, pA1, K_lds, KR_lds, qrf, qr, r32, hi, lane); BIAS(pA0, pA1, 0, cadd); partialSM(pA0, pA1, m_reg, mnA, alA, cadd);
;   BARL();
	v_add_u32_e32 v158, v8, v0
	ds_read_b128 v[0:3], v158 offset:32768
	ds_read_b128 v[4:7], v158 offset:40960
	s_waitcnt lgkmcnt(1)
	v_mfma_f32_32x32x16_bf16 v[32:47], v[0:3], v[100:103], 0
	v_and_b32_e32 v9, 0xf0, v20
	v_bitop3_b32 v0, v140, v9, 32 bitop3:0x36
	v_add_u32_e32 v160, v8, v0
	s_movk_i32 s10, 0x60
	s_mov_b32 s56, s53
	s_mov_b32 s57, s53
	s_mov_b32 s58, s53
	s_waitcnt lgkmcnt(0)
	v_mfma_f32_32x32x16_bf16 v[16:31], v[4:7], v[100:103], 0
	ds_read_b128 v[0:3], v160 offset:32768
	ds_read_b128 v[4:7], v160 offset:40960
	s_mov_b32 s59, s53
	s_mov_b32 s60, s53
	s_mov_b32 s61, s53
	s_mov_b32 s62, s53
	s_mov_b32 s63, s53
	s_mov_b32 s64, s53
	s_waitcnt lgkmcnt(1)
	v_mfma_f32_32x32x16_bf16 v[32:47], v[0:3], v[116:119], v[32:47]
	v_bitop3_b32 v0, v140, v9, 64 bitop3:0x36
	v_add_u32_e32 v161, v8, v0
	s_mov_b32 s65, s53
	s_mov_b32 s66, s53
	s_mov_b32 s67, s53
	v_cmp_gt_u32_e64 s[38:39], 32, v58
	v_mov_b32_e32 v141, 0
	s_waitcnt lgkmcnt(0)
	v_mfma_f32_32x32x16_bf16 v[16:31], v[4:7], v[116:119], v[16:31]
	ds_read_b128 v[0:3], v161 offset:32768
	ds_read_b128 v[4:7], v161 offset:40960
	s_waitcnt lgkmcnt(1)
	v_mfma_f32_32x32x16_bf16 v[32:47], v[0:3], v[124:127], v[32:47]
	v_bitop3_b32 v0, v140, v9, s10 bitop3:0x36
	v_add_u32_e32 v164, v8, v0
	s_movk_i32 s10, 0x80
	s_waitcnt lgkmcnt(0)
	v_mfma_f32_32x32x16_bf16 v[16:31], v[4:7], v[124:127], v[16:31]
	ds_read_b128 v[0:3], v164 offset:32768
	ds_read_b128 v[4:7], v164 offset:40960
	s_waitcnt lgkmcnt(1)
	v_mfma_f32_32x32x16_bf16 v[32:47], v[0:3], v[120:123], v[32:47]
	v_bitop3_b32 v0, v140, v9, s10 bitop3:0x36
	v_add_u32_e32 v165, v8, v0
	s_movk_i32 s10, 0xa0
	s_waitcnt lgkmcnt(0)
	v_mfma_f32_32x32x16_bf16 v[16:31], v[4:7], v[120:123], v[16:31]
	ds_read_b128 v[0:3], v165 offset:32768
	ds_read_b128 v[4:7], v165 offset:40960
	s_waitcnt lgkmcnt(1)
	v_mfma_f32_32x32x16_bf16 v[32:47], v[0:3], v[112:115], v[32:47]
	v_bitop3_b32 v0, v140, v9, s10 bitop3:0x36
	v_add_u32_e32 v163, v8, v0
	s_movk_i32 s10, 0xc0
	s_waitcnt lgkmcnt(0)
	v_mfma_f32_32x32x16_bf16 v[16:31], v[4:7], v[112:115], v[16:31]
	ds_read_b128 v[0:3], v163 offset:32768
	ds_read_b128 v[4:7], v163 offset:40960
	s_waitcnt lgkmcnt(1)
	v_mfma_f32_32x32x16_bf16 v[32:47], v[0:3], v[108:111], v[32:47]
	v_bitop3_b32 v0, v140, v9, s10 bitop3:0x36
	v_add_u32_e32 v162, v8, v0
	s_movk_i32 s10, 0xe0
	s_waitcnt lgkmcnt(0)
	v_mfma_f32_32x32x16_bf16 v[16:31], v[4:7], v[108:111], v[16:31]
	ds_read_b128 v[0:3], v162 offset:32768
	ds_read_b128 v[4:7], v162 offset:40960
	s_waitcnt lgkmcnt(1)
	v_mfma_f32_32x32x16_bf16 v[32:47], v[0:3], v[104:107], v[32:47]
	v_bitop3_b32 v0, v140, v9, s10 bitop3:0x36
	v_add_u32_e32 v159, v8, v0
	s_add_i32 s10, 0, 0x10800
	v_add_u32_e32 v55, s10, v59
	s_waitcnt lgkmcnt(0)
	v_mfma_f32_32x32x16_bf16 v[16:31], v[4:7], v[104:107], v[16:31]
	ds_read_b128 v[0:3], v159 offset:32768
	ds_read_b128 v[4:7], v159 offset:40960
	s_waitcnt lgkmcnt(1)
	v_mfma_f32_32x32x16_bf16 v[32:47], v[0:3], v[96:99], v[32:47]
	v_bitop3_b32 v0, v54, v50, 7 bitop3:0x78
	v_lshlrev_b32_e32 v166, 4, v0
	v_add_u32_e32 v167, v55, v166
	s_waitcnt lgkmcnt(0)
	v_mfma_f32_32x32x16_bf16 v[16:31], v[4:7], v[96:99], v[16:31]
	ds_read_b128 v[0:3], v167
	ds_read_b128 v[4:7], v153
	ds_read_b128 v[8:11], v167 offset:4096
	ds_read_b128 v[12:15], v153 offset:1024
	s_waitcnt lgkmcnt(2)
	v_mfma_f32_32x32x16_bf16 v[32:47], v[0:3], v[4:7], v[32:47]
	v_bitop3_b32 v0, v54, v56, 2 bitop3:0x36
	v_lshlrev_b32_e32 v168, 4, v0
	v_add_u32_e32 v169, v55, v168
	ds_read_b128 v[0:3], v169
	s_waitcnt lgkmcnt(2)
	v_mfma_f32_32x32x16_bf16 v[16:31], v[8:11], v[4:7], v[16:31]
	ds_read_b128 v[4:7], v169 offset:4096
	v_lshlrev_b32_e32 v8, 3, v58
	v_lshlrev_b32_e32 v10, 1, v49
	v_and_b32_e32 v10, 32, v10
	s_waitcnt lgkmcnt(0)
	v_mfma_f32_32x32x16_bf16 v[16:31], v[4:7], v[12:15], v[16:31]
	ds_read_b128 v[4:7], v153 offset:2048
	v_mfma_f32_32x32x16_bf16 v[32:47], v[0:3], v[12:15], v[32:47]
	v_and_b32_e32 v0, 0xc0, v51
	v_and_or_b32 v9, v8, 24, v0
	v_bitop3_b32 v0, v54, v56, 4 bitop3:0x36
	v_lshlrev_b32_e32 v170, 4, v0
	v_add_u32_e32 v171, v55, v170
	ds_read_b128 v[0:3], v171
	v_and_b32_e32 v8, 0x100, v8
	s_waitcnt lgkmcnt(0)
	v_mfma_f32_32x32x16_bf16 v[32:47], v[0:3], v[4:7], v[32:47]
	v_bitop3_b32 v0, v54, v56, 6 bitop3:0x36
	v_lshlrev_b32_e32 v172, 4, v0
	v_add_u32_e32 v173, v55, v172
	v_or3_b32 v49, v9, v10, v8
	ds_read_b128 v[8:11], v171 offset:4096
	ds_read_b128 v[50:53], v153 offset:3072
	ds_read_b128 v[0:3], v173
	ds_read_b128 v[54:57], v173 offset:4096
	s_waitcnt lgkmcnt(3)
	v_mfma_f32_32x32x16_bf16 v[16:31], v[8:11], v[4:7], v[16:31]
	s_waitcnt lgkmcnt(0)
	s_barrier
; #define DMA_K(t, b) do { const char* kb_ = (const char*)Kh + (size_t)(t) * (KVBLK * LDX * 2); \
;     dma16(kb_, voffK, ldsb + K_OFF + (b) * SHM_K + wid * 1024); dma16(kb_ + 32 * LDX * 2, voffK, ldsb + K_OFF + (b) * SHM_K + (wid + 8) * 1024); \
;     if constexpr (MODE == 0) dma16((const char*)Krh + (size_t)(t) * (KVBLK * 128), voffR, ldsb + KR_OFF + (b) * 8192 + wid * 1024); } while (0)
; #define DMA_V(t, b) do { const char* vb_ = (const char*)Vh + (size_t)(t) * (KVBLK * LDX * 2); \
;     dma16(vb_, voffV, ldsb + V_OFF + (b) * SHM_V + wid * 1024); dma16(vb_ + 32 * LDX * 2, voffV, ldsb + V_OFF + (b) * SHM_V + (wid + 8) * 1024); } while (0)
; #define BARL() asm volatile("s_waitcnt lgkmcnt(0)\n\ts_barrier" ::: "memory")
; #define BIAS(P0, P1, k0, CADD) do { CADD = 0.f; if constexpr (MODE == 1) { const int dd = (k0) - qw0; \
;     if (dd <= -191) CADD = cL; else if (dd >= 159) CADD = cR; else add_bias(P0, P1, tbl, (k0) - qme, hi); } } while (0)
; #define BARL() asm volatile("s_waitcnt lgkmcnt(0)\n\ts_barrier" ::: "memory")
; __device__ __forceinline__ void partialSM(f32x16& p0, f32x16& p1, float& m_reg, float& mn, float& alpha, float cadd) {
;   float pmax = p0[0];
; #pragma unroll
;   for (int r = 1; r < 16; ++r) pmax = fmaxf(pmax, p0[r]);
; #pragma unroll
;   for (int r = 0; r < 16; ++r) pmax = fmaxf(pmax, p1[r]);
;   { auto rr = __builtin_amdgcn_permlane32_swap(__float_as_uint(pmax), __float_as_uint(pmax), false, false);
;     pmax = fmaxf(__uint_as_float(rr[0]), __uint_as_float(rr[1])); }
;   pmax += cadd;
;   if (__builtin_expect(__all(pmax - m_reg <= THRL), 1)) { mn = m_reg; alpha = 1.f; }
;   else { mn = fmaxf(m_reg, pmax); alpha = __builtin_amdgcn_exp2f(m_reg - mn); m_reg = mn; }
;   const float off = cadd - mn;
; #pragma unroll
;   for (int r = 0; r < 16; ++r) p0[r] += off;
; #pragma unroll
;   for (int r = 0; r < 16; ++r) p1[r] += off;
; #pragma unroll
;   for (int r = 0; r < 16; ++r) p0[r] = __builtin_amdgcn_exp2f(p0[r]);
; }
; template <int MODE> ...
;     ...
;   qkt<MODE>(pA0, pA1, K_lds, KR_lds, qrf, qr, r32, hi, lane); BIAS(pA0, pA1, 0, cadd); partialSM(pA0, pA1, m_reg, mnA, alA, cadd);
;   BARL();
;   DMA_K(2, 0); DMA_V(1, 1);
	v_add_u32_e32 v152, 0, v49
	s_waitcnt lgkmcnt(1)
	v_mfma_f32_32x32x16_bf16 v[32:47], v[0:3], v[50:53], v[32:47]
	v_mov_b64_e32 v[0:1], s[52:53]
	v_mov_b64_e32 v[14:15], s[66:67]
	v_mov_b64_e32 v[2:3], s[54:55]
	v_mov_b64_e32 v[4:5], s[56:57]
	v_mov_b64_e32 v[6:7], s[58:59]
	v_mov_b64_e32 v[8:9], s[60:61]
	v_mov_b64_e32 v[10:11], s[62:63]
	s_waitcnt lgkmcnt(0)
	v_mfma_f32_32x32x16_bf16 v[16:31], v[54:57], v[50:53], v[16:31]
	s_nop 2
	v_max_f32_e32 v50, v33, v33
	v_max_f32_e32 v51, v32, v32
	v_max_f32_e32 v50, v51, v50
	v_max3_f32 v50, v50, v34, v35
	v_max3_f32 v50, v50, v36, v37
	v_max3_f32 v50, v50, v38, v39
	v_max3_f32 v50, v50, v40, v41
	v_max3_f32 v50, v50, v42, v43
	v_max3_f32 v50, v50, v44, v45
	v_max3_f32 v50, v50, v46, v47
	v_max3_f32 v50, v50, v16, v17
	v_max3_f32 v50, v50, v18, v19
	v_max3_f32 v50, v50, v20, v21
	v_max3_f32 v50, v50, v22, v23
	v_max3_f32 v50, v50, v24, v25
	v_max3_f32 v50, v50, v26, v27
	v_max3_f32 v50, v50, v28, v29
	v_max3_f32 v50, v50, v30, v31
	v_mov_b32_e32 v51, v50
	s_nop 1
	v_permlane32_swap_b32_e32 v50, v51
	v_max_f32_e32 v51, v51, v51
	v_max_f32_e32 v50, v50, v50
	v_max_f32_e32 v50, v50, v51
	v_add_f32_e32 v50, 0, v50
	v_add_f32_e32 v51, 0x7149f2ca, v50
	v_cmp_ge_f32_e32 vcc, s94, v51
	s_cmp_eq_u64 vcc, exec
	s_cselect_b64 vcc, -1, 0
	s_add_u32 s10, s30, 0x29480000
	s_addc_u32 s11, s31, 0
	s_mov_b32 m0, s22
	s_nop 0
	global_load_lds_dwordx4 v155, s[10:11]
	s_add_u32 s10, s30, 0x294a0000
	s_addc_u32 s11, s31, 0
	s_mov_b32 m0, s2
	s_nop 0
	global_load_lds_dwordx4 v155, s[10:11]
	s_add_u32 s10, s12, 0x1d004000
	s_addc_u32 s11, s13, 0
	v_max_f32_e32 v50, 0xf149f2ca, v50
	s_mov_b32 m0, s95
	s_nop 0
	global_load_lds_dwordx4 v157, s[10:11]
	s_add_u32 s10, s26, 0x31440000
	v_sub_f32_e32 v51, 0xf149f2ca, v50
	v_mov_b32_e32 v52, 0xf149f2ca
	s_addc_u32 s11, s27, 0
	v_exp_f32_e32 v51, v51
	v_cndmask_b32_e32 v174, v50, v52, vcc
	s_mov_b32 m0, s1
	s_nop 0
	global_load_lds_dwordx4 v156, s[10:11]
	s_add_u32 s10, s26, 0x31460000
	v_add_f32_e64 v32, v32, -v174
	v_add_f32_e64 v33, v33, -v174
	v_add_f32_e64 v34, v34, -v174
	v_add_f32_e64 v35, v35, -v174
	v_add_f32_e64 v36, v36, -v174
	v_add_f32_e64 v37, v37, -v174
	v_add_f32_e64 v38, v38, -v174
	v_add_f32_e64 v39, v39, -v174
	v_add_f32_e64 v40, v40, -v174
	v_add_f32_e64 v41, v41, -v174
	v_add_f32_e64 v42, v42, -v174
	v_add_f32_e64 v43, v43, -v174
	v_add_f32_e64 v44, v44, -v174
	v_add_f32_e64 v45, v45, -v174
	v_add_f32_e64 v46, v46, -v174
	v_add_f32_e64 v47, v47, -v174
	s_addc_u32 s11, s27, 0
	s_mov_b32 m0, s69
	s_nop 0
	global_load_lds_dwordx4 v156, s[10:11]
	s_add_i32 s10, 0, 0x12800
	v_exp_f32_e32 v197, v32
	v_exp_f32_e32 v198, v33
	v_exp_f32_e32 v199, v34
	v_exp_f32_e32 v201, v35
	v_exp_f32_e32 v202, v36
	v_exp_f32_e32 v204, v37
	v_exp_f32_e32 v200, v38
	v_exp_f32_e32 v203, v39
	v_exp_f32_e32 v193, v40
	v_exp_f32_e32 v194, v41
	v_exp_f32_e32 v195, v42
	v_exp_f32_e32 v196, v43
	v_exp_f32_e32 v182, v44
	v_exp_f32_e32 v183, v45
	v_exp_f32_e32 v184, v46
	v_exp_f32_e32 v192, v47
	v_add_u32_e32 v175, s10, v59
	v_readlane_b32 s10, v253, 43
	v_sub_f32_e32 v50, 0, v174
	v_mov_b64_e32 v[12:13], s[64:65]
	v_lshl_add_u32 v154, v48, 2, s10
	s_add_i32 s10, 0, 0x4000
	v_cndmask_b32_e64 v176, v51, 1.0, vcc
	v_pk_add_f32 v[134:135], v[30:31], v[50:51] op_sel_hi:[1,0]
	v_pk_add_f32 v[132:133], v[28:29], v[50:51] op_sel_hi:[1,0]
	v_pk_add_f32 v[128:129], v[26:27], v[50:51] op_sel_hi:[1,0]
	v_pk_add_f32 v[130:131], v[24:25], v[50:51] op_sel_hi:[1,0]
	v_pk_add_f32 v[136:137], v[22:23], v[50:51] op_sel_hi:[1,0]
	v_pk_add_f32 v[138:139], v[20:21], v[50:51] op_sel_hi:[1,0]
	v_pk_add_f32 v[142:143], v[18:19], v[50:51] op_sel_hi:[1,0]
	v_pk_add_f32 v[144:145], v[16:17], v[50:51] op_sel_hi:[1,0]
	v_add_u32_e32 v151, s10, v49
	s_add_u32 s10, s12, 0x1d006000
	v_mov_b64_e32 v[62:63], v[14:15]
	v_mov_b64_e32 v[46:47], v[14:15]
	v_mov_b64_e32 v[30:31], v[14:15]
	v_readlane_b32 s60, v255, 19
	v_readlane_b32 s59, v255, 18
	v_readlane_b32 s61, v255, 16
	s_addc_u32 s11, s13, 0
	s_mov_b32 s26, -1
	v_mov_b64_e32 v[60:61], v[12:13]
	v_mov_b64_e32 v[58:59], v[10:11]
	v_mov_b64_e32 v[56:57], v[8:9]
	v_mov_b64_e32 v[54:55], v[6:7]
	v_mov_b64_e32 v[52:53], v[4:5]
	v_mov_b64_e32 v[50:51], v[2:3]
	v_mov_b64_e32 v[48:49], v[0:1]
	v_mov_b64_e32 v[44:45], v[12:13]
	v_mov_b64_e32 v[42:43], v[10:11]
	v_mov_b64_e32 v[40:41], v[8:9]
	v_mov_b64_e32 v[38:39], v[6:7]
	v_mov_b64_e32 v[36:37], v[4:5]
	v_mov_b64_e32 v[34:35], v[2:3]
	v_mov_b64_e32 v[32:33], v[0:1]
	v_mov_b64_e32 v[28:29], v[12:13]
	v_mov_b64_e32 v[26:27], v[10:11]
	v_mov_b64_e32 v[24:25], v[8:9]
	v_mov_b64_e32 v[22:23], v[6:7]
	v_mov_b64_e32 v[20:21], v[4:5]
	v_mov_b64_e32 v[18:19], v[2:3]
	v_mov_b64_e32 v[16:17], v[0:1]
; #define SBAR() __builtin_amdgcn_sched_barrier(0)
; __device__ __forceinline__ void finishSM(f32x16& p0, f32x16& p1, float alpha, float& l_reg, bf16x8& pa0, bf16x8& pa1, bf16x8& pa2, bf16x8& pa3) {
; #pragma unroll
;   for (int r = 0; r < 16; ++r) p1[r] = __builtin_amdgcn_exp2f(p1[r]);
;   float ps = 0;
; #pragma unroll
;   for (int r = 0; r < 16; ++r) ps += p0[r];
; #pragma unroll
;   for (int r = 0; r < 16; ++r) ps += p1[r];
;   { auto rr = __builtin_amdgcn_permlane32_swap(__float_as_uint(ps), __float_as_uint(ps), false, false);
;     ps = __uint_as_float(rr[0]) + __uint_as_float(rr[1]); }
;   l_reg = l_reg * alpha + ps;
;     ...
;   PK4(p0, 0, pa0); PK4(p0, 8, pa1); PK4(p1, 0, pa2); PK4(p1, 8, pa3);
;     ...
; }
; template <int MODE> ...
;     ...
;     SBAR(); qkt<MODE>(pB0, pB1, K_lds + SHM_K, KR_lds + 8192, qrf, qr, r32, hi, lane);
;     finishSM(pA0, pA1, alA, l_reg, pa0, pa1, pa2, pa3); QK_PIPE(); SBAR();
.LBB0_939:
	ds_read_b128 v[64:67], v158 offset:49152
	ds_read_b128 v[68:71], v158 offset:57344
	s_waitcnt lgkmcnt(1)
	v_mfma_f32_32x32x16_bf16 v[80:95], v[64:67], v[100:103], 0
	s_waitcnt lgkmcnt(0)
	v_mfma_f32_32x32x16_bf16 v[64:79], v[68:71], v[100:103], 0
	ds_read_b128 v[206:209], v160 offset:49152
	ds_read_b128 v[210:213], v160 offset:57344
	v_exp_f32_e32 v181, v144
	v_exp_f32_e32 v190, v145
	v_add_f32_e32 v144, 0, v197
	v_add_u32_e32 v180, v175, v166
	v_add_u32_e32 v179, v175, v168
	v_add_u32_e32 v178, v175, v170
	v_add_u32_e32 v177, v175, v172
	v_add_f32_e32 v144, v198, v144
	s_waitcnt lgkmcnt(1)
	v_mfma_f32_32x32x16_bf16 v[80:95], v[206:209], v[116:119], v[80:95]
	s_waitcnt lgkmcnt(0)
	v_mfma_f32_32x32x16_bf16 v[64:79], v[210:213], v[116:119], v[64:79]
	ds_read_b128 v[206:209], v161 offset:49152
	ds_read_b128 v[210:213], v161 offset:57344
	v_exp_f32_e32 v191, v142
	v_exp_f32_e32 v205, v143
	v_add_f32_e32 v142, v199, v144
	v_add_f32_e32 v142, v201, v142
	v_add_f32_e32 v142, v202, v142
	v_add_f32_e32 v142, v204, v142
	v_add_f32_e32 v142, v200, v142
	v_add_f32_e32 v214, v203, v142
	s_waitcnt lgkmcnt(1)
	v_mfma_f32_32x32x16_bf16 v[80:95], v[206:209], v[124:127], v[80:95]
	s_waitcnt lgkmcnt(0)
	v_mfma_f32_32x32x16_bf16 v[64:79], v[210:213], v[124:127], v[64:79]
	ds_read_b128 v[142:145], v164 offset:49152
	ds_read_b128 v[206:209], v164 offset:57344
	v_exp_f32_e32 v210, v138
	v_exp_f32_e32 v211, v139
	v_add_f32_e32 v138, v193, v214
	v_add_f32_e32 v138, v194, v138
	v_add_f32_e32 v138, v195, v138
	v_add_f32_e32 v138, v196, v138
	v_add_f32_e32 v138, v182, v138
	v_add_f32_e32 v138, v183, v138
	s_waitcnt lgkmcnt(1)
	v_mfma_f32_32x32x16_bf16 v[80:95], v[142:145], v[120:123], v[80:95]
	s_waitcnt lgkmcnt(0)
	v_mfma_f32_32x32x16_bf16 v[64:79], v[206:209], v[120:123], v[64:79]
	ds_read_b128 v[142:145], v165 offset:49152
	ds_read_b128 v[206:209], v165 offset:57344
	v_exp_f32_e32 v212, v136
	v_exp_f32_e32 v213, v137
	v_add_f32_e32 v136, v184, v138
	v_add_f32_e32 v136, v192, v136
	v_add_f32_e32 v136, v181, v136
	v_add_f32_e32 v136, v190, v136
	v_add_f32_e32 v136, v191, v136
	v_add_f32_e32 v214, v205, v136
	s_waitcnt lgkmcnt(1)
	v_mfma_f32_32x32x16_bf16 v[80:95], v[142:145], v[112:115], v[80:95]
	s_waitcnt lgkmcnt(0)
	v_mfma_f32_32x32x16_bf16 v[64:79], v[206:209], v[112:115], v[64:79]
	ds_read_b128 v[136:139], v163 offset:49152
	ds_read_b128 v[142:145], v163 offset:57344
	v_exp_f32_e32 v206, v130
	v_exp_f32_e32 v207, v131
	v_add_f32_e32 v130, v210, v214
	v_add_f32_e32 v130, v211, v130
	v_add_f32_e32 v130, v212, v130
	v_add_f32_e32 v130, v213, v130
	v_add_f32_e32 v130, v206, v130
	v_add_f32_e32 v130, v207, v130
	s_waitcnt lgkmcnt(1)
	v_mfma_f32_32x32x16_bf16 v[80:95], v[136:139], v[108:111], v[80:95]
	s_waitcnt lgkmcnt(0)
	v_mfma_f32_32x32x16_bf16 v[64:79], v[142:145], v[108:111], v[64:79]
	ds_read_b128 v[136:139], v162 offset:49152
	ds_read_b128 v[142:145], v162 offset:57344
	v_exp_f32_e32 v208, v128
	v_exp_f32_e32 v209, v129
	v_cvt_pk_bf16_f32 v129, v199, v201
	v_cvt_pk_bf16_f32 v131, v200, v203
	v_add_f32_e32 v128, v208, v130
	v_add_f32_e32 v214, v209, v128
	v_cvt_pk_bf16_f32 v128, v197, v198
	v_cvt_pk_bf16_f32 v130, v202, v204
	s_waitcnt lgkmcnt(1)
	v_mfma_f32_32x32x16_bf16 v[80:95], v[136:139], v[104:107], v[80:95]
	s_waitcnt lgkmcnt(0)
	v_mfma_f32_32x32x16_bf16 v[64:79], v[142:145], v[104:107], v[64:79]
	ds_read_b128 v[136:139], v159 offset:49152
	ds_read_b128 v[142:145], v159 offset:57344
	v_exp_f32_e32 v215, v132
	v_exp_f32_e32 v216, v133
	v_permlane32_swap_b32_e32 v128, v130
	v_add_f32_e32 v132, v215, v214
	v_add_f32_e32 v202, v216, v132
	v_permlane32_swap_b32_e32 v129, v131
	v_cvt_pk_bf16_f32 v132, v193, v194
	v_cvt_pk_bf16_f32 v133, v195, v196
	s_waitcnt lgkmcnt(1)
	v_mfma_f32_32x32x16_bf16 v[80:95], v[136:139], v[96:99], v[80:95]
	s_waitcnt lgkmcnt(0)
	v_mfma_f32_32x32x16_bf16 v[64:79], v[142:145], v[96:99], v[64:79]
	ds_read_b128 v[136:139], v180
	ds_read_b128 v[194:197], v180 offset:4096
	ds_read_b128 v[198:201], v153
	v_exp_f32_e32 v144, v134
	v_exp_f32_e32 v145, v135
	v_cvt_pk_bf16_f32 v135, v184, v192
	v_add_f32_e32 v134, v144, v202
	v_add_f32_e32 v142, v145, v134
	v_mov_b32_e32 v143, v142
	s_nop 1
	v_permlane32_swap_b32_e32 v142, v143
	v_cvt_pk_bf16_f32 v134, v182, v183
	s_waitcnt lgkmcnt(0)
	v_mfma_f32_32x32x16_bf16 v[80:95], v[136:139], v[198:201], v[80:95]
	v_mfma_f32_32x32x16_bf16 v[64:79], v[194:197], v[198:201], v[64:79]
	ds_read_b128 v[192:195], v179
	ds_read_b128 v[196:199], v179 offset:4096
	ds_read_b128 v[200:203], v153 offset:1024
	v_permlane32_swap_b32_e32 v132, v134
	v_permlane32_swap_b32_e32 v133, v135
	v_cvt_pk_bf16_f32 v136, v181, v190
	v_cvt_pk_bf16_f32 v137, v191, v205
	v_cvt_pk_bf16_f32 v138, v210, v211
	v_cvt_pk_bf16_f32 v139, v212, v213
	s_waitcnt lgkmcnt(0)
	v_mfma_f32_32x32x16_bf16 v[80:95], v[192:195], v[200:203], v[80:95]
	v_mfma_f32_32x32x16_bf16 v[64:79], v[196:199], v[200:203], v[64:79]
	ds_read_b128 v[192:195], v178
	ds_read_b128 v[196:199], v178 offset:4096
	ds_read_b128 v[200:203], v153 offset:2048
	v_permlane32_swap_b32_e32 v136, v138
	v_permlane32_swap_b32_e32 v137, v139
	v_cvt_pk_bf16_f32 v204, v206, v207
	v_cvt_pk_bf16_f32 v205, v208, v209
	v_cvt_pk_bf16_f32 v206, v215, v216
	v_cvt_pk_bf16_f32 v207, v144, v145
	s_waitcnt lgkmcnt(0)
	v_mfma_f32_32x32x16_bf16 v[80:95], v[192:195], v[200:203], v[80:95]
	v_mfma_f32_32x32x16_bf16 v[64:79], v[196:199], v[200:203], v[64:79]
	ds_read_b128 v[192:195], v177
	ds_read_b128 v[200:203], v177 offset:4096
	ds_read_b128 v[196:199], v153 offset:3072
	v_permlane32_swap_b32_e32 v204, v206
	v_permlane32_swap_b32_e32 v205, v207
	s_waitcnt lgkmcnt(0)
; #define SBAR() __builtin_amdgcn_sched_barrier(0)
; template <int OFF> __device__ __forceinline__ s16x4 tr_read(unsigned vb) { s16x4 r; asm volatile("ds_read_b64_tr_b16 %0, %1 offset:%2" : "=&v"(r) : "v"(vb), "i"(OFF) : "memory"); return r; }
; #define BARL() asm volatile("s_waitcnt lgkmcnt(0)\n\ts_barrier" ::: "memory")
; template <int D0> __device__ __forceinline__ void pv_one(f32x16& od, unsigned vb, bf16x8 pa0, bf16x8 pa1, bf16x8 pa2, bf16x8 pa3) {
;   const s16x4 l0 = tr_read<v_rd_off(D0, 0, 0)>(vb), h0 = tr_read<v_rd_off(D0, 0, 1)>(vb), l1 = tr_read<v_rd_off(D0, 1, 0)>(vb), h1 = tr_read<v_rd_off(D0, 1, 1)>(vb);
;   const s16x4 l2 = tr_read<v_rd_off(D0, 2, 0)>(vb), h2 = tr_read<v_rd_off(D0, 2, 1)>(vb), l3 = tr_read<v_rd_off(D0, 3, 0)>(vb), h3 = tr_read<v_rd_off(D0, 3, 1)>(vb);
;   asm volatile("s_waitcnt lgkmcnt(0)" ::: "memory"); SBAR();
;     ...
;   od = __builtin_amdgcn_mfma_f32_32x32x16_bf16(pa0, PK(l0, h0), od, 0, 0, 0);
;   od = __builtin_amdgcn_mfma_f32_32x32x16_bf16(pa1, PK(l1, h1), od, 0, 0, 0);
;   od = __builtin_amdgcn_mfma_f32_32x32x16_bf16(pa2, PK(l2, h2), od, 0, 0, 0);
;   od = __builtin_amdgcn_mfma_f32_32x32x16_bf16(pa3, PK(l3, h3), od, 0, 0, 0);
;     ...
; }
; __device__ __forceinline__ void pv_d0(f32x16* o, unsigned vb, bf16x8 pa0, bf16x8 pa1, bf16x8 pa2, bf16x8 pa3) {
;   pv_one<0>(o[0], vb, pa0, pa1, pa2, pa3); pv_one<1>(o[1], vb, pa0, pa1, pa2, pa3); pv_one<2>(o[2], vb, pa0, pa1, pa2, pa3); pv_one<3>(o[3], vb, pa0, pa1, pa2, pa3);
; }
; __device__ __forceinline__ void partialSM(f32x16& p0, f32x16& p1, float& m_reg, float& mn, float& alpha, float cadd) {
;   float pmax = p0[0];
; #pragma unroll
;   for (int r = 1; r < 16; ++r) pmax = fmaxf(pmax, p0[r]);
; #pragma unroll
;   for (int r = 0; r < 16; ++r) pmax = fmaxf(pmax, p1[r]);
;   { auto rr = __builtin_amdgcn_permlane32_swap(__float_as_uint(pmax), __float_as_uint(pmax), false, false);
;     pmax = fmaxf(__uint_as_float(rr[0]), __uint_as_float(rr[1])); }
;   pmax += cadd;
;   if (__builtin_expect(__all(pmax - m_reg <= THRL), 1)) { mn = m_reg; alpha = 1.f; }
;   else { mn = fmaxf(m_reg, pmax); alpha = __builtin_amdgcn_exp2f(m_reg - mn); m_reg = mn; }
; template <int MODE> ...
;     ...
;     pv_d0(o, vb0, pa0, pa1, pa2, pa3); BIAS(pB0, pB1, j * KVBLK, cadd); partialSM(pB0, pB1, m_reg, mnB, alB, cadd);
;     BARL();
;     DMA_K(j + 2, 1); DMA_V(j + 1, 0);
;     WAITV();
;     RESC(alB); BARL();
	v_mfma_f32_32x32x16_bf16 v[80:95], v[192:195], v[196:199], v[80:95]
	v_mfma_f32_32x32x16_bf16 v[64:79], v[200:203], v[196:199], v[64:79]
	ds_read_b64_tr_b16 v[192:193], v152 offset:0
	ds_read_b64_tr_b16 v[194:195], v152 offset:0x800
	ds_read_b64_tr_b16 v[196:197], v152 offset:0x1000
	ds_read_b64_tr_b16 v[198:199], v152 offset:0x1800
	ds_read_b64_tr_b16 v[200:201], v152 offset:0x2000
	ds_read_b64_tr_b16 v[202:203], v152 offset:0x2800
	ds_read_b64_tr_b16 v[208:209], v152 offset:0x3000
	ds_read_b64_tr_b16 v[210:211], v152 offset:0x3800
	s_waitcnt lgkmcnt(0)
	s_nop 0
	v_mfma_f32_32x32x16_bf16 v[0:15], v[128:131], v[192:195], v[0:15]
	ds_read_b64_tr_b16 v[192:193], v152 offset:0x200
	ds_read_b64_tr_b16 v[194:195], v152 offset:0xa00
	v_mfma_f32_32x32x16_bf16 v[0:15], v[132:135], v[196:199], v[0:15]
	ds_read_b64_tr_b16 v[196:197], v152 offset:0x1200
	ds_read_b64_tr_b16 v[198:199], v152 offset:0x1a00
	v_mfma_f32_32x32x16_bf16 v[0:15], v[136:139], v[200:203], v[0:15]
	ds_read_b64_tr_b16 v[200:201], v152 offset:0x2200
	ds_read_b64_tr_b16 v[202:203], v152 offset:0x2a00
	v_mfma_f32_32x32x16_bf16 v[0:15], v[204:207], v[208:211], v[0:15]
	ds_read_b64_tr_b16 v[208:209], v152 offset:0x3200
	ds_read_b64_tr_b16 v[210:211], v152 offset:0x3a00
	s_waitcnt lgkmcnt(0)
	v_mfma_f32_32x32x16_bf16 v[48:63], v[128:131], v[192:195], v[48:63]
	ds_read_b64_tr_b16 v[192:193], v152 offset:0x400
	ds_read_b64_tr_b16 v[194:195], v152 offset:0xc00
	v_mfma_f32_32x32x16_bf16 v[48:63], v[132:135], v[196:199], v[48:63]
	ds_read_b64_tr_b16 v[196:197], v152 offset:0x1400
	ds_read_b64_tr_b16 v[198:199], v152 offset:0x1c00
	v_mfma_f32_32x32x16_bf16 v[48:63], v[136:139], v[200:203], v[48:63]
	ds_read_b64_tr_b16 v[200:201], v152 offset:0x2400
	ds_read_b64_tr_b16 v[202:203], v152 offset:0x2c00
	v_mfma_f32_32x32x16_bf16 v[48:63], v[204:207], v[208:211], v[48:63]
	ds_read_b64_tr_b16 v[208:209], v152 offset:0x3400
	ds_read_b64_tr_b16 v[210:211], v152 offset:0x3c00
	s_waitcnt lgkmcnt(0)
	v_mfma_f32_32x32x16_bf16 v[32:47], v[128:131], v[192:195], v[32:47]
	ds_read_b64_tr_b16 v[192:193], v152 offset:0x600
	ds_read_b64_tr_b16 v[194:195], v152 offset:0xe00
	v_mfma_f32_32x32x16_bf16 v[32:47], v[132:135], v[196:199], v[32:47]
	ds_read_b64_tr_b16 v[196:197], v152 offset:0x1600
	ds_read_b64_tr_b16 v[198:199], v152 offset:0x1e00
	v_mfma_f32_32x32x16_bf16 v[32:47], v[136:139], v[200:203], v[32:47]
	ds_read_b64_tr_b16 v[200:201], v152 offset:0x2600
	ds_read_b64_tr_b16 v[202:203], v152 offset:0x2e00
	v_mfma_f32_32x32x16_bf16 v[32:47], v[204:207], v[208:211], v[32:47]
	ds_read_b64_tr_b16 v[208:209], v152 offset:0x3600
	ds_read_b64_tr_b16 v[210:211], v152 offset:0x3e00
	s_waitcnt lgkmcnt(0)
	v_mfma_f32_32x32x16_bf16 v[16:31], v[128:131], v[192:195], v[16:31]
	v_max_f32_e32 v128, v81, v81
	v_max_f32_e32 v129, v80, v80
	v_max_f32_e32 v128, v129, v128
	v_max3_f32 v128, v128, v82, v83
	v_max3_f32 v128, v128, v84, v85
	v_max3_f32 v128, v128, v86, v87
	v_max3_f32 v128, v128, v88, v89
	v_max3_f32 v128, v128, v90, v91
	v_max3_f32 v128, v128, v92, v93
	v_max3_f32 v128, v128, v94, v95
	v_max3_f32 v128, v128, v64, v65
	v_max3_f32 v128, v128, v66, v67
	v_max3_f32 v128, v128, v68, v69
	v_max3_f32 v128, v128, v70, v71
	v_max3_f32 v128, v128, v72, v73
	v_max3_f32 v128, v128, v74, v75
	v_max3_f32 v128, v128, v76, v77
	v_mfma_f32_32x32x16_bf16 v[16:31], v[132:135], v[196:199], v[16:31]
	v_max3_f32 v128, v128, v78, v79
	v_mov_b32_e32 v129, v128
	s_nop 1
	v_permlane32_swap_b32_e32 v128, v129
	v_max_f32_e32 v129, v129, v129
	v_max_f32_e32 v128, v128, v128
	v_max_f32_e32 v128, v128, v129
	v_add_f32_e32 v128, 0, v128
	v_sub_f32_e32 v129, v128, v174
	v_cmp_ge_f32_e32 vcc, s94, v129
	v_mfma_f32_32x32x16_bf16 v[16:31], v[136:139], v[200:203], v[16:31]
	s_cmp_eq_u64 vcc, exec
	s_cselect_b64 s[40:41], -1, 0
	s_add_u32 s27, s19, s18
	s_addc_u32 s30, s21, 0
	s_add_u32 s12, s27, 0x294c0000
	s_waitcnt lgkmcnt(0)
	s_barrier
	s_addc_u32 s13, s30, 0
	s_mov_b32 m0, s14
	s_nop 0
	global_load_lds_dwordx4 v155, s[12:13]
	s_add_u32 s12, s27, 0x294e0000
	s_addc_u32 s13, s30, 0
	s_mov_b32 m0, s15
	s_nop 0
	global_load_lds_dwordx4 v155, s[12:13]
	v_max_f32_e32 v129, v174, v174
	s_add_u32 s27, s24, s18
	v_mfma_f32_32x32x16_bf16 v[16:31], v[204:207], v[208:211], v[16:31]
	v_max_f32_e32 v128, v129, v128
	v_readlane_b32 s13, v253, 48
	s_mov_b32 m0, s13
	s_nop 0
	global_load_lds_dwordx4 v157, s[10:11]
	s_addc_u32 s30, s25, 0
	v_sub_f32_e32 v129, v174, v128
	s_add_u32 s12, s27, 0x31480000
	v_exp_f32_e32 v129, v129
	s_addc_u32 s13, s30, 0
	s_mov_b32 m0, s76
	s_nop 0
	global_load_lds_dwordx4 v156, s[12:13]
	s_add_u32 s12, s27, 0x314a0000
	s_addc_u32 s13, s30, 0
	s_mov_b32 m0, s89
	s_nop 0
	global_load_lds_dwordx4 v156, s[12:13]
	s_waitcnt vmcnt(5)
	v_cndmask_b32_e64 v144, v129, 1.0, s[40:41]
	v_cmp_gt_f32_e32 vcc, 1.0, v144
	s_cbranch_vccz .LBB0_943
	s_and_saveexec_b64 s[12:13], s[38:39]
	ds_write_b32 v154, v144
	s_or_b64 exec, exec, s[12:13]
	v_readlane_b32 s12, v253, 45
	s_waitcnt lgkmcnt(0)
	s_nop 1
	v_add_u32_e32 v129, s12, v140
	v_readlane_b32 s12, v253, 46
	s_nop 1
	v_add_u32_e32 v134, s12, v140
	v_readlane_b32 s12, v253, 44
	ds_read_b128 v[130:133], v129
	ds_read_b128 v[134:137], v134
	v_add_u32_e32 v129, s12, v140
	v_readlane_b32 s12, v253, 43
	ds_read_b128 v[192:195], v129
	s_waitcnt lgkmcnt(2)
	v_pk_mul_f32 v[8:9], v[8:9], v[130:131]
	v_add_u32_e32 v129, s12, v140
	ds_read_b128 v[196:199], v129
	s_waitcnt lgkmcnt(2)
	v_pk_mul_f32 v[12:13], v[12:13], v[134:135]
	s_waitcnt lgkmcnt(1)
	v_pk_mul_f32 v[4:5], v[4:5], v[192:193]
	v_pk_mul_f32 v[14:15], v[14:15], v[136:137]
	v_pk_mul_f32 v[10:11], v[10:11], v[132:133]
	v_pk_mul_f32 v[6:7], v[6:7], v[194:195]
	s_waitcnt lgkmcnt(0)
	v_pk_mul_f32 v[2:3], v[2:3], v[198:199]
	v_pk_mul_f32 v[0:1], v[0:1], v[196:197]
	v_pk_mul_f32 v[60:61], v[134:135], v[60:61]
	v_pk_mul_f32 v[56:57], v[130:131], v[56:57]
	v_pk_mul_f32 v[52:53], v[192:193], v[52:53]
	v_pk_mul_f32 v[62:63], v[136:137], v[62:63]
	v_pk_mul_f32 v[58:59], v[132:133], v[58:59]
	v_pk_mul_f32 v[54:55], v[194:195], v[54:55]
	v_pk_mul_f32 v[50:51], v[198:199], v[50:51]
	v_pk_mul_f32 v[48:49], v[196:197], v[48:49]
	v_pk_mul_f32 v[44:45], v[134:135], v[44:45]
	v_pk_mul_f32 v[40:41], v[130:131], v[40:41]
	v_pk_mul_f32 v[36:37], v[192:193], v[36:37]
	v_pk_mul_f32 v[46:47], v[136:137], v[46:47]
	v_pk_mul_f32 v[42:43], v[132:133], v[42:43]
	v_pk_mul_f32 v[38:39], v[194:195], v[38:39]
	v_pk_mul_f32 v[34:35], v[198:199], v[34:35]
	v_pk_mul_f32 v[32:33], v[196:197], v[32:33]
	v_pk_mul_f32 v[28:29], v[134:135], v[28:29]
	v_pk_mul_f32 v[24:25], v[130:131], v[24:25]
	v_pk_mul_f32 v[20:21], v[192:193], v[20:21]
	v_pk_mul_f32 v[30:31], v[136:137], v[30:31]
	v_pk_mul_f32 v[26:27], v[132:133], v[26:27]
	v_pk_mul_f32 v[22:23], v[194:195], v[22:23]
	v_pk_mul_f32 v[18:19], v[198:199], v[18:19]
	v_pk_mul_f32 v[16:17], v[196:197], v[16:17]
; #define LAS __attribute__((address_space(3)))
; #define SBAR() __builtin_amdgcn_sched_barrier(0)
; __device__ __forceinline__ void partialSM(f32x16& p0, f32x16& p1, float& m_reg, float& mn, float& alpha, float cadd) {
;     ...
;   const float off = cadd - mn;
; #pragma unroll
;   for (int r = 0; r < 16; ++r) p0[r] += off;
; #pragma unroll
;   for (int r = 0; r < 16; ++r) p1[r] += off;
; #pragma unroll
;   for (int r = 0; r < 16; ++r) p0[r] = __builtin_amdgcn_exp2f(p0[r]);
; }
; __device__ __forceinline__ void finishSM(f32x16& p0, f32x16& p1, float alpha, float& l_reg, bf16x8& pa0, bf16x8& pa1, bf16x8& pa2, bf16x8& pa3) {
; #pragma unroll
;   for (int r = 0; r < 16; ++r) p1[r] = __builtin_amdgcn_exp2f(p1[r]);
;   float ps = 0;
; #pragma unroll
;   for (int r = 0; r < 16; ++r) ps += p0[r];
; #pragma unroll
;   for (int r = 0; r < 16; ++r) ps += p1[r];
;   { auto rr = __builtin_amdgcn_permlane32_swap(__float_as_uint(ps), __float_as_uint(ps), false, false);
;     ps = __uint_as_float(rr[0]) + __uint_as_float(rr[1]); }
;   l_reg = l_reg * alpha + ps;
;     ...
;   PK4(p0, 0, pa0); PK4(p0, 8, pa1); PK4(p1, 0, pa2); PK4(p1, 8, pa3);
;     ...
; }
; template <int MODE>
; __device__ __forceinline__ void qkt(f32x16& p0, f32x16& p1, const LAS unsigned char* Ks, const LAS unsigned char* Krs, const LAS unsigned char* qrf, const bf16x8* qr, int r32, int hi, int lane) {
;   p0 = f32x16{}; p1 = f32x16{};
; #pragma unroll
;   for (int d0 = 0; d0 < 8; ++d0) { const int cb = (d0 * 16 + hi * 8) * 2;
;     const bf16x8 b0 = *(const LAS bf16x8*)(Ks + KSWZ(r32, cb));
;     const bf16x8 b1 = *(const LAS bf16x8*)(Ks + KSWZ(32 + r32, cb));
;     p0 = __builtin_amdgcn_mfma_f32_32x32x16_bf16(b0, qr[d0], p0, 0, 0, 0);
;     p1 = __builtin_amdgcn_mfma_f32_32x32x16_bf16(b1, qr[d0], p1, 0, 0, 0); }
; template <int MODE> ...
;     ...
;     SBAR(); qkt<MODE>(pA0, pA1, K_lds, KR_lds, qrf, qr, r32, hi, lane);
;     finishSM(pB0, pB1, alB, l_reg, pa0, pa1, pa2, pa3); QK_PIPE(); SBAR();
.LBB0_943:
	s_waitcnt lgkmcnt(0)
	s_barrier
	v_cndmask_b32_e64 v145, v128, v174, s[40:41]
	s_add_i32 s26, s26, 2
	v_add_f32_e64 v80, v80, -v145
	v_add_f32_e64 v81, v81, -v145
	v_add_f32_e64 v82, v82, -v145
	v_add_f32_e64 v83, v83, -v145
	v_add_f32_e64 v84, v84, -v145
	v_add_f32_e64 v85, v85, -v145
	v_add_f32_e64 v86, v86, -v145
	v_add_f32_e64 v87, v87, -v145
	v_add_f32_e64 v88, v88, -v145
	v_add_f32_e64 v89, v89, -v145
	v_add_f32_e64 v90, v90, -v145
	v_add_f32_e64 v91, v91, -v145
	v_add_f32_e64 v92, v92, -v145
	v_add_f32_e64 v93, v93, -v145
	v_add_f32_e64 v94, v94, -v145
	v_add_f32_e64 v95, v95, -v145
	v_add_f32_e64 v174, v68, -v145
	v_add_f32_e64 v181, v69, -v145
	v_add_f32_e64 v182, v70, -v145
	v_add_f32_e64 v136, v64, -v145
	v_add_f32_e64 v137, v65, -v145
	v_add_f32_e64 v138, v66, -v145
	v_add_f32_e64 v139, v67, -v145
	v_add_f32_e64 v183, v71, -v145
	v_add_f32_e64 v184, v72, -v145
	v_add_f32_e64 v190, v73, -v145
	v_add_f32_e64 v191, v74, -v145
	v_add_f32_e64 v196, v75, -v145
	v_add_f32_e64 v197, v76, -v145
	v_add_f32_e64 v198, v77, -v145
	v_add_f32_e64 v204, v78, -v145
	v_add_f32_e64 v205, v79, -v145
	v_exp_f32_e32 v192, v80
	v_exp_f32_e32 v193, v81
	v_exp_f32_e32 v194, v82
	v_exp_f32_e32 v195, v83
	v_exp_f32_e32 v199, v84
	v_exp_f32_e32 v200, v85
	v_exp_f32_e32 v201, v86
	v_exp_f32_e32 v202, v87
	v_exp_f32_e32 v203, v88
	v_exp_f32_e32 v206, v89
	v_exp_f32_e32 v207, v90
	v_exp_f32_e32 v208, v91
	v_exp_f32_e32 v209, v92
	v_exp_f32_e32 v210, v93
	v_exp_f32_e32 v211, v94
	v_exp_f32_e32 v212, v95
	ds_read_b128 v[64:67], v158 offset:32768
	ds_read_b128 v[68:71], v158 offset:40960
	s_waitcnt lgkmcnt(1)
	v_mfma_f32_32x32x16_bf16 v[80:95], v[64:67], v[100:103], 0
	s_waitcnt lgkmcnt(0)
	v_mfma_f32_32x32x16_bf16 v[64:79], v[68:71], v[100:103], 0
	ds_read_b128 v[128:131], v160 offset:32768
	ds_read_b128 v[132:135], v160 offset:40960
	v_exp_f32_e32 v213, v136
	v_exp_f32_e32 v214, v137
	v_add_f32_e32 v136, 0, v192
	v_add_f32_e32 v136, v193, v136
	v_add_f32_e32 v136, v194, v136
	v_add_f32_e32 v136, v195, v136
	v_add_f32_e32 v136, v199, v136
	v_add_f32_e32 v136, v200, v136
	s_waitcnt lgkmcnt(1)
	v_mfma_f32_32x32x16_bf16 v[80:95], v[128:131], v[116:119], v[80:95]
	s_waitcnt lgkmcnt(0)
	v_mfma_f32_32x32x16_bf16 v[64:79], v[132:135], v[116:119], v[64:79]
	ds_read_b128 v[128:131], v161 offset:32768
	ds_read_b128 v[132:135], v161 offset:40960
	v_exp_f32_e32 v215, v138
	v_exp_f32_e32 v216, v139
	v_add_f32_e32 v136, v201, v136
	v_add_f32_e32 v136, v202, v136
	v_add_f32_e32 v136, v203, v136
	v_add_f32_e32 v136, v206, v136
	v_add_f32_e32 v136, v207, v136
	v_add_f32_e32 v136, v208, v136
	s_waitcnt lgkmcnt(1)
	v_mfma_f32_32x32x16_bf16 v[80:95], v[128:131], v[124:127], v[80:95]
	s_waitcnt lgkmcnt(0)
	v_mfma_f32_32x32x16_bf16 v[64:79], v[132:135], v[124:127], v[64:79]
	ds_read_b128 v[128:131], v164 offset:32768
	ds_read_b128 v[132:135], v164 offset:40960
	v_exp_f32_e32 v217, v174
	v_exp_f32_e32 v181, v181
	v_add_f32_e32 v136, v209, v136
	v_add_f32_e32 v136, v210, v136
	v_add_f32_e32 v136, v211, v136
	v_add_f32_e32 v136, v212, v136
	v_add_f32_e32 v136, v213, v136
	v_add_f32_e32 v136, v214, v136
	s_waitcnt lgkmcnt(1)
	v_mfma_f32_32x32x16_bf16 v[80:95], v[128:131], v[120:123], v[80:95]
	s_waitcnt lgkmcnt(0)
	v_mfma_f32_32x32x16_bf16 v[64:79], v[132:135], v[120:123], v[64:79]
	ds_read_b128 v[128:131], v165 offset:32768
	ds_read_b128 v[132:135], v165 offset:40960
	v_exp_f32_e32 v218, v182
	v_exp_f32_e32 v183, v183
	v_add_f32_e32 v136, v215, v136
	v_add_f32_e32 v136, v216, v136
	v_add_f32_e32 v136, v217, v136
	v_add_f32_e32 v136, v181, v136
	v_add_f32_e32 v136, v218, v136
	v_add_f32_e32 v174, v183, v136
	s_waitcnt lgkmcnt(1)
	v_mfma_f32_32x32x16_bf16 v[80:95], v[128:131], v[112:115], v[80:95]
	s_waitcnt lgkmcnt(0)
	v_mfma_f32_32x32x16_bf16 v[64:79], v[132:135], v[112:115], v[64:79]
	ds_read_b128 v[132:135], v163 offset:32768
	ds_read_b128 v[136:139], v163 offset:40960
	v_exp_f32_e32 v184, v184
	v_exp_f32_e32 v190, v190
	v_cvt_pk_bf16_f32 v129, v194, v195
	v_cvt_pk_bf16_f32 v130, v199, v200
	v_add_f32_e32 v128, v184, v174
	v_add_f32_e32 v174, v190, v128
	v_cvt_pk_bf16_f32 v128, v192, v193
	v_cvt_pk_bf16_f32 v131, v201, v202
	s_waitcnt lgkmcnt(1)
	v_mfma_f32_32x32x16_bf16 v[80:95], v[132:135], v[108:111], v[80:95]
	s_waitcnt lgkmcnt(0)
	v_mfma_f32_32x32x16_bf16 v[64:79], v[136:139], v[108:111], v[64:79]
	ds_read_b128 v[134:137], v162 offset:32768
	ds_read_b128 v[192:195], v162 offset:40960
	v_exp_f32_e32 v191, v191
	v_exp_f32_e32 v219, v196
	v_permlane32_swap_b32_e32 v128, v130
	v_add_f32_e32 v132, v191, v174
	v_add_f32_e32 v174, v219, v132
	v_permlane32_swap_b32_e32 v129, v131
	v_cvt_pk_bf16_f32 v132, v203, v206
	v_cvt_pk_bf16_f32 v133, v207, v208
	s_waitcnt lgkmcnt(1)
	v_mfma_f32_32x32x16_bf16 v[80:95], v[134:137], v[104:107], v[80:95]
	s_waitcnt lgkmcnt(0)
	v_mfma_f32_32x32x16_bf16 v[64:79], v[192:195], v[104:107], v[64:79]
	ds_read_b128 v[136:139], v159 offset:32768
	ds_read_b128 v[192:195], v159 offset:40960
	v_exp_f32_e32 v206, v197
	v_exp_f32_e32 v207, v198
	v_cvt_pk_bf16_f32 v135, v211, v212
	s_nop 1
	v_permlane32_swap_b32_e32 v133, v135
	v_add_f32_e32 v134, v206, v174
	v_add_f32_e32 v174, v207, v134
	v_cvt_pk_bf16_f32 v134, v209, v210
	s_nop 1
	v_permlane32_swap_b32_e32 v132, v134
	s_waitcnt lgkmcnt(1)
	v_mfma_f32_32x32x16_bf16 v[80:95], v[136:139], v[96:99], v[80:95]
	s_waitcnt lgkmcnt(0)
	v_mfma_f32_32x32x16_bf16 v[64:79], v[192:195], v[96:99], v[64:79]
	ds_read_b128 v[192:195], v167
	ds_read_b128 v[196:199], v167 offset:4096
	ds_read_b128 v[200:203], v153
	v_exp_f32_e32 v208, v204
	v_exp_f32_e32 v209, v205
	v_cvt_pk_bf16_f32 v137, v215, v216
	v_add_f32_e32 v136, v208, v174
	v_add_f32_e32 v174, v209, v136
	v_mov_b32_e32 v182, v174
	s_nop 1
	v_permlane32_swap_b32_e32 v174, v182
	v_cvt_pk_bf16_f32 v136, v213, v214
	s_waitcnt lgkmcnt(0)
; #define SBAR() __builtin_amdgcn_sched_barrier(0)
; template <int OFF> __device__ __forceinline__ s16x4 tr_read(unsigned vb) { s16x4 r; asm volatile("ds_read_b64_tr_b16 %0, %1 offset:%2" : "=&v"(r) : "v"(vb), "i"(OFF) : "memory"); return r; }
; template <int D0> __device__ __forceinline__ void pv_one(f32x16& od, unsigned vb, bf16x8 pa0, bf16x8 pa1, bf16x8 pa2, bf16x8 pa3) {
;   const s16x4 l0 = tr_read<v_rd_off(D0, 0, 0)>(vb), h0 = tr_read<v_rd_off(D0, 0, 1)>(vb), l1 = tr_read<v_rd_off(D0, 1, 0)>(vb), h1 = tr_read<v_rd_off(D0, 1, 1)>(vb);
;   const s16x4 l2 = tr_read<v_rd_off(D0, 2, 0)>(vb), h2 = tr_read<v_rd_off(D0, 2, 1)>(vb), l3 = tr_read<v_rd_off(D0, 3, 0)>(vb), h3 = tr_read<v_rd_off(D0, 3, 1)>(vb);
;   asm volatile("s_waitcnt lgkmcnt(0)" ::: "memory"); SBAR();
;     ...
;   od = __builtin_amdgcn_mfma_f32_32x32x16_bf16(pa0, PK(l0, h0), od, 0, 0, 0);
;   od = __builtin_amdgcn_mfma_f32_32x32x16_bf16(pa1, PK(l1, h1), od, 0, 0, 0);
;   od = __builtin_amdgcn_mfma_f32_32x32x16_bf16(pa2, PK(l2, h2), od, 0, 0, 0);
;   od = __builtin_amdgcn_mfma_f32_32x32x16_bf16(pa3, PK(l3, h3), od, 0, 0, 0);
;     ...
; }
; __device__ __forceinline__ void pv_d0(f32x16* o, unsigned vb, bf16x8 pa0, bf16x8 pa1, bf16x8 pa2, bf16x8 pa3) {
;   pv_one<0>(o[0], vb, pa0, pa1, pa2, pa3); pv_one<1>(o[1], vb, pa0, pa1, pa2, pa3); pv_one<2>(o[2], vb, pa0, pa1, pa2, pa3); pv_one<3>(o[3], vb, pa0, pa1, pa2, pa3);
; }
; __device__ __forceinline__ void partialSM(f32x16& p0, f32x16& p1, float& m_reg, float& mn, float& alpha, float cadd) {
;   float pmax = p0[0];
; #pragma unroll
;   for (int r = 1; r < 16; ++r) pmax = fmaxf(pmax, p0[r]);
; #pragma unroll
;   for (int r = 0; r < 16; ++r) pmax = fmaxf(pmax, p1[r]);
;   { auto rr = __builtin_amdgcn_permlane32_swap(__float_as_uint(pmax), __float_as_uint(pmax), false, false);
;     pmax = fmaxf(__uint_as_float(rr[0]), __uint_as_float(rr[1])); }
;   pmax += cadd;
;   if (__builtin_expect(__all(pmax - m_reg <= THRL), 1)) { mn = m_reg; alpha = 1.f; }
;   else { mn = fmaxf(m_reg, pmax); alpha = __builtin_amdgcn_exp2f(m_reg - mn); m_reg = mn; }
; template <int MODE> ...
;     ...
;     pv_d0(o, vb0 + SHM_V, pa0, pa1, pa2, pa3); BIAS(pA0, pA1, (j + 1) * KVBLK, cadd); partialSM(pA0, pA1, m_reg, mnA, alA, cadd);
;     BARL();
;     { const int tk = (j + 3 < NT) ? j + 3 : NT - 1; DMA_K(tk, 0); } DMA_V(j + 2, 1);
	v_mfma_f32_32x32x16_bf16 v[80:95], v[192:195], v[200:203], v[80:95]
	v_mfma_f32_32x32x16_bf16 v[64:79], v[196:199], v[200:203], v[64:79]
	ds_read_b128 v[192:195], v169
	ds_read_b128 v[196:199], v169 offset:4096
	ds_read_b128 v[200:203], v153 offset:1024
	v_cvt_pk_bf16_f32 v138, v217, v181
	v_cvt_pk_bf16_f32 v139, v218, v183
	s_nop 0
	v_permlane32_swap_b32_e32 v136, v138
	v_permlane32_swap_b32_e32 v137, v139
	v_cvt_pk_bf16_f32 v204, v184, v190
	v_cvt_pk_bf16_f32 v205, v191, v219
	s_waitcnt lgkmcnt(0)
	v_mfma_f32_32x32x16_bf16 v[80:95], v[192:195], v[200:203], v[80:95]
	v_mfma_f32_32x32x16_bf16 v[64:79], v[196:199], v[200:203], v[64:79]
	ds_read_b128 v[192:195], v171
	ds_read_b128 v[196:199], v171 offset:4096
	ds_read_b128 v[200:203], v153 offset:2048
	v_cvt_pk_bf16_f32 v206, v206, v207
	v_cvt_pk_bf16_f32 v207, v208, v209
	s_nop 0
	v_permlane32_swap_b32_e32 v204, v206
	v_permlane32_swap_b32_e32 v205, v207
	s_waitcnt lgkmcnt(0)
	v_mfma_f32_32x32x16_bf16 v[80:95], v[192:195], v[200:203], v[80:95]
	v_mfma_f32_32x32x16_bf16 v[64:79], v[196:199], v[200:203], v[64:79]
	ds_read_b128 v[192:195], v173
	ds_read_b128 v[200:203], v173 offset:4096
	ds_read_b128 v[196:199], v153 offset:3072
	s_waitcnt lgkmcnt(0)
	v_mfma_f32_32x32x16_bf16 v[80:95], v[192:195], v[196:199], v[80:95]
	v_mfma_f32_32x32x16_bf16 v[64:79], v[200:203], v[196:199], v[64:79]
	ds_read_b64_tr_b16 v[192:193], v151 offset:0
	ds_read_b64_tr_b16 v[194:195], v151 offset:0x800
	ds_read_b64_tr_b16 v[196:197], v151 offset:0x1000
	ds_read_b64_tr_b16 v[198:199], v151 offset:0x1800
	ds_read_b64_tr_b16 v[200:201], v151 offset:0x2000
	ds_read_b64_tr_b16 v[202:203], v151 offset:0x2800
	ds_read_b64_tr_b16 v[208:209], v151 offset:0x3000
	ds_read_b64_tr_b16 v[210:211], v151 offset:0x3800
	s_waitcnt lgkmcnt(0)
	s_nop 0
	v_mfma_f32_32x32x16_bf16 v[0:15], v[128:131], v[192:195], v[0:15]
	ds_read_b64_tr_b16 v[192:193], v151 offset:0x200
	ds_read_b64_tr_b16 v[194:195], v151 offset:0xa00
	v_mfma_f32_32x32x16_bf16 v[0:15], v[132:135], v[196:199], v[0:15]
	ds_read_b64_tr_b16 v[196:197], v151 offset:0x1200
	ds_read_b64_tr_b16 v[198:199], v151 offset:0x1a00
	v_mfma_f32_32x32x16_bf16 v[0:15], v[136:139], v[200:203], v[0:15]
	ds_read_b64_tr_b16 v[200:201], v151 offset:0x2200
	ds_read_b64_tr_b16 v[202:203], v151 offset:0x2a00
	v_mfma_f32_32x32x16_bf16 v[0:15], v[204:207], v[208:211], v[0:15]
	ds_read_b64_tr_b16 v[208:209], v151 offset:0x3200
	ds_read_b64_tr_b16 v[210:211], v151 offset:0x3a00
	s_waitcnt lgkmcnt(0)
	v_mfma_f32_32x32x16_bf16 v[48:63], v[128:131], v[192:195], v[48:63]
	ds_read_b64_tr_b16 v[192:193], v151 offset:0x400
	ds_read_b64_tr_b16 v[194:195], v151 offset:0xc00
	v_mfma_f32_32x32x16_bf16 v[48:63], v[132:135], v[196:199], v[48:63]
	ds_read_b64_tr_b16 v[196:197], v151 offset:0x1400
	ds_read_b64_tr_b16 v[198:199], v151 offset:0x1c00
	v_mfma_f32_32x32x16_bf16 v[48:63], v[136:139], v[200:203], v[48:63]
	ds_read_b64_tr_b16 v[200:201], v151 offset:0x2400
	ds_read_b64_tr_b16 v[202:203], v151 offset:0x2c00
	v_mfma_f32_32x32x16_bf16 v[48:63], v[204:207], v[208:211], v[48:63]
	ds_read_b64_tr_b16 v[208:209], v151 offset:0x3400
	ds_read_b64_tr_b16 v[210:211], v151 offset:0x3c00
	s_waitcnt lgkmcnt(0)
	v_mfma_f32_32x32x16_bf16 v[32:47], v[128:131], v[192:195], v[32:47]
	ds_read_b64_tr_b16 v[192:193], v151 offset:0x600
	ds_read_b64_tr_b16 v[194:195], v151 offset:0xe00
	v_mfma_f32_32x32x16_bf16 v[32:47], v[132:135], v[196:199], v[32:47]
	ds_read_b64_tr_b16 v[196:197], v151 offset:0x1600
	ds_read_b64_tr_b16 v[198:199], v151 offset:0x1e00
	v_mfma_f32_32x32x16_bf16 v[32:47], v[136:139], v[200:203], v[32:47]
	ds_read_b64_tr_b16 v[200:201], v151 offset:0x2600
	ds_read_b64_tr_b16 v[202:203], v151 offset:0x2e00
	v_mfma_f32_32x32x16_bf16 v[32:47], v[204:207], v[208:211], v[32:47]
	ds_read_b64_tr_b16 v[208:209], v151 offset:0x3600
	ds_read_b64_tr_b16 v[210:211], v151 offset:0x3e00
	s_waitcnt lgkmcnt(0)
	v_mfma_f32_32x32x16_bf16 v[16:31], v[128:131], v[192:195], v[16:31]
	v_max_f32_e32 v128, v81, v81
	v_max_f32_e32 v129, v80, v80
	v_max_f32_e32 v128, v129, v128
	v_max3_f32 v128, v128, v82, v83
	v_max3_f32 v128, v128, v84, v85
	v_max3_f32 v128, v128, v86, v87
	v_max3_f32 v128, v128, v88, v89
	v_max3_f32 v128, v128, v90, v91
	v_max3_f32 v128, v128, v92, v93
	v_max3_f32 v128, v128, v94, v95
	v_max3_f32 v128, v128, v64, v65
	v_max3_f32 v128, v128, v66, v67
	v_max3_f32 v128, v128, v68, v69
	v_max3_f32 v128, v128, v70, v71
	v_max3_f32 v128, v128, v72, v73
	v_max3_f32 v128, v128, v74, v75
	v_max3_f32 v128, v128, v76, v77
	v_max3_f32 v128, v128, v78, v79
	v_mfma_f32_32x32x16_bf16 v[16:31], v[132:135], v[196:199], v[16:31]
	v_mov_b32_e32 v129, v128
	s_nop 1
	v_permlane32_swap_b32_e32 v128, v129
	v_max_f32_e32 v129, v129, v129
	v_max_f32_e32 v128, v128, v128
	v_max_f32_e32 v128, v128, v129
	v_add_f32_e32 v128, 0, v128
	v_sub_f32_e32 v129, v128, v145
	v_cmp_ge_f32_e32 vcc, s94, v129
	s_cmp_eq_u64 vcc, exec
	v_mfma_f32_32x32x16_bf16 v[16:31], v[136:139], v[200:203], v[16:31]
	s_cselect_b64 s[40:41], -1, 0
	s_min_u32 s12, s26, 60
	s_add_i32 s31, s12, 3
	s_lshl_b32 s12, s31, 18
	s_add_u32 s12, s6, s12
	s_waitcnt lgkmcnt(0)
	s_barrier
; #define DMA_K(t, b) do { const char* kb_ = (const char*)Kh + (size_t)(t) * (KVBLK * LDX * 2); \
;     dma16(kb_, voffK, ldsb + K_OFF + (b) * SHM_K + wid * 1024); dma16(kb_ + 32 * LDX * 2, voffK, ldsb + K_OFF + (b) * SHM_K + (wid + 8) * 1024); \
;     if constexpr (MODE == 0) dma16((const char*)Krh + (size_t)(t) * (KVBLK * 128), voffR, ldsb + KR_OFF + (b) * 8192 + wid * 1024); } while (0)
; #define DMA_V(t, b) do { const char* vb_ = (const char*)Vh + (size_t)(t) * (KVBLK * LDX * 2); \
;     dma16(vb_, voffV, ldsb + V_OFF + (b) * SHM_V + wid * 1024); dma16(vb_ + 32 * LDX * 2, voffV, ldsb + V_OFF + (b) * SHM_V + (wid + 8) * 1024); } while (0)
; #define WAITV() do { if constexpr (MODE == 0) asm volatile("s_waitcnt vmcnt(5)" ::: "memory"); else asm volatile("s_waitcnt vmcnt(4)" ::: "memory"); } while (0)
; #define BARL() asm volatile("s_waitcnt lgkmcnt(0)\n\ts_barrier" ::: "memory")
; #define RESC(a) do { if (__any((a) < 1.f)) { if (hi == 0) al_l[r32] = (a); asm volatile("s_waitcnt lgkmcnt(0)" ::: "memory"); \
;     _Pragma("unroll") for (int d = 0; d < 4; ++d) _Pragma("unroll") for (int r = 0; r < 16; ++r) o[d][r] *= al_l[crow(r, hi)]; } } while (0)
; #define BARL() asm volatile("s_waitcnt lgkmcnt(0)\n\ts_barrier" ::: "memory")
; template <int MODE> ...
;     ...
;     { const int tk = (j + 3 < NT) ? j + 3 : NT - 1; DMA_K(tk, 0); } DMA_V(j + 2, 1);
;     WAITV();
;     RESC(alA); BARL();
	s_addc_u32 s13, s7, 0
	s_mov_b32 m0, s22
	s_nop 0
	global_load_lds_dwordx4 v155, s[12:13]
	s_add_u32 s12, s12, 0x20000
	s_addc_u32 s13, s13, 0
	s_mov_b32 m0, s2
	s_nop 0
	global_load_lds_dwordx4 v155, s[12:13]
	s_lshl_b32 s12, s31, 13
	v_max_f32_e32 v129, v145, v145
	s_add_u32 s12, s8, s12
	v_mfma_f32_32x32x16_bf16 v[16:31], v[204:207], v[208:211], v[16:31]
	v_max_f32_e32 v128, v129, v128
	s_addc_u32 s13, s9, 0
	v_sub_f32_e32 v129, v145, v128
	s_mov_b32 m0, s95
	s_nop 0
	global_load_lds_dwordx4 v157, s[12:13]
	s_add_u32 s12, s27, 0x314c0000
	v_exp_f32_e32 v129, v129
	s_addc_u32 s13, s30, 0
	s_mov_b32 m0, s1
	s_nop 0
	global_load_lds_dwordx4 v156, s[12:13]
	s_add_u32 s12, s27, 0x314e0000
	s_addc_u32 s13, s30, 0
	s_mov_b32 m0, s69
	s_nop 0
	global_load_lds_dwordx4 v156, s[12:13]
	s_waitcnt vmcnt(5)
	v_cndmask_b32_e64 v181, v129, 1.0, s[40:41]
	v_cmp_gt_f32_e32 vcc, 1.0, v181
	s_cbranch_vccz .LBB0_947
	s_and_saveexec_b64 s[12:13], s[38:39]
	ds_write_b32 v154, v181
	s_or_b64 exec, exec, s[12:13]
	v_readlane_b32 s12, v253, 45
	s_waitcnt lgkmcnt(0)
	s_nop 1
	v_add_u32_e32 v129, s12, v140
	v_readlane_b32 s12, v253, 46
	s_nop 1
	v_add_u32_e32 v134, s12, v140
	v_readlane_b32 s12, v253, 44
	ds_read_b128 v[130:133], v129
	ds_read_b128 v[134:137], v134
	v_add_u32_e32 v129, s12, v140
	v_readlane_b32 s12, v253, 43
	ds_read_b128 v[192:195], v129
	s_waitcnt lgkmcnt(2)
	v_pk_mul_f32 v[8:9], v[8:9], v[130:131]
	v_add_u32_e32 v129, s12, v140
	ds_read_b128 v[196:199], v129
	s_waitcnt lgkmcnt(2)
	v_pk_mul_f32 v[12:13], v[12:13], v[134:135]
	s_waitcnt lgkmcnt(1)
	v_pk_mul_f32 v[4:5], v[4:5], v[192:193]
	v_pk_mul_f32 v[14:15], v[14:15], v[136:137]
	v_pk_mul_f32 v[10:11], v[10:11], v[132:133]
	v_pk_mul_f32 v[6:7], v[6:7], v[194:195]
	s_waitcnt lgkmcnt(0)
	v_pk_mul_f32 v[2:3], v[2:3], v[198:199]
	v_pk_mul_f32 v[0:1], v[0:1], v[196:197]
	v_pk_mul_f32 v[60:61], v[134:135], v[60:61]
	v_pk_mul_f32 v[56:57], v[130:131], v[56:57]
	v_pk_mul_f32 v[52:53], v[192:193], v[52:53]
	v_pk_mul_f32 v[62:63], v[136:137], v[62:63]
	v_pk_mul_f32 v[58:59], v[132:133], v[58:59]
	v_pk_mul_f32 v[54:55], v[194:195], v[54:55]
	v_pk_mul_f32 v[50:51], v[198:199], v[50:51]
	v_pk_mul_f32 v[48:49], v[196:197], v[48:49]
	v_pk_mul_f32 v[44:45], v[134:135], v[44:45]
	v_pk_mul_f32 v[40:41], v[130:131], v[40:41]
	v_pk_mul_f32 v[36:37], v[192:193], v[36:37]
	v_pk_mul_f32 v[46:47], v[136:137], v[46:47]
	v_pk_mul_f32 v[42:43], v[132:133], v[42:43]
	v_pk_mul_f32 v[38:39], v[194:195], v[38:39]
	v_pk_mul_f32 v[34:35], v[198:199], v[34:35]
	v_pk_mul_f32 v[32:33], v[196:197], v[32:33]
	v_pk_mul_f32 v[28:29], v[134:135], v[28:29]
	v_pk_mul_f32 v[24:25], v[130:131], v[24:25]
	v_pk_mul_f32 v[20:21], v[192:193], v[20:21]
	v_pk_mul_f32 v[30:31], v[136:137], v[30:31]
	v_pk_mul_f32 v[26:27], v[132:133], v[26:27]
	v_pk_mul_f32 v[22:23], v[194:195], v[22:23]
	v_pk_mul_f32 v[18:19], v[198:199], v[18:19]
	v_pk_mul_f32 v[16:17], v[196:197], v[16:17]

; __host__ __device__ __forceinline__ int lds_byte(int r, int c) { return (r >> 3) * 1024 + (r & 7) * 128 + ((((c >> 3)) ^ ((r >> 1) & 7)) << 4) + (c & 7) * 2; }
; #define PG8_STAGE(bufoff, gbase, voff) do { _Pragma("unroll") for (int _i = 0; _i < 2; ++_i) \
;         dma16((const char*)(gbase), (voff)[_i], ldsb + (bufoff) + ldsw + _i * 8192); } while (0)
; #define PG8_WAIT_V(n) asm volatile("s_waitcnt vmcnt(" #n ")" ::: "memory")
; #define PG8_BAR __builtin_amdgcn_s_barrier()
; template <class Epi>
; __device__ __forceinline__ void gemm_phase(LAS unsigned char* lds, const Gemm g, const StaticOrder& S, const Epi& E, int wave_) {
;     ...
;     for (int i = 0; i < 2; ++i) { int R, C; stage_rc(tid * 16 + i * 8192, R, C); const int Rb = (R & ~31) + perm32(R & 31);
;         voffA[i] = (unsigned)(R * g.lda + C) * 2u; voffB[i] = (unsigned)(Rb * g.ldb + C) * 2u; }
;     const size_t kstep = (size_t)(BK * 2);
;     const size_t hstepA = (size_t)HALF * g.lda * 2, hstepB = (size_t)HALF * g.ldb * 2;
;     const size_t tstepA = 2 * hstepA, tstepB = 2 * hstepB;
;     const unsigned ldsw = (unsigned)wid * 1024u, ldsb = (unsigned)(uintptr_t)lds;
;     const int aoff0 = lds_byte(wr * 64 + fr, fq * 8), boff0 = lds_byte(wc * 32 + fr, fq * 8);
;     ...
;     Unit cur, nxt; int ui = 0;
;     if (!S.next(0, cur)) return;
;     f32x4 acc[2][2][4][2];
; #pragma unroll
;     for (int a = 0; a < 2; ++a)
; #pragma unroll
;         for (int b = 0; b < 2; ++b)
; #pragma unroll
;             for (int m = 0; m < 4; ++m)
; #pragma unroll
;                 for (int n = 0; n < 2; ++n) acc[a][b][m][n] = (f32x4){0.f, 0.f, 0.f, 0.f};
;     bf16x8 At[4][2], B0[2][2], B1[2][2];
;     const char* cA = (const char*)g.A + (size_t)cur.pm * tstepA; const char* cB = (const char*)g.Bt + (size_t)cur.pn * tstepB;
;     PG8_STAGE(PG8_SB(0, 0), cB, voffB); PG8_STAGE(PG8_SB(0, 1), cB + hstepB, voffB); PG8_STAGE(PG8_SA(0, 0), cA, voffA); PG8_STAGE(PG8_SA(0, 1), cA + hstepA, voffA);
;     if (wr == 1) PG8_BAR;
;     PG8_WAIT_V(2); PG8_BAR;
;     PG8_STAGE(PG8_SB(1, 0), cB + kstep, voffB); PG8_STAGE(PG8_SA(1, 0), cA + kstep, voffA); PG8_STAGE(PG8_SB(1, 1), cB + hstepB + kstep, voffB);
;     PG8_WAIT_V(6); PG8_BAR;
.LBB0_1091:
	s_or_b64 exec, exec, s[4:5]
	v_readlane_b32 s16, v255, 22
	s_lshl_b32 s16, s16, 1
	s_ashr_i32 s17, s16, 31
	v_writelane_b32 v255, s16, 37
	v_readlane_b32 s8, v252, 12
	v_readlane_b32 s9, v252, 13
	v_writelane_b32 v255, s17, 38
	s_lshl_b64 s[16:17], s[16:17], 15
	v_writelane_b32 v255, s16, 29
	s_mov_b64 s[10:11], s[8:9]
	s_mov_b64 s[12:13], s[8:9]
	v_writelane_b32 v255, s17, 30
	v_readlane_b32 s16, v253, 49
	v_readlane_b32 s17, v253, 50
	s_andn2_b64 vcc, exec, s[16:17]
	s_mov_b64 s[4:5], s[8:9]
	v_cndmask_b32_e64 v1, 0, 1, s[16:17]
	v_readlane_b32 s16, v253, 11
	v_readlane_b32 s17, v253, 12
	v_cmp_ne_u32_e64 s[66:67], 1, v1
	s_mov_b64 s[6:7], s[8:9]
	v_cndmask_b32_e64 v1, 0, 1, s[16:17]
	v_mov_b32_e32 v0, v220
	v_cmp_ne_u32_e64 s[38:39], 1, v1
	s_cbranch_vccnz .LBB0_1127
	v_bfe_i32 v3, v0, 27, 1
	v_lshlrev_b32_e32 v1, 4, v0
	v_lshrrev_b32_e32 v4, 22, v3
	v_add_u32_e32 v4, v1, v4
	v_and_b32_e32 v4, 0xfc00, v4
	v_sub_u32_e32 v4, v1, v4
	v_ashrrev_i16_e32 v5, 15, v4
	v_ashrrev_i32_e32 v2, 31, v0
	v_lshrrev_b16_e32 v5, 9, v5
	v_lshrrev_b32_e32 v3, 25, v3
	v_lshrrev_b32_e32 v2, 26, v2
	v_add_u16_e32 v4, v4, v5
	v_add_u32_e32 v3, v1, v3
	s_add_u32 s21, s10, 0x10000000
	v_add_u32_e32 v2, v0, v2
	v_ashrrev_i16_e32 v4, 7, v4
	v_and_b32_e32 v3, 0x80, v3
	s_addc_u32 s46, s11, 0
	v_readlane_b32 s10, v255, 24
	v_ashrrev_i32_e32 v2, 6, v2
	v_bfe_i32 v4, v4, 0, 16
	v_sub_u32_e32 v3, v1, v3
	v_mov_b32_e32 v7, 4
	s_add_u32 s10, s12, s10
	v_ashrrev_i16_sdwa v3, v7, sext(v3) dst_sel:DWORD dst_unused:UNUSED_PAD src0_sel:DWORD src1_sel:BYTE_0
	v_lshl_add_u32 v2, v2, 3, v4
	s_addc_u32 s11, s13, 0
	v_bfe_i32 v3, v3, 0, 16
	v_lshrrev_b32_e32 v5, 1, v2
	s_add_u32 s47, s10, 0x2800000
	v_bitop3_b32 v3, v5, v3, 7 bitop3:0x6c
	v_lshlrev_b32_e32 v5, 1, v2
	v_lshrrev_b32_e32 v6, 2, v2
	v_and_b32_e32 v4, 3, v4
	s_mov_b32 s10, 0xfffe0
	v_lshlrev_b32_e32 v3, 4, v3
	v_and_b32_e32 v5, 24, v5
	v_and_b32_e32 v6, 4, v6
	v_and_or_b32 v4, v2, s10, v4
	v_add_u32_e32 v1, 0x2000, v1
	v_or3_b32 v4, v4, v6, v5
	v_lshl_add_u32 v166, v2, 12, v3
	v_ashrrev_i32_e32 v2, 31, v1
	v_lshl_add_u32 v167, v4, 12, v3
	v_lshrrev_b32_e32 v3, 22, v2
	v_add_u32_e32 v3, v1, v3
	v_ashrrev_i32_e32 v3, 10, v3
	v_mul_i32_i24_e32 v4, 0x400, v3
	v_sub_u32_e32 v4, v1, v4
	v_ashrrev_i16_e32 v5, 15, v4
	v_lshrrev_b16_e32 v5, 9, v5
	v_lshrrev_b32_e32 v2, 25, v2
	v_add_u16_e32 v4, v4, v5
	v_add_u32_e32 v2, v1, v2
	v_ashrrev_i16_e32 v4, 7, v4
	v_and_b32_e32 v2, 0x80, v2
	v_bfe_i32 v4, v4, 0, 16
	v_sub_u32_e32 v1, v1, v2
	v_ashrrev_i16_sdwa v1, v7, sext(v1) dst_sel:DWORD dst_unused:UNUSED_PAD src0_sel:DWORD src1_sel:BYTE_0
	v_lshl_add_u32 v2, v3, 3, v4
	v_bfe_i32 v1, v1, 0, 16
	v_lshrrev_b32_e32 v3, 1, v2
	v_and_b32_e32 v4, 3, v4
	s_addc_u32 s48, s11, 0
	v_bitop3_b32 v1, v3, v1, 7 bitop3:0x6c
	v_lshlrev_b32_e32 v3, 1, v2
	v_lshrrev_b32_e32 v5, 2, v2
	v_and_or_b32 v4, v2, s10, v4
	v_readlane_b32 s10, v254, 13
	v_and_b32_e32 v3, 24, v3
	v_and_b32_e32 v5, 4, v5
	v_readlane_b32 s11, v254, 14
	s_add_u32 s12, s47, s10
	v_lshlrev_b32_e32 v1, 4, v1
	v_or3_b32 v3, v4, v5, v3
	s_addc_u32 s13, s48, s11
	s_mov_b32 m0, s80
	s_nop 0
	global_load_lds_dwordx4 v167, s[12:13]
	v_lshl_add_u32 v169, v3, 12, v1
	s_mov_b32 m0, s81
	s_nop 0
	global_load_lds_dwordx4 v169, s[12:13]
	s_add_u32 s10, s12, 0x80000
	s_addc_u32 s11, s13, 0
	s_mov_b32 m0, s29
	s_nop 0
	global_load_lds_dwordx4 v167, s[10:11]
	v_lshl_add_u32 v168, v2, 12, v1
	s_mov_b32 m0, s88
	s_nop 0
	global_load_lds_dwordx4 v169, s[10:11]
	v_readlane_b32 s10, v254, 39
	v_readlane_b32 s11, v254, 40
	s_add_u32 s30, s21, s10
	s_addc_u32 s31, s46, s11
	s_mov_b32 m0, s76
	s_nop 0
	global_load_lds_dwordx4 v166, s[30:31]
	s_nop 0
	s_mov_b32 m0, s89
	s_nop 0
	global_load_lds_dwordx4 v168, s[30:31]
	s_add_u32 s10, s30, 0x80000
	s_addc_u32 s11, s31, 0
	s_mov_b32 m0, s1
	s_nop 0
	global_load_lds_dwordx4 v166, s[10:11]
	s_and_b64 vcc, exec, s[38:39]
	s_mov_b32 m0, s69
	s_nop 0
	global_load_lds_dwordx4 v168, s[10:11]
	s_cbranch_vccnz .LBB0_1094
	s_barrier
.LBB0_1094:
	s_add_u32 s4, s4, 0x8000000
	s_addc_u32 s5, s5, 0
	v_readlane_b32 s10, v255, 29
	s_add_u32 s6, s6, 0x8000000
	v_readlane_b32 s11, v255, 30
	s_addc_u32 s7, s7, 0
	s_lshl_b64 s[10:11], s[10:11], 3
	s_add_u32 s8, s8, s10
	s_addc_u32 s9, s9, s11
	s_add_u32 s8, s8, 0x100000
	s_addc_u32 s9, s9, 0
	v_and_b32_e32 v2, 15, v0
	v_readlane_b32 s10, v253, 6
	s_waitcnt vmcnt(2)
	s_barrier
	v_lshrrev_b32_e32 v1, 4, v0
	v_or_b32_e32 v170, s10, v2
	s_add_u32 s10, s12, 0x80
	s_addc_u32 s11, s13, 0
	s_mov_b32 m0, s35
	s_nop 0
	global_load_lds_dwordx4 v167, s[10:11]
	v_bfe_u32 v3, v0, 4, 2
	s_mov_b32 m0, s33
	s_nop 0
	global_load_lds_dwordx4 v169, s[10:11]
	s_add_u32 s10, s30, 0x80
	s_addc_u32 s11, s31, 0
	s_mov_b32 m0, s22
	s_nop 0
	global_load_lds_dwordx4 v166, s[10:11]
	v_bfe_u32 v0, v0, 1, 3
	s_mov_b32 m0, s2
	s_nop 0
	global_load_lds_dwordx4 v168, s[10:11]
	s_add_u32 s10, s12, 0x80080
	s_addc_u32 s11, s13, 0
	s_mov_b32 m0, s77
	s_nop 0
	global_load_lds_dwordx4 v167, s[10:11]
	v_bitop3_b32 v0, v1, v0, 3 bitop3:0x6c
	s_mov_b32 m0, s3
	s_nop 0
	global_load_lds_dwordx4 v169, s[10:11]
	v_readlane_b32 s17, v253, 7
	s_waitcnt vmcnt(6)
	v_lshlrev_b32_e32 v0, 4, v0
	v_readlane_b32 s10, v254, 37
	v_or_b32_e32 v1, s17, v2
	v_lshl_or_b32 v171, v170, 7, v0
	v_lshl_or_b32 v172, v1, 7, v0
	s_mov_b32 s49, 0
	v_cmp_eq_u32_e64 s[42:43], 0, v3
	v_lshl_or_b32 v173, v3, 3, s17
	v_readlane_b32 s52, v254, 4
	s_mov_b32 s54, s10
	s_barrier
	v_readlane_b32 s11, v254, 38
	s_branch .LBB0_1097

; #define PG8_STAGE(bufoff, gbase, voff) do { _Pragma("unroll") for (int _i = 0; _i < 2; ++_i) \
;         dma16((const char*)(gbase), (voff)[_i], ldsb + (bufoff) + ldsw + _i * 8192); } while (0)
; #define PG8_LDA(dst, b, h) do { const int a1_ = opqv(aoff0) ^ 64; _Pragma("unroll") for (int m = 0; m < 4; ++m) { dst[m][0] = *(const LAS bf16x8*)(lds + PG8_SA(b, h) + aoff0 + m * 2048); dst[m][1] = *(const LAS bf16x8*)(lds + PG8_SA(b, h) + a1_ + m * 2048); } } while (0)
; #define PG8_LDB(dst, b, h) do { const int b1_ = opqv(boff0) ^ 64; _Pragma("unroll") for (int n = 0; n < 2; ++n) { dst[n][0] = *(const LAS bf16x8*)(lds + PG8_SB(b, h) + boff0 + n * 2048); dst[n][1] = *(const LAS bf16x8*)(lds + PG8_SB(b, h) + b1_ + n * 2048); } } while (0)
; #define PG8_MMA(ai, bj, At, Bt) do { __builtin_amdgcn_s_setprio(1); _Pragma("unroll") for (int m = 0; m < 4; ++m) _Pragma("unroll") for (int n = 0; n < 2; ++n) _Pragma("unroll") for (int k = 0; k < 2; ++k) \
;         acc[ai][bj][m][n] = __builtin_amdgcn_mfma_f32_16x16x32_bf16(Bt[n][k], At[m][k], acc[ai][bj][m][n], 0, 0, 0); __builtin_amdgcn_s_setprio(0); } while (0)
; #define PG8_WAIT_V(n) asm volatile("s_waitcnt vmcnt(" #n ")" ::: "memory")
; #define PG8_WAIT_L(n) asm volatile("s_waitcnt lgkmcnt(" #n ")" ::: "memory")
; #define PG8_BAR __builtin_amdgcn_s_barrier()
; #define PG8_SCHED __builtin_amdgcn_sched_barrier(0)
; template <class Epi>
; __device__ __forceinline__ void gemm_phase(LAS unsigned char* lds, const Gemm g, const StaticOrder& S, const Epi& E, int wave_) {
;     ...
;             PG8_STAGE(PG8_SA(1, 1), a1 + hstepA, voffA); PG8_LDB(B0, 0, 0); PG8_LDB(B1, 0, 1); PG8_SCHED; PG8_LDA(At, 0, 0);
;             PG8_WAIT_V(8); PG8_WAIT_L(0); PG8_BAR; PG8_MMA(0, 0, At, B0); PG8_MMA(0, 1, At, B1); PG8_BAR; PG8_SCHED;
;             PG8_STAGE(PG8_SB(0, 0), b2, voffB); PG8_STAGE(PG8_SB(0, 1), b2 + hstepB, voffB); PG8_STAGE(PG8_SA(0, 0), a2, voffA); PG8_LDA(At, 0, 1);
;             PG8_WAIT_V(8); PG8_WAIT_L(0); PG8_BAR; PG8_MMA(1, 0, At, B0); PG8_MMA(1, 1, At, B1); PG8_BAR; PG8_SCHED;
.LBB0_1104:
	s_add_u32 s30, s12, 0xfff80080
	s_addc_u32 s31, s13, -1
	s_cmp_eq_u32 s57, 28
	s_cselect_b32 s40, s17, s30
	s_cselect_b32 s41, s16, s31
	s_cselect_b32 s36, s19, s55
	s_cselect_b32 s37, s11, s56
	s_add_u32 s30, s40, 0x80
	v_mov_b32_e32 v128, v172
	s_addc_u32 s31, s41, 0
	v_add_u32_e32 v132, s23, v172
	v_xad_u32 v140, v128, 64, s23
	v_mov_b32_e32 v144, v172
	s_add_i32 s60, 0, 0x14000
	ds_read_b128 v[128:131], v132
	ds_read_b128 v[132:135], v132 offset:2048
	ds_read_b128 v[136:139], v140
	ds_read_b128 v[140:143], v140 offset:2048
	v_add_u32_e32 v148, s60, v172
	v_xad_u32 v156, v144, 64, s60
	ds_read_b128 v[144:147], v148
	ds_read_b128 v[148:151], v148 offset:2048
	ds_read_b128 v[152:155], v156
	ds_read_b128 v[156:159], v156 offset:2048
	v_mov_b32_e32 v160, v171
	v_add_u32_e32 v183, 0, v171
	v_xad_u32 v182, v160, 64, 0
	ds_read_b128 v[160:163], v183
	ds_read_b128 v[174:177], v183 offset:2048
	ds_read_b128 v[178:181], v182
	ds_read_b128 v[192:195], v182 offset:2048
	ds_read_b128 v[196:199], v183 offset:4096
	ds_read_b128 v[200:203], v183 offset:6144
	ds_read_b128 v[204:207], v182 offset:4096
	ds_read_b128 v[208:211], v182 offset:6144
	s_mov_b32 m0, s14
	s_nop 0
	global_load_lds_dwordx4 v166, s[12:13]
	s_mov_b32 m0, s15
	s_nop 0
	global_load_lds_dwordx4 v168, s[12:13]
	s_waitcnt vmcnt(8)
	s_waitcnt lgkmcnt(0)
	s_barrier
	s_setprio 1
	s_waitcnt lgkmcnt(0)
	v_mfma_f32_16x16x32_bf16 v[124:127], v[128:131], v[160:163], v[124:127]
	v_mfma_f32_16x16x32_bf16 v[120:123], v[132:135], v[160:163], v[120:123]
	v_mfma_f32_16x16x32_bf16 v[108:111], v[128:131], v[174:177], v[108:111]
	v_mfma_f32_16x16x32_bf16 v[104:107], v[132:135], v[174:177], v[104:107]
	v_mfma_f32_16x16x32_bf16 v[92:95], v[128:131], v[196:199], v[92:95]
	v_mfma_f32_16x16x32_bf16 v[88:91], v[132:135], v[196:199], v[88:91]
	v_mfma_f32_16x16x32_bf16 v[76:79], v[128:131], v[200:203], v[76:79]
	v_mfma_f32_16x16x32_bf16 v[72:75], v[132:135], v[200:203], v[72:75]
	v_mfma_f32_16x16x32_bf16 v[124:127], v[136:139], v[178:181], v[124:127]
	v_mfma_f32_16x16x32_bf16 v[120:123], v[140:143], v[178:181], v[120:123]
	v_mfma_f32_16x16x32_bf16 v[108:111], v[136:139], v[192:195], v[108:111]
	v_mfma_f32_16x16x32_bf16 v[104:107], v[140:143], v[192:195], v[104:107]
	v_mfma_f32_16x16x32_bf16 v[92:95], v[136:139], v[204:207], v[92:95]
	v_mfma_f32_16x16x32_bf16 v[88:91], v[140:143], v[204:207], v[88:91]
	v_mfma_f32_16x16x32_bf16 v[76:79], v[136:139], v[208:211], v[76:79]
	v_mfma_f32_16x16x32_bf16 v[72:75], v[140:143], v[208:211], v[72:75]
	s_setprio 0
	s_setprio 1
	v_mfma_f32_16x16x32_bf16 v[116:119], v[144:147], v[160:163], v[116:119]
	v_mfma_f32_16x16x32_bf16 v[112:115], v[148:151], v[160:163], v[112:115]
	v_mfma_f32_16x16x32_bf16 v[100:103], v[144:147], v[174:177], v[100:103]
	v_mfma_f32_16x16x32_bf16 v[96:99], v[148:151], v[174:177], v[96:99]
	v_mfma_f32_16x16x32_bf16 v[84:87], v[144:147], v[196:199], v[84:87]
	v_mfma_f32_16x16x32_bf16 v[80:83], v[148:151], v[196:199], v[80:83]
	v_mfma_f32_16x16x32_bf16 v[68:71], v[144:147], v[200:203], v[68:71]
	v_mfma_f32_16x16x32_bf16 v[64:67], v[148:151], v[200:203], v[64:67]
	v_mfma_f32_16x16x32_bf16 v[116:119], v[152:155], v[178:181], v[116:119]
	v_mfma_f32_16x16x32_bf16 v[112:115], v[156:159], v[178:181], v[112:115]
	v_mfma_f32_16x16x32_bf16 v[100:103], v[152:155], v[192:195], v[100:103]
	v_mfma_f32_16x16x32_bf16 v[96:99], v[156:159], v[192:195], v[96:99]
	v_mfma_f32_16x16x32_bf16 v[84:87], v[152:155], v[204:207], v[84:87]
	v_mfma_f32_16x16x32_bf16 v[80:83], v[156:159], v[204:207], v[80:83]
	v_mfma_f32_16x16x32_bf16 v[68:71], v[152:155], v[208:211], v[68:71]
	v_mfma_f32_16x16x32_bf16 v[64:67], v[156:159], v[208:211], v[64:67]
	s_setprio 0
	s_barrier
	v_mov_b32_e32 v160, v171
	s_add_u32 s60, s36, 0x80000
	s_addc_u32 s61, s37, 0
	s_nop 0
	s_nop 0
	s_nop 0
	v_xad_u32 v182, v160, 64, 0
	ds_read_b128 v[160:163], v183 offset:16384
	ds_read_b128 v[174:177], v183 offset:18432
	ds_read_b128 v[178:181], v182 offset:16384
	ds_read_b128 v[192:195], v182 offset:18432
	ds_read_b128 v[196:199], v183 offset:20480
	ds_read_b128 v[200:203], v183 offset:22528
	ds_read_b128 v[204:207], v182 offset:20480
	ds_read_b128 v[208:211], v182 offset:22528
	s_mov_b32 m0, s80
	s_nop 0
	global_load_lds_dwordx4 v167, s[36:37]
	s_mov_b32 m0, s81
	s_nop 0
	global_load_lds_dwordx4 v169, s[36:37]
	s_mov_b32 m0, s29
	s_nop 0
	global_load_lds_dwordx4 v167, s[60:61]
	s_mov_b32 m0, s88
	s_nop 0
	global_load_lds_dwordx4 v169, s[60:61]
	s_mov_b32 m0, s76
	s_nop 0
	global_load_lds_dwordx4 v166, s[40:41]
	s_mov_b32 m0, s89
	s_nop 0
	global_load_lds_dwordx4 v168, s[40:41]
	s_waitcnt vmcnt(8)
	s_waitcnt lgkmcnt(0)
	s_barrier
; #define PG8_STAGE(bufoff, gbase, voff) do { _Pragma("unroll") for (int _i = 0; _i < 2; ++_i) \
;         dma16((const char*)(gbase), (voff)[_i], ldsb + (bufoff) + ldsw + _i * 8192); } while (0)
; #define PG8_LDA(dst, b, h) do { const int a1_ = opqv(aoff0) ^ 64; _Pragma("unroll") for (int m = 0; m < 4; ++m) { dst[m][0] = *(const LAS bf16x8*)(lds + PG8_SA(b, h) + aoff0 + m * 2048); dst[m][1] = *(const LAS bf16x8*)(lds + PG8_SA(b, h) + a1_ + m * 2048); } } while (0)
; #define PG8_LDB(dst, b, h) do { const int b1_ = opqv(boff0) ^ 64; _Pragma("unroll") for (int n = 0; n < 2; ++n) { dst[n][0] = *(const LAS bf16x8*)(lds + PG8_SB(b, h) + boff0 + n * 2048); dst[n][1] = *(const LAS bf16x8*)(lds + PG8_SB(b, h) + b1_ + n * 2048); } } while (0)
; #define PG8_MMA(ai, bj, At, Bt) do { __builtin_amdgcn_s_setprio(1); _Pragma("unroll") for (int m = 0; m < 4; ++m) _Pragma("unroll") for (int n = 0; n < 2; ++n) _Pragma("unroll") for (int k = 0; k < 2; ++k) \
;         acc[ai][bj][m][n] = __builtin_amdgcn_mfma_f32_16x16x32_bf16(Bt[n][k], At[m][k], acc[ai][bj][m][n], 0, 0, 0); __builtin_amdgcn_s_setprio(0); } while (0)
; #define PG8_WAIT_V(n) asm volatile("s_waitcnt vmcnt(" #n ")" ::: "memory")
; #define PG8_WAIT_L(n) asm volatile("s_waitcnt lgkmcnt(" #n ")" ::: "memory")
; #define PG8_BAR __builtin_amdgcn_s_barrier()
; #define PG8_SCHED __builtin_amdgcn_sched_barrier(0)
; template <class Epi>
; __device__ __forceinline__ void gemm_phase(LAS unsigned char* lds, const Gemm g, const StaticOrder& S, const Epi& E, int wave_) {
;     ...
;             PG8_WAIT_V(8); PG8_WAIT_L(0); PG8_BAR; PG8_MMA(1, 0, At, B0); PG8_MMA(1, 1, At, B1); PG8_BAR; PG8_SCHED;
;             PG8_STAGE(PG8_SA(0, 1), a2 + hstepA, voffA); PG8_LDB(B0, 1, 0); PG8_LDB(B1, 1, 1); PG8_SCHED; PG8_LDA(At, 1, 0);
;             PG8_WAIT_V(8); PG8_WAIT_L(0); PG8_BAR; PG8_MMA(0, 0, At, B0); PG8_MMA(0, 1, At, B1); PG8_BAR; PG8_SCHED;
;             PG8_STAGE(PG8_SB(1, 0), b3, voffB); PG8_STAGE(PG8_SB(1, 1), b3 + hstepB, voffB); PG8_STAGE(PG8_SA(1, 0), a3, voffA); PG8_LDA(At, 1, 1);
	s_setprio 1
	s_waitcnt lgkmcnt(0)
	v_mfma_f32_16x16x32_bf16 v[60:63], v[128:131], v[160:163], v[60:63]
	v_mfma_f32_16x16x32_bf16 v[56:59], v[132:135], v[160:163], v[56:59]
	v_mfma_f32_16x16x32_bf16 v[44:47], v[128:131], v[174:177], v[44:47]
	v_mfma_f32_16x16x32_bf16 v[40:43], v[132:135], v[174:177], v[40:43]
	v_mfma_f32_16x16x32_bf16 v[28:31], v[128:131], v[196:199], v[28:31]
	v_mfma_f32_16x16x32_bf16 v[24:27], v[132:135], v[196:199], v[24:27]
	v_mfma_f32_16x16x32_bf16 v[12:15], v[128:131], v[200:203], v[12:15]
	v_mfma_f32_16x16x32_bf16 v[8:11], v[132:135], v[200:203], v[8:11]
	v_mfma_f32_16x16x32_bf16 v[60:63], v[136:139], v[178:181], v[60:63]
	v_mfma_f32_16x16x32_bf16 v[56:59], v[140:143], v[178:181], v[56:59]
	v_mfma_f32_16x16x32_bf16 v[44:47], v[136:139], v[192:195], v[44:47]
	v_mfma_f32_16x16x32_bf16 v[40:43], v[140:143], v[192:195], v[40:43]
	v_mfma_f32_16x16x32_bf16 v[28:31], v[136:139], v[204:207], v[28:31]
	v_mfma_f32_16x16x32_bf16 v[24:27], v[140:143], v[204:207], v[24:27]
	v_mfma_f32_16x16x32_bf16 v[12:15], v[136:139], v[208:211], v[12:15]
	v_mfma_f32_16x16x32_bf16 v[8:11], v[140:143], v[208:211], v[8:11]
	s_setprio 0
	s_setprio 1
	v_mfma_f32_16x16x32_bf16 v[52:55], v[144:147], v[160:163], v[52:55]
	v_mfma_f32_16x16x32_bf16 v[48:51], v[148:151], v[160:163], v[48:51]
	v_mfma_f32_16x16x32_bf16 v[36:39], v[144:147], v[174:177], v[36:39]
	v_mfma_f32_16x16x32_bf16 v[32:35], v[148:151], v[174:177], v[32:35]
	v_mfma_f32_16x16x32_bf16 v[20:23], v[144:147], v[196:199], v[20:23]
	v_mfma_f32_16x16x32_bf16 v[16:19], v[148:151], v[196:199], v[16:19]
	v_mfma_f32_16x16x32_bf16 v[4:7], v[144:147], v[200:203], v[4:7]
	v_mfma_f32_16x16x32_bf16 v[0:3], v[148:151], v[200:203], v[0:3]
	v_mfma_f32_16x16x32_bf16 v[52:55], v[152:155], v[178:181], v[52:55]
	v_mfma_f32_16x16x32_bf16 v[48:51], v[156:159], v[178:181], v[48:51]
	v_mfma_f32_16x16x32_bf16 v[36:39], v[152:155], v[192:195], v[36:39]
	v_mfma_f32_16x16x32_bf16 v[32:35], v[156:159], v[192:195], v[32:35]
	v_mfma_f32_16x16x32_bf16 v[20:23], v[152:155], v[204:207], v[20:23]
	v_mfma_f32_16x16x32_bf16 v[16:19], v[156:159], v[204:207], v[16:19]
	v_mfma_f32_16x16x32_bf16 v[4:7], v[152:155], v[208:211], v[4:7]
	v_mfma_f32_16x16x32_bf16 v[0:3], v[156:159], v[208:211], v[0:3]
	s_setprio 0
	s_barrier
	s_add_u32 s40, s40, 0x80000
	s_addc_u32 s41, s41, 0
	s_mov_b32 m0, s1
	s_nop 0
	global_load_lds_dwordx4 v166, s[40:41]
	v_mov_b32_e32 v128, v172
	s_mov_b32 m0, s69
	s_nop 0
	global_load_lds_dwordx4 v168, s[40:41]
	v_add_u32_e32 v132, s34, v172
	v_xad_u32 v140, v128, 64, s34
	v_mov_b32_e32 v144, v172
	s_add_i32 s40, 0, 0x1c000
	ds_read_b128 v[128:131], v132
	ds_read_b128 v[132:135], v132 offset:2048
	ds_read_b128 v[136:139], v140
	ds_read_b128 v[140:143], v140 offset:2048
	v_add_u32_e32 v148, s40, v172
	v_xad_u32 v156, v144, 64, s40
	ds_read_b128 v[144:147], v148
	ds_read_b128 v[148:151], v148 offset:2048
	ds_read_b128 v[152:155], v156
	ds_read_b128 v[156:159], v156 offset:2048
	v_mov_b32_e32 v160, v171
	s_nop 0
	v_xad_u32 v182, v160, 64, 0
	ds_read_b128 v[160:163], v183 offset:32768
	ds_read_b128 v[174:177], v183 offset:34816
	ds_read_b128 v[178:181], v182 offset:32768
	ds_read_b128 v[192:195], v182 offset:34816
	ds_read_b128 v[196:199], v183 offset:36864
	ds_read_b128 v[200:203], v183 offset:38912
	ds_read_b128 v[204:207], v182 offset:36864
	ds_read_b128 v[208:211], v182 offset:38912
	s_waitcnt vmcnt(8)
	s_waitcnt lgkmcnt(0)
	s_barrier
	s_setprio 1
	s_waitcnt lgkmcnt(0)
	v_mfma_f32_16x16x32_bf16 v[124:127], v[128:131], v[160:163], v[124:127]
	v_mfma_f32_16x16x32_bf16 v[120:123], v[132:135], v[160:163], v[120:123]
	v_mfma_f32_16x16x32_bf16 v[108:111], v[128:131], v[174:177], v[108:111]
	v_mfma_f32_16x16x32_bf16 v[104:107], v[132:135], v[174:177], v[104:107]
	v_mfma_f32_16x16x32_bf16 v[92:95], v[128:131], v[196:199], v[92:95]
	v_mfma_f32_16x16x32_bf16 v[88:91], v[132:135], v[196:199], v[88:91]
	v_mfma_f32_16x16x32_bf16 v[76:79], v[128:131], v[200:203], v[76:79]
	v_mfma_f32_16x16x32_bf16 v[72:75], v[132:135], v[200:203], v[72:75]
	v_mfma_f32_16x16x32_bf16 v[124:127], v[136:139], v[178:181], v[124:127]
	v_mfma_f32_16x16x32_bf16 v[120:123], v[140:143], v[178:181], v[120:123]
	v_mfma_f32_16x16x32_bf16 v[108:111], v[136:139], v[192:195], v[108:111]
	v_mfma_f32_16x16x32_bf16 v[104:107], v[140:143], v[192:195], v[104:107]
	v_mfma_f32_16x16x32_bf16 v[92:95], v[136:139], v[204:207], v[92:95]
	v_mfma_f32_16x16x32_bf16 v[88:91], v[140:143], v[204:207], v[88:91]
	v_mfma_f32_16x16x32_bf16 v[76:79], v[136:139], v[208:211], v[76:79]
	v_mfma_f32_16x16x32_bf16 v[72:75], v[140:143], v[208:211], v[72:75]
	s_setprio 0
	s_setprio 1
	v_mfma_f32_16x16x32_bf16 v[116:119], v[144:147], v[160:163], v[116:119]
	s_add_u32 s40, s36, 0x80
	s_addc_u32 s41, s37, 0
	v_mfma_f32_16x16x32_bf16 v[112:115], v[148:151], v[160:163], v[112:115]
	v_mfma_f32_16x16x32_bf16 v[100:103], v[144:147], v[174:177], v[100:103]
	v_mfma_f32_16x16x32_bf16 v[96:99], v[148:151], v[174:177], v[96:99]
	v_mfma_f32_16x16x32_bf16 v[84:87], v[144:147], v[196:199], v[84:87]
	v_mfma_f32_16x16x32_bf16 v[80:83], v[148:151], v[196:199], v[80:83]
	v_mfma_f32_16x16x32_bf16 v[68:71], v[144:147], v[200:203], v[68:71]
	v_mfma_f32_16x16x32_bf16 v[64:67], v[148:151], v[200:203], v[64:67]
	v_mfma_f32_16x16x32_bf16 v[116:119], v[152:155], v[178:181], v[116:119]
	v_mfma_f32_16x16x32_bf16 v[112:115], v[156:159], v[178:181], v[112:115]
	v_mfma_f32_16x16x32_bf16 v[100:103], v[152:155], v[192:195], v[100:103]
	v_mfma_f32_16x16x32_bf16 v[96:99], v[156:159], v[192:195], v[96:99]
	v_mfma_f32_16x16x32_bf16 v[84:87], v[152:155], v[204:207], v[84:87]
	v_mfma_f32_16x16x32_bf16 v[80:83], v[156:159], v[204:207], v[80:83]
	v_mfma_f32_16x16x32_bf16 v[68:71], v[152:155], v[208:211], v[68:71]
	v_mfma_f32_16x16x32_bf16 v[64:67], v[156:159], v[208:211], v[64:67]
	s_setprio 0
	s_barrier
; #define PG8_STAGE(bufoff, gbase, voff) do { _Pragma("unroll") for (int _i = 0; _i < 2; ++_i) \
;         dma16((const char*)(gbase), (voff)[_i], ldsb + (bufoff) + ldsw + _i * 8192); } while (0)
; #define PG8_LDA(dst, b, h) do { const int a1_ = opqv(aoff0) ^ 64; _Pragma("unroll") for (int m = 0; m < 4; ++m) { dst[m][0] = *(const LAS bf16x8*)(lds + PG8_SA(b, h) + aoff0 + m * 2048); dst[m][1] = *(const LAS bf16x8*)(lds + PG8_SA(b, h) + a1_ + m * 2048); } } while (0)
; #define PG8_MMA(ai, bj, At, Bt) do { __builtin_amdgcn_s_setprio(1); _Pragma("unroll") for (int m = 0; m < 4; ++m) _Pragma("unroll") for (int n = 0; n < 2; ++n) _Pragma("unroll") for (int k = 0; k < 2; ++k) \
;         acc[ai][bj][m][n] = __builtin_amdgcn_mfma_f32_16x16x32_bf16(Bt[n][k], At[m][k], acc[ai][bj][m][n], 0, 0, 0); __builtin_amdgcn_s_setprio(0); } while (0)
; #define PG8_WAIT_V(n) asm volatile("s_waitcnt vmcnt(" #n ")" ::: "memory")
; #define PG8_WAIT_L(n) asm volatile("s_waitcnt lgkmcnt(" #n ")" ::: "memory")
; #define PG8_BAR __builtin_amdgcn_s_barrier()
; #define PG8_SCHED __builtin_amdgcn_sched_barrier(0)
; template <class Epi>
; __device__ __forceinline__ void gemm_phase(LAS unsigned char* lds, const Gemm g, const StaticOrder& S, const Epi& E, int wave_) {
;     ...
;             PG8_STAGE(PG8_SB(1, 0), b3, voffB); PG8_STAGE(PG8_SB(1, 1), b3 + hstepB, voffB); PG8_STAGE(PG8_SA(1, 0), a3, voffA); PG8_LDA(At, 1, 1);
;             PG8_WAIT_V(8); PG8_WAIT_L(0); PG8_BAR; PG8_MMA(1, 0, At, B0); PG8_MMA(1, 1, At, B1); PG8_BAR; PG8_SCHED;
;         }
;         if (wr == 0) PG8_BAR;
	s_add_u32 s36, s36, 0x80080
	s_addc_u32 s37, s37, 0
	v_mov_b32_e32 v160, v171
	s_nop 0
	s_nop 0
	v_xad_u32 v182, v160, 64, 0
	ds_read_b128 v[160:163], v183 offset:49152
	ds_read_b128 v[174:177], v183 offset:51200
	ds_read_b128 v[178:181], v182 offset:49152
	ds_read_b128 v[192:195], v182 offset:51200
	ds_read_b128 v[196:199], v183 offset:53248
	ds_read_b128 v[200:203], v183 offset:55296
	ds_read_b128 v[204:207], v182 offset:53248
	ds_read_b128 v[208:211], v182 offset:55296
	s_mov_b32 m0, s35
	s_nop 0
	global_load_lds_dwordx4 v167, s[40:41]
	s_mov_b32 m0, s33
	s_nop 0
	global_load_lds_dwordx4 v169, s[40:41]
	s_mov_b32 m0, s77
	s_nop 0
	global_load_lds_dwordx4 v167, s[36:37]
	s_mov_b32 m0, s3
	s_nop 0
	global_load_lds_dwordx4 v169, s[36:37]
	s_mov_b32 m0, s22
	s_nop 0
	global_load_lds_dwordx4 v166, s[30:31]
	s_mov_b32 m0, s2
	s_nop 0
	global_load_lds_dwordx4 v168, s[30:31]
	s_waitcnt vmcnt(8)
	s_waitcnt lgkmcnt(0)
	s_barrier
	s_setprio 1
	s_waitcnt lgkmcnt(0)
	v_mfma_f32_16x16x32_bf16 v[60:63], v[128:131], v[160:163], v[60:63]
	v_mfma_f32_16x16x32_bf16 v[56:59], v[132:135], v[160:163], v[56:59]
	v_mfma_f32_16x16x32_bf16 v[44:47], v[128:131], v[174:177], v[44:47]
	v_mfma_f32_16x16x32_bf16 v[40:43], v[132:135], v[174:177], v[40:43]
	v_mfma_f32_16x16x32_bf16 v[28:31], v[128:131], v[196:199], v[28:31]
	v_mfma_f32_16x16x32_bf16 v[24:27], v[132:135], v[196:199], v[24:27]
	v_mfma_f32_16x16x32_bf16 v[12:15], v[128:131], v[200:203], v[12:15]
	v_mfma_f32_16x16x32_bf16 v[8:11], v[132:135], v[200:203], v[8:11]
	v_mfma_f32_16x16x32_bf16 v[60:63], v[136:139], v[178:181], v[60:63]
	v_mfma_f32_16x16x32_bf16 v[56:59], v[140:143], v[178:181], v[56:59]
	v_mfma_f32_16x16x32_bf16 v[44:47], v[136:139], v[192:195], v[44:47]
	v_mfma_f32_16x16x32_bf16 v[40:43], v[140:143], v[192:195], v[40:43]
	v_mfma_f32_16x16x32_bf16 v[28:31], v[136:139], v[204:207], v[28:31]
	v_mfma_f32_16x16x32_bf16 v[24:27], v[140:143], v[204:207], v[24:27]
	v_mfma_f32_16x16x32_bf16 v[12:15], v[136:139], v[208:211], v[12:15]
	v_mfma_f32_16x16x32_bf16 v[8:11], v[140:143], v[208:211], v[8:11]
	s_setprio 0
	s_setprio 1
	v_mfma_f32_16x16x32_bf16 v[52:55], v[144:147], v[160:163], v[52:55]
	v_mfma_f32_16x16x32_bf16 v[48:51], v[148:151], v[160:163], v[48:51]
	v_mfma_f32_16x16x32_bf16 v[36:39], v[144:147], v[174:177], v[36:39]
	v_mfma_f32_16x16x32_bf16 v[32:35], v[148:151], v[174:177], v[32:35]
	v_mfma_f32_16x16x32_bf16 v[20:23], v[144:147], v[196:199], v[20:23]
	v_mfma_f32_16x16x32_bf16 v[16:19], v[148:151], v[196:199], v[16:19]
	v_mfma_f32_16x16x32_bf16 v[4:7], v[144:147], v[200:203], v[4:7]
	v_mfma_f32_16x16x32_bf16 v[0:3], v[148:151], v[200:203], v[0:3]
	v_mfma_f32_16x16x32_bf16 v[52:55], v[152:155], v[178:181], v[52:55]
	v_mfma_f32_16x16x32_bf16 v[48:51], v[156:159], v[178:181], v[48:51]
	v_mfma_f32_16x16x32_bf16 v[36:39], v[152:155], v[192:195], v[36:39]
	v_mfma_f32_16x16x32_bf16 v[32:35], v[156:159], v[192:195], v[32:35]
	v_mfma_f32_16x16x32_bf16 v[20:23], v[152:155], v[204:207], v[20:23]
	v_mfma_f32_16x16x32_bf16 v[16:19], v[156:159], v[204:207], v[16:19]
	v_mfma_f32_16x16x32_bf16 v[4:7], v[152:155], v[208:211], v[4:7]
	v_mfma_f32_16x16x32_bf16 v[0:3], v[156:159], v[208:211], v[0:3]
	s_setprio 0
	s_barrier
	s_add_i32 s57, s57, 2
	s_add_u32 s55, s55, 0x100
	s_addc_u32 s56, s56, 0
	s_add_u32 s12, s12, 0x100
	s_addc_u32 s13, s13, 0
	s_cmp_gt_u32 s57, 29
	s_cbranch_scc0 .LBB0_1104
	v_readlane_b32 s12, v253, 13
	v_readlane_b32 s13, v253, 14
	s_and_b64 vcc, exec, s[12:13]
	s_cbranch_vccz .LBB0_1107
	s_barrier

; __host__ __device__ __forceinline__ int lds_byte(int r, int c) { return (r >> 3) * 1024 + (r & 7) * 128 + ((((c >> 3)) ^ ((r >> 1) & 7)) << 4) + (c & 7) * 2; }
; #define PG8_STAGE(bufoff, gbase, voff) do { _Pragma("unroll") for (int _i = 0; _i < 2; ++_i) \
;         dma16((const char*)(gbase), (voff)[_i], ldsb + (bufoff) + ldsw + _i * 8192); } while (0)
; #define PG8_WAIT_V(n) asm volatile("s_waitcnt vmcnt(" #n ")" ::: "memory")
; #define PG8_BAR __builtin_amdgcn_s_barrier()
; template <class Epi>
; __device__ __forceinline__ void gemm_phase(LAS unsigned char* lds, const Gemm g, const StaticOrder& S, const Epi& E, int wave_) {
;     ...
;     for (int i = 0; i < 2; ++i) { int R, C; stage_rc(tid * 16 + i * 8192, R, C); const int Rb = (R & ~31) + perm32(R & 31);
;         voffA[i] = (unsigned)(R * g.lda + C) * 2u; voffB[i] = (unsigned)(Rb * g.ldb + C) * 2u; }
;     const size_t kstep = (size_t)(BK * 2);
;     const size_t hstepA = (size_t)HALF * g.lda * 2, hstepB = (size_t)HALF * g.ldb * 2;
;     const size_t tstepA = 2 * hstepA, tstepB = 2 * hstepB;
;     const unsigned ldsw = (unsigned)wid * 1024u, ldsb = (unsigned)(uintptr_t)lds;
;     const int aoff0 = lds_byte(wr * 64 + fr, fq * 8), boff0 = lds_byte(wc * 32 + fr, fq * 8);
;     ...
;     Unit cur, nxt; int ui = 0;
;     if (!S.next(0, cur)) return;
;     f32x4 acc[2][2][4][2];
; #pragma unroll
;     for (int a = 0; a < 2; ++a)
; #pragma unroll
;         for (int b = 0; b < 2; ++b)
; #pragma unroll
;             for (int m = 0; m < 4; ++m)
; #pragma unroll
;                 for (int n = 0; n < 2; ++n) acc[a][b][m][n] = (f32x4){0.f, 0.f, 0.f, 0.f};
;     bf16x8 At[4][2], B0[2][2], B1[2][2];
;     const char* cA = (const char*)g.A + (size_t)cur.pm * tstepA; const char* cB = (const char*)g.Bt + (size_t)cur.pn * tstepB;
;     PG8_STAGE(PG8_SB(0, 0), cB, voffB); PG8_STAGE(PG8_SB(0, 1), cB + hstepB, voffB); PG8_STAGE(PG8_SA(0, 0), cA, voffA); PG8_STAGE(PG8_SA(0, 1), cA + hstepA, voffA);
;     if (wr == 1) PG8_BAR;
;     PG8_WAIT_V(2); PG8_BAR;
;     PG8_STAGE(PG8_SB(1, 0), cB + kstep, voffB); PG8_STAGE(PG8_SA(1, 0), cA + kstep, voffA); PG8_STAGE(PG8_SB(1, 1), cB + hstepB + kstep, voffB);
;     PG8_WAIT_V(6); PG8_BAR;
.LBB0_1313:
	s_or_b64 exec, exec, s[4:5]
	v_readlane_b32 s4, v255, 22
	s_mul_hi_i32 s5, s4, 0x6800
	s_mulk_i32 s4, 0x6800
	v_readlane_b32 s10, v252, 12
	v_readlane_b32 s18, v253, 51
	v_writelane_b32 v255, s4, 31
	v_readlane_b32 s11, v252, 13
	v_readlane_b32 s19, v253, 52
	v_writelane_b32 v255, s5, 32
	s_mov_b64 s[12:13], s[10:11]
	s_mov_b64 s[16:17], s[10:11]
	s_mov_b64 s[4:5], s[10:11]
	s_mov_b64 s[6:7], s[10:11]
	s_mov_b64 s[8:9], s[10:11]
	v_mov_b32_e32 v0, v220
	s_and_b64 vcc, exec, s[18:19]
	s_barrier
	s_cbranch_vccz .LBB0_1329
	v_bfe_i32 v3, v0, 27, 1
	v_lshlrev_b32_e32 v1, 4, v0
	v_lshrrev_b32_e32 v4, 22, v3
	v_add_u32_e32 v4, v1, v4
	v_and_b32_e32 v4, 0xfc00, v4
	v_sub_u32_e32 v4, v1, v4
	v_ashrrev_i16_e32 v5, 15, v4
	v_ashrrev_i32_e32 v2, 31, v0
	v_lshrrev_b16_e32 v5, 9, v5
	v_lshrrev_b32_e32 v3, 25, v3
	v_lshrrev_b32_e32 v2, 26, v2
	v_add_u16_e32 v4, v4, v5
	v_add_u32_e32 v3, v1, v3
	s_add_u32 s21, s12, 0x8000000
	v_add_u32_e32 v2, v0, v2
	v_ashrrev_i16_e32 v4, 7, v4
	v_and_b32_e32 v3, 0x80, v3
	s_addc_u32 s46, s13, 0
	v_readlane_b32 s12, v255, 24
	v_ashrrev_i32_e32 v2, 6, v2
	v_bfe_i32 v4, v4, 0, 16
	v_sub_u32_e32 v3, v1, v3
	v_mov_b32_e32 v7, 4
	s_add_u32 s12, s16, s12
	v_ashrrev_i16_sdwa v3, v7, sext(v3) dst_sel:DWORD dst_unused:UNUSED_PAD src0_sel:DWORD src1_sel:BYTE_0
	v_lshl_add_u32 v2, v2, 3, v4
	s_addc_u32 s13, s17, 0
	v_bfe_i32 v3, v3, 0, 16
	v_lshrrev_b32_e32 v5, 1, v2
	s_add_u32 s47, s12, 0x3000000
	v_bitop3_b32 v3, v5, v3, 7 bitop3:0x6c
	v_lshlrev_b32_e32 v5, 1, v2
	v_lshrrev_b32_e32 v6, 2, v2
	v_and_b32_e32 v4, 3, v4
	s_mov_b32 s12, 0xfffe0
	v_lshlrev_b32_e32 v3, 4, v3
	v_and_b32_e32 v5, 24, v5
	v_and_b32_e32 v6, 4, v6
	v_and_or_b32 v4, v2, s12, v4
	v_add_u32_e32 v1, 0x2000, v1
	v_or3_b32 v4, v4, v6, v5
	v_lshl_add_u32 v172, v2, 12, v3
	v_ashrrev_i32_e32 v2, 31, v1
	v_lshl_add_u32 v173, v4, 12, v3
	v_lshrrev_b32_e32 v3, 22, v2
	v_add_u32_e32 v3, v1, v3
	v_ashrrev_i32_e32 v3, 10, v3
	v_mul_i32_i24_e32 v4, 0x400, v3
	v_sub_u32_e32 v4, v1, v4
	v_ashrrev_i16_e32 v5, 15, v4
	v_lshrrev_b16_e32 v5, 9, v5
	v_lshrrev_b32_e32 v2, 25, v2
	v_add_u16_e32 v4, v4, v5
	v_add_u32_e32 v2, v1, v2
	v_ashrrev_i16_e32 v4, 7, v4
	v_and_b32_e32 v2, 0x80, v2
	v_bfe_i32 v4, v4, 0, 16
	v_sub_u32_e32 v1, v1, v2
	v_ashrrev_i16_sdwa v1, v7, sext(v1) dst_sel:DWORD dst_unused:UNUSED_PAD src0_sel:DWORD src1_sel:BYTE_0
	v_lshl_add_u32 v2, v3, 3, v4
	v_bfe_i32 v1, v1, 0, 16
	v_lshrrev_b32_e32 v3, 1, v2
	v_and_b32_e32 v4, 3, v4
	s_addc_u32 s48, s13, 0
	v_bitop3_b32 v1, v3, v1, 7 bitop3:0x6c
	v_lshlrev_b32_e32 v3, 1, v2
	v_lshrrev_b32_e32 v5, 2, v2
	v_and_or_b32 v4, v2, s12, v4
	v_readlane_b32 s12, v254, 2
	v_and_b32_e32 v3, 24, v3
	v_and_b32_e32 v5, 4, v5
	v_readlane_b32 s13, v254, 3
	s_add_u32 s12, s47, s12
	v_lshlrev_b32_e32 v1, 4, v1
	v_or3_b32 v3, v4, v5, v3
	s_addc_u32 s13, s48, s13
	s_mov_b32 m0, s80
	s_nop 0
	global_load_lds_dwordx4 v173, s[12:13]
	v_lshl_add_u32 v175, v3, 12, v1
	s_mov_b32 m0, s81
	s_nop 0
	global_load_lds_dwordx4 v175, s[12:13]
	s_add_u32 s16, s12, 0x80000
	s_addc_u32 s17, s13, 0
	s_mov_b32 m0, s29
	s_nop 0
	global_load_lds_dwordx4 v173, s[16:17]
	v_lshl_add_u32 v174, v2, 12, v1
	s_mov_b32 m0, s88
	s_nop 0
	global_load_lds_dwordx4 v175, s[16:17]
	v_readlane_b32 s16, v254, 25
	v_readlane_b32 s17, v254, 26
	s_add_u32 s36, s21, s16
	s_addc_u32 s37, s46, s17
	s_mov_b32 m0, s76
	s_nop 0
	global_load_lds_dwordx4 v172, s[36:37]
	s_nop 0
	s_mov_b32 m0, s89
	s_nop 0
	global_load_lds_dwordx4 v174, s[36:37]
	s_add_u32 s16, s36, 0x80000
	s_addc_u32 s17, s37, 0
	s_mov_b32 m0, s1
	s_nop 0
	global_load_lds_dwordx4 v172, s[16:17]
	s_and_b64 vcc, exec, s[38:39]
	s_mov_b32 m0, s69
	s_nop 0
	global_load_lds_dwordx4 v174, s[16:17]
	s_cbranch_vccnz .LBB0_1316
	s_barrier
.LBB0_1316:
	v_readlane_b32 s16, v255, 29
	s_add_u32 s4, s4, 0x19000000
	v_readlane_b32 s17, v255, 30
	s_addc_u32 s5, s5, 0
	s_lshl_b64 s[16:17], s[16:17], 3
	s_add_u32 s6, s6, s16
	s_addc_u32 s7, s7, s17
	v_readlane_b32 s16, v255, 31
	s_add_u32 s6, s6, 0x100000
	v_readlane_b32 s17, v255, 32
	s_addc_u32 s7, s7, 0
	s_lshl_b64 s[16:17], s[16:17], 2
	s_add_u32 s8, s8, s16
	s_addc_u32 s9, s9, s17
	s_add_u32 s8, s8, 0x700000
	s_addc_u32 s9, s9, 0
	s_add_u32 s10, s10, s16
	s_addc_u32 s11, s11, s17
	s_add_u32 s10, s10, 0x70b000
	s_addc_u32 s11, s11, 0
	v_and_b32_e32 v3, 15, v0
	v_readlane_b32 s16, v253, 6
	s_waitcnt vmcnt(2)
	s_barrier
	v_lshrrev_b32_e32 v1, 4, v0
	v_or_b32_e32 v176, s16, v3
	s_add_u32 s16, s12, 0x80
	s_addc_u32 s17, s13, 0
	s_mov_b32 m0, s35
	s_nop 0
	global_load_lds_dwordx4 v173, s[16:17]
	v_bfe_u32 v2, v0, 4, 2
	s_mov_b32 m0, s33
	s_nop 0
	global_load_lds_dwordx4 v175, s[16:17]
	s_add_u32 s16, s36, 0x80
	s_addc_u32 s17, s37, 0
	s_mov_b32 m0, s22
	s_nop 0
	global_load_lds_dwordx4 v172, s[16:17]
	v_bfe_u32 v0, v0, 1, 3
	s_mov_b32 m0, s2
	s_nop 0
	global_load_lds_dwordx4 v174, s[16:17]
	s_add_u32 s16, s12, 0x80080
	s_addc_u32 s17, s13, 0
	s_mov_b32 m0, s77
	s_nop 0
	global_load_lds_dwordx4 v173, s[16:17]
	v_bitop3_b32 v0, v1, v0, 3 bitop3:0x6c
	s_mov_b32 m0, s3
	s_nop 0
	global_load_lds_dwordx4 v175, s[16:17]
	v_readlane_b32 s19, v253, 7
	s_waitcnt vmcnt(6)
	v_lshlrev_b32_e32 v2, 3, v2
	v_lshlrev_b32_e32 v0, 4, v0
	v_or_b32_e32 v1, s19, v3
	v_readlane_b32 s16, v254, 23
	v_lshl_or_b32 v177, v176, 7, v0
	v_lshl_or_b32 v178, v1, 7, v0
	v_or_b32_e32 v179, s19, v2
	s_mov_b32 s49, 0
	v_lshlrev_b32_e32 v184, 1, v2
	v_readlane_b32 s52, v254, 1
	s_mov_b32 s54, s16
	s_barrier
	v_readlane_b32 s17, v254, 24
	s_branch .LBB0_1319

; #define PG8_STAGE(bufoff, gbase, voff) do { _Pragma("unroll") for (int _i = 0; _i < 2; ++_i) \
;         dma16((const char*)(gbase), (voff)[_i], ldsb + (bufoff) + ldsw + _i * 8192); } while (0)
; #define PG8_LDA(dst, b, h) do { const int a1_ = opqv(aoff0) ^ 64; _Pragma("unroll") for (int m = 0; m < 4; ++m) { dst[m][0] = *(const LAS bf16x8*)(lds + PG8_SA(b, h) + aoff0 + m * 2048); dst[m][1] = *(const LAS bf16x8*)(lds + PG8_SA(b, h) + a1_ + m * 2048); } } while (0)
; #define PG8_LDB(dst, b, h) do { const int b1_ = opqv(boff0) ^ 64; _Pragma("unroll") for (int n = 0; n < 2; ++n) { dst[n][0] = *(const LAS bf16x8*)(lds + PG8_SB(b, h) + boff0 + n * 2048); dst[n][1] = *(const LAS bf16x8*)(lds + PG8_SB(b, h) + b1_ + n * 2048); } } while (0)
; #define PG8_MMA(ai, bj, At, Bt) do { __builtin_amdgcn_s_setprio(1); _Pragma("unroll") for (int m = 0; m < 4; ++m) _Pragma("unroll") for (int n = 0; n < 2; ++n) _Pragma("unroll") for (int k = 0; k < 2; ++k) \
;         acc[ai][bj][m][n] = __builtin_amdgcn_mfma_f32_16x16x32_bf16(Bt[n][k], At[m][k], acc[ai][bj][m][n], 0, 0, 0); __builtin_amdgcn_s_setprio(0); } while (0)
; #define PG8_WAIT_V(n) asm volatile("s_waitcnt vmcnt(" #n ")" ::: "memory")
; #define PG8_WAIT_L(n) asm volatile("s_waitcnt lgkmcnt(" #n ")" ::: "memory")
; #define PG8_BAR __builtin_amdgcn_s_barrier()
; #define PG8_SCHED __builtin_amdgcn_sched_barrier(0)
; template <class Epi>
; __device__ __forceinline__ void gemm_phase(LAS unsigned char* lds, const Gemm g, const StaticOrder& S, const Epi& E, int wave_) {
;     ...
;             PG8_STAGE(PG8_SA(1, 1), a1 + hstepA, voffA); PG8_LDB(B0, 0, 0); PG8_LDB(B1, 0, 1); PG8_SCHED; PG8_LDA(At, 0, 0);
;             PG8_WAIT_V(8); PG8_WAIT_L(0); PG8_BAR; PG8_MMA(0, 0, At, B0); PG8_MMA(0, 1, At, B1); PG8_BAR; PG8_SCHED;
;             PG8_STAGE(PG8_SB(0, 0), b2, voffB); PG8_STAGE(PG8_SB(0, 1), b2 + hstepB, voffB); PG8_STAGE(PG8_SA(0, 0), a2, voffA); PG8_LDA(At, 0, 1);
;             PG8_WAIT_V(8); PG8_WAIT_L(0); PG8_BAR; PG8_MMA(1, 0, At, B0); PG8_MMA(1, 1, At, B1); PG8_BAR; PG8_SCHED;
.LBB0_1322:
	s_add_u32 s36, s12, 0xfff80080
	s_addc_u32 s37, s13, -1
	s_cmp_eq_u32 s57, 28
	s_cselect_b32 s44, s17, s36
	s_cselect_b32 s45, s16, s37
	s_cselect_b32 s40, s25, s55
	s_cselect_b32 s41, s19, s56
	s_add_u32 s36, s44, 0x80
	v_mov_b32_e32 v128, v178
	s_addc_u32 s37, s45, 0
	v_add_u32_e32 v132, s23, v178
	v_xad_u32 v140, v128, 64, s23
	v_mov_b32_e32 v144, v178
	s_add_i32 s60, 0, 0x14000
	ds_read_b128 v[128:131], v132
	ds_read_b128 v[132:135], v132 offset:2048
	ds_read_b128 v[136:139], v140
	ds_read_b128 v[140:143], v140 offset:2048
	v_add_u32_e32 v148, s60, v178
	v_xad_u32 v156, v144, 64, s60
	ds_read_b128 v[144:147], v148
	ds_read_b128 v[148:151], v148 offset:2048
	ds_read_b128 v[152:155], v156
	ds_read_b128 v[156:159], v156 offset:2048
	v_mov_b32_e32 v160, v177
	v_add_u32_e32 v169, 0, v177
	v_xad_u32 v168, v160, 64, 0
	ds_read_b128 v[160:163], v169
	ds_read_b128 v[164:167], v169 offset:2048
	ds_read_b128 v[180:183], v168
	ds_read_b128 v[192:195], v168 offset:2048
	ds_read_b128 v[196:199], v169 offset:4096
	ds_read_b128 v[200:203], v169 offset:6144
	ds_read_b128 v[204:207], v168 offset:4096
	ds_read_b128 v[208:211], v168 offset:6144
	s_mov_b32 m0, s14
	s_nop 0
	global_load_lds_dwordx4 v172, s[12:13]
	s_mov_b32 m0, s15
	s_nop 0
	global_load_lds_dwordx4 v174, s[12:13]
	s_waitcnt vmcnt(8)
	s_waitcnt lgkmcnt(0)
	s_barrier
	s_setprio 1
	s_waitcnt lgkmcnt(0)
	v_mfma_f32_16x16x32_bf16 v[124:127], v[128:131], v[160:163], v[124:127]
	v_mfma_f32_16x16x32_bf16 v[120:123], v[132:135], v[160:163], v[120:123]
	v_mfma_f32_16x16x32_bf16 v[108:111], v[128:131], v[164:167], v[108:111]
	v_mfma_f32_16x16x32_bf16 v[104:107], v[132:135], v[164:167], v[104:107]
	v_mfma_f32_16x16x32_bf16 v[92:95], v[128:131], v[196:199], v[92:95]
	v_mfma_f32_16x16x32_bf16 v[88:91], v[132:135], v[196:199], v[88:91]
	v_mfma_f32_16x16x32_bf16 v[76:79], v[128:131], v[200:203], v[76:79]
	v_mfma_f32_16x16x32_bf16 v[72:75], v[132:135], v[200:203], v[72:75]
	v_mfma_f32_16x16x32_bf16 v[124:127], v[136:139], v[180:183], v[124:127]
	v_mfma_f32_16x16x32_bf16 v[120:123], v[140:143], v[180:183], v[120:123]
	v_mfma_f32_16x16x32_bf16 v[108:111], v[136:139], v[192:195], v[108:111]
	v_mfma_f32_16x16x32_bf16 v[104:107], v[140:143], v[192:195], v[104:107]
	v_mfma_f32_16x16x32_bf16 v[92:95], v[136:139], v[204:207], v[92:95]
	v_mfma_f32_16x16x32_bf16 v[88:91], v[140:143], v[204:207], v[88:91]
	v_mfma_f32_16x16x32_bf16 v[76:79], v[136:139], v[208:211], v[76:79]
	v_mfma_f32_16x16x32_bf16 v[72:75], v[140:143], v[208:211], v[72:75]
	s_setprio 0
	s_setprio 1
	v_mfma_f32_16x16x32_bf16 v[116:119], v[144:147], v[160:163], v[116:119]
	v_mfma_f32_16x16x32_bf16 v[112:115], v[148:151], v[160:163], v[112:115]
	v_mfma_f32_16x16x32_bf16 v[100:103], v[144:147], v[164:167], v[100:103]
	v_mfma_f32_16x16x32_bf16 v[96:99], v[148:151], v[164:167], v[96:99]
	v_mfma_f32_16x16x32_bf16 v[84:87], v[144:147], v[196:199], v[84:87]
	v_mfma_f32_16x16x32_bf16 v[80:83], v[148:151], v[196:199], v[80:83]
	v_mfma_f32_16x16x32_bf16 v[68:71], v[144:147], v[200:203], v[68:71]
	v_mfma_f32_16x16x32_bf16 v[64:67], v[148:151], v[200:203], v[64:67]
	v_mfma_f32_16x16x32_bf16 v[116:119], v[152:155], v[180:183], v[116:119]
	v_mfma_f32_16x16x32_bf16 v[112:115], v[156:159], v[180:183], v[112:115]
	v_mfma_f32_16x16x32_bf16 v[100:103], v[152:155], v[192:195], v[100:103]
	v_mfma_f32_16x16x32_bf16 v[96:99], v[156:159], v[192:195], v[96:99]
	v_mfma_f32_16x16x32_bf16 v[84:87], v[152:155], v[204:207], v[84:87]
	v_mfma_f32_16x16x32_bf16 v[80:83], v[156:159], v[204:207], v[80:83]
	v_mfma_f32_16x16x32_bf16 v[68:71], v[152:155], v[208:211], v[68:71]
	v_mfma_f32_16x16x32_bf16 v[64:67], v[156:159], v[208:211], v[64:67]
	s_setprio 0
	s_barrier
	v_mov_b32_e32 v160, v177
	s_add_u32 s60, s40, 0x80000
	s_addc_u32 s61, s41, 0
	s_nop 0
	s_nop 0
	s_nop 0
	v_xad_u32 v168, v160, 64, 0
	ds_read_b128 v[160:163], v169 offset:16384
	ds_read_b128 v[164:167], v169 offset:18432
	ds_read_b128 v[180:183], v168 offset:16384
	ds_read_b128 v[192:195], v168 offset:18432
	ds_read_b128 v[196:199], v169 offset:20480
	ds_read_b128 v[200:203], v169 offset:22528
	ds_read_b128 v[204:207], v168 offset:20480
	ds_read_b128 v[208:211], v168 offset:22528
	s_mov_b32 m0, s80
	s_nop 0
	global_load_lds_dwordx4 v173, s[40:41]
	s_mov_b32 m0, s81
	s_nop 0
	global_load_lds_dwordx4 v175, s[40:41]
	s_mov_b32 m0, s29
	s_nop 0
	global_load_lds_dwordx4 v173, s[60:61]
	s_mov_b32 m0, s88
	s_nop 0
	global_load_lds_dwordx4 v175, s[60:61]
	s_mov_b32 m0, s76
	s_nop 0
	global_load_lds_dwordx4 v172, s[44:45]
	s_mov_b32 m0, s89
	s_nop 0
	global_load_lds_dwordx4 v174, s[44:45]
	s_waitcnt vmcnt(8)
	s_waitcnt lgkmcnt(0)
	s_barrier
; #define PG8_STAGE(bufoff, gbase, voff) do { _Pragma("unroll") for (int _i = 0; _i < 2; ++_i) \
;         dma16((const char*)(gbase), (voff)[_i], ldsb + (bufoff) + ldsw + _i * 8192); } while (0)
; #define PG8_LDA(dst, b, h) do { const int a1_ = opqv(aoff0) ^ 64; _Pragma("unroll") for (int m = 0; m < 4; ++m) { dst[m][0] = *(const LAS bf16x8*)(lds + PG8_SA(b, h) + aoff0 + m * 2048); dst[m][1] = *(const LAS bf16x8*)(lds + PG8_SA(b, h) + a1_ + m * 2048); } } while (0)
; #define PG8_LDB(dst, b, h) do { const int b1_ = opqv(boff0) ^ 64; _Pragma("unroll") for (int n = 0; n < 2; ++n) { dst[n][0] = *(const LAS bf16x8*)(lds + PG8_SB(b, h) + boff0 + n * 2048); dst[n][1] = *(const LAS bf16x8*)(lds + PG8_SB(b, h) + b1_ + n * 2048); } } while (0)
; #define PG8_MMA(ai, bj, At, Bt) do { __builtin_amdgcn_s_setprio(1); _Pragma("unroll") for (int m = 0; m < 4; ++m) _Pragma("unroll") for (int n = 0; n < 2; ++n) _Pragma("unroll") for (int k = 0; k < 2; ++k) \
;         acc[ai][bj][m][n] = __builtin_amdgcn_mfma_f32_16x16x32_bf16(Bt[n][k], At[m][k], acc[ai][bj][m][n], 0, 0, 0); __builtin_amdgcn_s_setprio(0); } while (0)
; #define PG8_WAIT_V(n) asm volatile("s_waitcnt vmcnt(" #n ")" ::: "memory")
; #define PG8_WAIT_L(n) asm volatile("s_waitcnt lgkmcnt(" #n ")" ::: "memory")
; #define PG8_BAR __builtin_amdgcn_s_barrier()
; #define PG8_SCHED __builtin_amdgcn_sched_barrier(0)
; template <class Epi>
; __device__ __forceinline__ void gemm_phase(LAS unsigned char* lds, const Gemm g, const StaticOrder& S, const Epi& E, int wave_) {
;     ...
;             PG8_WAIT_V(8); PG8_WAIT_L(0); PG8_BAR; PG8_MMA(1, 0, At, B0); PG8_MMA(1, 1, At, B1); PG8_BAR; PG8_SCHED;
;             PG8_STAGE(PG8_SA(0, 1), a2 + hstepA, voffA); PG8_LDB(B0, 1, 0); PG8_LDB(B1, 1, 1); PG8_SCHED; PG8_LDA(At, 1, 0);
;             PG8_WAIT_V(8); PG8_WAIT_L(0); PG8_BAR; PG8_MMA(0, 0, At, B0); PG8_MMA(0, 1, At, B1); PG8_BAR; PG8_SCHED;
;             PG8_STAGE(PG8_SB(1, 0), b3, voffB); PG8_STAGE(PG8_SB(1, 1), b3 + hstepB, voffB); PG8_STAGE(PG8_SA(1, 0), a3, voffA); PG8_LDA(At, 1, 1);
	s_setprio 1
	s_waitcnt lgkmcnt(0)
	v_mfma_f32_16x16x32_bf16 v[60:63], v[128:131], v[160:163], v[60:63]
	v_mfma_f32_16x16x32_bf16 v[56:59], v[132:135], v[160:163], v[56:59]
	v_mfma_f32_16x16x32_bf16 v[44:47], v[128:131], v[164:167], v[44:47]
	v_mfma_f32_16x16x32_bf16 v[40:43], v[132:135], v[164:167], v[40:43]
	v_mfma_f32_16x16x32_bf16 v[28:31], v[128:131], v[196:199], v[28:31]
	v_mfma_f32_16x16x32_bf16 v[24:27], v[132:135], v[196:199], v[24:27]
	v_mfma_f32_16x16x32_bf16 v[12:15], v[128:131], v[200:203], v[12:15]
	v_mfma_f32_16x16x32_bf16 v[8:11], v[132:135], v[200:203], v[8:11]
	v_mfma_f32_16x16x32_bf16 v[60:63], v[136:139], v[180:183], v[60:63]
	v_mfma_f32_16x16x32_bf16 v[56:59], v[140:143], v[180:183], v[56:59]
	v_mfma_f32_16x16x32_bf16 v[44:47], v[136:139], v[192:195], v[44:47]
	v_mfma_f32_16x16x32_bf16 v[40:43], v[140:143], v[192:195], v[40:43]
	v_mfma_f32_16x16x32_bf16 v[28:31], v[136:139], v[204:207], v[28:31]
	v_mfma_f32_16x16x32_bf16 v[24:27], v[140:143], v[204:207], v[24:27]
	v_mfma_f32_16x16x32_bf16 v[12:15], v[136:139], v[208:211], v[12:15]
	v_mfma_f32_16x16x32_bf16 v[8:11], v[140:143], v[208:211], v[8:11]
	s_setprio 0
	s_setprio 1
	v_mfma_f32_16x16x32_bf16 v[52:55], v[144:147], v[160:163], v[52:55]
	v_mfma_f32_16x16x32_bf16 v[48:51], v[148:151], v[160:163], v[48:51]
	v_mfma_f32_16x16x32_bf16 v[36:39], v[144:147], v[164:167], v[36:39]
	v_mfma_f32_16x16x32_bf16 v[32:35], v[148:151], v[164:167], v[32:35]
	v_mfma_f32_16x16x32_bf16 v[20:23], v[144:147], v[196:199], v[20:23]
	v_mfma_f32_16x16x32_bf16 v[16:19], v[148:151], v[196:199], v[16:19]
	v_mfma_f32_16x16x32_bf16 v[4:7], v[144:147], v[200:203], v[4:7]
	v_mfma_f32_16x16x32_bf16 v[0:3], v[148:151], v[200:203], v[0:3]
	v_mfma_f32_16x16x32_bf16 v[52:55], v[152:155], v[180:183], v[52:55]
	v_mfma_f32_16x16x32_bf16 v[48:51], v[156:159], v[180:183], v[48:51]
	v_mfma_f32_16x16x32_bf16 v[36:39], v[152:155], v[192:195], v[36:39]
	v_mfma_f32_16x16x32_bf16 v[32:35], v[156:159], v[192:195], v[32:35]
	v_mfma_f32_16x16x32_bf16 v[20:23], v[152:155], v[204:207], v[20:23]
	v_mfma_f32_16x16x32_bf16 v[16:19], v[156:159], v[204:207], v[16:19]
	v_mfma_f32_16x16x32_bf16 v[4:7], v[152:155], v[208:211], v[4:7]
	v_mfma_f32_16x16x32_bf16 v[0:3], v[156:159], v[208:211], v[0:3]
	s_setprio 0
	s_barrier
	s_add_u32 s44, s44, 0x80000
	s_addc_u32 s45, s45, 0
	s_mov_b32 m0, s1
	s_nop 0
	global_load_lds_dwordx4 v172, s[44:45]
	v_mov_b32_e32 v128, v178
	s_mov_b32 m0, s69
	s_nop 0
	global_load_lds_dwordx4 v174, s[44:45]
	v_add_u32_e32 v132, s34, v178
	v_xad_u32 v140, v128, 64, s34
	v_mov_b32_e32 v144, v178
	s_add_i32 s44, 0, 0x1c000
	ds_read_b128 v[128:131], v132
	ds_read_b128 v[132:135], v132 offset:2048
	ds_read_b128 v[136:139], v140
	ds_read_b128 v[140:143], v140 offset:2048
	v_add_u32_e32 v148, s44, v178
	v_xad_u32 v156, v144, 64, s44
	ds_read_b128 v[144:147], v148
	ds_read_b128 v[148:151], v148 offset:2048
	ds_read_b128 v[152:155], v156
	ds_read_b128 v[156:159], v156 offset:2048
	v_mov_b32_e32 v160, v177
	s_nop 0
	v_xad_u32 v168, v160, 64, 0
	ds_read_b128 v[160:163], v169 offset:32768
	ds_read_b128 v[164:167], v169 offset:34816
	ds_read_b128 v[180:183], v168 offset:32768
	ds_read_b128 v[192:195], v168 offset:34816
	ds_read_b128 v[196:199], v169 offset:36864
	ds_read_b128 v[200:203], v169 offset:38912
	ds_read_b128 v[204:207], v168 offset:36864
	ds_read_b128 v[208:211], v168 offset:38912
	s_waitcnt vmcnt(8)
	s_waitcnt lgkmcnt(0)
	s_barrier
	s_setprio 1
	s_waitcnt lgkmcnt(0)
	v_mfma_f32_16x16x32_bf16 v[124:127], v[128:131], v[160:163], v[124:127]
	v_mfma_f32_16x16x32_bf16 v[120:123], v[132:135], v[160:163], v[120:123]
	v_mfma_f32_16x16x32_bf16 v[108:111], v[128:131], v[164:167], v[108:111]
	v_mfma_f32_16x16x32_bf16 v[104:107], v[132:135], v[164:167], v[104:107]
	v_mfma_f32_16x16x32_bf16 v[92:95], v[128:131], v[196:199], v[92:95]
	v_mfma_f32_16x16x32_bf16 v[88:91], v[132:135], v[196:199], v[88:91]
	v_mfma_f32_16x16x32_bf16 v[76:79], v[128:131], v[200:203], v[76:79]
	v_mfma_f32_16x16x32_bf16 v[72:75], v[132:135], v[200:203], v[72:75]
	v_mfma_f32_16x16x32_bf16 v[124:127], v[136:139], v[180:183], v[124:127]
	v_mfma_f32_16x16x32_bf16 v[120:123], v[140:143], v[180:183], v[120:123]
	v_mfma_f32_16x16x32_bf16 v[108:111], v[136:139], v[192:195], v[108:111]
	v_mfma_f32_16x16x32_bf16 v[104:107], v[140:143], v[192:195], v[104:107]
	v_mfma_f32_16x16x32_bf16 v[92:95], v[136:139], v[204:207], v[92:95]
	v_mfma_f32_16x16x32_bf16 v[88:91], v[140:143], v[204:207], v[88:91]
	v_mfma_f32_16x16x32_bf16 v[76:79], v[136:139], v[208:211], v[76:79]
	v_mfma_f32_16x16x32_bf16 v[72:75], v[140:143], v[208:211], v[72:75]
	s_setprio 0
	s_setprio 1
	v_mfma_f32_16x16x32_bf16 v[116:119], v[144:147], v[160:163], v[116:119]
	s_add_u32 s44, s40, 0x80
	s_addc_u32 s45, s41, 0
	v_mfma_f32_16x16x32_bf16 v[112:115], v[148:151], v[160:163], v[112:115]
	v_mfma_f32_16x16x32_bf16 v[100:103], v[144:147], v[164:167], v[100:103]
	v_mfma_f32_16x16x32_bf16 v[96:99], v[148:151], v[164:167], v[96:99]
	v_mfma_f32_16x16x32_bf16 v[84:87], v[144:147], v[196:199], v[84:87]
	v_mfma_f32_16x16x32_bf16 v[80:83], v[148:151], v[196:199], v[80:83]
	v_mfma_f32_16x16x32_bf16 v[68:71], v[144:147], v[200:203], v[68:71]
	v_mfma_f32_16x16x32_bf16 v[64:67], v[148:151], v[200:203], v[64:67]
	v_mfma_f32_16x16x32_bf16 v[116:119], v[152:155], v[180:183], v[116:119]
	v_mfma_f32_16x16x32_bf16 v[112:115], v[156:159], v[180:183], v[112:115]
	v_mfma_f32_16x16x32_bf16 v[100:103], v[152:155], v[192:195], v[100:103]
	v_mfma_f32_16x16x32_bf16 v[96:99], v[156:159], v[192:195], v[96:99]
	v_mfma_f32_16x16x32_bf16 v[84:87], v[152:155], v[204:207], v[84:87]
	v_mfma_f32_16x16x32_bf16 v[80:83], v[156:159], v[204:207], v[80:83]
	v_mfma_f32_16x16x32_bf16 v[68:71], v[152:155], v[208:211], v[68:71]
	v_mfma_f32_16x16x32_bf16 v[64:67], v[156:159], v[208:211], v[64:67]
	s_setprio 0
	s_barrier
; #define PG8_STAGE(bufoff, gbase, voff) do { _Pragma("unroll") for (int _i = 0; _i < 2; ++_i) \
;         dma16((const char*)(gbase), (voff)[_i], ldsb + (bufoff) + ldsw + _i * 8192); } while (0)
; #define PG8_LDA(dst, b, h) do { const int a1_ = opqv(aoff0) ^ 64; _Pragma("unroll") for (int m = 0; m < 4; ++m) { dst[m][0] = *(const LAS bf16x8*)(lds + PG8_SA(b, h) + aoff0 + m * 2048); dst[m][1] = *(const LAS bf16x8*)(lds + PG8_SA(b, h) + a1_ + m * 2048); } } while (0)
; #define PG8_MMA(ai, bj, At, Bt) do { __builtin_amdgcn_s_setprio(1); _Pragma("unroll") for (int m = 0; m < 4; ++m) _Pragma("unroll") for (int n = 0; n < 2; ++n) _Pragma("unroll") for (int k = 0; k < 2; ++k) \
;         acc[ai][bj][m][n] = __builtin_amdgcn_mfma_f32_16x16x32_bf16(Bt[n][k], At[m][k], acc[ai][bj][m][n], 0, 0, 0); __builtin_amdgcn_s_setprio(0); } while (0)
; #define PG8_WAIT_V(n) asm volatile("s_waitcnt vmcnt(" #n ")" ::: "memory")
; #define PG8_WAIT_L(n) asm volatile("s_waitcnt lgkmcnt(" #n ")" ::: "memory")
; #define PG8_BAR __builtin_amdgcn_s_barrier()
; #define PG8_SCHED __builtin_amdgcn_sched_barrier(0)
; template <class Epi>
; __device__ __forceinline__ void gemm_phase(LAS unsigned char* lds, const Gemm g, const StaticOrder& S, const Epi& E, int wave_) {
;     ...
;             PG8_STAGE(PG8_SB(1, 0), b3, voffB); PG8_STAGE(PG8_SB(1, 1), b3 + hstepB, voffB); PG8_STAGE(PG8_SA(1, 0), a3, voffA); PG8_LDA(At, 1, 1);
;             PG8_WAIT_V(8); PG8_WAIT_L(0); PG8_BAR; PG8_MMA(1, 0, At, B0); PG8_MMA(1, 1, At, B1); PG8_BAR; PG8_SCHED;
;         }
;         if (wr == 0) PG8_BAR;
	s_add_u32 s40, s40, 0x80080
	s_addc_u32 s41, s41, 0
	v_mov_b32_e32 v160, v177
	s_nop 0
	s_nop 0
	v_xad_u32 v168, v160, 64, 0
	ds_read_b128 v[160:163], v169 offset:49152
	ds_read_b128 v[164:167], v169 offset:51200
	ds_read_b128 v[180:183], v168 offset:49152
	ds_read_b128 v[192:195], v168 offset:51200
	ds_read_b128 v[196:199], v169 offset:53248
	ds_read_b128 v[200:203], v169 offset:55296
	ds_read_b128 v[204:207], v168 offset:53248
	ds_read_b128 v[208:211], v168 offset:55296
	s_mov_b32 m0, s35
	s_nop 0
	global_load_lds_dwordx4 v173, s[44:45]
	s_mov_b32 m0, s33
	s_nop 0
	global_load_lds_dwordx4 v175, s[44:45]
	s_mov_b32 m0, s77
	s_nop 0
	global_load_lds_dwordx4 v173, s[40:41]
	s_mov_b32 m0, s3
	s_nop 0
	global_load_lds_dwordx4 v175, s[40:41]
	s_mov_b32 m0, s22
	s_nop 0
	global_load_lds_dwordx4 v172, s[36:37]
	s_mov_b32 m0, s2
	s_nop 0
	global_load_lds_dwordx4 v174, s[36:37]
	s_waitcnt vmcnt(8)
	s_waitcnt lgkmcnt(0)
	s_barrier
	s_setprio 1
	s_waitcnt lgkmcnt(0)
	v_mfma_f32_16x16x32_bf16 v[60:63], v[128:131], v[160:163], v[60:63]
	v_mfma_f32_16x16x32_bf16 v[56:59], v[132:135], v[160:163], v[56:59]
	v_mfma_f32_16x16x32_bf16 v[44:47], v[128:131], v[164:167], v[44:47]
	v_mfma_f32_16x16x32_bf16 v[40:43], v[132:135], v[164:167], v[40:43]
	v_mfma_f32_16x16x32_bf16 v[28:31], v[128:131], v[196:199], v[28:31]
	v_mfma_f32_16x16x32_bf16 v[24:27], v[132:135], v[196:199], v[24:27]
	v_mfma_f32_16x16x32_bf16 v[12:15], v[128:131], v[200:203], v[12:15]
	v_mfma_f32_16x16x32_bf16 v[8:11], v[132:135], v[200:203], v[8:11]
	v_mfma_f32_16x16x32_bf16 v[60:63], v[136:139], v[180:183], v[60:63]
	v_mfma_f32_16x16x32_bf16 v[56:59], v[140:143], v[180:183], v[56:59]
	v_mfma_f32_16x16x32_bf16 v[44:47], v[136:139], v[192:195], v[44:47]
	v_mfma_f32_16x16x32_bf16 v[40:43], v[140:143], v[192:195], v[40:43]
	v_mfma_f32_16x16x32_bf16 v[28:31], v[136:139], v[204:207], v[28:31]
	v_mfma_f32_16x16x32_bf16 v[24:27], v[140:143], v[204:207], v[24:27]
	v_mfma_f32_16x16x32_bf16 v[12:15], v[136:139], v[208:211], v[12:15]
	v_mfma_f32_16x16x32_bf16 v[8:11], v[140:143], v[208:211], v[8:11]
	s_setprio 0
	s_setprio 1
	v_mfma_f32_16x16x32_bf16 v[52:55], v[144:147], v[160:163], v[52:55]
	v_mfma_f32_16x16x32_bf16 v[48:51], v[148:151], v[160:163], v[48:51]
	v_mfma_f32_16x16x32_bf16 v[36:39], v[144:147], v[164:167], v[36:39]
	v_mfma_f32_16x16x32_bf16 v[32:35], v[148:151], v[164:167], v[32:35]
	v_mfma_f32_16x16x32_bf16 v[20:23], v[144:147], v[196:199], v[20:23]
	v_mfma_f32_16x16x32_bf16 v[16:19], v[148:151], v[196:199], v[16:19]
	v_mfma_f32_16x16x32_bf16 v[4:7], v[144:147], v[200:203], v[4:7]
	v_mfma_f32_16x16x32_bf16 v[0:3], v[148:151], v[200:203], v[0:3]
	v_mfma_f32_16x16x32_bf16 v[52:55], v[152:155], v[180:183], v[52:55]
	v_mfma_f32_16x16x32_bf16 v[48:51], v[156:159], v[180:183], v[48:51]
	v_mfma_f32_16x16x32_bf16 v[36:39], v[152:155], v[192:195], v[36:39]
	v_mfma_f32_16x16x32_bf16 v[32:35], v[156:159], v[192:195], v[32:35]
	v_mfma_f32_16x16x32_bf16 v[20:23], v[152:155], v[204:207], v[20:23]
	v_mfma_f32_16x16x32_bf16 v[16:19], v[156:159], v[204:207], v[16:19]
	v_mfma_f32_16x16x32_bf16 v[4:7], v[152:155], v[208:211], v[4:7]
	v_mfma_f32_16x16x32_bf16 v[0:3], v[156:159], v[208:211], v[0:3]
	s_setprio 0
	s_barrier
	s_add_i32 s57, s57, 2
	s_add_u32 s55, s55, 0x100
	s_addc_u32 s56, s56, 0
	s_add_u32 s12, s12, 0x100
	s_addc_u32 s13, s13, 0
	s_cmp_gt_u32 s57, 29
	s_cbranch_scc0 .LBB0_1322
	v_readlane_b32 s12, v253, 13
	v_readlane_b32 s13, v253, 14
	s_and_b64 vcc, exec, s[12:13]
	s_cbranch_vccz .LBB0_1325
	s_barrier

; __host__ __device__ __forceinline__ int lds_byte(int r, int c) { return (r >> 3) * 1024 + (r & 7) * 128 + ((((c >> 3)) ^ ((r >> 1) & 7)) << 4) + (c & 7) * 2; }
; #define PG8_STAGE(bufoff, gbase, voff) do { _Pragma("unroll") for (int _i = 0; _i < 2; ++_i) \
;         dma16((const char*)(gbase), (voff)[_i], ldsb + (bufoff) + ldsw + _i * 8192); } while (0)
; #define PG8_WAIT_V(n) asm volatile("s_waitcnt vmcnt(" #n ")" ::: "memory")
; #define PG8_BAR __builtin_amdgcn_s_barrier()
; template <class Epi>
; __device__ __forceinline__ void gemm_phase(LAS unsigned char* lds, const Gemm g, const StaticOrder& S, const Epi& E, int wave_) {
;     ...
;     for (int i = 0; i < 2; ++i) { int R, C; stage_rc(tid * 16 + i * 8192, R, C); const int Rb = (R & ~31) + perm32(R & 31);
;         voffA[i] = (unsigned)(R * g.lda + C) * 2u; voffB[i] = (unsigned)(Rb * g.ldb + C) * 2u; }
;     const size_t kstep = (size_t)(BK * 2);
;     const size_t hstepA = (size_t)HALF * g.lda * 2, hstepB = (size_t)HALF * g.ldb * 2;
;     const size_t tstepA = 2 * hstepA, tstepB = 2 * hstepB;
;     const unsigned ldsw = (unsigned)wid * 1024u, ldsb = (unsigned)(uintptr_t)lds;
;     const int aoff0 = lds_byte(wr * 64 + fr, fq * 8), boff0 = lds_byte(wc * 32 + fr, fq * 8);
;     ...
;     Unit cur, nxt; int ui = 0;
;     if (!S.next(0, cur)) return;
;     f32x4 acc[2][2][4][2];
; #pragma unroll
;     for (int a = 0; a < 2; ++a)
; #pragma unroll
;         for (int b = 0; b < 2; ++b)
; #pragma unroll
;             for (int m = 0; m < 4; ++m)
; #pragma unroll
;                 for (int n = 0; n < 2; ++n) acc[a][b][m][n] = (f32x4){0.f, 0.f, 0.f, 0.f};
;     bf16x8 At[4][2], B0[2][2], B1[2][2];
;     const char* cA = (const char*)g.A + (size_t)cur.pm * tstepA; const char* cB = (const char*)g.Bt + (size_t)cur.pn * tstepB;
;     PG8_STAGE(PG8_SB(0, 0), cB, voffB); PG8_STAGE(PG8_SB(0, 1), cB + hstepB, voffB); PG8_STAGE(PG8_SA(0, 0), cA, voffA); PG8_STAGE(PG8_SA(0, 1), cA + hstepA, voffA);
;     if (wr == 1) PG8_BAR;
;     PG8_WAIT_V(2); PG8_BAR;
;     PG8_STAGE(PG8_SB(1, 0), cB + kstep, voffB); PG8_STAGE(PG8_SA(1, 0), cA + kstep, voffA); PG8_STAGE(PG8_SB(1, 1), cB + hstepB + kstep, voffB);
;     PG8_WAIT_V(6); PG8_BAR;
.LBB0_1329:
	v_readlane_b32 s4, v252, 12
	v_readlane_b32 s10, v253, 49
	v_readlane_b32 s5, v252, 13
	v_readlane_b32 s11, v253, 50
	s_mov_b64 s[6:7], s[4:5]
	s_mov_b64 s[8:9], s[4:5]
	v_mov_b32_e32 v0, v220
	s_and_b64 vcc, exec, s[10:11]
	s_cbranch_vccz .LBB0_1349
	v_bfe_i32 v3, v0, 27, 1
	v_lshlrev_b32_e32 v1, 4, v0
	v_lshrrev_b32_e32 v4, 22, v3
	v_add_u32_e32 v4, v1, v4
	v_readlane_b32 s10, v255, 20
	v_and_b32_e32 v4, 0xfc00, v4
	v_readlane_b32 s11, v255, 21
	v_sub_u32_e32 v4, v1, v4
	s_and_b64 s[10:11], s[10:11], exec
	v_ashrrev_i16_e32 v5, 15, v4
	s_brev_b32 s10, 24
	v_ashrrev_i32_e32 v2, 31, v0
	v_lshrrev_b16_e32 v5, 9, v5
	v_lshrrev_b32_e32 v3, 25, v3
	s_cselect_b32 s10, s10, 0x40d00000
	v_lshrrev_b32_e32 v2, 26, v2
	v_add_u16_e32 v4, v4, v5
	v_add_u32_e32 v3, v1, v3
	s_add_u32 s16, s6, s10
	v_add_u32_e32 v2, v0, v2
	v_ashrrev_i16_e32 v4, 7, v4
	v_and_b32_e32 v3, 0x80, v3
	s_addc_u32 s17, s7, 0
	v_readlane_b32 s6, v255, 24
	v_ashrrev_i32_e32 v2, 6, v2
	v_bfe_i32 v4, v4, 0, 16
	v_sub_u32_e32 v3, v1, v3
	v_mov_b32_e32 v7, 4
	s_add_u32 s6, s8, s6
	v_ashrrev_i16_sdwa v3, v7, sext(v3) dst_sel:DWORD dst_unused:UNUSED_PAD src0_sel:DWORD src1_sel:BYTE_0
	v_lshl_add_u32 v2, v2, 3, v4
	s_addc_u32 s7, s9, 0
	v_bfe_i32 v3, v3, 0, 16
	v_lshrrev_b32_e32 v5, 1, v2
	s_add_u32 s21, s6, 0x7a00000
	v_bitop3_b32 v3, v5, v3, 7 bitop3:0x6c
	v_lshlrev_b32_e32 v5, 1, v2
	v_lshrrev_b32_e32 v6, 2, v2
	v_and_b32_e32 v4, 3, v4
	s_mov_b32 s6, 0x7fffe0
	v_lshlrev_b32_e32 v3, 4, v3
	v_and_b32_e32 v5, 24, v5
	v_and_b32_e32 v6, 4, v6
	v_and_or_b32 v4, v2, s6, v4
	v_add_u32_e32 v1, 0x2000, v1
	v_or3_b32 v4, v4, v6, v5
	v_lshl_add_u32 v130, v2, 9, v3
	v_ashrrev_i32_e32 v2, 31, v1
	v_lshl_add_u32 v131, v4, 9, v3
	v_lshrrev_b32_e32 v3, 22, v2
	v_add_u32_e32 v3, v1, v3
	v_ashrrev_i32_e32 v3, 10, v3
	v_mul_i32_i24_e32 v4, 0x400, v3
	v_sub_u32_e32 v4, v1, v4
	v_ashrrev_i16_e32 v5, 15, v4
	v_lshrrev_b16_e32 v5, 9, v5
	v_lshrrev_b32_e32 v2, 25, v2
	v_add_u16_e32 v4, v4, v5
	v_add_u32_e32 v2, v1, v2
	v_ashrrev_i16_e32 v4, 7, v4
	v_and_b32_e32 v2, 0x80, v2
	v_bfe_i32 v4, v4, 0, 16
	v_sub_u32_e32 v1, v1, v2
	v_ashrrev_i16_sdwa v1, v7, sext(v1) dst_sel:DWORD dst_unused:UNUSED_PAD src0_sel:DWORD src1_sel:BYTE_0
	v_lshl_add_u32 v2, v3, 3, v4
	v_bfe_i32 v1, v1, 0, 16
	v_lshrrev_b32_e32 v3, 1, v2
	v_and_b32_e32 v4, 3, v4
	s_addc_u32 s52, s7, 0
	v_bitop3_b32 v1, v3, v1, 7 bitop3:0x6c
	v_lshlrev_b32_e32 v3, 1, v2
	v_lshrrev_b32_e32 v5, 2, v2
	v_and_or_b32 v4, v2, s6, v4
	v_readlane_b32 s6, v254, 11
	v_and_b32_e32 v3, 24, v3
	v_and_b32_e32 v5, 4, v5
	v_readlane_b32 s7, v254, 12
	s_add_u32 s24, s21, s6
	v_lshlrev_b32_e32 v1, 4, v1
	v_or3_b32 v3, v4, v5, v3
	s_addc_u32 s25, s52, s7
	s_mov_b32 m0, s80
	s_nop 0
	global_load_lds_dwordx4 v131, s[24:25]
	v_lshl_add_u32 v133, v3, 9, v1
	s_mov_b32 m0, s81
	s_nop 0
	global_load_lds_dwordx4 v133, s[24:25]
	s_add_u32 s6, s24, 0x10000
	s_addc_u32 s7, s25, 0
	s_mov_b32 m0, s29
	s_nop 0
	global_load_lds_dwordx4 v131, s[6:7]
	v_lshl_add_u32 v132, v2, 9, v1
	s_mov_b32 m0, s88
	s_nop 0
	global_load_lds_dwordx4 v133, s[6:7]
	v_readlane_b32 s6, v254, 27
	v_readlane_b32 s7, v254, 28
	s_add_u32 s26, s16, s6
	s_addc_u32 s27, s17, s7
	s_mov_b32 m0, s76
	s_nop 0
	global_load_lds_dwordx4 v130, s[26:27]
	s_nop 0
	s_mov_b32 m0, s89
	s_nop 0
	global_load_lds_dwordx4 v132, s[26:27]
	s_add_u32 s6, s26, 0x10000
	s_addc_u32 s7, s27, 0
	s_mov_b32 m0, s1
	s_nop 0
	global_load_lds_dwordx4 v130, s[6:7]
	s_and_b64 vcc, exec, s[38:39]
	s_mov_b32 m0, s69
	s_nop 0
	global_load_lds_dwordx4 v132, s[6:7]
	s_cbranch_vccnz .LBB0_1332
	s_barrier
.LBB0_1332:
	s_add_u32 s4, s4, 0x2f000000
	s_addc_u32 s5, s5, 0
	v_and_b32_e32 v2, 15, v0
	v_readlane_b32 s6, v253, 6
	s_waitcnt vmcnt(2)
	s_barrier
	v_lshrrev_b32_e32 v1, 4, v0
	v_or_b32_e32 v134, s6, v2
	s_add_u32 s6, s24, 0x80
	s_addc_u32 s7, s25, 0
	s_mov_b32 m0, s35
	s_nop 0
	global_load_lds_dwordx4 v131, s[6:7]
	v_bfe_u32 v3, v0, 4, 2
	s_mov_b32 m0, s33
	s_nop 0
	global_load_lds_dwordx4 v133, s[6:7]
	s_add_u32 s6, s26, 0x80
	s_addc_u32 s7, s27, 0
	s_mov_b32 m0, s22
	s_nop 0
	global_load_lds_dwordx4 v130, s[6:7]
	v_bfe_u32 v0, v0, 1, 3
	s_mov_b32 m0, s2
	s_nop 0
	global_load_lds_dwordx4 v132, s[6:7]
	s_add_u32 s6, s24, 0x10080
	s_addc_u32 s7, s25, 0
	s_mov_b32 m0, s77
	s_nop 0
	global_load_lds_dwordx4 v131, s[6:7]
	v_bitop3_b32 v0, v1, v0, 3 bitop3:0x6c
	s_mov_b32 m0, s3
	s_nop 0
	global_load_lds_dwordx4 v133, s[6:7]
	v_readlane_b32 s9, v253, 7
	s_waitcnt vmcnt(6)
	v_lshlrev_b32_e32 v0, 4, v0
	v_readlane_b32 s6, v254, 37
	v_or_b32_e32 v1, s9, v2
	v_lshl_or_b32 v135, v134, 7, v0
	v_lshl_or_b32 v136, v1, 7, v0
	v_lshl_or_b32 v137, v3, 3, s9
	s_mov_b32 s54, 0
	v_readlane_b32 s55, v254, 4
	s_mov_b32 s60, s6
	s_barrier
	v_readlane_b32 s7, v254, 38
	s_branch .LBB0_1335

; #define PG8_STAGE(bufoff, gbase, voff) do { _Pragma("unroll") for (int _i = 0; _i < 2; ++_i) \
;         dma16((const char*)(gbase), (voff)[_i], ldsb + (bufoff) + ldsw + _i * 8192); } while (0)
; #define PG8_LDA(dst, b, h) do { const int a1_ = opqv(aoff0) ^ 64; _Pragma("unroll") for (int m = 0; m < 4; ++m) { dst[m][0] = *(const LAS bf16x8*)(lds + PG8_SA(b, h) + aoff0 + m * 2048); dst[m][1] = *(const LAS bf16x8*)(lds + PG8_SA(b, h) + a1_ + m * 2048); } } while (0)
; #define PG8_LDB(dst, b, h) do { const int b1_ = opqv(boff0) ^ 64; _Pragma("unroll") for (int n = 0; n < 2; ++n) { dst[n][0] = *(const LAS bf16x8*)(lds + PG8_SB(b, h) + boff0 + n * 2048); dst[n][1] = *(const LAS bf16x8*)(lds + PG8_SB(b, h) + b1_ + n * 2048); } } while (0)
; #define PG8_MMA(ai, bj, At, Bt) do { __builtin_amdgcn_s_setprio(1); _Pragma("unroll") for (int m = 0; m < 4; ++m) _Pragma("unroll") for (int n = 0; n < 2; ++n) _Pragma("unroll") for (int k = 0; k < 2; ++k) \
;         acc[ai][bj][m][n] = __builtin_amdgcn_mfma_f32_16x16x32_bf16(Bt[n][k], At[m][k], acc[ai][bj][m][n], 0, 0, 0); __builtin_amdgcn_s_setprio(0); } while (0)
; #define PG8_WAIT_V(n) asm volatile("s_waitcnt vmcnt(" #n ")" ::: "memory")
; #define PG8_WAIT_L(n) asm volatile("s_waitcnt lgkmcnt(" #n ")" ::: "memory")
; #define PG8_BAR __builtin_amdgcn_s_barrier()
; #define PG8_SCHED __builtin_amdgcn_sched_barrier(0)
; template <class Epi>
; __device__ __forceinline__ void gemm_phase(LAS unsigned char* lds, const Gemm g, const StaticOrder& S, const Epi& E, int wave_) {
;     ...
;             PG8_STAGE(PG8_SA(1, 1), a1 + hstepA, voffA); PG8_LDB(B0, 0, 0); PG8_LDB(B1, 0, 1); PG8_SCHED; PG8_LDA(At, 0, 0);
;             PG8_WAIT_V(8); PG8_WAIT_L(0); PG8_BAR; PG8_MMA(0, 0, At, B0); PG8_MMA(0, 1, At, B1); PG8_BAR; PG8_SCHED;
;             PG8_STAGE(PG8_SB(0, 0), b2, voffB); PG8_STAGE(PG8_SB(0, 1), b2 + hstepB, voffB); PG8_STAGE(PG8_SA(0, 0), a2, voffA); PG8_LDA(At, 0, 1);
;             PG8_WAIT_V(8); PG8_WAIT_L(0); PG8_BAR; PG8_MMA(1, 0, At, B0); PG8_MMA(1, 1, At, B1); PG8_BAR; PG8_SCHED;
.LBB0_1342:
	s_add_u32 s46, s26, s30
	s_addc_u32 s47, s27, s31
	s_add_u32 s44, s46, 0x100
	s_addc_u32 s45, s47, 0
	s_and_b64 s[40:41], s[36:37], exec
	s_cselect_b32 s45, s9, s45
	s_cselect_b32 s44, s61, s44
	s_add_u32 s30, s24, s30
	s_addc_u32 s31, s25, s31
	s_add_u32 s40, s30, 0x100
	s_addc_u32 s41, s31, 0
	s_add_u32 s30, s44, 0x80
	s_addc_u32 s31, s45, 0
	s_add_u32 s56, s46, 0x10080
	s_addc_u32 s57, s47, 0
	s_mov_b32 m0, s14
	s_nop 0
	global_load_lds_dwordx4 v130, s[56:57]
	v_mov_b32_e32 v128, v136
	s_mov_b32 m0, s15
	s_nop 0
	global_load_lds_dwordx4 v132, s[56:57]
	s_and_b64 s[36:37], s[36:37], exec
	v_xad_u32 v128, v128, 64, s23
	v_add_u32_e32 v129, s23, v136
	s_cselect_b32 s49, s7, s41
	s_cselect_b32 s48, s62, s40
	s_add_i32 s37, 0, 0x14000
	ds_read_b128 v[138:141], v129
	ds_read_b128 v[142:145], v129 offset:2048
	ds_read_b128 v[146:149], v128
	ds_read_b128 v[150:153], v128 offset:2048
	v_mov_b32_e32 v128, v136
	v_add_u32_e32 v129, s37, v136
	s_add_u32 s46, s48, 0x10000
	v_xad_u32 v128, v128, 64, s37
	ds_read_b128 v[154:157], v129
	ds_read_b128 v[158:161], v129 offset:2048
	ds_read_b128 v[162:165], v128
	ds_read_b128 v[166:169], v128 offset:2048
	s_addc_u32 s47, s49, 0
	s_add_u32 s40, s44, 0x10000
	s_addc_u32 s41, s45, 0
	s_add_i32 s63, 0, 0x1c000
	s_add_u32 s36, s48, 0x80
	s_addc_u32 s37, s49, 0
	s_add_u32 s56, s48, 0x10080
	s_addc_u32 s57, s49, 0
	v_mov_b32_e32 v128, v135
	v_add_u32_e32 v129, 0, v135
	v_xad_u32 v128, v128, 64, 0
	ds_read_b128 v[172:175], v129
	ds_read_b128 v[176:179], v129 offset:2048
	ds_read_b128 v[180:183], v128
	ds_read_b128 v[192:195], v128 offset:2048
	ds_read_b128 v[196:199], v129 offset:4096
	ds_read_b128 v[200:203], v129 offset:6144
	ds_read_b128 v[204:207], v128 offset:4096
	ds_read_b128 v[208:211], v128 offset:6144
	s_waitcnt vmcnt(8)
	s_waitcnt lgkmcnt(0)
	s_barrier
	s_setprio 1
	s_waitcnt lgkmcnt(0)
	v_mfma_f32_16x16x32_bf16 v[124:127], v[138:141], v[172:175], v[124:127]
	v_mfma_f32_16x16x32_bf16 v[120:123], v[142:145], v[172:175], v[120:123]
	v_mfma_f32_16x16x32_bf16 v[116:119], v[138:141], v[176:179], v[116:119]
	v_mfma_f32_16x16x32_bf16 v[108:111], v[142:145], v[176:179], v[108:111]
	v_mfma_f32_16x16x32_bf16 v[100:103], v[138:141], v[196:199], v[100:103]
	v_mfma_f32_16x16x32_bf16 v[92:95], v[142:145], v[196:199], v[92:95]
	v_mfma_f32_16x16x32_bf16 v[84:87], v[138:141], v[200:203], v[84:87]
	v_mfma_f32_16x16x32_bf16 v[76:79], v[142:145], v[200:203], v[76:79]
	v_mfma_f32_16x16x32_bf16 v[124:127], v[146:149], v[180:183], v[124:127]
	v_mfma_f32_16x16x32_bf16 v[120:123], v[150:153], v[180:183], v[120:123]
	v_mfma_f32_16x16x32_bf16 v[116:119], v[146:149], v[192:195], v[116:119]
	v_mfma_f32_16x16x32_bf16 v[108:111], v[150:153], v[192:195], v[108:111]
	v_mfma_f32_16x16x32_bf16 v[100:103], v[146:149], v[204:207], v[100:103]
	v_mfma_f32_16x16x32_bf16 v[92:95], v[150:153], v[204:207], v[92:95]
	v_mfma_f32_16x16x32_bf16 v[84:87], v[146:149], v[208:211], v[84:87]
	v_mfma_f32_16x16x32_bf16 v[76:79], v[150:153], v[208:211], v[76:79]
	s_setprio 0
	s_setprio 1
	v_mfma_f32_16x16x32_bf16 v[112:115], v[154:157], v[172:175], v[112:115]
	v_mfma_f32_16x16x32_bf16 v[104:107], v[158:161], v[172:175], v[104:107]
	v_mfma_f32_16x16x32_bf16 v[96:99], v[154:157], v[176:179], v[96:99]
	v_mfma_f32_16x16x32_bf16 v[88:91], v[158:161], v[176:179], v[88:91]
	v_mfma_f32_16x16x32_bf16 v[80:83], v[154:157], v[196:199], v[80:83]
	v_mfma_f32_16x16x32_bf16 v[72:75], v[158:161], v[196:199], v[72:75]
	v_mfma_f32_16x16x32_bf16 v[68:71], v[154:157], v[200:203], v[68:71]
	v_mfma_f32_16x16x32_bf16 v[64:67], v[158:161], v[200:203], v[64:67]
	v_mfma_f32_16x16x32_bf16 v[112:115], v[162:165], v[180:183], v[112:115]
	v_mfma_f32_16x16x32_bf16 v[104:107], v[166:169], v[180:183], v[104:107]
	v_mfma_f32_16x16x32_bf16 v[96:99], v[162:165], v[192:195], v[96:99]
	v_mfma_f32_16x16x32_bf16 v[88:91], v[166:169], v[192:195], v[88:91]
	v_mfma_f32_16x16x32_bf16 v[80:83], v[162:165], v[204:207], v[80:83]
	v_mfma_f32_16x16x32_bf16 v[72:75], v[166:169], v[204:207], v[72:75]
	v_mfma_f32_16x16x32_bf16 v[68:71], v[162:165], v[208:211], v[68:71]
	v_mfma_f32_16x16x32_bf16 v[64:67], v[166:169], v[208:211], v[64:67]
	s_setprio 0
	s_barrier
	v_mov_b32_e32 v128, v135
	s_nop 0
	s_nop 0
	s_nop 0
	v_xad_u32 v128, v128, 64, 0
	ds_read_b128 v[172:175], v129 offset:16384
	ds_read_b128 v[176:179], v129 offset:18432
	ds_read_b128 v[180:183], v128 offset:16384
	ds_read_b128 v[192:195], v128 offset:18432
	ds_read_b128 v[196:199], v129 offset:20480
	ds_read_b128 v[200:203], v129 offset:22528
	ds_read_b128 v[204:207], v128 offset:20480
	ds_read_b128 v[208:211], v128 offset:22528
	s_mov_b32 m0, s80
	s_nop 0
	global_load_lds_dwordx4 v131, s[48:49]
	s_mov_b32 m0, s81
	s_nop 0
	global_load_lds_dwordx4 v133, s[48:49]
	s_mov_b32 m0, s29
	s_nop 0
	global_load_lds_dwordx4 v131, s[46:47]
	s_mov_b32 m0, s88
	s_nop 0
	global_load_lds_dwordx4 v133, s[46:47]
	s_mov_b32 m0, s76
	s_nop 0
	global_load_lds_dwordx4 v130, s[44:45]
	s_mov_b32 m0, s89
	s_nop 0
	global_load_lds_dwordx4 v132, s[44:45]
	s_waitcnt vmcnt(8)
	s_waitcnt lgkmcnt(0)
	s_barrier
; #define PG8_STAGE(bufoff, gbase, voff) do { _Pragma("unroll") for (int _i = 0; _i < 2; ++_i) \
;         dma16((const char*)(gbase), (voff)[_i], ldsb + (bufoff) + ldsw + _i * 8192); } while (0)
; #define PG8_LDA(dst, b, h) do { const int a1_ = opqv(aoff0) ^ 64; _Pragma("unroll") for (int m = 0; m < 4; ++m) { dst[m][0] = *(const LAS bf16x8*)(lds + PG8_SA(b, h) + aoff0 + m * 2048); dst[m][1] = *(const LAS bf16x8*)(lds + PG8_SA(b, h) + a1_ + m * 2048); } } while (0)
; #define PG8_LDB(dst, b, h) do { const int b1_ = opqv(boff0) ^ 64; _Pragma("unroll") for (int n = 0; n < 2; ++n) { dst[n][0] = *(const LAS bf16x8*)(lds + PG8_SB(b, h) + boff0 + n * 2048); dst[n][1] = *(const LAS bf16x8*)(lds + PG8_SB(b, h) + b1_ + n * 2048); } } while (0)
; #define PG8_MMA(ai, bj, At, Bt) do { __builtin_amdgcn_s_setprio(1); _Pragma("unroll") for (int m = 0; m < 4; ++m) _Pragma("unroll") for (int n = 0; n < 2; ++n) _Pragma("unroll") for (int k = 0; k < 2; ++k) \
;         acc[ai][bj][m][n] = __builtin_amdgcn_mfma_f32_16x16x32_bf16(Bt[n][k], At[m][k], acc[ai][bj][m][n], 0, 0, 0); __builtin_amdgcn_s_setprio(0); } while (0)
; #define PG8_WAIT_V(n) asm volatile("s_waitcnt vmcnt(" #n ")" ::: "memory")
; #define PG8_WAIT_L(n) asm volatile("s_waitcnt lgkmcnt(" #n ")" ::: "memory")
; #define PG8_BAR __builtin_amdgcn_s_barrier()
; #define PG8_SCHED __builtin_amdgcn_sched_barrier(0)
; template <class Epi>
; __device__ __forceinline__ void gemm_phase(LAS unsigned char* lds, const Gemm g, const StaticOrder& S, const Epi& E, int wave_) {
;     ...
;             PG8_WAIT_V(8); PG8_WAIT_L(0); PG8_BAR; PG8_MMA(1, 0, At, B0); PG8_MMA(1, 1, At, B1); PG8_BAR; PG8_SCHED;
;             PG8_STAGE(PG8_SA(0, 1), a2 + hstepA, voffA); PG8_LDB(B0, 1, 0); PG8_LDB(B1, 1, 1); PG8_SCHED; PG8_LDA(At, 1, 0);
;             PG8_WAIT_V(8); PG8_WAIT_L(0); PG8_BAR; PG8_MMA(0, 0, At, B0); PG8_MMA(0, 1, At, B1); PG8_BAR; PG8_SCHED;
;             PG8_STAGE(PG8_SB(1, 0), b3, voffB); PG8_STAGE(PG8_SB(1, 1), b3 + hstepB, voffB); PG8_STAGE(PG8_SA(1, 0), a3, voffA); PG8_LDA(At, 1, 1);
	s_setprio 1
	s_waitcnt lgkmcnt(0)
	v_mfma_f32_16x16x32_bf16 v[60:63], v[138:141], v[172:175], v[60:63]
	v_mfma_f32_16x16x32_bf16 v[56:59], v[142:145], v[172:175], v[56:59]
	v_mfma_f32_16x16x32_bf16 v[52:55], v[138:141], v[176:179], v[52:55]
	v_mfma_f32_16x16x32_bf16 v[44:47], v[142:145], v[176:179], v[44:47]
	v_mfma_f32_16x16x32_bf16 v[36:39], v[138:141], v[196:199], v[36:39]
	v_mfma_f32_16x16x32_bf16 v[28:31], v[142:145], v[196:199], v[28:31]
	v_mfma_f32_16x16x32_bf16 v[20:23], v[138:141], v[200:203], v[20:23]
	v_mfma_f32_16x16x32_bf16 v[12:15], v[142:145], v[200:203], v[12:15]
	v_mfma_f32_16x16x32_bf16 v[60:63], v[146:149], v[180:183], v[60:63]
	v_mfma_f32_16x16x32_bf16 v[56:59], v[150:153], v[180:183], v[56:59]
	v_mfma_f32_16x16x32_bf16 v[52:55], v[146:149], v[192:195], v[52:55]
	v_mfma_f32_16x16x32_bf16 v[44:47], v[150:153], v[192:195], v[44:47]
	v_mfma_f32_16x16x32_bf16 v[36:39], v[146:149], v[204:207], v[36:39]
	v_mfma_f32_16x16x32_bf16 v[28:31], v[150:153], v[204:207], v[28:31]
	v_mfma_f32_16x16x32_bf16 v[20:23], v[146:149], v[208:211], v[20:23]
	v_mfma_f32_16x16x32_bf16 v[12:15], v[150:153], v[208:211], v[12:15]
	s_setprio 0
	s_setprio 1
	v_mfma_f32_16x16x32_bf16 v[48:51], v[154:157], v[172:175], v[48:51]
	v_mfma_f32_16x16x32_bf16 v[40:43], v[158:161], v[172:175], v[40:43]
	v_mfma_f32_16x16x32_bf16 v[32:35], v[154:157], v[176:179], v[32:35]
	v_mfma_f32_16x16x32_bf16 v[24:27], v[158:161], v[176:179], v[24:27]
	v_mfma_f32_16x16x32_bf16 v[16:19], v[154:157], v[196:199], v[16:19]
	v_mfma_f32_16x16x32_bf16 v[8:11], v[158:161], v[196:199], v[8:11]
	v_mfma_f32_16x16x32_bf16 v[4:7], v[154:157], v[200:203], v[4:7]
	v_mfma_f32_16x16x32_bf16 v[0:3], v[158:161], v[200:203], v[0:3]
	v_mfma_f32_16x16x32_bf16 v[48:51], v[162:165], v[180:183], v[48:51]
	v_mfma_f32_16x16x32_bf16 v[40:43], v[166:169], v[180:183], v[40:43]
	v_mfma_f32_16x16x32_bf16 v[32:35], v[162:165], v[192:195], v[32:35]
	v_mfma_f32_16x16x32_bf16 v[24:27], v[166:169], v[192:195], v[24:27]
	v_mfma_f32_16x16x32_bf16 v[16:19], v[162:165], v[204:207], v[16:19]
	v_mfma_f32_16x16x32_bf16 v[8:11], v[166:169], v[204:207], v[8:11]
	v_mfma_f32_16x16x32_bf16 v[4:7], v[162:165], v[208:211], v[4:7]
	v_mfma_f32_16x16x32_bf16 v[0:3], v[166:169], v[208:211], v[0:3]
	s_setprio 0
	s_barrier
	v_mov_b32_e32 v128, v136
	v_add_u32_e32 v142, s34, v136
	v_xad_u32 v128, v128, 64, s34
	ds_read_b128 v[138:141], v142
	ds_read_b128 v[142:145], v142 offset:2048
	ds_read_b128 v[146:149], v128
	ds_read_b128 v[150:153], v128 offset:2048
	v_mov_b32_e32 v128, v136
	v_add_u32_e32 v158, s63, v136
	v_xad_u32 v128, v128, 64, s63
	ds_read_b128 v[154:157], v158
	ds_read_b128 v[158:161], v158 offset:2048
	ds_read_b128 v[162:165], v128
	ds_read_b128 v[166:169], v128 offset:2048
	v_mov_b32_e32 v128, v135
	s_nop 0
	v_xad_u32 v128, v128, 64, 0
	ds_read_b128 v[172:175], v129 offset:32768
	ds_read_b128 v[176:179], v129 offset:34816
	ds_read_b128 v[180:183], v128 offset:32768
	ds_read_b128 v[192:195], v128 offset:34816
	ds_read_b128 v[196:199], v129 offset:36864
	ds_read_b128 v[200:203], v129 offset:38912
	ds_read_b128 v[204:207], v128 offset:36864
	ds_read_b128 v[208:211], v128 offset:38912
	s_mov_b32 m0, s1
	s_nop 0
	global_load_lds_dwordx4 v130, s[40:41]
	s_mov_b32 m0, s69
	s_nop 0
	global_load_lds_dwordx4 v132, s[40:41]
	s_waitcnt vmcnt(8)
	s_waitcnt lgkmcnt(0)
	s_barrier
	s_setprio 1
	s_waitcnt lgkmcnt(0)
	v_mfma_f32_16x16x32_bf16 v[124:127], v[138:141], v[172:175], v[124:127]
	v_mfma_f32_16x16x32_bf16 v[120:123], v[142:145], v[172:175], v[120:123]
	v_mfma_f32_16x16x32_bf16 v[116:119], v[138:141], v[176:179], v[116:119]
	v_mfma_f32_16x16x32_bf16 v[108:111], v[142:145], v[176:179], v[108:111]
	v_mfma_f32_16x16x32_bf16 v[100:103], v[138:141], v[196:199], v[100:103]
	v_mfma_f32_16x16x32_bf16 v[92:95], v[142:145], v[196:199], v[92:95]
	v_mfma_f32_16x16x32_bf16 v[84:87], v[138:141], v[200:203], v[84:87]
	v_mfma_f32_16x16x32_bf16 v[76:79], v[142:145], v[200:203], v[76:79]
	v_mfma_f32_16x16x32_bf16 v[124:127], v[146:149], v[180:183], v[124:127]
	v_mfma_f32_16x16x32_bf16 v[120:123], v[150:153], v[180:183], v[120:123]
	v_mfma_f32_16x16x32_bf16 v[116:119], v[146:149], v[192:195], v[116:119]
	v_mfma_f32_16x16x32_bf16 v[108:111], v[150:153], v[192:195], v[108:111]
	v_mfma_f32_16x16x32_bf16 v[100:103], v[146:149], v[204:207], v[100:103]
	v_mfma_f32_16x16x32_bf16 v[92:95], v[150:153], v[204:207], v[92:95]
	v_mfma_f32_16x16x32_bf16 v[84:87], v[146:149], v[208:211], v[84:87]
	v_mfma_f32_16x16x32_bf16 v[76:79], v[150:153], v[208:211], v[76:79]
	s_setprio 0
	s_setprio 1
	v_mfma_f32_16x16x32_bf16 v[112:115], v[154:157], v[172:175], v[112:115]
	v_mfma_f32_16x16x32_bf16 v[104:107], v[158:161], v[172:175], v[104:107]
	v_mfma_f32_16x16x32_bf16 v[96:99], v[154:157], v[176:179], v[96:99]
	v_mfma_f32_16x16x32_bf16 v[88:91], v[158:161], v[176:179], v[88:91]
	v_mfma_f32_16x16x32_bf16 v[80:83], v[154:157], v[196:199], v[80:83]
	v_mfma_f32_16x16x32_bf16 v[72:75], v[158:161], v[196:199], v[72:75]
	v_mfma_f32_16x16x32_bf16 v[68:71], v[154:157], v[200:203], v[68:71]
	v_mfma_f32_16x16x32_bf16 v[64:67], v[158:161], v[200:203], v[64:67]
	v_mfma_f32_16x16x32_bf16 v[112:115], v[162:165], v[180:183], v[112:115]
	v_mfma_f32_16x16x32_bf16 v[104:107], v[166:169], v[180:183], v[104:107]
	v_mfma_f32_16x16x32_bf16 v[96:99], v[162:165], v[192:195], v[96:99]
	v_mfma_f32_16x16x32_bf16 v[88:91], v[166:169], v[192:195], v[88:91]
	v_mfma_f32_16x16x32_bf16 v[80:83], v[162:165], v[204:207], v[80:83]
	v_mfma_f32_16x16x32_bf16 v[72:75], v[166:169], v[204:207], v[72:75]
	v_mfma_f32_16x16x32_bf16 v[68:71], v[162:165], v[208:211], v[68:71]
	v_mfma_f32_16x16x32_bf16 v[64:67], v[166:169], v[208:211], v[64:67]
	s_setprio 0
	s_barrier
; #define PG8_STAGE(bufoff, gbase, voff) do { _Pragma("unroll") for (int _i = 0; _i < 2; ++_i) \
;         dma16((const char*)(gbase), (voff)[_i], ldsb + (bufoff) + ldsw + _i * 8192); } while (0)
; #define PG8_LDA(dst, b, h) do { const int a1_ = opqv(aoff0) ^ 64; _Pragma("unroll") for (int m = 0; m < 4; ++m) { dst[m][0] = *(const LAS bf16x8*)(lds + PG8_SA(b, h) + aoff0 + m * 2048); dst[m][1] = *(const LAS bf16x8*)(lds + PG8_SA(b, h) + a1_ + m * 2048); } } while (0)
; #define PG8_MMA(ai, bj, At, Bt) do { __builtin_amdgcn_s_setprio(1); _Pragma("unroll") for (int m = 0; m < 4; ++m) _Pragma("unroll") for (int n = 0; n < 2; ++n) _Pragma("unroll") for (int k = 0; k < 2; ++k) \
;         acc[ai][bj][m][n] = __builtin_amdgcn_mfma_f32_16x16x32_bf16(Bt[n][k], At[m][k], acc[ai][bj][m][n], 0, 0, 0); __builtin_amdgcn_s_setprio(0); } while (0)
; #define PG8_WAIT_V(n) asm volatile("s_waitcnt vmcnt(" #n ")" ::: "memory")
; #define PG8_WAIT_L(n) asm volatile("s_waitcnt lgkmcnt(" #n ")" ::: "memory")
; #define PG8_BAR __builtin_amdgcn_s_barrier()
; #define PG8_SCHED __builtin_amdgcn_sched_barrier(0)
; __device__ __forceinline__ void dma16(const void* sbase, unsigned voff, unsigned lds_dst) {
;   unsigned keep;
;   asm volatile("s_mov_b32 %0, m0\n\ts_mov_b32 m0, %3\n\ts_nop 0\n\tglobal_load_lds_dwordx4 %2, %1\n\ts_mov_b32 m0, %0" : "=&s"(keep) : "s"(sbase), "v"(voff), "s"(lds_dst) : "memory");
; }
; template <class Epi>
; __device__ __forceinline__ void gemm_phase(LAS unsigned char* lds, const Gemm g, const StaticOrder& S, const Epi& E, int wave_) {
;     ...
;             PG8_STAGE(PG8_SB(1, 0), b3, voffB); PG8_STAGE(PG8_SB(1, 1), b3 + hstepB, voffB); PG8_STAGE(PG8_SA(1, 0), a3, voffA); PG8_LDA(At, 1, 1);
;             PG8_WAIT_V(8); PG8_WAIT_L(0); PG8_BAR; PG8_MMA(1, 0, At, B0); PG8_MMA(1, 1, At, B1); PG8_BAR; PG8_SCHED;
;         }
	v_mov_b32_e32 v128, v135
	s_nop 0
	s_nop 0
	s_nop 0
	s_nop 0
	v_xad_u32 v128, v128, 64, 0
	ds_read_b128 v[172:175], v129 offset:49152
	ds_read_b128 v[176:179], v129 offset:51200
	ds_read_b128 v[180:183], v128 offset:49152
	ds_read_b128 v[192:195], v128 offset:51200
	ds_read_b128 v[196:199], v129 offset:53248
	ds_read_b128 v[200:203], v129 offset:55296
	ds_read_b128 v[204:207], v128 offset:53248
	ds_read_b128 v[208:211], v128 offset:55296
	s_mov_b32 m0, s35
	s_nop 0
	global_load_lds_dwordx4 v131, s[36:37]
	s_mov_b32 m0, s33
	s_nop 0
	global_load_lds_dwordx4 v133, s[36:37]
	s_mov_b32 m0, s77
	s_nop 0
	global_load_lds_dwordx4 v131, s[56:57]
	s_mov_b32 m0, s3
	s_nop 0
	global_load_lds_dwordx4 v133, s[56:57]
	s_mov_b32 m0, s22
	s_nop 0
	global_load_lds_dwordx4 v130, s[30:31]
	s_mov_b32 m0, s2
	s_nop 0
	global_load_lds_dwordx4 v132, s[30:31]
	s_waitcnt vmcnt(8)
	s_waitcnt lgkmcnt(0)
	s_barrier
	s_setprio 1
	s_waitcnt lgkmcnt(0)
	v_mfma_f32_16x16x32_bf16 v[60:63], v[138:141], v[172:175], v[60:63]
	v_mfma_f32_16x16x32_bf16 v[56:59], v[142:145], v[172:175], v[56:59]
	v_mfma_f32_16x16x32_bf16 v[52:55], v[138:141], v[176:179], v[52:55]
	v_mfma_f32_16x16x32_bf16 v[44:47], v[142:145], v[176:179], v[44:47]
	v_mfma_f32_16x16x32_bf16 v[36:39], v[138:141], v[196:199], v[36:39]
	v_mfma_f32_16x16x32_bf16 v[28:31], v[142:145], v[196:199], v[28:31]
	v_mfma_f32_16x16x32_bf16 v[20:23], v[138:141], v[200:203], v[20:23]
	v_mfma_f32_16x16x32_bf16 v[12:15], v[142:145], v[200:203], v[12:15]
	v_mfma_f32_16x16x32_bf16 v[60:63], v[146:149], v[180:183], v[60:63]
	v_mfma_f32_16x16x32_bf16 v[56:59], v[150:153], v[180:183], v[56:59]
	v_mfma_f32_16x16x32_bf16 v[52:55], v[146:149], v[192:195], v[52:55]
	v_mfma_f32_16x16x32_bf16 v[44:47], v[150:153], v[192:195], v[44:47]
	v_mfma_f32_16x16x32_bf16 v[36:39], v[146:149], v[204:207], v[36:39]
	v_mfma_f32_16x16x32_bf16 v[28:31], v[150:153], v[204:207], v[28:31]
	v_mfma_f32_16x16x32_bf16 v[20:23], v[146:149], v[208:211], v[20:23]
	v_mfma_f32_16x16x32_bf16 v[12:15], v[150:153], v[208:211], v[12:15]
	s_setprio 0
	s_setprio 1
	v_mfma_f32_16x16x32_bf16 v[48:51], v[154:157], v[172:175], v[48:51]
	v_mfma_f32_16x16x32_bf16 v[40:43], v[158:161], v[172:175], v[40:43]
	v_mfma_f32_16x16x32_bf16 v[32:35], v[154:157], v[176:179], v[32:35]
	v_mfma_f32_16x16x32_bf16 v[24:27], v[158:161], v[176:179], v[24:27]
	v_mfma_f32_16x16x32_bf16 v[16:19], v[154:157], v[196:199], v[16:19]
	v_mfma_f32_16x16x32_bf16 v[8:11], v[158:161], v[196:199], v[8:11]
	v_mfma_f32_16x16x32_bf16 v[4:7], v[154:157], v[200:203], v[4:7]
	v_mfma_f32_16x16x32_bf16 v[0:3], v[158:161], v[200:203], v[0:3]
	v_mfma_f32_16x16x32_bf16 v[48:51], v[162:165], v[180:183], v[48:51]
	v_mfma_f32_16x16x32_bf16 v[40:43], v[166:169], v[180:183], v[40:43]
	v_mfma_f32_16x16x32_bf16 v[32:35], v[162:165], v[192:195], v[32:35]
	v_mfma_f32_16x16x32_bf16 v[24:27], v[166:169], v[192:195], v[24:27]
	v_mfma_f32_16x16x32_bf16 v[16:19], v[162:165], v[204:207], v[16:19]
	v_mfma_f32_16x16x32_bf16 v[8:11], v[166:169], v[204:207], v[8:11]
	v_mfma_f32_16x16x32_bf16 v[4:7], v[162:165], v[208:211], v[4:7]
	v_mfma_f32_16x16x32_bf16 v[0:3], v[166:169], v[208:211], v[0:3]
	s_setprio 0
	s_barrier
	s_andn2_b64 vcc, exec, s[12:13]
	s_mov_b64 s[36:37], -1
	s_mov_b64 s[12:13], 0
	s_mov_b64 s[30:31], 0x100
	s_cbranch_vccz .LBB0_1342
	v_readlane_b32 s12, v253, 13
	v_readlane_b32 s13, v253, 14
	s_and_b64 vcc, exec, s[12:13]
	v_readlane_b32 s61, v255, 16
	s_cbranch_vccz .LBB0_1345
	s_barrier

; __device__ __forceinline__ int tid_of(int wave) { return opqv(wave * 64 + (int)__builtin_amdgcn_mbcnt_hi(~0u, __builtin_amdgcn_mbcnt_lo(~0u, 0u))); }
; __host__ __device__ __forceinline__ int lds_byte(int r, int c) { return (r >> 3) * 1024 + (r & 7) * 128 + ((((c >> 3)) ^ ((r >> 1) & 7)) << 4) + (c & 7) * 2; }
; #define PG8_WAIT_V(n) asm volatile("s_waitcnt vmcnt(" #n ")" ::: "memory")
; #define PG8_BAR __builtin_amdgcn_s_barrier()
; template <class Epi>
; __device__ __forceinline__ void gemm_phase(LAS unsigned char* lds, const Gemm g, const StaticOrder& S, const Epi& E, int wave_) {
;     const int tid = tid_of(wave_), wid = wave_, lane = tid & 63, wr = wid >> 2, wc = wid & 3, fr = lane & 15, fq = lane >> 4;
;     const int K = g.K, nt = K / BK;
;     unsigned voffA[2], voffB[2];
; #pragma unroll
;     for (int i = 0; i < 2; ++i) { int R, C; stage_rc(tid * 16 + i * 8192, R, C); const int Rb = (R & ~31) + perm32(R & 31);
;         voffA[i] = (unsigned)(R * g.lda + C) * 2u; voffB[i] = (unsigned)(Rb * g.ldb + C) * 2u; }
;     const size_t kstep = (size_t)(BK * 2);
;     const size_t hstepA = (size_t)HALF * g.lda * 2, hstepB = (size_t)HALF * g.ldb * 2;
;     const size_t tstepA = 2 * hstepA, tstepB = 2 * hstepB;
;     const unsigned ldsw = (unsigned)wid * 1024u, ldsb = (unsigned)(uintptr_t)lds;
;     const int aoff0 = lds_byte(wr * 64 + fr, fq * 8), boff0 = lds_byte(wc * 32 + fr, fq * 8);
;     ...
;     Unit cur, nxt; int ui = 0;
;     if (!S.next(0, cur)) return;
;     f32x4 acc[2][2][4][2];
; #pragma unroll
;     for (int a = 0; a < 2; ++a)
; #pragma unroll
;         for (int b = 0; b < 2; ++b)
; #pragma unroll
;             for (int m = 0; m < 4; ++m)
; #pragma unroll
;                 for (int n = 0; n < 2; ++n) acc[a][b][m][n] = (f32x4){0.f, 0.f, 0.f, 0.f};
;     bf16x8 At[4][2], B0[2][2], B1[2][2];
;     const char* cA = (const char*)g.A + (size_t)cur.pm * tstepA; const char* cB = (const char*)g.Bt + (size_t)cur.pn * tstepB;
;     PG8_STAGE(PG8_SB(0, 0), cB, voffB); PG8_STAGE(PG8_SB(0, 1), cB + hstepB, voffB); PG8_STAGE(PG8_SA(0, 0), cA, voffA); PG8_STAGE(PG8_SA(0, 1), cA + hstepA, voffA);
;     if (wr == 1) PG8_BAR;
;     PG8_WAIT_V(2); PG8_BAR;
;     PG8_STAGE(PG8_SB(1, 0), cB + kstep, voffB); PG8_STAGE(PG8_SA(1, 0), cA + kstep, voffA); PG8_STAGE(PG8_SB(1, 1), cB + hstepB + kstep, voffB);
;     PG8_WAIT_V(6); PG8_BAR;
.LBB0_1535:
	s_or_b64 exec, exec, s[4:5]
	v_readlane_b32 s26, v255, 37
	s_or_b32 s18, s26, 1
	s_ashr_i32 s19, s18, 31
	s_lshl_b64 s[18:19], s[18:19], 15
	v_readlane_b32 s27, v255, 38
	v_writelane_b32 v255, s18, 20
	v_readlane_b32 s10, v252, 12
	v_readlane_b32 s24, v252, 14
	v_writelane_b32 v255, s19, 21
	s_lshl_b64 s[26:27], s[26:27], 11
	v_readlane_b32 s11, v252, 13
	v_readlane_b32 s25, v252, 15
	v_writelane_b32 v255, s26, 37
	s_mov_b64 s[12:13], s[10:11]
	s_mov_b64 s[16:17], s[10:11]
	s_mov_b64 s[4:5], s[10:11]
	s_mov_b64 s[6:7], s[10:11]
	s_mov_b64 s[8:9], s[10:11]
	s_mov_b64 s[18:19], s[24:25]
	v_writelane_b32 v255, s27, 38
	v_mov_b32_e32 v0, v220
	s_and_b64 vcc, exec, s[66:67]
	s_barrier
	s_cbranch_vccnz .LBB0_1575
	v_bfe_i32 v3, v0, 27, 1
	v_lshlrev_b32_e32 v1, 4, v0
	v_lshrrev_b32_e32 v4, 22, v3
	v_add_u32_e32 v4, v1, v4
	v_and_b32_e32 v4, 0xfc00, v4
	v_sub_u32_e32 v4, v1, v4
	v_ashrrev_i16_e32 v5, 15, v4
	v_ashrrev_i32_e32 v2, 31, v0
	v_lshrrev_b16_e32 v5, 9, v5
	v_lshrrev_b32_e32 v3, 25, v3
	s_add_u32 s21, s12, 0x19000000
	v_lshrrev_b32_e32 v2, 26, v2
	v_add_u16_e32 v4, v4, v5
	v_add_u32_e32 v3, v1, v3
	s_addc_u32 s48, s13, 0
	v_readlane_b32 s12, v255, 24
	v_add_u32_e32 v2, v0, v2
	v_ashrrev_i16_e32 v4, 7, v4
	v_and_b32_e32 v3, 0x80, v3
	s_add_u32 s12, s16, s12
	v_ashrrev_i32_e32 v2, 6, v2
	v_bfe_i32 v4, v4, 0, 16
	v_sub_u32_e32 v3, v1, v3
	v_mov_b32_e32 v7, 4
	s_addc_u32 s13, s17, 0
	v_ashrrev_i16_sdwa v3, v7, sext(v3) dst_sel:DWORD dst_unused:UNUSED_PAD src0_sel:DWORD src1_sel:BYTE_0
	v_lshl_add_u32 v2, v2, 3, v4
	s_add_u32 s49, s12, 0x5c00000
	v_bfe_i32 v3, v3, 0, 16
	v_lshrrev_b32_e32 v5, 1, v2
	s_addc_u32 s52, s13, 0
	v_bitop3_b32 v3, v5, v3, 7 bitop3:0x6c
	v_lshlrev_b32_e32 v5, 1, v2
	v_lshrrev_b32_e32 v6, 2, v2
	v_and_b32_e32 v4, 3, v4
	s_mov_b32 s13, 0x7fffe0
	v_and_b32_e32 v5, 24, v5
	v_and_b32_e32 v6, 4, v6
	v_and_or_b32 v4, v2, s13, v4
	s_movk_i32 s12, 0x1600
	v_lshlrev_b32_e32 v3, 3, v3
	v_or3_b32 v4, v4, v6, v5
	v_mul_lo_u32 v2, v2, s12
	v_add_lshl_u32 v184, v3, v2, 1
	v_mul_u32_u24_e32 v2, 0x1600, v4
	v_add_u32_e32 v1, 0x2000, v1
	v_add_lshl_u32 v214, v2, v3, 1
	v_ashrrev_i32_e32 v2, 31, v1
	v_lshrrev_b32_e32 v3, 22, v2
	v_add_u32_e32 v3, v1, v3
	v_ashrrev_i32_e32 v3, 10, v3
	v_mul_i32_i24_e32 v4, 0x400, v3
	v_sub_u32_e32 v4, v1, v4
	v_ashrrev_i16_e32 v5, 15, v4
	v_lshrrev_b16_e32 v5, 9, v5
	v_lshrrev_b32_e32 v2, 25, v2
	v_add_u16_e32 v4, v4, v5
	v_add_u32_e32 v2, v1, v2
	v_ashrrev_i16_e32 v4, 7, v4
	v_and_b32_e32 v2, 0x80, v2
	v_bfe_i32 v4, v4, 0, 16
	v_sub_u32_e32 v1, v1, v2
	v_ashrrev_i16_sdwa v1, v7, sext(v1) dst_sel:DWORD dst_unused:UNUSED_PAD src0_sel:DWORD src1_sel:BYTE_0
	v_lshl_add_u32 v2, v3, 3, v4
	v_bfe_i32 v1, v1, 0, 16
	v_lshrrev_b32_e32 v3, 1, v2
	v_and_b32_e32 v4, 3, v4
	v_bitop3_b32 v1, v3, v1, 7 bitop3:0x6c
	v_lshlrev_b32_e32 v3, 1, v2
	v_lshrrev_b32_e32 v5, 2, v2
	v_and_or_b32 v4, v2, s13, v4
	v_readlane_b32 s13, v254, 4
	v_and_b32_e32 v3, 24, v3
	v_and_b32_e32 v5, 4, v5
	v_mul_lo_u32 v2, v2, s12
	s_mul_i32 s12, s13, 0x2c0000
	v_lshlrev_b32_e32 v1, 3, v1
	v_or3_b32 v3, v4, v5, v3
	s_add_u32 s12, s49, s12
	s_mul_hi_i32 s13, s13, 0x2c0000
	s_load_dwordx2 s[18:19], s[18:19], 0x68
	s_nop 0
	s_load_dwordx2 s[24:25], s[24:25], 0x70
	v_add_lshl_u32 v215, v1, v2, 1
	v_mul_u32_u24_e32 v2, 0x1600, v3
	s_addc_u32 s13, s52, s13
	s_mov_b32 m0, s80
	s_nop 0
	global_load_lds_dwordx4 v214, s[12:13]
	v_add_lshl_u32 v216, v2, v1, 1
	s_mov_b32 m0, s81
	s_nop 0
	global_load_lds_dwordx4 v216, s[12:13]
	s_add_u32 s16, s12, 0x160000
	s_addc_u32 s17, s13, 0
	s_mov_b32 m0, s29
	s_nop 0
	global_load_lds_dwordx4 v214, s[16:17]
	s_nop 0
	s_mov_b32 m0, s88
	s_nop 0
	global_load_lds_dwordx4 v216, s[16:17]
	v_readlane_b32 s16, v254, 37
	s_mov_b32 s26, s16
	s_mul_i32 s16, s16, 0x2c0000
	s_add_u32 s36, s21, s16
	s_mul_hi_i32 s16, s26, 0x2c0000
	s_addc_u32 s37, s48, s16
	s_mov_b32 m0, s76
	s_nop 0
	global_load_lds_dwordx4 v184, s[36:37]
	v_readlane_b32 s17, v254, 38
	s_mov_b32 m0, s89
	s_nop 0
	global_load_lds_dwordx4 v215, s[36:37]
	s_add_u32 s16, s36, 0x160000
	s_addc_u32 s17, s37, 0
	s_mov_b32 m0, s1
	s_nop 0
	global_load_lds_dwordx4 v184, s[16:17]
	s_and_b64 vcc, exec, s[38:39]
	s_mov_b32 m0, s69
	s_nop 0
	global_load_lds_dwordx4 v215, s[16:17]
	s_cbranch_vccnz .LBB0_1538
	s_barrier
.LBB0_1538:
	s_add_u32 s4, s4, 0x8000000
	s_addc_u32 s5, s5, 0
	v_readlane_b32 s16, v255, 29
	s_add_u32 s6, s6, 0x10000000
	v_readlane_b32 s17, v255, 30
	s_addc_u32 s7, s7, 0
	s_lshl_b64 s[16:17], s[16:17], 3
	s_add_u32 s8, s8, s16
	s_addc_u32 s9, s9, s17
	v_readlane_b32 s16, v255, 20
	s_add_u32 s8, s8, 0x100000
	v_readlane_b32 s17, v255, 21
	s_addc_u32 s9, s9, 0
	s_lshl_b64 s[16:17], s[16:17], 3
	s_add_u32 s10, s10, s16
	s_addc_u32 s11, s11, s17
	v_readlane_b32 s16, v255, 37
	s_add_u32 s10, s10, 0x100000
	v_readlane_b32 s17, v255, 38
	s_addc_u32 s11, s11, 0
	s_lshl_b64 s[16:17], s[16:17], 2
	s_waitcnt lgkmcnt(0)
	s_add_u32 s18, s18, s16
	s_addc_u32 s19, s19, s17
	s_add_u32 s24, s24, s16
	s_addc_u32 s25, s25, s17
	v_and_b32_e32 v2, 15, v0
	v_readlane_b32 s16, v253, 6
	s_waitcnt vmcnt(2)
	s_barrier
	v_lshrrev_b32_e32 v1, 4, v0
	v_or_b32_e32 v217, s16, v2
	s_add_u32 s16, s12, 0x80
	s_addc_u32 s17, s13, 0
	s_mov_b32 m0, s35
	s_nop 0
	global_load_lds_dwordx4 v214, s[16:17]
	v_bfe_u32 v3, v0, 4, 2
	s_mov_b32 m0, s33
	s_nop 0
	global_load_lds_dwordx4 v216, s[16:17]
	s_add_u32 s16, s36, 0x80
	s_addc_u32 s17, s37, 0
	s_mov_b32 m0, s22
	s_nop 0
	global_load_lds_dwordx4 v184, s[16:17]
	v_bfe_u32 v0, v0, 1, 3
	s_mov_b32 m0, s2
	s_nop 0
	global_load_lds_dwordx4 v215, s[16:17]
	s_add_u32 s16, s12, 0x160080
	s_addc_u32 s17, s13, 0
	s_mov_b32 m0, s77
	s_nop 0
	global_load_lds_dwordx4 v214, s[16:17]
	v_bitop3_b32 v0, v1, v0, 3 bitop3:0x6c
	s_mov_b32 m0, s3
	s_nop 0
	global_load_lds_dwordx4 v216, s[16:17]
	v_readlane_b32 s27, v253, 7
	s_waitcnt vmcnt(6)
	v_lshlrev_b32_e32 v0, 4, v0
	v_readlane_b32 s16, v254, 37
	v_or_b32_e32 v1, s27, v2
	v_lshl_or_b32 v218, v217, 7, v0
	v_lshl_or_b32 v219, v1, 7, v0
	s_mov_b32 s54, 0
	v_cmp_eq_u32_e64 s[42:43], 0, v3
	v_lshl_or_b32 v231, v3, 3, s27
	v_readlane_b32 s58, v254, 4
	s_mov_b32 s57, s16
	s_barrier
	v_readlane_b32 s17, v254, 38
	s_branch .LBB0_1541

; #define PG8_STAGE(bufoff, gbase, voff) do { _Pragma("unroll") for (int _i = 0; _i < 2; ++_i) \
;         dma16((const char*)(gbase), (voff)[_i], ldsb + (bufoff) + ldsw + _i * 8192); } while (0)
; #define PG8_LDA(dst, b, h) do { const int a1_ = opqv(aoff0) ^ 64; _Pragma("unroll") for (int m = 0; m < 4; ++m) { dst[m][0] = *(const LAS bf16x8*)(lds + PG8_SA(b, h) + aoff0 + m * 2048); dst[m][1] = *(const LAS bf16x8*)(lds + PG8_SA(b, h) + a1_ + m * 2048); } } while (0)
; #define PG8_LDB(dst, b, h) do { const int b1_ = opqv(boff0) ^ 64; _Pragma("unroll") for (int n = 0; n < 2; ++n) { dst[n][0] = *(const LAS bf16x8*)(lds + PG8_SB(b, h) + boff0 + n * 2048); dst[n][1] = *(const LAS bf16x8*)(lds + PG8_SB(b, h) + b1_ + n * 2048); } } while (0)
; #define PG8_MMA(ai, bj, At, Bt) do { __builtin_amdgcn_s_setprio(1); _Pragma("unroll") for (int m = 0; m < 4; ++m) _Pragma("unroll") for (int n = 0; n < 2; ++n) _Pragma("unroll") for (int k = 0; k < 2; ++k) \
;         acc[ai][bj][m][n] = __builtin_amdgcn_mfma_f32_16x16x32_bf16(Bt[n][k], At[m][k], acc[ai][bj][m][n], 0, 0, 0); __builtin_amdgcn_s_setprio(0); } while (0)
; #define PG8_WAIT_V(n) asm volatile("s_waitcnt vmcnt(" #n ")" ::: "memory")
; #define PG8_WAIT_L(n) asm volatile("s_waitcnt lgkmcnt(" #n ")" ::: "memory")
; #define PG8_BAR __builtin_amdgcn_s_barrier()
; #define PG8_SCHED __builtin_amdgcn_sched_barrier(0)
; template <class Epi>
; __device__ __forceinline__ void gemm_phase(LAS unsigned char* lds, const Gemm g, const StaticOrder& S, const Epi& E, int wave_) {
;     ...
;             const bool last = (t == nt - 2);
;             const char* a1 = cA + (size_t)(t + 1) * kstep;
;             const char* a2 = last ? nA : cA + (size_t)(t + 2) * kstep; const char* b2 = last ? nB : cB + (size_t)(t + 2) * kstep;
;             const char* a3 = a2 + kstep; const char* b3 = b2 + kstep;
;             PG8_STAGE(PG8_SA(1, 1), a1 + hstepA, voffA); PG8_LDB(B0, 0, 0); PG8_LDB(B1, 0, 1); PG8_SCHED; PG8_LDA(At, 0, 0);
;             PG8_WAIT_V(8); PG8_WAIT_L(0); PG8_BAR; PG8_MMA(0, 0, At, B0); PG8_MMA(0, 1, At, B1); PG8_BAR; PG8_SCHED;
;             PG8_STAGE(PG8_SB(0, 0), b2, voffB); PG8_STAGE(PG8_SB(0, 1), b2 + hstepB, voffB); PG8_STAGE(PG8_SA(0, 0), a2, voffA); PG8_LDA(At, 0, 1);
;             PG8_WAIT_V(8); PG8_WAIT_L(0); PG8_BAR; PG8_MMA(1, 0, At, B0); PG8_MMA(1, 1, At, B1); PG8_BAR; PG8_SCHED;
.LBB0_1552:
	s_add_u32 s36, s12, 0xffea0080
	s_addc_u32 s37, s13, -1
	s_cmpk_eq_i32 s59, 0x54
	s_cselect_b32 s46, s26, s36
	s_cselect_b32 s47, s27, s37
	s_cselect_b32 s40, s30, s16
	s_cselect_b32 s41, s31, s17
	s_add_u32 s36, s46, 0x80
	v_mov_b32_e32 v64, v219
	s_addc_u32 s37, s47, 0
	v_add_u32_e32 v68, s23, v219
	v_xad_u32 v76, v64, 64, s23
	v_mov_b32_e32 v80, v219
	s_add_i32 s60, 0, 0x14000
	ds_read_b128 v[64:67], v68
	ds_read_b128 v[68:71], v68 offset:2048
	ds_read_b128 v[72:75], v76
	ds_read_b128 v[76:79], v76 offset:2048
	v_add_u32_e32 v84, s60, v219
	v_xad_u32 v92, v80, 64, s60
	ds_read_b128 v[80:83], v84
	ds_read_b128 v[84:87], v84 offset:2048
	ds_read_b128 v[88:91], v92
	ds_read_b128 v[92:95], v92 offset:2048
	v_mov_b32_e32 v160, v218
	v_add_u32_e32 v191, 0, v218
	v_xad_u32 v190, v160, 64, 0
	ds_read_b128 v[160:163], v191
	ds_read_b128 v[164:167], v191 offset:2048
	ds_read_b128 v[168:171], v190
	ds_read_b128 v[172:175], v190 offset:2048
	ds_read_b128 v[176:179], v191 offset:4096
	ds_read_b128 v[180:183], v191 offset:6144
	ds_read_b128 v[192:195], v190 offset:4096
	ds_read_b128 v[196:199], v190 offset:6144
	s_mov_b32 m0, s14
	s_nop 0
	global_load_lds_dwordx4 v184, s[12:13]
	s_mov_b32 m0, s15
	s_nop 0
	global_load_lds_dwordx4 v215, s[12:13]
	s_waitcnt vmcnt(8)
	s_waitcnt lgkmcnt(0)
	s_barrier
	s_setprio 1
	s_waitcnt lgkmcnt(0)
	v_mfma_f32_16x16x32_bf16 v[156:159], v[64:67], v[160:163], v[156:159]
	v_mfma_f32_16x16x32_bf16 v[152:155], v[68:71], v[160:163], v[152:155]
	v_mfma_f32_16x16x32_bf16 v[140:143], v[64:67], v[164:167], v[140:143]
	v_mfma_f32_16x16x32_bf16 v[136:139], v[68:71], v[164:167], v[136:139]
	v_mfma_f32_16x16x32_bf16 v[124:127], v[64:67], v[176:179], v[124:127]
	v_mfma_f32_16x16x32_bf16 v[120:123], v[68:71], v[176:179], v[120:123]
	v_mfma_f32_16x16x32_bf16 v[108:111], v[64:67], v[180:183], v[108:111]
	v_mfma_f32_16x16x32_bf16 v[104:107], v[68:71], v[180:183], v[104:107]
	v_mfma_f32_16x16x32_bf16 v[156:159], v[72:75], v[168:171], v[156:159]
	v_mfma_f32_16x16x32_bf16 v[152:155], v[76:79], v[168:171], v[152:155]
	v_mfma_f32_16x16x32_bf16 v[140:143], v[72:75], v[172:175], v[140:143]
	v_mfma_f32_16x16x32_bf16 v[136:139], v[76:79], v[172:175], v[136:139]
	v_mfma_f32_16x16x32_bf16 v[124:127], v[72:75], v[192:195], v[124:127]
	v_mfma_f32_16x16x32_bf16 v[120:123], v[76:79], v[192:195], v[120:123]
	v_mfma_f32_16x16x32_bf16 v[108:111], v[72:75], v[196:199], v[108:111]
	v_mfma_f32_16x16x32_bf16 v[104:107], v[76:79], v[196:199], v[104:107]
	s_setprio 0
	s_setprio 1
	v_mfma_f32_16x16x32_bf16 v[148:151], v[80:83], v[160:163], v[148:151]
	v_mfma_f32_16x16x32_bf16 v[144:147], v[84:87], v[160:163], v[144:147]
	v_mfma_f32_16x16x32_bf16 v[132:135], v[80:83], v[164:167], v[132:135]
	v_mfma_f32_16x16x32_bf16 v[128:131], v[84:87], v[164:167], v[128:131]
	v_mfma_f32_16x16x32_bf16 v[116:119], v[80:83], v[176:179], v[116:119]
	v_mfma_f32_16x16x32_bf16 v[112:115], v[84:87], v[176:179], v[112:115]
	v_mfma_f32_16x16x32_bf16 v[100:103], v[80:83], v[180:183], v[100:103]
	v_mfma_f32_16x16x32_bf16 v[96:99], v[84:87], v[180:183], v[96:99]
	v_mfma_f32_16x16x32_bf16 v[148:151], v[88:91], v[168:171], v[148:151]
	v_mfma_f32_16x16x32_bf16 v[144:147], v[92:95], v[168:171], v[144:147]
	v_mfma_f32_16x16x32_bf16 v[132:135], v[88:91], v[172:175], v[132:135]
	v_mfma_f32_16x16x32_bf16 v[128:131], v[92:95], v[172:175], v[128:131]
	v_mfma_f32_16x16x32_bf16 v[116:119], v[88:91], v[192:195], v[116:119]
	v_mfma_f32_16x16x32_bf16 v[112:115], v[92:95], v[192:195], v[112:115]
	v_mfma_f32_16x16x32_bf16 v[100:103], v[88:91], v[196:199], v[100:103]
	v_mfma_f32_16x16x32_bf16 v[96:99], v[92:95], v[196:199], v[96:99]
	s_setprio 0
	s_barrier
	v_mov_b32_e32 v160, v218
	s_add_u32 s60, s40, 0x160000
	s_addc_u32 s61, s41, 0
	s_nop 0
	s_nop 0
	s_nop 0
	v_xad_u32 v190, v160, 64, 0
	ds_read_b128 v[160:163], v191 offset:16384
	ds_read_b128 v[164:167], v191 offset:18432
	ds_read_b128 v[168:171], v190 offset:16384
	ds_read_b128 v[172:175], v190 offset:18432
	ds_read_b128 v[176:179], v191 offset:20480
	ds_read_b128 v[180:183], v191 offset:22528
	ds_read_b128 v[192:195], v190 offset:20480
	ds_read_b128 v[196:199], v190 offset:22528
	s_mov_b32 m0, s80
	s_nop 0
	global_load_lds_dwordx4 v214, s[40:41]
	s_mov_b32 m0, s81
	s_nop 0
	global_load_lds_dwordx4 v216, s[40:41]
	s_mov_b32 m0, s29
	s_nop 0
	global_load_lds_dwordx4 v214, s[60:61]
	s_mov_b32 m0, s88
	s_nop 0
	global_load_lds_dwordx4 v216, s[60:61]
	s_mov_b32 m0, s76
	s_nop 0
	global_load_lds_dwordx4 v184, s[46:47]
	s_mov_b32 m0, s89
	s_nop 0
	global_load_lds_dwordx4 v215, s[46:47]
	s_waitcnt vmcnt(8)
	s_waitcnt lgkmcnt(0)
	s_barrier
; #define PG8_STAGE(bufoff, gbase, voff) do { _Pragma("unroll") for (int _i = 0; _i < 2; ++_i) \
;         dma16((const char*)(gbase), (voff)[_i], ldsb + (bufoff) + ldsw + _i * 8192); } while (0)
; #define PG8_LDA(dst, b, h) do { const int a1_ = opqv(aoff0) ^ 64; _Pragma("unroll") for (int m = 0; m < 4; ++m) { dst[m][0] = *(const LAS bf16x8*)(lds + PG8_SA(b, h) + aoff0 + m * 2048); dst[m][1] = *(const LAS bf16x8*)(lds + PG8_SA(b, h) + a1_ + m * 2048); } } while (0)
; #define PG8_LDB(dst, b, h) do { const int b1_ = opqv(boff0) ^ 64; _Pragma("unroll") for (int n = 0; n < 2; ++n) { dst[n][0] = *(const LAS bf16x8*)(lds + PG8_SB(b, h) + boff0 + n * 2048); dst[n][1] = *(const LAS bf16x8*)(lds + PG8_SB(b, h) + b1_ + n * 2048); } } while (0)
; #define PG8_MMA(ai, bj, At, Bt) do { __builtin_amdgcn_s_setprio(1); _Pragma("unroll") for (int m = 0; m < 4; ++m) _Pragma("unroll") for (int n = 0; n < 2; ++n) _Pragma("unroll") for (int k = 0; k < 2; ++k) \
;         acc[ai][bj][m][n] = __builtin_amdgcn_mfma_f32_16x16x32_bf16(Bt[n][k], At[m][k], acc[ai][bj][m][n], 0, 0, 0); __builtin_amdgcn_s_setprio(0); } while (0)
; #define PG8_WAIT_V(n) asm volatile("s_waitcnt vmcnt(" #n ")" ::: "memory")
; #define PG8_WAIT_L(n) asm volatile("s_waitcnt lgkmcnt(" #n ")" ::: "memory")
; #define PG8_BAR __builtin_amdgcn_s_barrier()
; #define PG8_SCHED __builtin_amdgcn_sched_barrier(0)
; template <class Epi>
; __device__ __forceinline__ void gemm_phase(LAS unsigned char* lds, const Gemm g, const StaticOrder& S, const Epi& E, int wave_) {
;     ...
;             PG8_WAIT_V(8); PG8_WAIT_L(0); PG8_BAR; PG8_MMA(1, 0, At, B0); PG8_MMA(1, 1, At, B1); PG8_BAR; PG8_SCHED;
;             PG8_STAGE(PG8_SA(0, 1), a2 + hstepA, voffA); PG8_LDB(B0, 1, 0); PG8_LDB(B1, 1, 1); PG8_SCHED; PG8_LDA(At, 1, 0);
;             PG8_WAIT_V(8); PG8_WAIT_L(0); PG8_BAR; PG8_MMA(0, 0, At, B0); PG8_MMA(0, 1, At, B1); PG8_BAR; PG8_SCHED;
	s_setprio 1
	s_waitcnt lgkmcnt(0)
	v_mfma_f32_16x16x32_bf16 v[60:63], v[64:67], v[160:163], v[60:63]
	v_mfma_f32_16x16x32_bf16 v[56:59], v[68:71], v[160:163], v[56:59]
	v_mfma_f32_16x16x32_bf16 v[44:47], v[64:67], v[164:167], v[44:47]
	v_mfma_f32_16x16x32_bf16 v[40:43], v[68:71], v[164:167], v[40:43]
	v_mfma_f32_16x16x32_bf16 v[28:31], v[64:67], v[176:179], v[28:31]
	v_mfma_f32_16x16x32_bf16 v[24:27], v[68:71], v[176:179], v[24:27]
	v_mfma_f32_16x16x32_bf16 v[12:15], v[64:67], v[180:183], v[12:15]
	v_mfma_f32_16x16x32_bf16 v[8:11], v[68:71], v[180:183], v[8:11]
	v_mfma_f32_16x16x32_bf16 v[60:63], v[72:75], v[168:171], v[60:63]
	v_mfma_f32_16x16x32_bf16 v[56:59], v[76:79], v[168:171], v[56:59]
	v_mfma_f32_16x16x32_bf16 v[44:47], v[72:75], v[172:175], v[44:47]
	v_mfma_f32_16x16x32_bf16 v[40:43], v[76:79], v[172:175], v[40:43]
	v_mfma_f32_16x16x32_bf16 v[28:31], v[72:75], v[192:195], v[28:31]
	v_mfma_f32_16x16x32_bf16 v[24:27], v[76:79], v[192:195], v[24:27]
	v_mfma_f32_16x16x32_bf16 v[12:15], v[72:75], v[196:199], v[12:15]
	v_mfma_f32_16x16x32_bf16 v[8:11], v[76:79], v[196:199], v[8:11]
	s_setprio 0
	s_setprio 1
	v_mfma_f32_16x16x32_bf16 v[52:55], v[80:83], v[160:163], v[52:55]
	v_mfma_f32_16x16x32_bf16 v[48:51], v[84:87], v[160:163], v[48:51]
	v_mfma_f32_16x16x32_bf16 v[36:39], v[80:83], v[164:167], v[36:39]
	v_mfma_f32_16x16x32_bf16 v[32:35], v[84:87], v[164:167], v[32:35]
	v_mfma_f32_16x16x32_bf16 v[20:23], v[80:83], v[176:179], v[20:23]
	v_mfma_f32_16x16x32_bf16 v[16:19], v[84:87], v[176:179], v[16:19]
	v_mfma_f32_16x16x32_bf16 v[4:7], v[80:83], v[180:183], v[4:7]
	v_mfma_f32_16x16x32_bf16 v[0:3], v[84:87], v[180:183], v[0:3]
	v_mfma_f32_16x16x32_bf16 v[52:55], v[88:91], v[168:171], v[52:55]
	v_mfma_f32_16x16x32_bf16 v[48:51], v[92:95], v[168:171], v[48:51]
	v_mfma_f32_16x16x32_bf16 v[36:39], v[88:91], v[172:175], v[36:39]
	v_mfma_f32_16x16x32_bf16 v[32:35], v[92:95], v[172:175], v[32:35]
	v_mfma_f32_16x16x32_bf16 v[20:23], v[88:91], v[192:195], v[20:23]
	v_mfma_f32_16x16x32_bf16 v[16:19], v[92:95], v[192:195], v[16:19]
	v_mfma_f32_16x16x32_bf16 v[4:7], v[88:91], v[196:199], v[4:7]
	v_mfma_f32_16x16x32_bf16 v[0:3], v[92:95], v[196:199], v[0:3]
	s_setprio 0
	s_barrier
	s_add_u32 s46, s46, 0x160000
	s_addc_u32 s47, s47, 0
	s_mov_b32 m0, s1
	s_nop 0
	global_load_lds_dwordx4 v184, s[46:47]
	v_mov_b32_e32 v64, v219
	s_mov_b32 m0, s69
	s_nop 0
	global_load_lds_dwordx4 v215, s[46:47]
	v_add_u32_e32 v68, s34, v219
	v_xad_u32 v76, v64, 64, s34
	v_mov_b32_e32 v80, v219
	s_add_i32 s46, 0, 0x1c000
	ds_read_b128 v[64:67], v68
	ds_read_b128 v[68:71], v68 offset:2048
	ds_read_b128 v[72:75], v76
	ds_read_b128 v[76:79], v76 offset:2048
	v_add_u32_e32 v84, s46, v219
	v_xad_u32 v92, v80, 64, s46
	ds_read_b128 v[80:83], v84
	ds_read_b128 v[84:87], v84 offset:2048
	ds_read_b128 v[88:91], v92
	ds_read_b128 v[92:95], v92 offset:2048
	v_mov_b32_e32 v160, v218
	s_nop 0
	v_xad_u32 v190, v160, 64, 0
	ds_read_b128 v[160:163], v191 offset:32768
	ds_read_b128 v[164:167], v191 offset:34816
	ds_read_b128 v[168:171], v190 offset:32768
	ds_read_b128 v[172:175], v190 offset:34816
	ds_read_b128 v[176:179], v191 offset:36864
	ds_read_b128 v[180:183], v191 offset:38912
	ds_read_b128 v[192:195], v190 offset:36864
	ds_read_b128 v[196:199], v190 offset:38912
	s_waitcnt vmcnt(8)
	s_waitcnt lgkmcnt(0)
	s_barrier
	s_setprio 1
	s_waitcnt lgkmcnt(0)
	v_mfma_f32_16x16x32_bf16 v[156:159], v[64:67], v[160:163], v[156:159]
	v_mfma_f32_16x16x32_bf16 v[152:155], v[68:71], v[160:163], v[152:155]
	v_mfma_f32_16x16x32_bf16 v[140:143], v[64:67], v[164:167], v[140:143]
	v_mfma_f32_16x16x32_bf16 v[136:139], v[68:71], v[164:167], v[136:139]
	v_mfma_f32_16x16x32_bf16 v[124:127], v[64:67], v[176:179], v[124:127]
	v_mfma_f32_16x16x32_bf16 v[120:123], v[68:71], v[176:179], v[120:123]
	v_mfma_f32_16x16x32_bf16 v[108:111], v[64:67], v[180:183], v[108:111]
	v_mfma_f32_16x16x32_bf16 v[104:107], v[68:71], v[180:183], v[104:107]
	v_mfma_f32_16x16x32_bf16 v[156:159], v[72:75], v[168:171], v[156:159]
	v_mfma_f32_16x16x32_bf16 v[152:155], v[76:79], v[168:171], v[152:155]
	v_mfma_f32_16x16x32_bf16 v[140:143], v[72:75], v[172:175], v[140:143]
	v_mfma_f32_16x16x32_bf16 v[136:139], v[76:79], v[172:175], v[136:139]
	v_mfma_f32_16x16x32_bf16 v[124:127], v[72:75], v[192:195], v[124:127]
	v_mfma_f32_16x16x32_bf16 v[120:123], v[76:79], v[192:195], v[120:123]
	v_mfma_f32_16x16x32_bf16 v[108:111], v[72:75], v[196:199], v[108:111]
	v_mfma_f32_16x16x32_bf16 v[104:107], v[76:79], v[196:199], v[104:107]
	s_setprio 0
	s_setprio 1
	v_mfma_f32_16x16x32_bf16 v[148:151], v[80:83], v[160:163], v[148:151]
	s_add_u32 s46, s40, 0x80
	s_addc_u32 s47, s41, 0
	v_mfma_f32_16x16x32_bf16 v[144:147], v[84:87], v[160:163], v[144:147]
	v_mfma_f32_16x16x32_bf16 v[132:135], v[80:83], v[164:167], v[132:135]
	v_mfma_f32_16x16x32_bf16 v[128:131], v[84:87], v[164:167], v[128:131]
	v_mfma_f32_16x16x32_bf16 v[116:119], v[80:83], v[176:179], v[116:119]
	v_mfma_f32_16x16x32_bf16 v[112:115], v[84:87], v[176:179], v[112:115]
	v_mfma_f32_16x16x32_bf16 v[100:103], v[80:83], v[180:183], v[100:103]
	v_mfma_f32_16x16x32_bf16 v[96:99], v[84:87], v[180:183], v[96:99]
	v_mfma_f32_16x16x32_bf16 v[148:151], v[88:91], v[168:171], v[148:151]
	v_mfma_f32_16x16x32_bf16 v[144:147], v[92:95], v[168:171], v[144:147]
	v_mfma_f32_16x16x32_bf16 v[132:135], v[88:91], v[172:175], v[132:135]
	v_mfma_f32_16x16x32_bf16 v[128:131], v[92:95], v[172:175], v[128:131]
	v_mfma_f32_16x16x32_bf16 v[116:119], v[88:91], v[192:195], v[116:119]
	v_mfma_f32_16x16x32_bf16 v[112:115], v[92:95], v[192:195], v[112:115]
	v_mfma_f32_16x16x32_bf16 v[100:103], v[88:91], v[196:199], v[100:103]
	v_mfma_f32_16x16x32_bf16 v[96:99], v[92:95], v[196:199], v[96:99]
	s_setprio 0
	s_barrier
; #define PG8_STAGE(bufoff, gbase, voff) do { _Pragma("unroll") for (int _i = 0; _i < 2; ++_i) \
;         dma16((const char*)(gbase), (voff)[_i], ldsb + (bufoff) + ldsw + _i * 8192); } while (0)
; #define PG8_LDA(dst, b, h) do { const int a1_ = opqv(aoff0) ^ 64; _Pragma("unroll") for (int m = 0; m < 4; ++m) { dst[m][0] = *(const LAS bf16x8*)(lds + PG8_SA(b, h) + aoff0 + m * 2048); dst[m][1] = *(const LAS bf16x8*)(lds + PG8_SA(b, h) + a1_ + m * 2048); } } while (0)
; #define PG8_MMA(ai, bj, At, Bt) do { __builtin_amdgcn_s_setprio(1); _Pragma("unroll") for (int m = 0; m < 4; ++m) _Pragma("unroll") for (int n = 0; n < 2; ++n) _Pragma("unroll") for (int k = 0; k < 2; ++k) \
;         acc[ai][bj][m][n] = __builtin_amdgcn_mfma_f32_16x16x32_bf16(Bt[n][k], At[m][k], acc[ai][bj][m][n], 0, 0, 0); __builtin_amdgcn_s_setprio(0); } while (0)
; #define PG8_WAIT_V(n) asm volatile("s_waitcnt vmcnt(" #n ")" ::: "memory")
; #define PG8_WAIT_L(n) asm volatile("s_waitcnt lgkmcnt(" #n ")" ::: "memory")
; #define PG8_BAR __builtin_amdgcn_s_barrier()
; #define PG8_SCHED __builtin_amdgcn_sched_barrier(0)
; template <class Epi>
; __device__ __forceinline__ void gemm_phase(LAS unsigned char* lds, const Gemm g, const StaticOrder& S, const Epi& E, int wave_) {
;     ...
;             PG8_STAGE(PG8_SB(1, 0), b3, voffB); PG8_STAGE(PG8_SB(1, 1), b3 + hstepB, voffB); PG8_STAGE(PG8_SA(1, 0), a3, voffA); PG8_LDA(At, 1, 1);
;             PG8_WAIT_V(8); PG8_WAIT_L(0); PG8_BAR; PG8_MMA(1, 0, At, B0); PG8_MMA(1, 1, At, B1); PG8_BAR; PG8_SCHED;
;         }
	s_add_u32 s40, s40, 0x160080
	s_addc_u32 s41, s41, 0
	v_mov_b32_e32 v160, v218
	s_nop 0
	s_nop 0
	v_xad_u32 v190, v160, 64, 0
	ds_read_b128 v[160:163], v191 offset:49152
	ds_read_b128 v[164:167], v191 offset:51200
	ds_read_b128 v[168:171], v190 offset:49152
	ds_read_b128 v[172:175], v190 offset:51200
	ds_read_b128 v[176:179], v191 offset:53248
	ds_read_b128 v[180:183], v191 offset:55296
	ds_read_b128 v[192:195], v190 offset:53248
	ds_read_b128 v[196:199], v190 offset:55296
	s_mov_b32 m0, s35
	s_nop 0
	global_load_lds_dwordx4 v214, s[46:47]
	s_mov_b32 m0, s33
	s_nop 0
	global_load_lds_dwordx4 v216, s[46:47]
	s_mov_b32 m0, s77
	s_nop 0
	global_load_lds_dwordx4 v214, s[40:41]
	s_mov_b32 m0, s3
	s_nop 0
	global_load_lds_dwordx4 v216, s[40:41]
	s_mov_b32 m0, s22
	s_nop 0
	global_load_lds_dwordx4 v184, s[36:37]
	s_mov_b32 m0, s2
	s_nop 0
	global_load_lds_dwordx4 v215, s[36:37]
	s_waitcnt vmcnt(8)
	s_waitcnt lgkmcnt(0)
	s_barrier
	s_setprio 1
	s_waitcnt lgkmcnt(0)
	v_mfma_f32_16x16x32_bf16 v[60:63], v[64:67], v[160:163], v[60:63]
	v_mfma_f32_16x16x32_bf16 v[56:59], v[68:71], v[160:163], v[56:59]
	v_mfma_f32_16x16x32_bf16 v[44:47], v[64:67], v[164:167], v[44:47]
	v_mfma_f32_16x16x32_bf16 v[40:43], v[68:71], v[164:167], v[40:43]
	v_mfma_f32_16x16x32_bf16 v[28:31], v[64:67], v[176:179], v[28:31]
	v_mfma_f32_16x16x32_bf16 v[24:27], v[68:71], v[176:179], v[24:27]
	v_mfma_f32_16x16x32_bf16 v[12:15], v[64:67], v[180:183], v[12:15]
	v_mfma_f32_16x16x32_bf16 v[8:11], v[68:71], v[180:183], v[8:11]
	v_mfma_f32_16x16x32_bf16 v[60:63], v[72:75], v[168:171], v[60:63]
	v_mfma_f32_16x16x32_bf16 v[56:59], v[76:79], v[168:171], v[56:59]
	v_mfma_f32_16x16x32_bf16 v[44:47], v[72:75], v[172:175], v[44:47]
	v_mfma_f32_16x16x32_bf16 v[40:43], v[76:79], v[172:175], v[40:43]
	v_mfma_f32_16x16x32_bf16 v[28:31], v[72:75], v[192:195], v[28:31]
	v_mfma_f32_16x16x32_bf16 v[24:27], v[76:79], v[192:195], v[24:27]
	v_mfma_f32_16x16x32_bf16 v[12:15], v[72:75], v[196:199], v[12:15]
	v_mfma_f32_16x16x32_bf16 v[8:11], v[76:79], v[196:199], v[8:11]
	s_setprio 0
	s_setprio 1
	v_mfma_f32_16x16x32_bf16 v[52:55], v[80:83], v[160:163], v[52:55]
	v_mfma_f32_16x16x32_bf16 v[48:51], v[84:87], v[160:163], v[48:51]
	v_mfma_f32_16x16x32_bf16 v[36:39], v[80:83], v[164:167], v[36:39]
	v_mfma_f32_16x16x32_bf16 v[32:35], v[84:87], v[164:167], v[32:35]
	v_mfma_f32_16x16x32_bf16 v[20:23], v[80:83], v[176:179], v[20:23]
	v_mfma_f32_16x16x32_bf16 v[16:19], v[84:87], v[176:179], v[16:19]
	v_mfma_f32_16x16x32_bf16 v[4:7], v[80:83], v[180:183], v[4:7]
	v_mfma_f32_16x16x32_bf16 v[0:3], v[84:87], v[180:183], v[0:3]
	v_mfma_f32_16x16x32_bf16 v[52:55], v[88:91], v[168:171], v[52:55]
	v_mfma_f32_16x16x32_bf16 v[48:51], v[92:95], v[168:171], v[48:51]
	v_mfma_f32_16x16x32_bf16 v[36:39], v[88:91], v[172:175], v[36:39]
	v_mfma_f32_16x16x32_bf16 v[32:35], v[92:95], v[172:175], v[32:35]
	v_mfma_f32_16x16x32_bf16 v[20:23], v[88:91], v[192:195], v[20:23]
	v_mfma_f32_16x16x32_bf16 v[16:19], v[92:95], v[192:195], v[16:19]
	v_mfma_f32_16x16x32_bf16 v[4:7], v[88:91], v[196:199], v[4:7]
	v_mfma_f32_16x16x32_bf16 v[0:3], v[92:95], v[196:199], v[0:3]
	s_setprio 0
	s_barrier
	s_add_i32 s59, s59, 2
	s_add_u32 s16, s16, 0x100
	s_addc_u32 s17, s17, 0
	s_add_u32 s12, s12, 0x100
	s_addc_u32 s13, s13, 0
	s_cmpk_gt_u32 s59, 0x55
	s_cbranch_scc0 .LBB0_1552
	v_readlane_b32 s12, v253, 13
	v_readlane_b32 s13, v253, 14
	s_and_b64 vcc, exec, s[12:13]
	s_cbranch_vccz .LBB0_1555
	s_barrier

; __device__ __forceinline__ int tid_of(int wave) { return opqv(wave * 64 + (int)__builtin_amdgcn_mbcnt_hi(~0u, __builtin_amdgcn_mbcnt_lo(~0u, 0u))); }
; __host__ __device__ __forceinline__ int lds_byte(int r, int c) { return (r >> 3) * 1024 + (r & 7) * 128 + ((((c >> 3)) ^ ((r >> 1) & 7)) << 4) + (c & 7) * 2; }
; #define PG8_WAIT_V(n) asm volatile("s_waitcnt vmcnt(" #n ")" ::: "memory")
; #define PG8_BAR __builtin_amdgcn_s_barrier()
; template <class Epi>
; __device__ __forceinline__ void gemm_phase(LAS unsigned char* lds, const Gemm g, const StaticOrder& S, const Epi& E, int wave_) {
;     const int tid = tid_of(wave_), wid = wave_, lane = tid & 63, wr = wid >> 2, wc = wid & 3, fr = lane & 15, fq = lane >> 4;
;     const int K = g.K, nt = K / BK;
;     unsigned voffA[2], voffB[2];
; #pragma unroll
;     for (int i = 0; i < 2; ++i) { int R, C; stage_rc(tid * 16 + i * 8192, R, C); const int Rb = (R & ~31) + perm32(R & 31);
;         voffA[i] = (unsigned)(R * g.lda + C) * 2u; voffB[i] = (unsigned)(Rb * g.ldb + C) * 2u; }
;     const size_t kstep = (size_t)(BK * 2);
;     const size_t hstepA = (size_t)HALF * g.lda * 2, hstepB = (size_t)HALF * g.ldb * 2;
;     const size_t tstepA = 2 * hstepA, tstepB = 2 * hstepB;
;     const unsigned ldsw = (unsigned)wid * 1024u, ldsb = (unsigned)(uintptr_t)lds;
;     const int aoff0 = lds_byte(wr * 64 + fr, fq * 8), boff0 = lds_byte(wc * 32 + fr, fq * 8);
;     ...
;     Unit cur, nxt; int ui = 0;
;     if (!S.next(0, cur)) return;
;     f32x4 acc[2][2][4][2];
; #pragma unroll
;     for (int a = 0; a < 2; ++a)
; #pragma unroll
;         for (int b = 0; b < 2; ++b)
; #pragma unroll
;             for (int m = 0; m < 4; ++m)
; #pragma unroll
;                 for (int n = 0; n < 2; ++n) acc[a][b][m][n] = (f32x4){0.f, 0.f, 0.f, 0.f};
;     bf16x8 At[4][2], B0[2][2], B1[2][2];
;     const char* cA = (const char*)g.A + (size_t)cur.pm * tstepA; const char* cB = (const char*)g.Bt + (size_t)cur.pn * tstepB;
;     PG8_STAGE(PG8_SB(0, 0), cB, voffB); PG8_STAGE(PG8_SB(0, 1), cB + hstepB, voffB); PG8_STAGE(PG8_SA(0, 0), cA, voffA); PG8_STAGE(PG8_SA(0, 1), cA + hstepA, voffA);
;     if (wr == 1) PG8_BAR;
;     PG8_WAIT_V(2); PG8_BAR;
;     PG8_STAGE(PG8_SB(1, 0), cB + kstep, voffB); PG8_STAGE(PG8_SA(1, 0), cA + kstep, voffA); PG8_STAGE(PG8_SB(1, 1), cB + hstepB + kstep, voffB);
;     PG8_WAIT_V(6); PG8_BAR;
.LBB0_1763:
	v_readlane_b32 s30, v252, 12
	v_readlane_b32 s16, v252, 14
	v_readlane_b32 s31, v252, 13
	v_readlane_b32 s17, v252, 15
	s_mov_b64 s[6:7], s[30:31]
	s_mov_b64 s[8:9], s[30:31]
	s_mov_b64 s[10:11], s[16:17]
	s_mov_b64 s[24:25], s[30:31]
	s_mov_b64 s[26:27], s[30:31]
	v_mov_b32_e32 v0, v220
	s_and_b64 vcc, exec, s[66:67]
	s_cbranch_vccnz .LBB0_1911
	v_bfe_i32 v3, v0, 27, 1
	v_lshlrev_b32_e32 v1, 4, v0
	v_lshrrev_b32_e32 v4, 22, v3
	v_add_u32_e32 v4, v1, v4
	v_and_b32_e32 v4, 0xfc00, v4
	v_sub_u32_e32 v4, v1, v4
	v_ashrrev_i16_e32 v5, 15, v4
	v_ashrrev_i32_e32 v2, 31, v0
	v_lshrrev_b16_e32 v5, 9, v5
	v_lshrrev_b32_e32 v3, 25, v3
	v_lshrrev_b32_e32 v2, 26, v2
	v_add_u16_e32 v4, v4, v5
	v_add_u32_e32 v3, v1, v3
	v_add_u32_e32 v2, v0, v2
	v_ashrrev_i16_e32 v4, 7, v4
	v_and_b32_e32 v3, 0x80, v3
	v_ashrrev_i32_e32 v2, 6, v2
	v_bfe_i32 v4, v4, 0, 16
	v_sub_u32_e32 v3, v1, v3
	v_mov_b32_e32 v7, 4
	v_ashrrev_i16_sdwa v3, v7, sext(v3) dst_sel:DWORD dst_unused:UNUSED_PAD src0_sel:DWORD src1_sel:BYTE_0
	v_lshl_add_u32 v2, v2, 3, v4
	v_bfe_i32 v3, v3, 0, 16
	v_lshrrev_b32_e32 v5, 1, v2
	s_load_dwordx2 s[10:11], s[10:11], 0x68
	s_nop 0
	s_load_dwordx2 s[18:19], s[16:17], 0x70
	v_bitop3_b32 v3, v5, v3, 7 bitop3:0x6c
	v_lshlrev_b32_e32 v5, 1, v2
	v_lshrrev_b32_e32 v6, 2, v2
	v_and_b32_e32 v4, 3, v4
	s_mov_b32 s16, 0xfffe0
	v_lshlrev_b32_e32 v3, 4, v3
	v_and_b32_e32 v5, 24, v5
	v_and_b32_e32 v6, 4, v6
	v_and_or_b32 v4, v2, s16, v4
	v_add_u32_e32 v1, 0x2000, v1
	v_or3_b32 v4, v4, v6, v5
	v_lshl_add_u32 v184, v2, 12, v3
	v_ashrrev_i32_e32 v2, 31, v1
	v_lshl_add_u32 v233, v4, 12, v3
	v_lshrrev_b32_e32 v3, 22, v2
	v_add_u32_e32 v3, v1, v3
	v_ashrrev_i32_e32 v3, 10, v3
	v_mul_i32_i24_e32 v4, 0x400, v3
	v_sub_u32_e32 v4, v1, v4
	v_ashrrev_i16_e32 v5, 15, v4
	v_lshrrev_b16_e32 v5, 9, v5
	v_lshrrev_b32_e32 v2, 25, v2
	v_add_u16_e32 v4, v4, v5
	v_add_u32_e32 v2, v1, v2
	s_add_u32 s21, s12, 0x10000000
	v_ashrrev_i16_e32 v4, 7, v4
	v_and_b32_e32 v2, 0x80, v2
	s_addc_u32 s52, s13, 0
	v_readlane_b32 s12, v255, 24
	v_bfe_i32 v4, v4, 0, 16
	v_sub_u32_e32 v1, v1, v2
	s_add_u32 s12, s40, s12
	v_ashrrev_i16_sdwa v1, v7, sext(v1) dst_sel:DWORD dst_unused:UNUSED_PAD src0_sel:DWORD src1_sel:BYTE_0
	v_lshl_add_u32 v2, v3, 3, v4
	s_addc_u32 s13, s41, 0
	v_bfe_i32 v1, v1, 0, 16
	v_lshrrev_b32_e32 v3, 1, v2
	s_add_u32 s66, s12, 0x7200000
	v_bitop3_b32 v1, v3, v1, 7 bitop3:0x6c
	v_lshlrev_b32_e32 v3, 1, v2
	v_lshrrev_b32_e32 v5, 2, v2
	v_and_b32_e32 v4, 3, v4
	s_addc_u32 s67, s13, 0
	v_readlane_b32 s12, v254, 13
	v_and_b32_e32 v3, 24, v3
	v_and_b32_e32 v5, 4, v5
	v_and_or_b32 v4, v2, s16, v4
	v_readlane_b32 s13, v254, 14
	s_add_u32 s12, s66, s12
	v_lshlrev_b32_e32 v1, 4, v1
	v_or3_b32 v3, v4, v5, v3
	s_addc_u32 s13, s67, s13
	s_mov_b32 m0, s80
	s_nop 0
	global_load_lds_dwordx4 v233, s[12:13]
	v_lshl_add_u32 v235, v3, 12, v1
	s_mov_b32 m0, s81
	s_nop 0
	global_load_lds_dwordx4 v235, s[12:13]
	s_add_u32 s16, s12, 0x80000
	s_addc_u32 s17, s13, 0
	s_mov_b32 m0, s29
	s_nop 0
	global_load_lds_dwordx4 v233, s[16:17]
	v_lshl_add_u32 v234, v2, 12, v1
	s_mov_b32 m0, s88
	s_nop 0
	global_load_lds_dwordx4 v235, s[16:17]
	v_readlane_b32 s16, v254, 39
	v_readlane_b32 s17, v254, 40
	s_add_u32 s46, s21, s16
	s_addc_u32 s47, s52, s17
	s_mov_b32 m0, s76
	s_nop 0
	global_load_lds_dwordx4 v184, s[46:47]
	s_nop 0
	s_mov_b32 m0, s89
	s_nop 0
	global_load_lds_dwordx4 v234, s[46:47]
	s_add_u32 s16, s46, 0x80000
	s_addc_u32 s17, s47, 0
	s_mov_b32 m0, s1
	s_nop 0
	global_load_lds_dwordx4 v184, s[16:17]
	s_and_b64 vcc, exec, s[38:39]
	s_mov_b32 m0, s69
	s_nop 0
	global_load_lds_dwordx4 v234, s[16:17]
	s_cbranch_vccnz .LBB0_1766
	s_barrier
.LBB0_1766:
	v_readlane_b32 s16, v255, 20
	s_add_u32 s6, s6, 0x8000000
	v_readlane_b32 s17, v255, 21
	s_addc_u32 s7, s7, 0
	s_lshl_b64 s[16:17], s[16:17], 3
	s_add_u32 s8, s8, s16
	s_addc_u32 s9, s9, s17
	v_readlane_b32 s16, v255, 37
	s_add_u32 s8, s8, 0x100000
	v_readlane_b32 s17, v255, 38
	s_addc_u32 s9, s9, 0
	s_lshl_b64 s[16:17], s[16:17], 2
	s_waitcnt lgkmcnt(0)
	s_add_u32 s10, s10, s16
	s_addc_u32 s11, s11, s17
	s_add_u32 s10, s10, 0x2000
	s_addc_u32 s11, s11, 0
	s_add_u32 s16, s18, s16
	s_addc_u32 s17, s19, s17
	s_add_u32 s18, s16, 0x2000
	s_addc_u32 s19, s17, 0
	v_readlane_b32 s16, v255, 31
	v_readlane_b32 s17, v255, 32
	s_lshl_b64 s[16:17], s[16:17], 2
	s_add_u32 s24, s24, s16
	s_addc_u32 s25, s25, s17
	s_add_u32 s24, s24, 0x716000
	s_addc_u32 s25, s25, 0
	s_add_u32 s16, s26, s16
	s_addc_u32 s17, s27, s17
	s_add_u32 s26, s16, 0x718000
	s_addc_u32 s27, s17, 0
	s_add_u32 s30, s30, 0x2f000000
	s_addc_u32 s31, s31, 0
	s_add_u32 s36, s36, 0x10000000
	v_and_b32_e32 v2, 15, v0
	v_readlane_b32 s16, v253, 6
	s_addc_u32 s37, s37, 0
	s_waitcnt vmcnt(2)
	s_barrier
	v_or_b32_e32 v236, s16, v2
	s_add_u32 s16, s12, 0x80
	s_addc_u32 s17, s13, 0
	s_mov_b32 m0, s35
	s_nop 0
	global_load_lds_dwordx4 v233, s[16:17]
	v_lshrrev_b32_e32 v1, 4, v0
	s_mov_b32 m0, s33
	s_nop 0
	global_load_lds_dwordx4 v235, s[16:17]
	s_add_u32 s16, s46, 0x80
	s_addc_u32 s17, s47, 0
	s_mov_b32 m0, s22
	s_nop 0
	global_load_lds_dwordx4 v184, s[16:17]
	v_bfe_u32 v3, v0, 4, 2
	s_mov_b32 m0, s2
	s_nop 0
	global_load_lds_dwordx4 v234, s[16:17]
	s_add_u32 s16, s12, 0x80080
	s_addc_u32 s17, s13, 0
	s_mov_b32 m0, s77
	s_nop 0
	global_load_lds_dwordx4 v233, s[16:17]
	v_bfe_u32 v0, v0, 1, 3
	s_mov_b32 m0, s3
	s_nop 0
	global_load_lds_dwordx4 v235, s[16:17]
	v_bitop3_b32 v0, v1, v0, 3 bitop3:0x6c
	v_readlane_b32 s44, v253, 7
	s_waitcnt vmcnt(6)
	v_lshlrev_b32_e32 v0, 4, v0
	s_cmp_lg_u64 s[4:5], 0
	v_or_b32_e32 v1, s44, v2
	v_readlane_b32 s16, v254, 37
	v_lshl_or_b32 v237, v236, 7, v0
	v_lshl_or_b32 v238, v1, 7, v0
	v_cmp_gt_u32_e64 s[40:41], 8, v2
	v_cmp_lt_u32_e64 s[42:43], 7, v2
	s_cselect_b64 s[54:55], -1, 0
	v_lshl_or_b32 v239, v3, 3, s44
	s_mov_b32 s70, 0
	v_readlane_b32 s71, v254, 4
	s_mov_b32 s74, s16
	s_barrier
	v_readlane_b32 s17, v254, 38
	s_branch .LBB0_1769

; #define PG8_STAGE(bufoff, gbase, voff) do { _Pragma("unroll") for (int _i = 0; _i < 2; ++_i) \
;         dma16((const char*)(gbase), (voff)[_i], ldsb + (bufoff) + ldsw + _i * 8192); } while (0)
; #define PG8_LDA(dst, b, h) do { const int a1_ = opqv(aoff0) ^ 64; _Pragma("unroll") for (int m = 0; m < 4; ++m) { dst[m][0] = *(const LAS bf16x8*)(lds + PG8_SA(b, h) + aoff0 + m * 2048); dst[m][1] = *(const LAS bf16x8*)(lds + PG8_SA(b, h) + a1_ + m * 2048); } } while (0)
; #define PG8_LDB(dst, b, h) do { const int b1_ = opqv(boff0) ^ 64; _Pragma("unroll") for (int n = 0; n < 2; ++n) { dst[n][0] = *(const LAS bf16x8*)(lds + PG8_SB(b, h) + boff0 + n * 2048); dst[n][1] = *(const LAS bf16x8*)(lds + PG8_SB(b, h) + b1_ + n * 2048); } } while (0)
; #define PG8_MMA(ai, bj, At, Bt) do { __builtin_amdgcn_s_setprio(1); _Pragma("unroll") for (int m = 0; m < 4; ++m) _Pragma("unroll") for (int n = 0; n < 2; ++n) _Pragma("unroll") for (int k = 0; k < 2; ++k) \
;         acc[ai][bj][m][n] = __builtin_amdgcn_mfma_f32_16x16x32_bf16(Bt[n][k], At[m][k], acc[ai][bj][m][n], 0, 0, 0); __builtin_amdgcn_s_setprio(0); } while (0)
; #define PG8_WAIT_V(n) asm volatile("s_waitcnt vmcnt(" #n ")" ::: "memory")
; #define PG8_WAIT_L(n) asm volatile("s_waitcnt lgkmcnt(" #n ")" ::: "memory")
; #define PG8_BAR __builtin_amdgcn_s_barrier()
; #define PG8_SCHED __builtin_amdgcn_sched_barrier(0)
; template <class Epi>
; __device__ __forceinline__ void gemm_phase(LAS unsigned char* lds, const Gemm g, const StaticOrder& S, const Epi& E, int wave_) {
;     ...
;             const bool last = (t == nt - 2);
;             const char* a1 = cA + (size_t)(t + 1) * kstep;
;             const char* a2 = last ? nA : cA + (size_t)(t + 2) * kstep; const char* b2 = last ? nB : cB + (size_t)(t + 2) * kstep;
;             const char* a3 = a2 + kstep; const char* b3 = b2 + kstep;
;             PG8_STAGE(PG8_SA(1, 1), a1 + hstepA, voffA); PG8_LDB(B0, 0, 0); PG8_LDB(B1, 0, 1); PG8_SCHED; PG8_LDA(At, 0, 0);
;             PG8_WAIT_V(8); PG8_WAIT_L(0); PG8_BAR; PG8_MMA(0, 0, At, B0); PG8_MMA(0, 1, At, B1); PG8_BAR; PG8_SCHED;
;             PG8_STAGE(PG8_SB(0, 0), b2, voffB); PG8_STAGE(PG8_SB(0, 1), b2 + hstepB, voffB); PG8_STAGE(PG8_SA(0, 0), a2, voffA); PG8_LDA(At, 0, 1);
;             PG8_WAIT_V(8); PG8_WAIT_L(0); PG8_BAR; PG8_MMA(1, 0, At, B0); PG8_MMA(1, 1, At, B1); PG8_BAR; PG8_SCHED;
.LBB0_1776:
	s_add_u32 s46, s12, 0xfff80080
	s_addc_u32 s47, s13, -1
	s_cmp_eq_u32 s79, 28
	s_cselect_b32 s64, s17, s46
	s_cselect_b32 s65, s16, s47
	s_cselect_b32 s48, s59, s75
	s_cselect_b32 s49, s57, s78
	s_add_u32 s46, s64, 0x80
	v_mov_b32_e32 v88, v238
	s_addc_u32 s47, s65, 0
	v_add_u32_e32 v92, s23, v238
	v_xad_u32 v100, v88, 64, s23
	v_mov_b32_e32 v108, v238
	s_add_i32 s82, 0, 0x14000
	ds_read_b128 v[88:91], v92
	ds_read_b128 v[92:95], v92 offset:2048
	ds_read_b128 v[96:99], v100
	ds_read_b128 v[100:103], v100 offset:2048
	v_add_u32_e32 v112, s82, v238
	v_xad_u32 v124, v108, 64, s82
	ds_read_b128 v[108:111], v112
	ds_read_b128 v[112:115], v112 offset:2048
	ds_read_b128 v[120:123], v124
	ds_read_b128 v[124:127], v124 offset:2048
	v_mov_b32_e32 v160, v237
	v_add_u32_e32 v191, 0, v237
	v_xad_u32 v190, v160, 64, 0
	ds_read_b128 v[160:163], v191
	ds_read_b128 v[164:167], v191 offset:2048
	ds_read_b128 v[168:171], v190
	ds_read_b128 v[172:175], v190 offset:2048
	ds_read_b128 v[176:179], v191 offset:4096
	ds_read_b128 v[180:183], v191 offset:6144
	ds_read_b128 v[192:195], v190 offset:4096
	ds_read_b128 v[196:199], v190 offset:6144
	s_mov_b32 m0, s14
	s_nop 0
	global_load_lds_dwordx4 v184, s[12:13]
	s_mov_b32 m0, s15
	s_nop 0
	global_load_lds_dwordx4 v234, s[12:13]
	s_waitcnt vmcnt(8)
	s_waitcnt lgkmcnt(0)
	s_barrier
	s_setprio 1
	s_waitcnt lgkmcnt(0)
	v_mfma_f32_16x16x32_bf16 v[156:159], v[88:91], v[160:163], v[156:159]
	v_mfma_f32_16x16x32_bf16 v[152:155], v[92:95], v[160:163], v[152:155]
	v_mfma_f32_16x16x32_bf16 v[148:151], v[88:91], v[164:167], v[148:151]
	v_mfma_f32_16x16x32_bf16 v[144:147], v[92:95], v[164:167], v[144:147]
	v_mfma_f32_16x16x32_bf16 v[140:143], v[88:91], v[176:179], v[140:143]
	v_mfma_f32_16x16x32_bf16 v[136:139], v[92:95], v[176:179], v[136:139]
	v_mfma_f32_16x16x32_bf16 v[132:135], v[88:91], v[180:183], v[132:135]
	v_mfma_f32_16x16x32_bf16 v[128:131], v[92:95], v[180:183], v[128:131]
	v_mfma_f32_16x16x32_bf16 v[156:159], v[96:99], v[168:171], v[156:159]
	v_mfma_f32_16x16x32_bf16 v[152:155], v[100:103], v[168:171], v[152:155]
	v_mfma_f32_16x16x32_bf16 v[148:151], v[96:99], v[172:175], v[148:151]
	v_mfma_f32_16x16x32_bf16 v[144:147], v[100:103], v[172:175], v[144:147]
	v_mfma_f32_16x16x32_bf16 v[140:143], v[96:99], v[192:195], v[140:143]
	v_mfma_f32_16x16x32_bf16 v[136:139], v[100:103], v[192:195], v[136:139]
	v_mfma_f32_16x16x32_bf16 v[132:135], v[96:99], v[196:199], v[132:135]
	v_mfma_f32_16x16x32_bf16 v[128:131], v[100:103], v[196:199], v[128:131]
	s_setprio 0
	s_setprio 1
	v_mfma_f32_16x16x32_bf16 v[60:63], v[108:111], v[160:163], v[60:63]
	v_mfma_f32_16x16x32_bf16 v[56:59], v[112:115], v[160:163], v[56:59]
	v_mfma_f32_16x16x32_bf16 v[52:55], v[108:111], v[164:167], v[52:55]
	v_mfma_f32_16x16x32_bf16 v[48:51], v[112:115], v[164:167], v[48:51]
	v_mfma_f32_16x16x32_bf16 v[44:47], v[108:111], v[176:179], v[44:47]
	v_mfma_f32_16x16x32_bf16 v[40:43], v[112:115], v[176:179], v[40:43]
	v_mfma_f32_16x16x32_bf16 v[36:39], v[108:111], v[180:183], v[36:39]
	v_mfma_f32_16x16x32_bf16 v[32:35], v[112:115], v[180:183], v[32:35]
	v_mfma_f32_16x16x32_bf16 v[60:63], v[120:123], v[168:171], v[60:63]
	v_mfma_f32_16x16x32_bf16 v[56:59], v[124:127], v[168:171], v[56:59]
	v_mfma_f32_16x16x32_bf16 v[52:55], v[120:123], v[172:175], v[52:55]
	v_mfma_f32_16x16x32_bf16 v[48:51], v[124:127], v[172:175], v[48:51]
	v_mfma_f32_16x16x32_bf16 v[44:47], v[120:123], v[192:195], v[44:47]
	v_mfma_f32_16x16x32_bf16 v[40:43], v[124:127], v[192:195], v[40:43]
	v_mfma_f32_16x16x32_bf16 v[36:39], v[120:123], v[196:199], v[36:39]
	v_mfma_f32_16x16x32_bf16 v[32:35], v[124:127], v[196:199], v[32:35]
	s_setprio 0
	s_barrier
	v_mov_b32_e32 v160, v237
	s_add_u32 s82, s48, 0x80000
	s_addc_u32 s83, s49, 0
	s_nop 0
	s_nop 0
	s_nop 0
	v_xad_u32 v190, v160, 64, 0
	ds_read_b128 v[160:163], v191 offset:16384
	ds_read_b128 v[164:167], v191 offset:18432
	ds_read_b128 v[168:171], v190 offset:16384
	ds_read_b128 v[172:175], v190 offset:18432
	ds_read_b128 v[176:179], v191 offset:20480
	ds_read_b128 v[180:183], v191 offset:22528
	ds_read_b128 v[192:195], v190 offset:20480
	ds_read_b128 v[196:199], v190 offset:22528
	s_mov_b32 m0, s80
	s_nop 0
	global_load_lds_dwordx4 v233, s[48:49]
	s_mov_b32 m0, s81
	s_nop 0
	global_load_lds_dwordx4 v235, s[48:49]
	s_mov_b32 m0, s29
	s_nop 0
	global_load_lds_dwordx4 v233, s[82:83]
	s_mov_b32 m0, s88
	s_nop 0
	global_load_lds_dwordx4 v235, s[82:83]
	s_mov_b32 m0, s76
	s_nop 0
	global_load_lds_dwordx4 v184, s[64:65]
	s_mov_b32 m0, s89
	s_nop 0
	global_load_lds_dwordx4 v234, s[64:65]
	s_waitcnt vmcnt(8)
	s_waitcnt lgkmcnt(0)
	s_barrier
; #define PG8_STAGE(bufoff, gbase, voff) do { _Pragma("unroll") for (int _i = 0; _i < 2; ++_i) \
;         dma16((const char*)(gbase), (voff)[_i], ldsb + (bufoff) + ldsw + _i * 8192); } while (0)
; #define PG8_LDA(dst, b, h) do { const int a1_ = opqv(aoff0) ^ 64; _Pragma("unroll") for (int m = 0; m < 4; ++m) { dst[m][0] = *(const LAS bf16x8*)(lds + PG8_SA(b, h) + aoff0 + m * 2048); dst[m][1] = *(const LAS bf16x8*)(lds + PG8_SA(b, h) + a1_ + m * 2048); } } while (0)
; #define PG8_LDB(dst, b, h) do { const int b1_ = opqv(boff0) ^ 64; _Pragma("unroll") for (int n = 0; n < 2; ++n) { dst[n][0] = *(const LAS bf16x8*)(lds + PG8_SB(b, h) + boff0 + n * 2048); dst[n][1] = *(const LAS bf16x8*)(lds + PG8_SB(b, h) + b1_ + n * 2048); } } while (0)
; #define PG8_MMA(ai, bj, At, Bt) do { __builtin_amdgcn_s_setprio(1); _Pragma("unroll") for (int m = 0; m < 4; ++m) _Pragma("unroll") for (int n = 0; n < 2; ++n) _Pragma("unroll") for (int k = 0; k < 2; ++k) \
;         acc[ai][bj][m][n] = __builtin_amdgcn_mfma_f32_16x16x32_bf16(Bt[n][k], At[m][k], acc[ai][bj][m][n], 0, 0, 0); __builtin_amdgcn_s_setprio(0); } while (0)
; #define PG8_WAIT_V(n) asm volatile("s_waitcnt vmcnt(" #n ")" ::: "memory")
; #define PG8_WAIT_L(n) asm volatile("s_waitcnt lgkmcnt(" #n ")" ::: "memory")
; #define PG8_BAR __builtin_amdgcn_s_barrier()
; #define PG8_SCHED __builtin_amdgcn_sched_barrier(0)
; template <class Epi>
; __device__ __forceinline__ void gemm_phase(LAS unsigned char* lds, const Gemm g, const StaticOrder& S, const Epi& E, int wave_) {
;     ...
;             PG8_WAIT_V(8); PG8_WAIT_L(0); PG8_BAR; PG8_MMA(1, 0, At, B0); PG8_MMA(1, 1, At, B1); PG8_BAR; PG8_SCHED;
;             PG8_STAGE(PG8_SA(0, 1), a2 + hstepA, voffA); PG8_LDB(B0, 1, 0); PG8_LDB(B1, 1, 1); PG8_SCHED; PG8_LDA(At, 1, 0);
;             PG8_WAIT_V(8); PG8_WAIT_L(0); PG8_BAR; PG8_MMA(0, 0, At, B0); PG8_MMA(0, 1, At, B1); PG8_BAR; PG8_SCHED;
	s_setprio 1
	s_waitcnt lgkmcnt(0)
	v_mfma_f32_16x16x32_bf16 v[116:119], v[88:91], v[160:163], v[116:119]
	v_mfma_f32_16x16x32_bf16 v[104:107], v[92:95], v[160:163], v[104:107]
	v_mfma_f32_16x16x32_bf16 v[84:87], v[88:91], v[164:167], v[84:87]
	v_mfma_f32_16x16x32_bf16 v[80:83], v[92:95], v[164:167], v[80:83]
	v_mfma_f32_16x16x32_bf16 v[76:79], v[88:91], v[176:179], v[76:79]
	v_mfma_f32_16x16x32_bf16 v[72:75], v[92:95], v[176:179], v[72:75]
	v_mfma_f32_16x16x32_bf16 v[68:71], v[88:91], v[180:183], v[68:71]
	v_mfma_f32_16x16x32_bf16 v[64:67], v[92:95], v[180:183], v[64:67]
	v_mfma_f32_16x16x32_bf16 v[116:119], v[96:99], v[168:171], v[116:119]
	v_mfma_f32_16x16x32_bf16 v[104:107], v[100:103], v[168:171], v[104:107]
	v_mfma_f32_16x16x32_bf16 v[84:87], v[96:99], v[172:175], v[84:87]
	v_mfma_f32_16x16x32_bf16 v[80:83], v[100:103], v[172:175], v[80:83]
	v_mfma_f32_16x16x32_bf16 v[76:79], v[96:99], v[192:195], v[76:79]
	v_mfma_f32_16x16x32_bf16 v[72:75], v[100:103], v[192:195], v[72:75]
	v_mfma_f32_16x16x32_bf16 v[68:71], v[96:99], v[196:199], v[68:71]
	v_mfma_f32_16x16x32_bf16 v[64:67], v[100:103], v[196:199], v[64:67]
	s_setprio 0
	s_setprio 1
	v_mfma_f32_16x16x32_bf16 v[28:31], v[108:111], v[160:163], v[28:31]
	v_mfma_f32_16x16x32_bf16 v[24:27], v[112:115], v[160:163], v[24:27]
	v_mfma_f32_16x16x32_bf16 v[20:23], v[108:111], v[164:167], v[20:23]
	v_mfma_f32_16x16x32_bf16 v[16:19], v[112:115], v[164:167], v[16:19]
	v_mfma_f32_16x16x32_bf16 v[12:15], v[108:111], v[176:179], v[12:15]
	v_mfma_f32_16x16x32_bf16 v[8:11], v[112:115], v[176:179], v[8:11]
	v_mfma_f32_16x16x32_bf16 v[4:7], v[108:111], v[180:183], v[4:7]
	v_mfma_f32_16x16x32_bf16 v[0:3], v[112:115], v[180:183], v[0:3]
	v_mfma_f32_16x16x32_bf16 v[28:31], v[120:123], v[168:171], v[28:31]
	v_mfma_f32_16x16x32_bf16 v[24:27], v[124:127], v[168:171], v[24:27]
	v_mfma_f32_16x16x32_bf16 v[20:23], v[120:123], v[172:175], v[20:23]
	v_mfma_f32_16x16x32_bf16 v[16:19], v[124:127], v[172:175], v[16:19]
	v_mfma_f32_16x16x32_bf16 v[12:15], v[120:123], v[192:195], v[12:15]
	v_mfma_f32_16x16x32_bf16 v[8:11], v[124:127], v[192:195], v[8:11]
	v_mfma_f32_16x16x32_bf16 v[4:7], v[120:123], v[196:199], v[4:7]
	v_mfma_f32_16x16x32_bf16 v[0:3], v[124:127], v[196:199], v[0:3]
	s_setprio 0
	s_barrier
	s_add_u32 s64, s64, 0x80000
	s_addc_u32 s65, s65, 0
	s_mov_b32 m0, s1
	s_nop 0
	global_load_lds_dwordx4 v184, s[64:65]
	v_mov_b32_e32 v88, v238
	s_mov_b32 m0, s69
	s_nop 0
	global_load_lds_dwordx4 v234, s[64:65]
	v_add_u32_e32 v92, s34, v238
	v_xad_u32 v100, v88, 64, s34
	v_mov_b32_e32 v108, v238
	s_add_i32 s64, 0, 0x1c000
	ds_read_b128 v[88:91], v92
	ds_read_b128 v[92:95], v92 offset:2048
	ds_read_b128 v[96:99], v100
	ds_read_b128 v[100:103], v100 offset:2048
	v_add_u32_e32 v112, s64, v238
	v_xad_u32 v124, v108, 64, s64
	ds_read_b128 v[108:111], v112
	ds_read_b128 v[112:115], v112 offset:2048
	ds_read_b128 v[120:123], v124
	ds_read_b128 v[124:127], v124 offset:2048
	v_mov_b32_e32 v160, v237
	s_nop 0
	v_xad_u32 v190, v160, 64, 0
	ds_read_b128 v[160:163], v191 offset:32768
	ds_read_b128 v[164:167], v191 offset:34816
	ds_read_b128 v[168:171], v190 offset:32768
	ds_read_b128 v[172:175], v190 offset:34816
	ds_read_b128 v[176:179], v191 offset:36864
	ds_read_b128 v[180:183], v191 offset:38912
	ds_read_b128 v[192:195], v190 offset:36864
	ds_read_b128 v[196:199], v190 offset:38912
	s_waitcnt vmcnt(8)
	s_waitcnt lgkmcnt(0)
	s_barrier
	s_setprio 1
	s_waitcnt lgkmcnt(0)
	v_mfma_f32_16x16x32_bf16 v[156:159], v[88:91], v[160:163], v[156:159]
	v_mfma_f32_16x16x32_bf16 v[152:155], v[92:95], v[160:163], v[152:155]
	v_mfma_f32_16x16x32_bf16 v[148:151], v[88:91], v[164:167], v[148:151]
	v_mfma_f32_16x16x32_bf16 v[144:147], v[92:95], v[164:167], v[144:147]
	v_mfma_f32_16x16x32_bf16 v[140:143], v[88:91], v[176:179], v[140:143]
	v_mfma_f32_16x16x32_bf16 v[136:139], v[92:95], v[176:179], v[136:139]
	v_mfma_f32_16x16x32_bf16 v[132:135], v[88:91], v[180:183], v[132:135]
	v_mfma_f32_16x16x32_bf16 v[128:131], v[92:95], v[180:183], v[128:131]
	v_mfma_f32_16x16x32_bf16 v[156:159], v[96:99], v[168:171], v[156:159]
	v_mfma_f32_16x16x32_bf16 v[152:155], v[100:103], v[168:171], v[152:155]
	v_mfma_f32_16x16x32_bf16 v[148:151], v[96:99], v[172:175], v[148:151]
	v_mfma_f32_16x16x32_bf16 v[144:147], v[100:103], v[172:175], v[144:147]
	v_mfma_f32_16x16x32_bf16 v[140:143], v[96:99], v[192:195], v[140:143]
	v_mfma_f32_16x16x32_bf16 v[136:139], v[100:103], v[192:195], v[136:139]
	v_mfma_f32_16x16x32_bf16 v[132:135], v[96:99], v[196:199], v[132:135]
	v_mfma_f32_16x16x32_bf16 v[128:131], v[100:103], v[196:199], v[128:131]
	s_setprio 0
	s_setprio 1
	v_mfma_f32_16x16x32_bf16 v[60:63], v[108:111], v[160:163], v[60:63]
	s_add_u32 s64, s48, 0x80
	s_addc_u32 s65, s49, 0
	v_mfma_f32_16x16x32_bf16 v[56:59], v[112:115], v[160:163], v[56:59]
	v_mfma_f32_16x16x32_bf16 v[52:55], v[108:111], v[164:167], v[52:55]
	v_mfma_f32_16x16x32_bf16 v[48:51], v[112:115], v[164:167], v[48:51]
	v_mfma_f32_16x16x32_bf16 v[44:47], v[108:111], v[176:179], v[44:47]
	v_mfma_f32_16x16x32_bf16 v[40:43], v[112:115], v[176:179], v[40:43]
	v_mfma_f32_16x16x32_bf16 v[36:39], v[108:111], v[180:183], v[36:39]
	v_mfma_f32_16x16x32_bf16 v[32:35], v[112:115], v[180:183], v[32:35]
	v_mfma_f32_16x16x32_bf16 v[60:63], v[120:123], v[168:171], v[60:63]
	v_mfma_f32_16x16x32_bf16 v[56:59], v[124:127], v[168:171], v[56:59]
	v_mfma_f32_16x16x32_bf16 v[52:55], v[120:123], v[172:175], v[52:55]
	v_mfma_f32_16x16x32_bf16 v[48:51], v[124:127], v[172:175], v[48:51]
	v_mfma_f32_16x16x32_bf16 v[44:47], v[120:123], v[192:195], v[44:47]
	v_mfma_f32_16x16x32_bf16 v[40:43], v[124:127], v[192:195], v[40:43]
	v_mfma_f32_16x16x32_bf16 v[36:39], v[120:123], v[196:199], v[36:39]
	v_mfma_f32_16x16x32_bf16 v[32:35], v[124:127], v[196:199], v[32:35]
	s_setprio 0
	s_barrier
; #define PG8_STAGE(bufoff, gbase, voff) do { _Pragma("unroll") for (int _i = 0; _i < 2; ++_i) \
;         dma16((const char*)(gbase), (voff)[_i], ldsb + (bufoff) + ldsw + _i * 8192); } while (0)
; #define PG8_LDA(dst, b, h) do { const int a1_ = opqv(aoff0) ^ 64; _Pragma("unroll") for (int m = 0; m < 4; ++m) { dst[m][0] = *(const LAS bf16x8*)(lds + PG8_SA(b, h) + aoff0 + m * 2048); dst[m][1] = *(const LAS bf16x8*)(lds + PG8_SA(b, h) + a1_ + m * 2048); } } while (0)
; #define PG8_MMA(ai, bj, At, Bt) do { __builtin_amdgcn_s_setprio(1); _Pragma("unroll") for (int m = 0; m < 4; ++m) _Pragma("unroll") for (int n = 0; n < 2; ++n) _Pragma("unroll") for (int k = 0; k < 2; ++k) \
;         acc[ai][bj][m][n] = __builtin_amdgcn_mfma_f32_16x16x32_bf16(Bt[n][k], At[m][k], acc[ai][bj][m][n], 0, 0, 0); __builtin_amdgcn_s_setprio(0); } while (0)
; #define PG8_WAIT_V(n) asm volatile("s_waitcnt vmcnt(" #n ")" ::: "memory")
; #define PG8_WAIT_L(n) asm volatile("s_waitcnt lgkmcnt(" #n ")" ::: "memory")
; #define PG8_BAR __builtin_amdgcn_s_barrier()
; #define PG8_SCHED __builtin_amdgcn_sched_barrier(0)
; template <class Epi>
; __device__ __forceinline__ void gemm_phase(LAS unsigned char* lds, const Gemm g, const StaticOrder& S, const Epi& E, int wave_) {
;     ...
;             PG8_STAGE(PG8_SB(1, 0), b3, voffB); PG8_STAGE(PG8_SB(1, 1), b3 + hstepB, voffB); PG8_STAGE(PG8_SA(1, 0), a3, voffA); PG8_LDA(At, 1, 1);
;             PG8_WAIT_V(8); PG8_WAIT_L(0); PG8_BAR; PG8_MMA(1, 0, At, B0); PG8_MMA(1, 1, At, B1); PG8_BAR; PG8_SCHED;
;         }
	s_add_u32 s48, s48, 0x80080
	s_addc_u32 s49, s49, 0
	v_mov_b32_e32 v160, v237
	s_nop 0
	s_nop 0
	v_xad_u32 v190, v160, 64, 0
	ds_read_b128 v[160:163], v191 offset:49152
	ds_read_b128 v[164:167], v191 offset:51200
	ds_read_b128 v[168:171], v190 offset:49152
	ds_read_b128 v[172:175], v190 offset:51200
	ds_read_b128 v[176:179], v191 offset:53248
	ds_read_b128 v[180:183], v191 offset:55296
	ds_read_b128 v[192:195], v190 offset:53248
	ds_read_b128 v[196:199], v190 offset:55296
	s_mov_b32 m0, s35
	s_nop 0
	global_load_lds_dwordx4 v233, s[64:65]
	s_mov_b32 m0, s33
	s_nop 0
	global_load_lds_dwordx4 v235, s[64:65]
	s_mov_b32 m0, s77
	s_nop 0
	global_load_lds_dwordx4 v233, s[48:49]
	s_mov_b32 m0, s3
	s_nop 0
	global_load_lds_dwordx4 v235, s[48:49]
	s_mov_b32 m0, s22
	s_nop 0
	global_load_lds_dwordx4 v184, s[46:47]
	s_mov_b32 m0, s2
	s_nop 0
	global_load_lds_dwordx4 v234, s[46:47]
	s_waitcnt vmcnt(8)
	s_waitcnt lgkmcnt(0)
	s_barrier
	s_setprio 1
	s_waitcnt lgkmcnt(0)
	v_mfma_f32_16x16x32_bf16 v[116:119], v[88:91], v[160:163], v[116:119]
	v_mfma_f32_16x16x32_bf16 v[104:107], v[92:95], v[160:163], v[104:107]
	v_mfma_f32_16x16x32_bf16 v[84:87], v[88:91], v[164:167], v[84:87]
	v_mfma_f32_16x16x32_bf16 v[80:83], v[92:95], v[164:167], v[80:83]
	v_mfma_f32_16x16x32_bf16 v[76:79], v[88:91], v[176:179], v[76:79]
	v_mfma_f32_16x16x32_bf16 v[72:75], v[92:95], v[176:179], v[72:75]
	v_mfma_f32_16x16x32_bf16 v[68:71], v[88:91], v[180:183], v[68:71]
	v_mfma_f32_16x16x32_bf16 v[64:67], v[92:95], v[180:183], v[64:67]
	v_mfma_f32_16x16x32_bf16 v[116:119], v[96:99], v[168:171], v[116:119]
	v_mfma_f32_16x16x32_bf16 v[104:107], v[100:103], v[168:171], v[104:107]
	v_mfma_f32_16x16x32_bf16 v[84:87], v[96:99], v[172:175], v[84:87]
	v_mfma_f32_16x16x32_bf16 v[80:83], v[100:103], v[172:175], v[80:83]
	v_mfma_f32_16x16x32_bf16 v[76:79], v[96:99], v[192:195], v[76:79]
	v_mfma_f32_16x16x32_bf16 v[72:75], v[100:103], v[192:195], v[72:75]
	v_mfma_f32_16x16x32_bf16 v[68:71], v[96:99], v[196:199], v[68:71]
	v_mfma_f32_16x16x32_bf16 v[64:67], v[100:103], v[196:199], v[64:67]
	s_setprio 0
	s_setprio 1
	v_mfma_f32_16x16x32_bf16 v[28:31], v[108:111], v[160:163], v[28:31]
	v_mfma_f32_16x16x32_bf16 v[24:27], v[112:115], v[160:163], v[24:27]
	v_mfma_f32_16x16x32_bf16 v[20:23], v[108:111], v[164:167], v[20:23]
	v_mfma_f32_16x16x32_bf16 v[16:19], v[112:115], v[164:167], v[16:19]
	v_mfma_f32_16x16x32_bf16 v[12:15], v[108:111], v[176:179], v[12:15]
	v_mfma_f32_16x16x32_bf16 v[8:11], v[112:115], v[176:179], v[8:11]
	v_mfma_f32_16x16x32_bf16 v[4:7], v[108:111], v[180:183], v[4:7]
	v_mfma_f32_16x16x32_bf16 v[0:3], v[112:115], v[180:183], v[0:3]
	v_mfma_f32_16x16x32_bf16 v[28:31], v[120:123], v[168:171], v[28:31]
	v_mfma_f32_16x16x32_bf16 v[24:27], v[124:127], v[168:171], v[24:27]
	v_mfma_f32_16x16x32_bf16 v[20:23], v[120:123], v[172:175], v[20:23]
	v_mfma_f32_16x16x32_bf16 v[16:19], v[124:127], v[172:175], v[16:19]
	v_mfma_f32_16x16x32_bf16 v[12:15], v[120:123], v[192:195], v[12:15]
	v_mfma_f32_16x16x32_bf16 v[8:11], v[124:127], v[192:195], v[8:11]
	v_mfma_f32_16x16x32_bf16 v[4:7], v[120:123], v[196:199], v[4:7]
	v_mfma_f32_16x16x32_bf16 v[0:3], v[124:127], v[196:199], v[0:3]
	s_setprio 0
	s_barrier
	s_add_i32 s79, s79, 2
	s_add_u32 s75, s75, 0x100
	s_addc_u32 s78, s78, 0
	s_add_u32 s12, s12, 0x100
	s_addc_u32 s13, s13, 0
	s_cmp_gt_u32 s79, 29
	s_cbranch_scc0 .LBB0_1776
	v_readlane_b32 s12, v253, 13
	v_readlane_b32 s13, v253, 14
	s_and_b64 vcc, exec, s[12:13]
	s_cbranch_vccz .LBB0_1779
	s_barrier
